# GEMM epilogue output stores made write-through (sc1) so the grid barrier's L2 write-back after each GEMM phase finds little dirty data
# baseline (speedup 1.0000x reference)
; __device__ __forceinline__ unsigned cvt_pk_bf16(float lo, float hi) { const f32x2 v = {lo, hi}; const bf16v2_ r = __builtin_convertvector(v, bf16v2_); return __builtin_bit_cast(unsigned, r); }
;     __device__ __forceinline__ void operator()(const f32x4 (&acc)[2][2][4][2], const Unit& u, int wr, int wc, int ui, int) const {
;     ...
;             for (int m = 0; m < 4; ++m) { const int row = row0 + ai * HALF + m * 16; const float r = r_[ai][m];
; #pragma unroll
;                 for (int bj = 0; bj < 2; ++bj) { const f32x4 v0 = acc[ai][bj][m][0] * r, v1 = acc[ai][bj][m][1] * r;
;                     u32x4 w; w.x = cvt_pk_bf16(v0[0], v0[1]); w.y = cvt_pk_bf16(v0[2], v0[3]); w.z = cvt_pk_bf16(v1[0], v1[1]); w.w = cvt_pk_bf16(v1[2], v1[3]);
;                     bf16_t* p = cmp ? cb + ((size_t)((row / T) * 2 + bj) * T + (row % T)) * 128 + wc * 32 + 8 * fq
;                                     : O + (size_t)row * ldc + col0 + bj * HALF;
;                     *(u32x4*)p = w; } }
.LBB0_357:
	v_pk_mul_f32 v[130:131], v[130:131], v[164:165] op_sel_hi:[1,0]
	v_pk_mul_f32 v[128:129], v[128:129], v[164:165] op_sel_hi:[1,0]
	v_pk_mul_f32 v[172:173], v[126:127], v[164:165] op_sel_hi:[1,0]
	v_pk_mul_f32 v[126:127], v[124:125], v[164:165] op_sel_hi:[1,0]
	v_cndmask_b32_e64 v2, 0, 1, s[6:7]
	v_cvt_pk_bf16_f32 v124, v128, v129
	v_cvt_pk_bf16_f32 v125, v130, v131
	v_cvt_pk_bf16_f32 v126, v126, v127
	v_cvt_pk_bf16_f32 v127, v172, v173
	v_cmp_ne_u32_e64 s[44:45], 1, v2
	s_andn2_b64 vcc, exec, s[6:7]
	s_mov_b64 s[6:7], -1
	global_store_dwordx4 v[170:171], v[124:127], off sc1
	s_cbranch_vccnz .LBB0_359
	s_nop 0
	v_mov_b64_e32 v[124:125], s[92:93]
	s_movk_i32 s1, 0x3600
	v_mad_i64_i32 v[124:125], s[6:7], v148, s1, v[124:125]
	v_lshl_add_u64 v[124:125], v[146:147], 1, v[124:125]
	s_mov_b64 s[6:7], 0x100
	v_lshl_add_u64 v[124:125], v[124:125], 0, s[6:7]
	s_mov_b64 s[6:7], 0

; __device__ __forceinline__ unsigned cvt_pk_bf16(float lo, float hi) { const f32x2 v = {lo, hi}; const bf16v2_ r = __builtin_convertvector(v, bf16v2_); return __builtin_bit_cast(unsigned, r); }
;     __device__ __forceinline__ void operator()(const f32x4 (&acc)[2][2][4][2], const Unit& u, int wr, int wc, int ui, int) const {
;     ...
;             for (int m = 0; m < 4; ++m) { const int row = row0 + ai * HALF + m * 16; const float r = r_[ai][m];
; #pragma unroll
;                 for (int bj = 0; bj < 2; ++bj) { const f32x4 v0 = acc[ai][bj][m][0] * r, v1 = acc[ai][bj][m][1] * r;
;                     u32x4 w; w.x = cvt_pk_bf16(v0[0], v0[1]); w.y = cvt_pk_bf16(v0[2], v0[3]); w.z = cvt_pk_bf16(v1[0], v1[1]); w.w = cvt_pk_bf16(v1[2], v1[3]);
;                     bf16_t* p = cmp ? cb + ((size_t)((row / T) * 2 + bj) * T + (row % T)) * 128 + wc * 32 + 8 * fq
;                                     : O + (size_t)row * ldc + col0 + bj * HALF;
;                     *(u32x4*)p = w; } }
.LBB0_361:
	v_mov_b32_e32 v165, v164
	v_mov_b32_e32 v126, v164
	v_mov_b32_e32 v127, v164
	v_pk_mul_f32 v[122:123], v[122:123], v[126:127]
	v_pk_mul_f32 v[120:121], v[120:121], v[164:165]
	v_pk_mul_f32 v[126:127], v[118:119], v[126:127]
	v_pk_mul_f32 v[118:119], v[116:117], v[164:165]
	v_cvt_pk_bf16_f32 v116, v120, v121
	v_cvt_pk_bf16_f32 v117, v122, v123
	v_cvt_pk_bf16_f32 v118, v118, v119
	v_cvt_pk_bf16_f32 v119, v126, v127
	v_or_b32_e32 v122, 16, v148
	s_and_b64 vcc, exec, s[44:45]
	s_mov_b64 s[6:7], -1
	global_store_dwordx4 v[124:125], v[116:119], off sc1
	s_cbranch_vccnz .LBB0_363
	s_nop 0
	v_mov_b64_e32 v[116:117], s[92:93]
	s_movk_i32 s1, 0x3600
	v_mad_i64_i32 v[116:117], s[6:7], v122, s1, v[116:117]
	v_lshl_add_u64 v[120:121], v[146:147], 1, v[116:117]
	s_mov_b64 s[6:7], 0

; __device__ __forceinline__ unsigned cvt_pk_bf16(float lo, float hi) { const f32x2 v = {lo, hi}; const bf16v2_ r = __builtin_convertvector(v, bf16v2_); return __builtin_bit_cast(unsigned, r); }
;     __device__ __forceinline__ void operator()(const f32x4 (&acc)[2][2][4][2], const Unit& u, int wr, int wc, int ui, int) const {
;     ...
;             for (int m = 0; m < 4; ++m) { const int row = row0 + ai * HALF + m * 16; const float r = r_[ai][m];
; #pragma unroll
;                 for (int bj = 0; bj < 2; ++bj) { const f32x4 v0 = acc[ai][bj][m][0] * r, v1 = acc[ai][bj][m][1] * r;
;                     u32x4 w; w.x = cvt_pk_bf16(v0[0], v0[1]); w.y = cvt_pk_bf16(v0[2], v0[3]); w.z = cvt_pk_bf16(v1[0], v1[1]); w.w = cvt_pk_bf16(v1[2], v1[3]);
;                     bf16_t* p = cmp ? cb + ((size_t)((row / T) * 2 + bj) * T + (row % T)) * 128 + wc * 32 + 8 * fq
;                                     : O + (size_t)row * ldc + col0 + bj * HALF;
;                     *(u32x4*)p = w; } }
.LBB0_365:
	v_pk_mul_f32 v[114:115], v[114:115], v[162:163] op_sel_hi:[1,0]
	v_pk_mul_f32 v[112:113], v[112:113], v[162:163] op_sel_hi:[1,0]
	v_pk_mul_f32 v[124:125], v[110:111], v[162:163] op_sel_hi:[1,0]
	v_pk_mul_f32 v[110:111], v[108:109], v[162:163] op_sel_hi:[1,0]
	v_cvt_pk_bf16_f32 v108, v112, v113
	v_cvt_pk_bf16_f32 v109, v114, v115
	v_cvt_pk_bf16_f32 v110, v110, v111
	v_cvt_pk_bf16_f32 v111, v124, v125
	s_and_b64 vcc, exec, s[44:45]
	s_mov_b64 s[6:7], -1
	global_store_dwordx4 v[120:121], v[108:111], off sc1
	s_cbranch_vccnz .LBB0_367
	s_nop 0
	v_mov_b64_e32 v[108:109], s[92:93]
	s_movk_i32 s1, 0x3600
	v_mad_i64_i32 v[108:109], s[6:7], v122, s1, v[108:109]
	v_lshl_add_u64 v[108:109], v[146:147], 1, v[108:109]
	s_mov_b64 s[6:7], 0x100
	v_lshl_add_u64 v[108:109], v[108:109], 0, s[6:7]
	s_mov_b64 s[6:7], 0

; __device__ __forceinline__ unsigned cvt_pk_bf16(float lo, float hi) { const f32x2 v = {lo, hi}; const bf16v2_ r = __builtin_convertvector(v, bf16v2_); return __builtin_bit_cast(unsigned, r); }
;     __device__ __forceinline__ void operator()(const f32x4 (&acc)[2][2][4][2], const Unit& u, int wr, int wc, int ui, int) const {
;     ...
;             for (int m = 0; m < 4; ++m) { const int row = row0 + ai * HALF + m * 16; const float r = r_[ai][m];
; #pragma unroll
;                 for (int bj = 0; bj < 2; ++bj) { const f32x4 v0 = acc[ai][bj][m][0] * r, v1 = acc[ai][bj][m][1] * r;
;                     u32x4 w; w.x = cvt_pk_bf16(v0[0], v0[1]); w.y = cvt_pk_bf16(v0[2], v0[3]); w.z = cvt_pk_bf16(v1[0], v1[1]); w.w = cvt_pk_bf16(v1[2], v1[3]);
;                     bf16_t* p = cmp ? cb + ((size_t)((row / T) * 2 + bj) * T + (row % T)) * 128 + wc * 32 + 8 * fq
;                                     : O + (size_t)row * ldc + col0 + bj * HALF;
;                     *(u32x4*)p = w; } }
.LBB0_369:
	v_mov_b32_e32 v163, v162
	v_mov_b32_e32 v110, v162
	v_mov_b32_e32 v111, v162
	v_pk_mul_f32 v[106:107], v[106:107], v[110:111]
	v_pk_mul_f32 v[104:105], v[104:105], v[162:163]
	v_pk_mul_f32 v[110:111], v[102:103], v[110:111]
	v_pk_mul_f32 v[102:103], v[100:101], v[162:163]
	v_cvt_pk_bf16_f32 v100, v104, v105
	v_cvt_pk_bf16_f32 v101, v106, v107
	v_cvt_pk_bf16_f32 v102, v102, v103
	v_cvt_pk_bf16_f32 v103, v110, v111
	v_or_b32_e32 v106, 32, v148
	s_and_b64 vcc, exec, s[44:45]
	s_mov_b64 s[6:7], -1
	global_store_dwordx4 v[108:109], v[100:103], off sc1
	s_cbranch_vccnz .LBB0_371
	s_nop 0
	v_mov_b64_e32 v[100:101], s[92:93]
	s_movk_i32 s1, 0x3600
	v_mad_i64_i32 v[100:101], s[6:7], v106, s1, v[100:101]
	v_lshl_add_u64 v[104:105], v[146:147], 1, v[100:101]
	s_mov_b64 s[6:7], 0

; __device__ __forceinline__ unsigned cvt_pk_bf16(float lo, float hi) { const f32x2 v = {lo, hi}; const bf16v2_ r = __builtin_convertvector(v, bf16v2_); return __builtin_bit_cast(unsigned, r); }
;     __device__ __forceinline__ void operator()(const f32x4 (&acc)[2][2][4][2], const Unit& u, int wr, int wc, int ui, int) const {
;     ...
;             for (int m = 0; m < 4; ++m) { const int row = row0 + ai * HALF + m * 16; const float r = r_[ai][m];
; #pragma unroll
;                 for (int bj = 0; bj < 2; ++bj) { const f32x4 v0 = acc[ai][bj][m][0] * r, v1 = acc[ai][bj][m][1] * r;
;                     u32x4 w; w.x = cvt_pk_bf16(v0[0], v0[1]); w.y = cvt_pk_bf16(v0[2], v0[3]); w.z = cvt_pk_bf16(v1[0], v1[1]); w.w = cvt_pk_bf16(v1[2], v1[3]);
;                     bf16_t* p = cmp ? cb + ((size_t)((row / T) * 2 + bj) * T + (row % T)) * 128 + wc * 32 + 8 * fq
;                                     : O + (size_t)row * ldc + col0 + bj * HALF;
;                     *(u32x4*)p = w; } }
.LBB0_373:
	v_pk_mul_f32 v[98:99], v[98:99], v[160:161] op_sel_hi:[1,0]
	v_pk_mul_f32 v[96:97], v[96:97], v[160:161] op_sel_hi:[1,0]
	v_pk_mul_f32 v[108:109], v[94:95], v[160:161] op_sel_hi:[1,0]
	v_pk_mul_f32 v[94:95], v[92:93], v[160:161] op_sel_hi:[1,0]
	v_cvt_pk_bf16_f32 v92, v96, v97
	v_cvt_pk_bf16_f32 v93, v98, v99
	v_cvt_pk_bf16_f32 v94, v94, v95
	v_cvt_pk_bf16_f32 v95, v108, v109
	s_and_b64 vcc, exec, s[44:45]
	s_mov_b64 s[6:7], -1
	global_store_dwordx4 v[104:105], v[92:95], off sc1
	s_cbranch_vccnz .LBB0_375
	s_nop 0
	v_mov_b64_e32 v[92:93], s[92:93]
	s_movk_i32 s1, 0x3600
	v_mad_i64_i32 v[92:93], s[6:7], v106, s1, v[92:93]
	v_lshl_add_u64 v[92:93], v[146:147], 1, v[92:93]
	s_mov_b64 s[6:7], 0x100
	v_lshl_add_u64 v[92:93], v[92:93], 0, s[6:7]
	s_mov_b64 s[6:7], 0

; __device__ __forceinline__ unsigned cvt_pk_bf16(float lo, float hi) { const f32x2 v = {lo, hi}; const bf16v2_ r = __builtin_convertvector(v, bf16v2_); return __builtin_bit_cast(unsigned, r); }
;     __device__ __forceinline__ void operator()(const f32x4 (&acc)[2][2][4][2], const Unit& u, int wr, int wc, int ui, int) const {
;     ...
;             for (int m = 0; m < 4; ++m) { const int row = row0 + ai * HALF + m * 16; const float r = r_[ai][m];
; #pragma unroll
;                 for (int bj = 0; bj < 2; ++bj) { const f32x4 v0 = acc[ai][bj][m][0] * r, v1 = acc[ai][bj][m][1] * r;
;                     u32x4 w; w.x = cvt_pk_bf16(v0[0], v0[1]); w.y = cvt_pk_bf16(v0[2], v0[3]); w.z = cvt_pk_bf16(v1[0], v1[1]); w.w = cvt_pk_bf16(v1[2], v1[3]);
;                     bf16_t* p = cmp ? cb + ((size_t)((row / T) * 2 + bj) * T + (row % T)) * 128 + wc * 32 + 8 * fq
;                                     : O + (size_t)row * ldc + col0 + bj * HALF;
;                     *(u32x4*)p = w; } }
.LBB0_377:
	v_mov_b32_e32 v161, v160
	v_mov_b32_e32 v94, v160
	v_mov_b32_e32 v95, v160
	v_pk_mul_f32 v[90:91], v[90:91], v[94:95]
	v_pk_mul_f32 v[88:89], v[88:89], v[160:161]
	v_pk_mul_f32 v[94:95], v[86:87], v[94:95]
	v_pk_mul_f32 v[86:87], v[84:85], v[160:161]
	v_cvt_pk_bf16_f32 v84, v88, v89
	v_cvt_pk_bf16_f32 v85, v90, v91
	v_cvt_pk_bf16_f32 v86, v86, v87
	v_cvt_pk_bf16_f32 v87, v94, v95
	v_or_b32_e32 v90, 48, v148
	s_and_b64 vcc, exec, s[44:45]
	s_mov_b64 s[6:7], -1
	global_store_dwordx4 v[92:93], v[84:87], off sc1
	s_cbranch_vccnz .LBB0_379
	s_nop 0
	v_mov_b64_e32 v[84:85], s[92:93]
	s_movk_i32 s1, 0x3600
	v_mad_i64_i32 v[84:85], s[6:7], v90, s1, v[84:85]
	v_lshl_add_u64 v[88:89], v[146:147], 1, v[84:85]
	s_mov_b64 s[6:7], 0

; __device__ __forceinline__ unsigned cvt_pk_bf16(float lo, float hi) { const f32x2 v = {lo, hi}; const bf16v2_ r = __builtin_convertvector(v, bf16v2_); return __builtin_bit_cast(unsigned, r); }
;     __device__ __forceinline__ void operator()(const f32x4 (&acc)[2][2][4][2], const Unit& u, int wr, int wc, int ui, int) const {
;     ...
;             for (int m = 0; m < 4; ++m) { const int row = row0 + ai * HALF + m * 16; const float r = r_[ai][m];
; #pragma unroll
;                 for (int bj = 0; bj < 2; ++bj) { const f32x4 v0 = acc[ai][bj][m][0] * r, v1 = acc[ai][bj][m][1] * r;
;                     u32x4 w; w.x = cvt_pk_bf16(v0[0], v0[1]); w.y = cvt_pk_bf16(v0[2], v0[3]); w.z = cvt_pk_bf16(v1[0], v1[1]); w.w = cvt_pk_bf16(v1[2], v1[3]);
;                     bf16_t* p = cmp ? cb + ((size_t)((row / T) * 2 + bj) * T + (row % T)) * 128 + wc * 32 + 8 * fq
;                                     : O + (size_t)row * ldc + col0 + bj * HALF;
;                     *(u32x4*)p = w; } }
.LBB0_381:
	v_pk_mul_f32 v[82:83], v[82:83], v[158:159] op_sel_hi:[1,0]
	v_pk_mul_f32 v[80:81], v[80:81], v[158:159] op_sel_hi:[1,0]
	v_pk_mul_f32 v[92:93], v[78:79], v[158:159] op_sel_hi:[1,0]
	v_pk_mul_f32 v[78:79], v[76:77], v[158:159] op_sel_hi:[1,0]
	v_cvt_pk_bf16_f32 v76, v80, v81
	v_cvt_pk_bf16_f32 v77, v82, v83
	v_cvt_pk_bf16_f32 v78, v78, v79
	v_cvt_pk_bf16_f32 v79, v92, v93
	s_and_b64 vcc, exec, s[44:45]
	s_mov_b64 s[6:7], -1
	global_store_dwordx4 v[88:89], v[76:79], off sc1
	s_cbranch_vccnz .LBB0_383
	s_nop 0
	v_mov_b64_e32 v[76:77], s[92:93]
	s_movk_i32 s1, 0x3600
	v_mad_i64_i32 v[76:77], s[6:7], v90, s1, v[76:77]
	v_lshl_add_u64 v[76:77], v[146:147], 1, v[76:77]
	s_mov_b64 s[6:7], 0x100
	v_lshl_add_u64 v[76:77], v[76:77], 0, s[6:7]
	s_mov_b64 s[6:7], 0

; __device__ __forceinline__ unsigned cvt_pk_bf16(float lo, float hi) { const f32x2 v = {lo, hi}; const bf16v2_ r = __builtin_convertvector(v, bf16v2_); return __builtin_bit_cast(unsigned, r); }
;     __device__ __forceinline__ void operator()(const f32x4 (&acc)[2][2][4][2], const Unit& u, int wr, int wc, int ui, int) const {
;     ...
;             for (int m = 0; m < 4; ++m) { const int row = row0 + ai * HALF + m * 16; const float r = r_[ai][m];
; #pragma unroll
;                 for (int bj = 0; bj < 2; ++bj) { const f32x4 v0 = acc[ai][bj][m][0] * r, v1 = acc[ai][bj][m][1] * r;
;                     u32x4 w; w.x = cvt_pk_bf16(v0[0], v0[1]); w.y = cvt_pk_bf16(v0[2], v0[3]); w.z = cvt_pk_bf16(v1[0], v1[1]); w.w = cvt_pk_bf16(v1[2], v1[3]);
;                     bf16_t* p = cmp ? cb + ((size_t)((row / T) * 2 + bj) * T + (row % T)) * 128 + wc * 32 + 8 * fq
;                                     : O + (size_t)row * ldc + col0 + bj * HALF;
;                     *(u32x4*)p = w; } }
.LBB0_385:
	v_mov_b32_e32 v159, v158
	v_mov_b32_e32 v78, v158
	v_mov_b32_e32 v79, v158
	v_pk_mul_f32 v[74:75], v[74:75], v[78:79]
	v_pk_mul_f32 v[72:73], v[72:73], v[158:159]
	v_pk_mul_f32 v[78:79], v[70:71], v[78:79]
	v_pk_mul_f32 v[70:71], v[68:69], v[158:159]
	v_cvt_pk_bf16_f32 v68, v72, v73
	v_cvt_pk_bf16_f32 v69, v74, v75
	v_cvt_pk_bf16_f32 v70, v70, v71
	v_cvt_pk_bf16_f32 v71, v78, v79
	v_add_u32_e32 v2, 0x80, v148
	s_and_b64 vcc, exec, s[44:45]
	s_mov_b64 s[6:7], -1
	global_store_dwordx4 v[76:77], v[68:71], off sc1
	s_cbranch_vccnz .LBB0_387
	s_nop 0
	v_mov_b64_e32 v[68:69], s[92:93]
	s_movk_i32 s1, 0x3600
	v_mad_i64_i32 v[68:69], s[6:7], v2, s1, v[68:69]
	v_lshl_add_u64 v[72:73], v[146:147], 1, v[68:69]
	s_mov_b64 s[6:7], 0

; __device__ __forceinline__ unsigned cvt_pk_bf16(float lo, float hi) { const f32x2 v = {lo, hi}; const bf16v2_ r = __builtin_convertvector(v, bf16v2_); return __builtin_bit_cast(unsigned, r); }
;     __device__ __forceinline__ void operator()(const f32x4 (&acc)[2][2][4][2], const Unit& u, int wr, int wc, int ui, int) const {
;     ...
;             for (int m = 0; m < 4; ++m) { const int row = row0 + ai * HALF + m * 16; const float r = r_[ai][m];
; #pragma unroll
;                 for (int bj = 0; bj < 2; ++bj) { const f32x4 v0 = acc[ai][bj][m][0] * r, v1 = acc[ai][bj][m][1] * r;
;                     u32x4 w; w.x = cvt_pk_bf16(v0[0], v0[1]); w.y = cvt_pk_bf16(v0[2], v0[3]); w.z = cvt_pk_bf16(v1[0], v1[1]); w.w = cvt_pk_bf16(v1[2], v1[3]);
;                     bf16_t* p = cmp ? cb + ((size_t)((row / T) * 2 + bj) * T + (row % T)) * 128 + wc * 32 + 8 * fq
;                                     : O + (size_t)row * ldc + col0 + bj * HALF;
;                     *(u32x4*)p = w; } }
.LBB0_389:
	v_pk_mul_f32 v[66:67], v[66:67], v[156:157] op_sel_hi:[1,0]
	v_pk_mul_f32 v[64:65], v[64:65], v[156:157] op_sel_hi:[1,0]
	v_pk_mul_f32 v[74:75], v[62:63], v[156:157] op_sel_hi:[1,0]
	v_pk_mul_f32 v[62:63], v[60:61], v[156:157] op_sel_hi:[1,0]
	v_cvt_pk_bf16_f32 v60, v64, v65
	v_cvt_pk_bf16_f32 v61, v66, v67
	v_cvt_pk_bf16_f32 v62, v62, v63
	v_cvt_pk_bf16_f32 v63, v74, v75
	s_and_b64 vcc, exec, s[44:45]
	s_mov_b64 s[6:7], -1
	global_store_dwordx4 v[72:73], v[60:63], off sc1
	s_cbranch_vccnz .LBB0_391
	s_nop 0
	v_mov_b64_e32 v[60:61], s[92:93]
	s_movk_i32 s1, 0x3600
	v_mad_i64_i32 v[60:61], s[6:7], v2, s1, v[60:61]
	v_lshl_add_u64 v[60:61], v[146:147], 1, v[60:61]
	s_mov_b64 s[6:7], 0x100
	v_lshl_add_u64 v[60:61], v[60:61], 0, s[6:7]
	s_mov_b64 s[6:7], 0

; __device__ __forceinline__ unsigned cvt_pk_bf16(float lo, float hi) { const f32x2 v = {lo, hi}; const bf16v2_ r = __builtin_convertvector(v, bf16v2_); return __builtin_bit_cast(unsigned, r); }
;     __device__ __forceinline__ void operator()(const f32x4 (&acc)[2][2][4][2], const Unit& u, int wr, int wc, int ui, int) const {
;     ...
;             for (int m = 0; m < 4; ++m) { const int row = row0 + ai * HALF + m * 16; const float r = r_[ai][m];
; #pragma unroll
;                 for (int bj = 0; bj < 2; ++bj) { const f32x4 v0 = acc[ai][bj][m][0] * r, v1 = acc[ai][bj][m][1] * r;
;                     u32x4 w; w.x = cvt_pk_bf16(v0[0], v0[1]); w.y = cvt_pk_bf16(v0[2], v0[3]); w.z = cvt_pk_bf16(v1[0], v1[1]); w.w = cvt_pk_bf16(v1[2], v1[3]);
;                     bf16_t* p = cmp ? cb + ((size_t)((row / T) * 2 + bj) * T + (row % T)) * 128 + wc * 32 + 8 * fq
;                                     : O + (size_t)row * ldc + col0 + bj * HALF;
;                     *(u32x4*)p = w; } }
.LBB0_393:
	v_mov_b32_e32 v157, v156
	v_mov_b32_e32 v62, v156
	v_mov_b32_e32 v63, v156
	v_pk_mul_f32 v[58:59], v[58:59], v[62:63]
	v_pk_mul_f32 v[56:57], v[56:57], v[156:157]
	v_pk_mul_f32 v[62:63], v[54:55], v[62:63]
	v_pk_mul_f32 v[54:55], v[52:53], v[156:157]
	v_cvt_pk_bf16_f32 v52, v56, v57
	v_cvt_pk_bf16_f32 v53, v58, v59
	v_cvt_pk_bf16_f32 v54, v54, v55
	v_cvt_pk_bf16_f32 v55, v62, v63
	v_add_u32_e32 v2, 0x90, v148
	s_and_b64 vcc, exec, s[44:45]
	s_mov_b64 s[6:7], -1
	global_store_dwordx4 v[60:61], v[52:55], off sc1
	s_cbranch_vccnz .LBB0_395
	s_nop 0
	v_mov_b64_e32 v[52:53], s[92:93]
	s_movk_i32 s1, 0x3600
	v_mad_i64_i32 v[52:53], s[6:7], v2, s1, v[52:53]
	v_lshl_add_u64 v[56:57], v[146:147], 1, v[52:53]
	s_mov_b64 s[6:7], 0

; __device__ __forceinline__ unsigned cvt_pk_bf16(float lo, float hi) { const f32x2 v = {lo, hi}; const bf16v2_ r = __builtin_convertvector(v, bf16v2_); return __builtin_bit_cast(unsigned, r); }
;     __device__ __forceinline__ void operator()(const f32x4 (&acc)[2][2][4][2], const Unit& u, int wr, int wc, int ui, int) const {
;     ...
;             for (int m = 0; m < 4; ++m) { const int row = row0 + ai * HALF + m * 16; const float r = r_[ai][m];
; #pragma unroll
;                 for (int bj = 0; bj < 2; ++bj) { const f32x4 v0 = acc[ai][bj][m][0] * r, v1 = acc[ai][bj][m][1] * r;
;                     u32x4 w; w.x = cvt_pk_bf16(v0[0], v0[1]); w.y = cvt_pk_bf16(v0[2], v0[3]); w.z = cvt_pk_bf16(v1[0], v1[1]); w.w = cvt_pk_bf16(v1[2], v1[3]);
;                     bf16_t* p = cmp ? cb + ((size_t)((row / T) * 2 + bj) * T + (row % T)) * 128 + wc * 32 + 8 * fq
;                                     : O + (size_t)row * ldc + col0 + bj * HALF;
;                     *(u32x4*)p = w; } }
.LBB0_397:
	v_pk_mul_f32 v[50:51], v[50:51], v[154:155] op_sel_hi:[1,0]
	v_pk_mul_f32 v[48:49], v[48:49], v[154:155] op_sel_hi:[1,0]
	v_pk_mul_f32 v[58:59], v[46:47], v[154:155] op_sel_hi:[1,0]
	v_pk_mul_f32 v[46:47], v[44:45], v[154:155] op_sel_hi:[1,0]
	v_cvt_pk_bf16_f32 v44, v48, v49
	v_cvt_pk_bf16_f32 v45, v50, v51
	v_cvt_pk_bf16_f32 v46, v46, v47
	v_cvt_pk_bf16_f32 v47, v58, v59
	s_and_b64 vcc, exec, s[44:45]
	s_mov_b64 s[6:7], -1
	global_store_dwordx4 v[56:57], v[44:47], off sc1
	s_cbranch_vccnz .LBB0_399
	s_nop 0
	v_mov_b64_e32 v[44:45], s[92:93]
	s_movk_i32 s1, 0x3600
	v_mad_i64_i32 v[44:45], s[6:7], v2, s1, v[44:45]
	v_lshl_add_u64 v[44:45], v[146:147], 1, v[44:45]
	s_mov_b64 s[6:7], 0x100
	v_lshl_add_u64 v[44:45], v[44:45], 0, s[6:7]
	s_mov_b64 s[6:7], 0

; __device__ __forceinline__ unsigned cvt_pk_bf16(float lo, float hi) { const f32x2 v = {lo, hi}; const bf16v2_ r = __builtin_convertvector(v, bf16v2_); return __builtin_bit_cast(unsigned, r); }
;     __device__ __forceinline__ void operator()(const f32x4 (&acc)[2][2][4][2], const Unit& u, int wr, int wc, int ui, int) const {
;     ...
;             for (int m = 0; m < 4; ++m) { const int row = row0 + ai * HALF + m * 16; const float r = r_[ai][m];
; #pragma unroll
;                 for (int bj = 0; bj < 2; ++bj) { const f32x4 v0 = acc[ai][bj][m][0] * r, v1 = acc[ai][bj][m][1] * r;
;                     u32x4 w; w.x = cvt_pk_bf16(v0[0], v0[1]); w.y = cvt_pk_bf16(v0[2], v0[3]); w.z = cvt_pk_bf16(v1[0], v1[1]); w.w = cvt_pk_bf16(v1[2], v1[3]);
;                     bf16_t* p = cmp ? cb + ((size_t)((row / T) * 2 + bj) * T + (row % T)) * 128 + wc * 32 + 8 * fq
;                                     : O + (size_t)row * ldc + col0 + bj * HALF;
;                     *(u32x4*)p = w; } }
.LBB0_401:
	v_mov_b32_e32 v155, v154
	v_mov_b32_e32 v46, v154
	v_mov_b32_e32 v47, v154
	v_pk_mul_f32 v[42:43], v[42:43], v[46:47]
	v_pk_mul_f32 v[40:41], v[40:41], v[154:155]
	v_pk_mul_f32 v[46:47], v[38:39], v[46:47]
	v_pk_mul_f32 v[38:39], v[36:37], v[154:155]
	v_cvt_pk_bf16_f32 v36, v40, v41
	v_cvt_pk_bf16_f32 v37, v42, v43
	v_cvt_pk_bf16_f32 v38, v38, v39
	v_cvt_pk_bf16_f32 v39, v46, v47
	v_add_u32_e32 v2, 0xa0, v148
	s_and_b64 vcc, exec, s[44:45]
	s_mov_b64 s[6:7], -1
	global_store_dwordx4 v[44:45], v[36:39], off sc1
	s_cbranch_vccnz .LBB0_403
	s_nop 0
	v_mov_b64_e32 v[36:37], s[92:93]
	s_movk_i32 s1, 0x3600
	v_mad_i64_i32 v[36:37], s[6:7], v2, s1, v[36:37]
	v_lshl_add_u64 v[40:41], v[146:147], 1, v[36:37]
	s_mov_b64 s[6:7], 0

; __device__ __forceinline__ unsigned cvt_pk_bf16(float lo, float hi) { const f32x2 v = {lo, hi}; const bf16v2_ r = __builtin_convertvector(v, bf16v2_); return __builtin_bit_cast(unsigned, r); }
;     __device__ __forceinline__ void operator()(const f32x4 (&acc)[2][2][4][2], const Unit& u, int wr, int wc, int ui, int) const {
;     ...
;             for (int m = 0; m < 4; ++m) { const int row = row0 + ai * HALF + m * 16; const float r = r_[ai][m];
; #pragma unroll
;                 for (int bj = 0; bj < 2; ++bj) { const f32x4 v0 = acc[ai][bj][m][0] * r, v1 = acc[ai][bj][m][1] * r;
;                     u32x4 w; w.x = cvt_pk_bf16(v0[0], v0[1]); w.y = cvt_pk_bf16(v0[2], v0[3]); w.z = cvt_pk_bf16(v1[0], v1[1]); w.w = cvt_pk_bf16(v1[2], v1[3]);
;                     bf16_t* p = cmp ? cb + ((size_t)((row / T) * 2 + bj) * T + (row % T)) * 128 + wc * 32 + 8 * fq
;                                     : O + (size_t)row * ldc + col0 + bj * HALF;
;                     *(u32x4*)p = w; } }
.LBB0_405:
	v_pk_mul_f32 v[34:35], v[34:35], v[152:153] op_sel_hi:[1,0]
	v_pk_mul_f32 v[32:33], v[32:33], v[152:153] op_sel_hi:[1,0]
	v_pk_mul_f32 v[42:43], v[30:31], v[152:153] op_sel_hi:[1,0]
	v_pk_mul_f32 v[30:31], v[28:29], v[152:153] op_sel_hi:[1,0]
	v_cvt_pk_bf16_f32 v28, v32, v33
	v_cvt_pk_bf16_f32 v29, v34, v35
	v_cvt_pk_bf16_f32 v30, v30, v31
	v_cvt_pk_bf16_f32 v31, v42, v43
	s_and_b64 vcc, exec, s[44:45]
	s_mov_b64 s[6:7], -1
	global_store_dwordx4 v[40:41], v[28:31], off sc1
	s_cbranch_vccnz .LBB0_407
	s_nop 0
	v_mov_b64_e32 v[28:29], s[92:93]
	s_movk_i32 s1, 0x3600
	v_mad_i64_i32 v[28:29], s[6:7], v2, s1, v[28:29]
	v_lshl_add_u64 v[28:29], v[146:147], 1, v[28:29]
	s_mov_b64 s[6:7], 0x100
	v_lshl_add_u64 v[28:29], v[28:29], 0, s[6:7]
	s_mov_b64 s[6:7], 0

; __device__ __forceinline__ unsigned cvt_pk_bf16(float lo, float hi) { const f32x2 v = {lo, hi}; const bf16v2_ r = __builtin_convertvector(v, bf16v2_); return __builtin_bit_cast(unsigned, r); }
;     __device__ __forceinline__ void operator()(const f32x4 (&acc)[2][2][4][2], const Unit& u, int wr, int wc, int ui, int) const {
;     ...
;             for (int m = 0; m < 4; ++m) { const int row = row0 + ai * HALF + m * 16; const float r = r_[ai][m];
; #pragma unroll
;                 for (int bj = 0; bj < 2; ++bj) { const f32x4 v0 = acc[ai][bj][m][0] * r, v1 = acc[ai][bj][m][1] * r;
;                     u32x4 w; w.x = cvt_pk_bf16(v0[0], v0[1]); w.y = cvt_pk_bf16(v0[2], v0[3]); w.z = cvt_pk_bf16(v1[0], v1[1]); w.w = cvt_pk_bf16(v1[2], v1[3]);
;                     bf16_t* p = cmp ? cb + ((size_t)((row / T) * 2 + bj) * T + (row % T)) * 128 + wc * 32 + 8 * fq
;                                     : O + (size_t)row * ldc + col0 + bj * HALF;
;                     *(u32x4*)p = w; } }
.LBB0_409:
	v_mov_b32_e32 v153, v152
	v_mov_b32_e32 v30, v152
	v_mov_b32_e32 v31, v152
	v_pk_mul_f32 v[26:27], v[26:27], v[30:31]
	v_pk_mul_f32 v[24:25], v[24:25], v[152:153]
	v_pk_mul_f32 v[30:31], v[22:23], v[30:31]
	v_pk_mul_f32 v[22:23], v[20:21], v[152:153]
	v_cvt_pk_bf16_f32 v20, v24, v25
	v_cvt_pk_bf16_f32 v21, v26, v27
	v_cvt_pk_bf16_f32 v22, v22, v23
	v_cvt_pk_bf16_f32 v23, v30, v31
	v_add_u32_e32 v2, 0xb0, v148
	s_and_b64 vcc, exec, s[44:45]
	s_mov_b64 s[6:7], -1
	global_store_dwordx4 v[28:29], v[20:23], off sc1
	s_cbranch_vccnz .LBB0_411
	s_nop 0
	v_mov_b64_e32 v[20:21], s[92:93]
	s_movk_i32 s1, 0x3600
	v_mad_i64_i32 v[20:21], s[6:7], v2, s1, v[20:21]
	v_lshl_add_u64 v[24:25], v[146:147], 1, v[20:21]
	s_mov_b64 s[6:7], 0

; __device__ __forceinline__ unsigned cvt_pk_bf16(float lo, float hi) { const f32x2 v = {lo, hi}; const bf16v2_ r = __builtin_convertvector(v, bf16v2_); return __builtin_bit_cast(unsigned, r); }
;     __device__ __forceinline__ void operator()(const f32x4 (&acc)[2][2][4][2], const Unit& u, int wr, int wc, int ui, int) const {
;     ...
;             for (int m = 0; m < 4; ++m) { const int row = row0 + ai * HALF + m * 16; const float r = r_[ai][m];
; #pragma unroll
;                 for (int bj = 0; bj < 2; ++bj) { const f32x4 v0 = acc[ai][bj][m][0] * r, v1 = acc[ai][bj][m][1] * r;
;                     u32x4 w; w.x = cvt_pk_bf16(v0[0], v0[1]); w.y = cvt_pk_bf16(v0[2], v0[3]); w.z = cvt_pk_bf16(v1[0], v1[1]); w.w = cvt_pk_bf16(v1[2], v1[3]);
;                     bf16_t* p = cmp ? cb + ((size_t)((row / T) * 2 + bj) * T + (row % T)) * 128 + wc * 32 + 8 * fq
;                                     : O + (size_t)row * ldc + col0 + bj * HALF;
;                     *(u32x4*)p = w; } }
.LBB0_413:
	v_pk_mul_f32 v[18:19], v[18:19], v[144:145] op_sel_hi:[1,0]
	v_pk_mul_f32 v[16:17], v[16:17], v[144:145] op_sel_hi:[1,0]
	v_pk_mul_f32 v[26:27], v[14:15], v[144:145] op_sel_hi:[1,0]
	v_pk_mul_f32 v[14:15], v[12:13], v[144:145] op_sel_hi:[1,0]
	v_cvt_pk_bf16_f32 v12, v16, v17
	v_cvt_pk_bf16_f32 v13, v18, v19
	v_cvt_pk_bf16_f32 v14, v14, v15
	v_cvt_pk_bf16_f32 v15, v26, v27
	s_and_b64 vcc, exec, s[44:45]
	s_mov_b64 s[6:7], -1
	global_store_dwordx4 v[24:25], v[12:15], off sc1
	s_cbranch_vccnz .LBB0_415
	s_nop 0
	v_mov_b64_e32 v[12:13], s[92:93]
	s_movk_i32 s1, 0x3600
	v_mad_i64_i32 v[12:13], s[6:7], v2, s1, v[12:13]
	v_lshl_add_u64 v[12:13], v[146:147], 1, v[12:13]
	s_mov_b64 s[6:7], 0x100
	v_lshl_add_u64 v[12:13], v[12:13], 0, s[6:7]
	s_mov_b64 s[6:7], 0

; __device__ __forceinline__ unsigned cvt_pk_bf16(float lo, float hi) { const f32x2 v = {lo, hi}; const bf16v2_ r = __builtin_convertvector(v, bf16v2_); return __builtin_bit_cast(unsigned, r); }
; __device__ __forceinline__ float gelu_tanh(float x) { const float y = 0.7978845608028654f * (x + 0.044715f * x * x * x); return x * __builtin_amdgcn_rcpf(1.f + __expf(-2.f * y)); }
;     __device__ __forceinline__ void operator()(const f32x4 (&acc)[2][2][4][2], const Unit& u, int wr, int wc, int, int) const {
;     ...
;         for (int bj = 0; bj < 2; ++bj) { f32x4 b0 = (f32x4){0.f, 0.f, 0.f, 0.f}, b1 = b0;
; #pragma unroll 8
;             for (int pp = 0; pp < 32; ++pp) { b0 += *(const f32x4*)(bias + pp * 256 + col0 + bj * HALF); b1 += *(const f32x4*)(bias + pp * 256 + col0 + bj * HALF + 4); }
; #pragma unroll
;             for (int ai = 0; ai < 2; ++ai)
; #pragma unroll
;                 for (int m = 0; m < 4; ++m) { const f32x4 v0 = acc[ai][bj][m][0] + b0, v1 = acc[ai][bj][m][1] + b1;
;                     u32x4 w; w.x = cvt_pk_bf16(gelu_tanh(v0[0]), gelu_tanh(v0[1])); w.y = cvt_pk_bf16(gelu_tanh(v0[2]), gelu_tanh(v0[3]));
;                     w.z = cvt_pk_bf16(gelu_tanh(v1[0]), gelu_tanh(v1[1])); w.w = cvt_pk_bf16(gelu_tanh(v1[2]), gelu_tanh(v1[3]));
;                     *(u32x4*)(O + (size_t)(row0 + ai * HALF + m * 16) * ldc + col0 + bj * HALF) = w; } }
.LBB0_493:
	v_lshl_add_u64 v[152:153], v[142:143], 0, s[4:5]
	s_mov_b64 s[6:7], 0x18c90000
	v_add_co_u32_e32 v166, vcc, 0x18c90000, v152
	v_lshl_add_u64 v[162:163], v[152:153], 0, s[6:7]
	s_nop 0
	v_addc_co_u32_e32 v167, vcc, 0, v153, vcc
	global_load_dwordx4 v[158:161], v[166:167], off
	s_nop 0
	global_load_dwordx4 v[162:165], v[162:163], off offset:16
	s_mov_b64 s[6:7], 0x18c90400
	s_add_u32 s4, s4, 0x2000
	s_addc_u32 s5, s5, 0
	s_cmpk_eq_u32 s4, 0x8000
	s_waitcnt vmcnt(0)
	v_pk_add_f32 v[158:159], v[148:149], v[158:159]
	v_lshl_add_u64 v[148:149], v[152:153], 0, s[6:7]
	v_pk_add_f32 v[160:161], v[150:151], v[160:161]
	v_pk_add_f32 v[162:163], v[144:145], v[162:163]
	v_pk_add_f32 v[164:165], v[146:147], v[164:165]
	global_load_dwordx4 v[144:147], v[166:167], off offset:1024
	s_nop 0
	global_load_dwordx4 v[148:151], v[148:149], off offset:16
	s_mov_b64 s[6:7], 0x18c90800
	s_waitcnt vmcnt(0)
	v_pk_add_f32 v[160:161], v[160:161], v[146:147]
	v_pk_add_f32 v[162:163], v[162:163], v[148:149]
	v_lshl_add_u64 v[148:149], v[152:153], 0, s[6:7]
	v_pk_add_f32 v[158:159], v[158:159], v[144:145]
	v_pk_add_f32 v[164:165], v[164:165], v[150:151]
	global_load_dwordx4 v[144:147], v[166:167], off offset:2048
	s_nop 0
	global_load_dwordx4 v[148:151], v[148:149], off offset:16
	s_mov_b64 s[6:7], 0x18c90c00
	s_waitcnt vmcnt(0)
	v_pk_add_f32 v[160:161], v[160:161], v[146:147]
	v_pk_add_f32 v[162:163], v[162:163], v[148:149]
	v_lshl_add_u64 v[148:149], v[152:153], 0, s[6:7]
	v_pk_add_f32 v[158:159], v[158:159], v[144:145]
	v_pk_add_f32 v[164:165], v[164:165], v[150:151]
	global_load_dwordx4 v[144:147], v[166:167], off offset:3072
	s_nop 0
	global_load_dwordx4 v[148:151], v[148:149], off offset:16
	s_mov_b64 s[6:7], 0x18c91000
	v_add_co_u32_e32 v166, vcc, s26, v152
	s_waitcnt vmcnt(0)
	v_pk_add_f32 v[160:161], v[160:161], v[146:147]
	v_pk_add_f32 v[162:163], v[162:163], v[148:149]
	v_lshl_add_u64 v[148:149], v[152:153], 0, s[6:7]
	v_addc_co_u32_e32 v167, vcc, 0, v153, vcc
	v_pk_add_f32 v[158:159], v[158:159], v[144:145]
	v_pk_add_f32 v[164:165], v[164:165], v[150:151]
	global_load_dwordx4 v[144:147], v[166:167], off
	s_nop 0
	global_load_dwordx4 v[148:151], v[148:149], off offset:16
	s_mov_b64 s[6:7], 0x18c91400
	s_waitcnt vmcnt(0)
	v_pk_add_f32 v[160:161], v[160:161], v[146:147]
	v_pk_add_f32 v[162:163], v[162:163], v[148:149]
	v_lshl_add_u64 v[148:149], v[152:153], 0, s[6:7]
	v_pk_add_f32 v[158:159], v[158:159], v[144:145]
	v_pk_add_f32 v[164:165], v[164:165], v[150:151]
	global_load_dwordx4 v[144:147], v[166:167], off offset:1024
	s_nop 0
	global_load_dwordx4 v[148:151], v[148:149], off offset:16
	s_mov_b64 s[6:7], 0x18c91800
	s_waitcnt vmcnt(0)
	v_pk_add_f32 v[160:161], v[160:161], v[146:147]
	v_pk_add_f32 v[162:163], v[162:163], v[148:149]
	v_lshl_add_u64 v[148:149], v[152:153], 0, s[6:7]
	v_pk_add_f32 v[158:159], v[158:159], v[144:145]
	v_pk_add_f32 v[164:165], v[164:165], v[150:151]
	global_load_dwordx4 v[144:147], v[166:167], off offset:2048
	s_nop 0
	global_load_dwordx4 v[148:151], v[148:149], off offset:16
	s_mov_b64 s[6:7], 0x18c91c00
	s_waitcnt vmcnt(0)
	v_pk_add_f32 v[168:169], v[160:161], v[146:147]
	v_pk_add_f32 v[170:171], v[158:159], v[144:145]
	v_pk_add_f32 v[162:163], v[162:163], v[148:149]
	v_lshl_add_u64 v[148:149], v[152:153], 0, s[6:7]
	global_load_dwordx4 v[144:147], v[166:167], off offset:3072
	global_load_dwordx4 v[158:161], v[148:149], off offset:16
	v_pk_add_f32 v[164:165], v[164:165], v[150:151]
	s_waitcnt vmcnt(0)
	v_pk_add_f32 v[150:151], v[168:169], v[146:147]
	v_pk_add_f32 v[148:149], v[170:171], v[144:145]
	v_pk_add_f32 v[146:147], v[164:165], v[160:161]
	v_pk_add_f32 v[144:145], v[162:163], v[158:159]
	s_cbranch_scc0 .LBB0_493
	v_pk_add_f32 v[128:129], v[128:129], v[148:149]
	v_pk_add_f32 v[130:131], v[130:131], v[150:151]
	v_mul_f32_e32 v153, 0x3d372713, v128
	v_mul_f32_e32 v153, v128, v153
	v_fma_f32 v153, v128, v153, v128
	v_mul_f32_e32 v153, 0x3f4c422a, v153
	v_mul_f32_e32 v153, -2.0, v153
	v_mul_f32_e32 v153, 0x3fb8aa3b, v153
	v_exp_f32_e32 v153, v153
	v_pk_add_f32 v[124:125], v[124:125], v[144:145]
	v_pk_add_f32 v[126:127], v[126:127], v[146:147]
	s_lshl_b32 s0, s0, 8
	v_add_f32_e32 v153, 1.0, v153
	v_rcp_f32_e32 v158, v153
	v_mul_f32_e32 v153, 0x3d372713, v129
	v_mul_f32_e32 v153, v129, v153
	v_fma_f32 v153, v129, v153, v129
	v_mul_f32_e32 v153, 0x3f4c422a, v153
	v_mul_f32_e32 v153, -2.0, v153
	v_mul_f32_e32 v153, 0x3fb8aa3b, v153
	v_exp_f32_e32 v153, v153
	s_add_i32 s0, s0, s60
	v_and_or_b32 v152, v157, 15, s0
	v_pk_add_f32 v[120:121], v[120:121], v[148:149]
	v_add_f32_e32 v153, 1.0, v153
	v_rcp_f32_e32 v159, v153
	v_ashrrev_i32_e32 v153, 31, v152
	v_pk_add_f32 v[122:123], v[122:123], v[150:151]
	v_pk_add_f32 v[116:117], v[116:117], v[144:145]
	v_pk_mul_f32 v[128:129], v[128:129], v[158:159]
	v_pk_add_f32 v[112:113], v[112:113], v[148:149]
	v_cvt_pk_bf16_f32 v128, v128, v129
	v_mul_f32_e32 v129, 0x3d372713, v130
	v_mul_f32_e32 v129, v130, v129
	v_fma_f32 v129, v130, v129, v130
	v_mul_f32_e32 v129, 0x3f4c422a, v129
	v_mul_f32_e32 v129, -2.0, v129
	v_mul_f32_e32 v129, 0x3fb8aa3b, v129
	v_exp_f32_e32 v129, v129
	v_pk_add_f32 v[114:115], v[114:115], v[150:151]
	v_pk_add_f32 v[108:109], v[108:109], v[144:145]
	v_pk_add_f32 v[104:105], v[104:105], v[148:149]
	v_add_f32_e32 v129, 1.0, v129
	v_rcp_f32_e32 v158, v129
	v_mul_f32_e32 v129, 0x3d372713, v131
	v_mul_f32_e32 v129, v131, v129
	v_fma_f32 v129, v131, v129, v131
	v_mul_f32_e32 v129, 0x3f4c422a, v129
	v_mul_f32_e32 v129, -2.0, v129
	v_mul_f32_e32 v129, 0x3fb8aa3b, v129
	v_exp_f32_e32 v129, v129
	v_pk_add_f32 v[106:107], v[106:107], v[150:151]
; __device__ __forceinline__ unsigned cvt_pk_bf16(float lo, float hi) { const f32x2 v = {lo, hi}; const bf16v2_ r = __builtin_convertvector(v, bf16v2_); return __builtin_bit_cast(unsigned, r); }
; __device__ __forceinline__ float gelu_tanh(float x) { const float y = 0.7978845608028654f * (x + 0.044715f * x * x * x); return x * __builtin_amdgcn_rcpf(1.f + __expf(-2.f * y)); }
;     __device__ __forceinline__ void operator()(const f32x4 (&acc)[2][2][4][2], const Unit& u, int wr, int wc, int, int) const {
;     ...
;             for (int ai = 0; ai < 2; ++ai)
; #pragma unroll
;                 for (int m = 0; m < 4; ++m) { const f32x4 v0 = acc[ai][bj][m][0] + b0, v1 = acc[ai][bj][m][1] + b1;
;                     u32x4 w; w.x = cvt_pk_bf16(gelu_tanh(v0[0]), gelu_tanh(v0[1])); w.y = cvt_pk_bf16(gelu_tanh(v0[2]), gelu_tanh(v0[3]));
;                     w.z = cvt_pk_bf16(gelu_tanh(v1[0]), gelu_tanh(v1[1])); w.w = cvt_pk_bf16(gelu_tanh(v1[2]), gelu_tanh(v1[3]));
;                     *(u32x4*)(O + (size_t)(row0 + ai * HALF + m * 16) * ldc + col0 + bj * HALF) = w; } }
	v_pk_add_f32 v[100:101], v[100:101], v[144:145]
	v_pk_add_f32 v[96:97], v[96:97], v[148:149]
	v_add_f32_e32 v129, 1.0, v129
	v_rcp_f32_e32 v159, v129
	v_pk_add_f32 v[98:99], v[98:99], v[150:151]
	v_pk_add_f32 v[92:93], v[92:93], v[144:145]
	s_mov_b64 s[0:1], 0x10000
	v_pk_mul_f32 v[130:131], v[130:131], v[158:159]
	v_pk_add_f32 v[88:89], v[88:89], v[148:149]
	v_cvt_pk_bf16_f32 v129, v130, v131
	v_mul_f32_e32 v130, 0x3d372713, v124
	v_mul_f32_e32 v131, 0x3d372713, v125
	v_mul_f32_e32 v130, v124, v130
	v_mul_f32_e32 v131, v125, v131
	v_fma_f32 v130, v124, v130, v124
	v_fma_f32 v131, v125, v131, v125
	v_mul_f32_e32 v130, 0x3f4c422a, v130
	v_mul_f32_e32 v131, 0x3f4c422a, v131
	v_mul_f32_e32 v130, -2.0, v130
	v_mul_f32_e32 v131, -2.0, v131
	v_mul_f32_e32 v130, 0x3fb8aa3b, v130
	v_mul_f32_e32 v131, 0x3fb8aa3b, v131
	v_exp_f32_e32 v130, v130
	v_exp_f32_e32 v131, v131
	v_pk_add_f32 v[90:91], v[90:91], v[150:151]
	v_pk_add_f32 v[84:85], v[84:85], v[144:145]
	v_add_f32_e32 v130, 1.0, v130
	v_add_f32_e32 v131, 1.0, v131
	v_rcp_f32_e32 v130, v130
	v_rcp_f32_e32 v131, v131
	v_pk_add_f32 v[80:81], v[80:81], v[148:149]
	v_pk_add_f32 v[82:83], v[82:83], v[150:151]
	v_pk_add_f32 v[76:77], v[76:77], v[144:145]
	v_pk_mul_f32 v[124:125], v[124:125], v[130:131]
	v_pk_add_f32 v[72:73], v[72:73], v[148:149]
	v_cvt_pk_bf16_f32 v130, v124, v125
	v_mul_f32_e32 v124, 0x3d372713, v126
	v_mul_f32_e32 v125, 0x3d372713, v127
	v_mul_f32_e32 v124, v126, v124
	v_mul_f32_e32 v125, v127, v125
	v_fma_f32 v124, v126, v124, v126
	v_fma_f32 v125, v127, v125, v127
	v_mul_f32_e32 v124, 0x3f4c422a, v124
	v_mul_f32_e32 v125, 0x3f4c422a, v125
	v_mul_f32_e32 v124, -2.0, v124
	v_mul_f32_e32 v125, -2.0, v125
	v_mul_f32_e32 v124, 0x3fb8aa3b, v124
	v_mul_f32_e32 v125, 0x3fb8aa3b, v125
	v_exp_f32_e32 v124, v124
	v_exp_f32_e32 v125, v125
	v_pk_add_f32 v[74:75], v[74:75], v[150:151]
	v_pk_add_f32 v[68:69], v[68:69], v[144:145]
	v_add_f32_e32 v124, 1.0, v124
	v_add_f32_e32 v125, 1.0, v125
	v_rcp_f32_e32 v124, v124
	v_rcp_f32_e32 v125, v125
	s_nop 0
	v_pk_mul_f32 v[124:125], v[126:127], v[124:125]
	s_nop 0
	v_cvt_pk_bf16_f32 v131, v124, v125
	v_lshlrev_b64 v[124:125], 9, v[152:153]
	v_lshl_add_u64 v[124:125], s[40:41], 0, v[124:125]
	v_lshlrev_b64 v[126:127], 1, v[154:155]
	v_lshl_add_u64 v[124:125], v[124:125], 0, v[126:127]
	global_store_dwordx4 v[124:125], v[128:131], off sc1
	s_nop 1
	v_pk_add_f32 v[128:129], v[118:119], v[146:147]
	v_mul_f32_e32 v118, 0x3d372713, v120
	v_mul_f32_e32 v119, 0x3d372713, v121
	v_mul_f32_e32 v118, v120, v118
	v_mul_f32_e32 v119, v121, v119
	v_fma_f32 v118, v120, v118, v120
	v_fma_f32 v119, v121, v119, v121
	v_mul_f32_e32 v118, 0x3f4c422a, v118
	v_mul_f32_e32 v119, 0x3f4c422a, v119
	v_mul_f32_e32 v118, -2.0, v118
	v_mul_f32_e32 v119, -2.0, v119
	v_mul_f32_e32 v118, 0x3fb8aa3b, v118
	v_mul_f32_e32 v119, 0x3fb8aa3b, v119
	v_exp_f32_e32 v118, v118
	v_exp_f32_e32 v119, v119
	v_add_f32_e32 v118, 1.0, v118
	v_add_f32_e32 v119, 1.0, v119
	v_rcp_f32_e32 v118, v118
	v_rcp_f32_e32 v119, v119
	s_nop 0
	v_pk_mul_f32 v[118:119], v[120:121], v[118:119]
	s_nop 0
	v_cvt_pk_bf16_f32 v118, v118, v119
	v_mul_f32_e32 v119, 0x3d372713, v122
	v_mul_f32_e32 v119, v122, v119
	v_fma_f32 v119, v122, v119, v122
	v_mul_f32_e32 v119, 0x3f4c422a, v119
	v_mul_f32_e32 v119, -2.0, v119
	v_mul_f32_e32 v119, 0x3fb8aa3b, v119
	v_exp_f32_e32 v119, v119
	s_nop 0
	v_add_f32_e32 v119, 1.0, v119
	v_rcp_f32_e32 v120, v119
	v_mul_f32_e32 v119, 0x3d372713, v123
	v_mul_f32_e32 v119, v123, v119
	v_fma_f32 v119, v123, v119, v123
	v_mul_f32_e32 v119, 0x3f4c422a, v119
	v_mul_f32_e32 v119, -2.0, v119
	v_mul_f32_e32 v119, 0x3fb8aa3b, v119
	v_exp_f32_e32 v119, v119
	s_nop 0
	v_add_f32_e32 v119, 1.0, v119
	v_rcp_f32_e32 v121, v119
	s_nop 0
	v_pk_mul_f32 v[120:121], v[122:123], v[120:121]
	s_nop 0
	v_cvt_pk_bf16_f32 v119, v120, v121
	v_mul_f32_e32 v120, 0x3d372713, v116
	v_mul_f32_e32 v121, 0x3d372713, v117
	v_mul_f32_e32 v120, v116, v120
	v_mul_f32_e32 v121, v117, v121
	v_fma_f32 v120, v116, v120, v116
	v_fma_f32 v121, v117, v121, v117
	v_mul_f32_e32 v120, 0x3f4c422a, v120
	v_mul_f32_e32 v121, 0x3f4c422a, v121
	v_mul_f32_e32 v120, -2.0, v120
	v_mul_f32_e32 v121, -2.0, v121
	v_mul_f32_e32 v120, 0x3fb8aa3b, v120
	v_mul_f32_e32 v121, 0x3fb8aa3b, v121
	v_exp_f32_e32 v120, v120
	v_exp_f32_e32 v121, v121
	v_add_f32_e32 v120, 1.0, v120
	v_add_f32_e32 v121, 1.0, v121
	v_rcp_f32_e32 v120, v120
	v_rcp_f32_e32 v121, v121
	s_nop 0
	v_pk_mul_f32 v[116:117], v[116:117], v[120:121]
	s_nop 0
	v_cvt_pk_bf16_f32 v120, v116, v117
	v_mul_f32_e32 v116, 0x3d372713, v128
	v_mul_f32_e32 v117, 0x3d372713, v129
	v_mul_f32_e32 v116, v128, v116
	v_mul_f32_e32 v117, v129, v117
	v_fma_f32 v116, v128, v116, v128
	v_fma_f32 v117, v129, v117, v129
	v_mul_f32_e32 v116, 0x3f4c422a, v116
	v_mul_f32_e32 v117, 0x3f4c422a, v117
	v_mul_f32_e32 v116, -2.0, v116
	v_mul_f32_e32 v117, -2.0, v117
	v_mul_f32_e32 v116, 0x3fb8aa3b, v116
	v_mul_f32_e32 v117, 0x3fb8aa3b, v117
	v_exp_f32_e32 v116, v116
	v_exp_f32_e32 v117, v117
	v_add_f32_e32 v116, 1.0, v116
	v_add_f32_e32 v117, 1.0, v117
	v_rcp_f32_e32 v116, v116
	v_rcp_f32_e32 v117, v117
	s_nop 0
	v_pk_mul_f32 v[116:117], v[128:129], v[116:117]
	s_nop 0
	v_cvt_pk_bf16_f32 v121, v116, v117
	v_or_b32_e32 v116, 16, v152
	v_ashrrev_i32_e32 v117, 31, v116
	v_lshlrev_b64 v[116:117], 9, v[116:117]
	v_lshl_add_u64 v[116:117], s[40:41], 0, v[116:117]
	v_lshl_add_u64 v[116:117], v[116:117], 0, v[126:127]
	global_store_dwordx4 v[116:117], v[118:121], off sc1
	s_nop 1
	v_pk_add_f32 v[118:119], v[110:111], v[146:147]
	v_mul_f32_e32 v110, 0x3d372713, v112
	v_mul_f32_e32 v111, 0x3d372713, v113
	v_mul_f32_e32 v110, v112, v110
; __device__ __forceinline__ unsigned cvt_pk_bf16(float lo, float hi) { const f32x2 v = {lo, hi}; const bf16v2_ r = __builtin_convertvector(v, bf16v2_); return __builtin_bit_cast(unsigned, r); }
; __device__ __forceinline__ float gelu_tanh(float x) { const float y = 0.7978845608028654f * (x + 0.044715f * x * x * x); return x * __builtin_amdgcn_rcpf(1.f + __expf(-2.f * y)); }
;     __device__ __forceinline__ void operator()(const f32x4 (&acc)[2][2][4][2], const Unit& u, int wr, int wc, int, int) const {
;     ...
;             for (int ai = 0; ai < 2; ++ai)
; #pragma unroll
;                 for (int m = 0; m < 4; ++m) { const f32x4 v0 = acc[ai][bj][m][0] + b0, v1 = acc[ai][bj][m][1] + b1;
;                     u32x4 w; w.x = cvt_pk_bf16(gelu_tanh(v0[0]), gelu_tanh(v0[1])); w.y = cvt_pk_bf16(gelu_tanh(v0[2]), gelu_tanh(v0[3]));
;                     w.z = cvt_pk_bf16(gelu_tanh(v1[0]), gelu_tanh(v1[1])); w.w = cvt_pk_bf16(gelu_tanh(v1[2]), gelu_tanh(v1[3]));
;                     *(u32x4*)(O + (size_t)(row0 + ai * HALF + m * 16) * ldc + col0 + bj * HALF) = w; } }
	v_mul_f32_e32 v111, v113, v111
	v_fma_f32 v110, v112, v110, v112
	v_fma_f32 v111, v113, v111, v113
	v_mul_f32_e32 v110, 0x3f4c422a, v110
	v_mul_f32_e32 v111, 0x3f4c422a, v111
	v_mul_f32_e32 v110, -2.0, v110
	v_mul_f32_e32 v111, -2.0, v111
	v_mul_f32_e32 v110, 0x3fb8aa3b, v110
	v_mul_f32_e32 v111, 0x3fb8aa3b, v111
	v_exp_f32_e32 v110, v110
	v_exp_f32_e32 v111, v111
	v_add_f32_e32 v110, 1.0, v110
	v_add_f32_e32 v111, 1.0, v111
	v_rcp_f32_e32 v110, v110
	v_rcp_f32_e32 v111, v111
	s_nop 0
	v_pk_mul_f32 v[110:111], v[112:113], v[110:111]
	s_nop 0
	v_cvt_pk_bf16_f32 v110, v110, v111
	v_mul_f32_e32 v111, 0x3d372713, v114
	v_mul_f32_e32 v111, v114, v111
	v_fma_f32 v111, v114, v111, v114
	v_mul_f32_e32 v111, 0x3f4c422a, v111
	v_mul_f32_e32 v111, -2.0, v111
	v_mul_f32_e32 v111, 0x3fb8aa3b, v111
	v_exp_f32_e32 v111, v111
	s_nop 0
	v_add_f32_e32 v111, 1.0, v111
	v_rcp_f32_e32 v112, v111
	v_mul_f32_e32 v111, 0x3d372713, v115
	v_mul_f32_e32 v111, v115, v111
	v_fma_f32 v111, v115, v111, v115
	v_mul_f32_e32 v111, 0x3f4c422a, v111
	v_mul_f32_e32 v111, -2.0, v111
	v_mul_f32_e32 v111, 0x3fb8aa3b, v111
	v_exp_f32_e32 v111, v111
	s_nop 0
	v_add_f32_e32 v111, 1.0, v111
	v_rcp_f32_e32 v113, v111
	s_nop 0
	v_pk_mul_f32 v[112:113], v[114:115], v[112:113]
	s_nop 0
	v_cvt_pk_bf16_f32 v111, v112, v113
	v_mul_f32_e32 v112, 0x3d372713, v108
	v_mul_f32_e32 v113, 0x3d372713, v109
	v_mul_f32_e32 v112, v108, v112
	v_mul_f32_e32 v113, v109, v113
	v_fma_f32 v112, v108, v112, v108
	v_fma_f32 v113, v109, v113, v109
	v_mul_f32_e32 v112, 0x3f4c422a, v112
	v_mul_f32_e32 v113, 0x3f4c422a, v113
	v_mul_f32_e32 v112, -2.0, v112
	v_mul_f32_e32 v113, -2.0, v113
	v_mul_f32_e32 v112, 0x3fb8aa3b, v112
	v_mul_f32_e32 v113, 0x3fb8aa3b, v113
	v_exp_f32_e32 v112, v112
	v_exp_f32_e32 v113, v113
	v_add_f32_e32 v112, 1.0, v112
	v_add_f32_e32 v113, 1.0, v113
	v_rcp_f32_e32 v112, v112
	v_rcp_f32_e32 v113, v113
	s_nop 0
	v_pk_mul_f32 v[108:109], v[108:109], v[112:113]
	s_nop 0
	v_cvt_pk_bf16_f32 v112, v108, v109
	v_mul_f32_e32 v108, 0x3d372713, v118
	v_mul_f32_e32 v109, 0x3d372713, v119
	v_mul_f32_e32 v108, v118, v108
	v_mul_f32_e32 v109, v119, v109
	v_fma_f32 v108, v118, v108, v118
	v_fma_f32 v109, v119, v109, v119
	v_mul_f32_e32 v108, 0x3f4c422a, v108
	v_mul_f32_e32 v109, 0x3f4c422a, v109
	v_mul_f32_e32 v108, -2.0, v108
	v_mul_f32_e32 v109, -2.0, v109
	v_mul_f32_e32 v108, 0x3fb8aa3b, v108
	v_mul_f32_e32 v109, 0x3fb8aa3b, v109
	v_exp_f32_e32 v108, v108
	v_exp_f32_e32 v109, v109
	v_add_f32_e32 v108, 1.0, v108
	v_add_f32_e32 v109, 1.0, v109
	v_rcp_f32_e32 v108, v108
	v_rcp_f32_e32 v109, v109
	s_nop 0
	v_pk_mul_f32 v[108:109], v[118:119], v[108:109]
	s_nop 0
	v_cvt_pk_bf16_f32 v113, v108, v109
	v_or_b32_e32 v108, 32, v152
	v_ashrrev_i32_e32 v109, 31, v108
	v_lshlrev_b64 v[108:109], 9, v[108:109]
	v_lshl_add_u64 v[108:109], s[40:41], 0, v[108:109]
	v_lshl_add_u64 v[108:109], v[108:109], 0, v[126:127]
	global_store_dwordx4 v[108:109], v[110:113], off sc1
	s_nop 1
	v_pk_add_f32 v[110:111], v[102:103], v[146:147]
	v_mul_f32_e32 v102, 0x3d372713, v104
	v_mul_f32_e32 v103, 0x3d372713, v105
	v_mul_f32_e32 v102, v104, v102
	v_mul_f32_e32 v103, v105, v103
	v_fma_f32 v102, v104, v102, v104
	v_fma_f32 v103, v105, v103, v105
	v_mul_f32_e32 v102, 0x3f4c422a, v102
	v_mul_f32_e32 v103, 0x3f4c422a, v103
	v_mul_f32_e32 v102, -2.0, v102
	v_mul_f32_e32 v103, -2.0, v103
	v_mul_f32_e32 v102, 0x3fb8aa3b, v102
	v_mul_f32_e32 v103, 0x3fb8aa3b, v103
	v_exp_f32_e32 v102, v102
	v_exp_f32_e32 v103, v103
	v_add_f32_e32 v102, 1.0, v102
	v_add_f32_e32 v103, 1.0, v103
	v_rcp_f32_e32 v102, v102
	v_rcp_f32_e32 v103, v103
	s_nop 0
	v_pk_mul_f32 v[102:103], v[104:105], v[102:103]
	s_nop 0
	v_cvt_pk_bf16_f32 v102, v102, v103
	v_mul_f32_e32 v103, 0x3d372713, v106
	v_mul_f32_e32 v103, v106, v103
	v_fma_f32 v103, v106, v103, v106
	v_mul_f32_e32 v103, 0x3f4c422a, v103
	v_mul_f32_e32 v103, -2.0, v103
	v_mul_f32_e32 v103, 0x3fb8aa3b, v103
	v_exp_f32_e32 v103, v103
	s_nop 0
	v_add_f32_e32 v103, 1.0, v103
	v_rcp_f32_e32 v104, v103
	v_mul_f32_e32 v103, 0x3d372713, v107
	v_mul_f32_e32 v103, v107, v103
	v_fma_f32 v103, v107, v103, v107
	v_mul_f32_e32 v103, 0x3f4c422a, v103
	v_mul_f32_e32 v103, -2.0, v103
	v_mul_f32_e32 v103, 0x3fb8aa3b, v103
	v_exp_f32_e32 v103, v103
	s_nop 0
	v_add_f32_e32 v103, 1.0, v103
	v_rcp_f32_e32 v105, v103
	s_nop 0
	v_pk_mul_f32 v[104:105], v[106:107], v[104:105]
	s_nop 0
	v_cvt_pk_bf16_f32 v103, v104, v105
	v_mul_f32_e32 v104, 0x3d372713, v100
	v_mul_f32_e32 v105, 0x3d372713, v101
	v_mul_f32_e32 v104, v100, v104
	v_mul_f32_e32 v105, v101, v105
	v_fma_f32 v104, v100, v104, v100
	v_fma_f32 v105, v101, v105, v101
	v_mul_f32_e32 v104, 0x3f4c422a, v104
	v_mul_f32_e32 v105, 0x3f4c422a, v105
	v_mul_f32_e32 v104, -2.0, v104
	v_mul_f32_e32 v105, -2.0, v105
	v_mul_f32_e32 v104, 0x3fb8aa3b, v104
	v_mul_f32_e32 v105, 0x3fb8aa3b, v105
	v_exp_f32_e32 v104, v104
	v_exp_f32_e32 v105, v105
	v_add_f32_e32 v104, 1.0, v104
	v_add_f32_e32 v105, 1.0, v105
	v_rcp_f32_e32 v104, v104
	v_rcp_f32_e32 v105, v105
	s_nop 0
	v_pk_mul_f32 v[100:101], v[100:101], v[104:105]
	s_nop 0
	v_cvt_pk_bf16_f32 v104, v100, v101
	v_mul_f32_e32 v100, 0x3d372713, v110
	v_mul_f32_e32 v101, 0x3d372713, v111
	v_mul_f32_e32 v100, v110, v100
	v_mul_f32_e32 v101, v111, v101
	v_fma_f32 v100, v110, v100, v110
	v_fma_f32 v101, v111, v101, v111
	v_mul_f32_e32 v100, 0x3f4c422a, v100
	v_mul_f32_e32 v101, 0x3f4c422a, v101
	v_mul_f32_e32 v100, -2.0, v100
	v_mul_f32_e32 v101, -2.0, v101
	v_mul_f32_e32 v100, 0x3fb8aa3b, v100
	v_mul_f32_e32 v101, 0x3fb8aa3b, v101
	v_exp_f32_e32 v100, v100
	v_exp_f32_e32 v101, v101
	v_add_f32_e32 v100, 1.0, v100
	v_add_f32_e32 v101, 1.0, v101
; __device__ __forceinline__ unsigned cvt_pk_bf16(float lo, float hi) { const f32x2 v = {lo, hi}; const bf16v2_ r = __builtin_convertvector(v, bf16v2_); return __builtin_bit_cast(unsigned, r); }
; __device__ __forceinline__ float gelu_tanh(float x) { const float y = 0.7978845608028654f * (x + 0.044715f * x * x * x); return x * __builtin_amdgcn_rcpf(1.f + __expf(-2.f * y)); }
;     __device__ __forceinline__ void operator()(const f32x4 (&acc)[2][2][4][2], const Unit& u, int wr, int wc, int, int) const {
;     ...
;             for (int ai = 0; ai < 2; ++ai)
; #pragma unroll
;                 for (int m = 0; m < 4; ++m) { const f32x4 v0 = acc[ai][bj][m][0] + b0, v1 = acc[ai][bj][m][1] + b1;
;                     u32x4 w; w.x = cvt_pk_bf16(gelu_tanh(v0[0]), gelu_tanh(v0[1])); w.y = cvt_pk_bf16(gelu_tanh(v0[2]), gelu_tanh(v0[3]));
;                     w.z = cvt_pk_bf16(gelu_tanh(v1[0]), gelu_tanh(v1[1])); w.w = cvt_pk_bf16(gelu_tanh(v1[2]), gelu_tanh(v1[3]));
;                     *(u32x4*)(O + (size_t)(row0 + ai * HALF + m * 16) * ldc + col0 + bj * HALF) = w; } }
	v_rcp_f32_e32 v100, v100
	v_rcp_f32_e32 v101, v101
	s_nop 0
	v_pk_mul_f32 v[100:101], v[110:111], v[100:101]
	s_nop 0
	v_cvt_pk_bf16_f32 v105, v100, v101
	v_or_b32_e32 v100, 48, v152
	v_ashrrev_i32_e32 v101, 31, v100
	v_lshlrev_b64 v[100:101], 9, v[100:101]
	v_lshl_add_u64 v[100:101], s[40:41], 0, v[100:101]
	v_lshl_add_u64 v[100:101], v[100:101], 0, v[126:127]
	global_store_dwordx4 v[100:101], v[102:105], off sc1
	s_nop 1
	v_pk_add_f32 v[102:103], v[94:95], v[146:147]
	v_mul_f32_e32 v94, 0x3d372713, v96
	v_mul_f32_e32 v95, 0x3d372713, v97
	v_mul_f32_e32 v94, v96, v94
	v_mul_f32_e32 v95, v97, v95
	v_fma_f32 v94, v96, v94, v96
	v_fma_f32 v95, v97, v95, v97
	v_mul_f32_e32 v94, 0x3f4c422a, v94
	v_mul_f32_e32 v95, 0x3f4c422a, v95
	v_mul_f32_e32 v94, -2.0, v94
	v_mul_f32_e32 v95, -2.0, v95
	v_mul_f32_e32 v94, 0x3fb8aa3b, v94
	v_mul_f32_e32 v95, 0x3fb8aa3b, v95
	v_exp_f32_e32 v94, v94
	v_exp_f32_e32 v95, v95
	v_add_f32_e32 v94, 1.0, v94
	v_add_f32_e32 v95, 1.0, v95
	v_rcp_f32_e32 v94, v94
	v_rcp_f32_e32 v95, v95
	s_nop 0
	v_pk_mul_f32 v[94:95], v[96:97], v[94:95]
	s_nop 0
	v_cvt_pk_bf16_f32 v94, v94, v95
	v_mul_f32_e32 v95, 0x3d372713, v98
	v_mul_f32_e32 v95, v98, v95
	v_fma_f32 v95, v98, v95, v98
	v_mul_f32_e32 v95, 0x3f4c422a, v95
	v_mul_f32_e32 v95, -2.0, v95
	v_mul_f32_e32 v95, 0x3fb8aa3b, v95
	v_exp_f32_e32 v95, v95
	s_nop 0
	v_add_f32_e32 v95, 1.0, v95
	v_rcp_f32_e32 v96, v95
	v_mul_f32_e32 v95, 0x3d372713, v99
	v_mul_f32_e32 v95, v99, v95
	v_fma_f32 v95, v99, v95, v99
	v_mul_f32_e32 v95, 0x3f4c422a, v95
	v_mul_f32_e32 v95, -2.0, v95
	v_mul_f32_e32 v95, 0x3fb8aa3b, v95
	v_exp_f32_e32 v95, v95
	s_nop 0
	v_add_f32_e32 v95, 1.0, v95
	v_rcp_f32_e32 v97, v95
	s_nop 0
	v_pk_mul_f32 v[96:97], v[98:99], v[96:97]
	s_nop 0
	v_cvt_pk_bf16_f32 v95, v96, v97
	v_mul_f32_e32 v96, 0x3d372713, v92
	v_mul_f32_e32 v97, 0x3d372713, v93
	v_mul_f32_e32 v96, v92, v96
	v_mul_f32_e32 v97, v93, v97
	v_fma_f32 v96, v92, v96, v92
	v_fma_f32 v97, v93, v97, v93
	v_mul_f32_e32 v96, 0x3f4c422a, v96
	v_mul_f32_e32 v97, 0x3f4c422a, v97
	v_mul_f32_e32 v96, -2.0, v96
	v_mul_f32_e32 v97, -2.0, v97
	v_mul_f32_e32 v96, 0x3fb8aa3b, v96
	v_mul_f32_e32 v97, 0x3fb8aa3b, v97
	v_exp_f32_e32 v96, v96
	v_exp_f32_e32 v97, v97
	v_add_f32_e32 v96, 1.0, v96
	v_add_f32_e32 v97, 1.0, v97
	v_rcp_f32_e32 v96, v96
	v_rcp_f32_e32 v97, v97
	s_nop 0
	v_pk_mul_f32 v[92:93], v[92:93], v[96:97]
	s_nop 0
	v_cvt_pk_bf16_f32 v96, v92, v93
	v_mul_f32_e32 v92, 0x3d372713, v102
	v_mul_f32_e32 v93, 0x3d372713, v103
	v_mul_f32_e32 v92, v102, v92
	v_mul_f32_e32 v93, v103, v93
	v_fma_f32 v92, v102, v92, v102
	v_fma_f32 v93, v103, v93, v103
	v_mul_f32_e32 v92, 0x3f4c422a, v92
	v_mul_f32_e32 v93, 0x3f4c422a, v93
	v_mul_f32_e32 v92, -2.0, v92
	v_mul_f32_e32 v93, -2.0, v93
	v_mul_f32_e32 v92, 0x3fb8aa3b, v92
	v_mul_f32_e32 v93, 0x3fb8aa3b, v93
	v_exp_f32_e32 v92, v92
	v_exp_f32_e32 v93, v93
	v_add_f32_e32 v92, 1.0, v92
	v_add_f32_e32 v93, 1.0, v93
	v_rcp_f32_e32 v92, v92
	v_rcp_f32_e32 v93, v93
	s_nop 0
	v_pk_mul_f32 v[92:93], v[102:103], v[92:93]
	s_nop 0
	v_cvt_pk_bf16_f32 v97, v92, v93
	v_lshl_add_u64 v[92:93], v[124:125], 0, s[0:1]
	s_mov_b32 s0, 0x10000
	v_add_co_u32_e32 v98, vcc, s0, v124
	s_mov_b64 s[0:1], 0x12000
	s_nop 0
	v_addc_co_u32_e32 v99, vcc, 0, v125, vcc
	global_store_dwordx4 v[98:99], v[94:97], off sc1
	s_nop 1
	v_pk_add_f32 v[94:95], v[86:87], v[146:147]
	v_mul_f32_e32 v86, 0x3d372713, v88
	v_mul_f32_e32 v87, 0x3d372713, v89
	v_mul_f32_e32 v86, v88, v86
	v_mul_f32_e32 v87, v89, v87
	v_fma_f32 v86, v88, v86, v88
	v_fma_f32 v87, v89, v87, v89
	v_mul_f32_e32 v86, 0x3f4c422a, v86
	v_mul_f32_e32 v87, 0x3f4c422a, v87
	v_mul_f32_e32 v86, -2.0, v86
	v_mul_f32_e32 v87, -2.0, v87
	v_mul_f32_e32 v86, 0x3fb8aa3b, v86
	v_mul_f32_e32 v87, 0x3fb8aa3b, v87
	v_exp_f32_e32 v86, v86
	v_exp_f32_e32 v87, v87
	v_add_f32_e32 v86, 1.0, v86
	v_add_f32_e32 v87, 1.0, v87
	v_rcp_f32_e32 v86, v86
	v_rcp_f32_e32 v87, v87
	s_nop 0
	v_pk_mul_f32 v[86:87], v[88:89], v[86:87]
	s_nop 0
	v_cvt_pk_bf16_f32 v86, v86, v87
	v_mul_f32_e32 v87, 0x3d372713, v90
	v_mul_f32_e32 v87, v90, v87
	v_fma_f32 v87, v90, v87, v90
	v_mul_f32_e32 v87, 0x3f4c422a, v87
	v_mul_f32_e32 v87, -2.0, v87
	v_mul_f32_e32 v87, 0x3fb8aa3b, v87
	v_exp_f32_e32 v87, v87
	s_nop 0
	v_add_f32_e32 v87, 1.0, v87
	v_rcp_f32_e32 v88, v87
	v_mul_f32_e32 v87, 0x3d372713, v91
	v_mul_f32_e32 v87, v91, v87
	v_fma_f32 v87, v91, v87, v91
	v_mul_f32_e32 v87, 0x3f4c422a, v87
	v_mul_f32_e32 v87, -2.0, v87
	v_mul_f32_e32 v87, 0x3fb8aa3b, v87
	v_exp_f32_e32 v87, v87
	s_nop 0
	v_add_f32_e32 v87, 1.0, v87
	v_rcp_f32_e32 v89, v87
	s_nop 0
	v_pk_mul_f32 v[88:89], v[90:91], v[88:89]
	s_nop 0
	v_cvt_pk_bf16_f32 v87, v88, v89
	v_mul_f32_e32 v88, 0x3d372713, v84
	v_mul_f32_e32 v89, 0x3d372713, v85
	v_mul_f32_e32 v88, v84, v88
	v_mul_f32_e32 v89, v85, v89
	v_fma_f32 v88, v84, v88, v84
	v_fma_f32 v89, v85, v89, v85
	v_mul_f32_e32 v88, 0x3f4c422a, v88
	v_mul_f32_e32 v89, 0x3f4c422a, v89
	v_mul_f32_e32 v88, -2.0, v88
	v_mul_f32_e32 v89, -2.0, v89
	v_mul_f32_e32 v88, 0x3fb8aa3b, v88
	v_mul_f32_e32 v89, 0x3fb8aa3b, v89
	v_exp_f32_e32 v88, v88
	v_exp_f32_e32 v89, v89
	v_add_co_u32_e32 v90, vcc, s80, v124
	v_add_f32_e32 v88, 1.0, v88
	v_add_f32_e32 v89, 1.0, v89
	v_rcp_f32_e32 v88, v88
	v_rcp_f32_e32 v89, v89
	v_addc_co_u32_e32 v91, vcc, 0, v125, vcc
	v_pk_mul_f32 v[84:85], v[84:85], v[88:89]
	s_nop 0
	v_cvt_pk_bf16_f32 v88, v84, v85
	v_mul_f32_e32 v84, 0x3d372713, v94
	v_mul_f32_e32 v85, 0x3d372713, v95
	v_mul_f32_e32 v84, v94, v84
	v_mul_f32_e32 v85, v95, v85
	v_fma_f32 v84, v94, v84, v94
	v_fma_f32 v85, v95, v85, v95
	v_mul_f32_e32 v84, 0x3f4c422a, v84
	v_mul_f32_e32 v85, 0x3f4c422a, v85
; __device__ __forceinline__ unsigned cvt_pk_bf16(float lo, float hi) { const f32x2 v = {lo, hi}; const bf16v2_ r = __builtin_convertvector(v, bf16v2_); return __builtin_bit_cast(unsigned, r); }
; __device__ __forceinline__ float gelu_tanh(float x) { const float y = 0.7978845608028654f * (x + 0.044715f * x * x * x); return x * __builtin_amdgcn_rcpf(1.f + __expf(-2.f * y)); }
;     __device__ __forceinline__ void operator()(const f32x4 (&acc)[2][2][4][2], const Unit& u, int wr, int wc, int, int) const {
;     ...
;             for (int ai = 0; ai < 2; ++ai)
; #pragma unroll
;                 for (int m = 0; m < 4; ++m) { const f32x4 v0 = acc[ai][bj][m][0] + b0, v1 = acc[ai][bj][m][1] + b1;
;                     u32x4 w; w.x = cvt_pk_bf16(gelu_tanh(v0[0]), gelu_tanh(v0[1])); w.y = cvt_pk_bf16(gelu_tanh(v0[2]), gelu_tanh(v0[3]));
;                     w.z = cvt_pk_bf16(gelu_tanh(v1[0]), gelu_tanh(v1[1])); w.w = cvt_pk_bf16(gelu_tanh(v1[2]), gelu_tanh(v1[3]));
;                     *(u32x4*)(O + (size_t)(row0 + ai * HALF + m * 16) * ldc + col0 + bj * HALF) = w; } }
	v_mul_f32_e32 v84, -2.0, v84
	v_mul_f32_e32 v85, -2.0, v85
	v_mul_f32_e32 v84, 0x3fb8aa3b, v84
	v_mul_f32_e32 v85, 0x3fb8aa3b, v85
	v_exp_f32_e32 v84, v84
	v_exp_f32_e32 v85, v85
	v_add_f32_e32 v84, 1.0, v84
	v_add_f32_e32 v85, 1.0, v85
	v_rcp_f32_e32 v84, v84
	v_rcp_f32_e32 v85, v85
	s_nop 0
	v_pk_mul_f32 v[84:85], v[94:95], v[84:85]
	s_nop 0
	v_cvt_pk_bf16_f32 v89, v84, v85
	global_store_dwordx4 v[90:91], v[86:89], off sc1
	v_lshl_add_u64 v[84:85], v[124:125], 0, s[0:1]
	s_mov_b64 s[0:1], 0x14000
	v_pk_add_f32 v[86:87], v[78:79], v[146:147]
	v_mul_f32_e32 v78, 0x3d372713, v80
	v_mul_f32_e32 v79, 0x3d372713, v81
	v_mul_f32_e32 v78, v80, v78
	v_mul_f32_e32 v79, v81, v79
	v_fma_f32 v78, v80, v78, v80
	v_fma_f32 v79, v81, v79, v81
	v_mul_f32_e32 v78, 0x3f4c422a, v78
	v_mul_f32_e32 v79, 0x3f4c422a, v79
	v_mul_f32_e32 v78, -2.0, v78
	v_mul_f32_e32 v79, -2.0, v79
	v_mul_f32_e32 v78, 0x3fb8aa3b, v78
	v_mul_f32_e32 v79, 0x3fb8aa3b, v79
	v_exp_f32_e32 v78, v78
	v_exp_f32_e32 v79, v79
	v_add_f32_e32 v78, 1.0, v78
	v_add_f32_e32 v79, 1.0, v79
	v_rcp_f32_e32 v78, v78
	v_rcp_f32_e32 v79, v79
	s_nop 0
	v_pk_mul_f32 v[78:79], v[80:81], v[78:79]
	s_nop 0
	v_cvt_pk_bf16_f32 v78, v78, v79
	v_mul_f32_e32 v79, 0x3d372713, v82
	v_mul_f32_e32 v79, v82, v79
	v_fma_f32 v79, v82, v79, v82
	v_mul_f32_e32 v79, 0x3f4c422a, v79
	v_mul_f32_e32 v79, -2.0, v79
	v_mul_f32_e32 v79, 0x3fb8aa3b, v79
	v_exp_f32_e32 v79, v79
	s_nop 0
	v_add_f32_e32 v79, 1.0, v79
	v_rcp_f32_e32 v80, v79
	v_mul_f32_e32 v79, 0x3d372713, v83
	v_mul_f32_e32 v79, v83, v79
	v_fma_f32 v79, v83, v79, v83
	v_mul_f32_e32 v79, 0x3f4c422a, v79
	v_mul_f32_e32 v79, -2.0, v79
	v_mul_f32_e32 v79, 0x3fb8aa3b, v79
	v_exp_f32_e32 v79, v79
	s_nop 0
	v_add_f32_e32 v79, 1.0, v79
	v_rcp_f32_e32 v81, v79
	s_nop 0
	v_pk_mul_f32 v[80:81], v[82:83], v[80:81]
	s_nop 0
	v_cvt_pk_bf16_f32 v79, v80, v81
	v_mul_f32_e32 v80, 0x3d372713, v76
	v_mul_f32_e32 v81, 0x3d372713, v77
	v_mul_f32_e32 v80, v76, v80
	v_mul_f32_e32 v81, v77, v81
	v_fma_f32 v80, v76, v80, v76
	v_fma_f32 v81, v77, v81, v77
	v_mul_f32_e32 v80, 0x3f4c422a, v80
	v_mul_f32_e32 v81, 0x3f4c422a, v81
	v_mul_f32_e32 v80, -2.0, v80
	v_mul_f32_e32 v81, -2.0, v81
	v_mul_f32_e32 v80, 0x3fb8aa3b, v80
	v_mul_f32_e32 v81, 0x3fb8aa3b, v81
	v_exp_f32_e32 v80, v80
	v_exp_f32_e32 v81, v81
	v_add_f32_e32 v80, 1.0, v80
	v_add_f32_e32 v81, 1.0, v81
	v_rcp_f32_e32 v80, v80
	v_rcp_f32_e32 v81, v81
	s_nop 0
	v_pk_mul_f32 v[76:77], v[76:77], v[80:81]
	s_nop 0
	v_cvt_pk_bf16_f32 v80, v76, v77
	v_mul_f32_e32 v76, 0x3d372713, v86
	v_mul_f32_e32 v77, 0x3d372713, v87
	v_mul_f32_e32 v76, v86, v76
	v_mul_f32_e32 v77, v87, v77
	v_fma_f32 v76, v86, v76, v86
	v_fma_f32 v77, v87, v77, v87
	v_mul_f32_e32 v76, 0x3f4c422a, v76
	v_mul_f32_e32 v77, 0x3f4c422a, v77
	v_mul_f32_e32 v76, -2.0, v76
	v_mul_f32_e32 v77, -2.0, v77
	v_mul_f32_e32 v76, 0x3fb8aa3b, v76
	v_mul_f32_e32 v77, 0x3fb8aa3b, v77
	v_exp_f32_e32 v76, v76
	v_exp_f32_e32 v77, v77
	v_add_f32_e32 v76, 1.0, v76
	v_add_f32_e32 v77, 1.0, v77
	v_rcp_f32_e32 v76, v76
	v_rcp_f32_e32 v77, v77
	s_nop 0
	v_pk_mul_f32 v[76:77], v[86:87], v[76:77]
	s_nop 0
	v_cvt_pk_bf16_f32 v81, v76, v77
	v_lshl_add_u64 v[76:77], v[124:125], 0, s[0:1]
	s_mov_b32 s0, 0x14000
	v_add_co_u32_e32 v82, vcc, s0, v124
	s_mov_b64 s[0:1], 0x16000
	s_nop 0
	v_addc_co_u32_e32 v83, vcc, 0, v125, vcc
	global_store_dwordx4 v[82:83], v[78:81], off sc1
	s_nop 1
	v_pk_add_f32 v[78:79], v[70:71], v[146:147]
	v_mul_f32_e32 v70, 0x3d372713, v72
	v_mul_f32_e32 v71, 0x3d372713, v73
	v_mul_f32_e32 v70, v72, v70
	v_mul_f32_e32 v71, v73, v71
	v_fma_f32 v70, v72, v70, v72
	v_fma_f32 v71, v73, v71, v73
	v_mul_f32_e32 v70, 0x3f4c422a, v70
	v_mul_f32_e32 v71, 0x3f4c422a, v71
	v_mul_f32_e32 v70, -2.0, v70
	v_mul_f32_e32 v71, -2.0, v71
	v_mul_f32_e32 v70, 0x3fb8aa3b, v70
	v_mul_f32_e32 v71, 0x3fb8aa3b, v71
	v_exp_f32_e32 v70, v70
	v_exp_f32_e32 v71, v71
	v_add_f32_e32 v70, 1.0, v70
	v_add_f32_e32 v71, 1.0, v71
	v_rcp_f32_e32 v70, v70
	v_rcp_f32_e32 v71, v71
	s_nop 0
	v_pk_mul_f32 v[70:71], v[72:73], v[70:71]
	s_nop 0
	v_cvt_pk_bf16_f32 v70, v70, v71
	v_mul_f32_e32 v71, 0x3d372713, v74
	v_mul_f32_e32 v71, v74, v71
	v_fma_f32 v71, v74, v71, v74
	v_mul_f32_e32 v71, 0x3f4c422a, v71
	v_mul_f32_e32 v71, -2.0, v71
	v_mul_f32_e32 v71, 0x3fb8aa3b, v71
	v_exp_f32_e32 v71, v71
	s_nop 0
	v_add_f32_e32 v71, 1.0, v71
	v_rcp_f32_e32 v72, v71
	v_mul_f32_e32 v71, 0x3d372713, v75
	v_mul_f32_e32 v71, v75, v71
	v_fma_f32 v71, v75, v71, v75
	v_mul_f32_e32 v71, 0x3f4c422a, v71
	v_mul_f32_e32 v71, -2.0, v71
	v_mul_f32_e32 v71, 0x3fb8aa3b, v71
	v_exp_f32_e32 v71, v71
	s_nop 0
	v_add_f32_e32 v71, 1.0, v71
	v_rcp_f32_e32 v73, v71
	s_nop 0
	v_pk_mul_f32 v[72:73], v[74:75], v[72:73]
	s_nop 0
	v_cvt_pk_bf16_f32 v71, v72, v73
	v_mul_f32_e32 v72, 0x3d372713, v68
	v_mul_f32_e32 v73, 0x3d372713, v69
	v_mul_f32_e32 v72, v68, v72
	v_mul_f32_e32 v73, v69, v73
	v_fma_f32 v72, v68, v72, v68
	v_fma_f32 v73, v69, v73, v69
	v_mul_f32_e32 v72, 0x3f4c422a, v72
	v_mul_f32_e32 v73, 0x3f4c422a, v73
	v_mul_f32_e32 v72, -2.0, v72
	v_mul_f32_e32 v73, -2.0, v73
	v_mul_f32_e32 v72, 0x3fb8aa3b, v72
	v_mul_f32_e32 v73, 0x3fb8aa3b, v73
	v_exp_f32_e32 v72, v72
	v_exp_f32_e32 v73, v73
	v_add_co_u32_e32 v74, vcc, 0x16000, v124
	v_add_f32_e32 v72, 1.0, v72
	v_add_f32_e32 v73, 1.0, v73
	v_rcp_f32_e32 v72, v72
	v_rcp_f32_e32 v73, v73
	v_addc_co_u32_e32 v75, vcc, 0, v125, vcc
	v_pk_mul_f32 v[68:69], v[68:69], v[72:73]
	s_nop 0
	v_cvt_pk_bf16_f32 v72, v68, v69
	v_mul_f32_e32 v68, 0x3d372713, v78
	v_mul_f32_e32 v69, 0x3d372713, v79
	v_mul_f32_e32 v68, v78, v68
	v_mul_f32_e32 v69, v79, v69
	v_fma_f32 v68, v78, v68, v78
	v_fma_f32 v69, v79, v69, v79
	v_mul_f32_e32 v68, 0x3f4c422a, v68
	v_mul_f32_e32 v69, 0x3f4c422a, v69
	v_mul_f32_e32 v68, -2.0, v68
	v_mul_f32_e32 v69, -2.0, v69
	v_mul_f32_e32 v68, 0x3fb8aa3b, v68
	v_mul_f32_e32 v69, 0x3fb8aa3b, v69
	v_exp_f32_e32 v68, v68
	v_exp_f32_e32 v69, v69
	v_add_f32_e32 v68, 1.0, v68
	v_add_f32_e32 v69, 1.0, v69
	v_rcp_f32_e32 v68, v68
	v_rcp_f32_e32 v69, v69
	s_nop 0
	v_pk_mul_f32 v[68:69], v[78:79], v[68:69]
	s_nop 0
	v_cvt_pk_bf16_f32 v73, v68, v69
	global_store_dwordx4 v[74:75], v[70:73], off sc1
	v_lshl_add_u64 v[68:69], v[124:125], 0, s[0:1]
	s_mov_b64 s[0:1], 0
	v_mov_b32_e32 v70, 0
	v_mov_b32_e32 v71, v70
	v_mov_b32_e32 v72, v70
	v_mov_b32_e32 v73, v70
	v_mov_b32_e32 v74, v70
	v_mov_b32_e32 v75, v70
	v_mov_b32_e32 v78, v70
	v_mov_b32_e32 v79, v70
; __device__ __forceinline__ unsigned cvt_pk_bf16(float lo, float hi) { const f32x2 v = {lo, hi}; const bf16v2_ r = __builtin_convertvector(v, bf16v2_); return __builtin_bit_cast(unsigned, r); }
; __device__ __forceinline__ float gelu_tanh(float x) { const float y = 0.7978845608028654f * (x + 0.044715f * x * x * x); return x * __builtin_amdgcn_rcpf(1.f + __expf(-2.f * y)); }
;     __device__ __forceinline__ void operator()(const f32x4 (&acc)[2][2][4][2], const Unit& u, int wr, int wc, int, int) const {
;     ...
;         for (int bj = 0; bj < 2; ++bj) { f32x4 b0 = (f32x4){0.f, 0.f, 0.f, 0.f}, b1 = b0;
; #pragma unroll 8
;             for (int pp = 0; pp < 32; ++pp) { b0 += *(const f32x4*)(bias + pp * 256 + col0 + bj * HALF); b1 += *(const f32x4*)(bias + pp * 256 + col0 + bj * HALF + 4); }
; #pragma unroll
;             for (int ai = 0; ai < 2; ++ai)
; #pragma unroll
;                 for (int m = 0; m < 4; ++m) { const f32x4 v0 = acc[ai][bj][m][0] + b0, v1 = acc[ai][bj][m][1] + b1;
;                     u32x4 w; w.x = cvt_pk_bf16(gelu_tanh(v0[0]), gelu_tanh(v0[1])); w.y = cvt_pk_bf16(gelu_tanh(v0[2]), gelu_tanh(v0[3]));
;                     w.z = cvt_pk_bf16(gelu_tanh(v1[0]), gelu_tanh(v1[1])); w.w = cvt_pk_bf16(gelu_tanh(v1[2]), gelu_tanh(v1[3]));
;                     *(u32x4*)(O + (size_t)(row0 + ai * HALF + m * 16) * ldc + col0 + bj * HALF) = w; } }
.LBB0_495:
	v_lshl_add_u64 v[80:81], v[142:143], 0, s[0:1]
	v_add_co_u32_e32 v90, vcc, 0x18c90000, v80
	s_mov_b64 s[4:5], 0x18c90200
	s_nop 0
	v_addc_co_u32_e32 v91, vcc, 0, v81, vcc
	v_lshl_add_u64 v[82:83], v[80:81], 0, s[4:5]
	global_load_dwordx4 v[86:89], v[90:91], off offset:512
	global_load_dwordx4 v[94:97], v[82:83], off offset:16
	s_mov_b64 s[4:5], 0x18c90600
	s_add_u32 s0, s0, 0x2000
	s_addc_u32 s1, s1, 0
	s_cmpk_lg_u32 s0, 0x8000
	s_waitcnt vmcnt(0)
	v_pk_add_f32 v[74:75], v[74:75], v[86:87]
	v_lshl_add_u64 v[86:87], v[80:81], 0, s[4:5]
	v_pk_add_f32 v[78:79], v[78:79], v[88:89]
	v_pk_add_f32 v[82:83], v[70:71], v[94:95]
	v_pk_add_f32 v[94:95], v[72:73], v[96:97]
	global_load_dwordx4 v[70:73], v[90:91], off offset:1536
	s_nop 0
	global_load_dwordx4 v[86:89], v[86:87], off offset:16
	s_mov_b64 s[4:5], 0x18c90a00
	s_waitcnt vmcnt(0)
	v_pk_add_f32 v[78:79], v[78:79], v[72:73]
	v_pk_add_f32 v[82:83], v[82:83], v[86:87]
	v_lshl_add_u64 v[86:87], v[80:81], 0, s[4:5]
	v_pk_add_f32 v[74:75], v[74:75], v[70:71]
	v_pk_add_f32 v[94:95], v[94:95], v[88:89]
	global_load_dwordx4 v[70:73], v[90:91], off offset:2560
	s_nop 0
	global_load_dwordx4 v[86:89], v[86:87], off offset:16
	s_mov_b64 s[4:5], 0x18c90e00
	s_waitcnt vmcnt(0)
	v_pk_add_f32 v[78:79], v[78:79], v[72:73]
	v_pk_add_f32 v[82:83], v[82:83], v[86:87]
	v_lshl_add_u64 v[86:87], v[80:81], 0, s[4:5]
	v_pk_add_f32 v[74:75], v[74:75], v[70:71]
	v_pk_add_f32 v[94:95], v[94:95], v[88:89]
	global_load_dwordx4 v[70:73], v[90:91], off offset:3584
	s_nop 0
	global_load_dwordx4 v[86:89], v[86:87], off offset:16
	s_mov_b64 s[4:5], 0x18c91200
	s_waitcnt vmcnt(0)
	v_pk_add_f32 v[78:79], v[78:79], v[72:73]
	v_pk_add_f32 v[90:91], v[94:95], v[88:89]
	v_add_co_u32_e32 v94, vcc, s26, v80
	v_pk_add_f32 v[82:83], v[82:83], v[86:87]
	v_lshl_add_u64 v[86:87], v[80:81], 0, s[4:5]
	v_addc_co_u32_e32 v95, vcc, 0, v81, vcc
	v_pk_add_f32 v[74:75], v[74:75], v[70:71]
	global_load_dwordx4 v[70:73], v[94:95], off offset:512
	s_nop 0
	global_load_dwordx4 v[86:89], v[86:87], off offset:16
	s_mov_b64 s[4:5], 0x18c91600
	s_waitcnt vmcnt(0)
	v_pk_add_f32 v[78:79], v[78:79], v[72:73]
	v_pk_add_f32 v[82:83], v[82:83], v[86:87]
	v_lshl_add_u64 v[86:87], v[80:81], 0, s[4:5]
	v_pk_add_f32 v[74:75], v[74:75], v[70:71]
	v_pk_add_f32 v[90:91], v[90:91], v[88:89]
	global_load_dwordx4 v[70:73], v[94:95], off offset:1536
	s_nop 0
	global_load_dwordx4 v[86:89], v[86:87], off offset:16
	s_mov_b64 s[4:5], 0x18c91a00
	s_waitcnt vmcnt(0)
	v_pk_add_f32 v[78:79], v[78:79], v[72:73]
	v_pk_add_f32 v[82:83], v[82:83], v[86:87]
	v_lshl_add_u64 v[86:87], v[80:81], 0, s[4:5]
	v_pk_add_f32 v[74:75], v[74:75], v[70:71]
	v_pk_add_f32 v[90:91], v[90:91], v[88:89]
	global_load_dwordx4 v[70:73], v[94:95], off offset:2560
	s_nop 0
	global_load_dwordx4 v[86:89], v[86:87], off offset:16
	s_mov_b64 s[4:5], 0x18c91e00
	v_lshl_add_u64 v[80:81], v[80:81], 0, s[4:5]
	s_waitcnt vmcnt(0)
	v_pk_add_f32 v[78:79], v[78:79], v[72:73]
	v_pk_add_f32 v[74:75], v[74:75], v[70:71]
	v_pk_add_f32 v[86:87], v[82:83], v[86:87]
	global_load_dwordx4 v[70:73], v[94:95], off offset:3584
	s_nop 0
	global_load_dwordx4 v[80:83], v[80:81], off offset:16
	v_pk_add_f32 v[88:89], v[90:91], v[88:89]
	s_waitcnt vmcnt(0)
	v_pk_add_f32 v[78:79], v[78:79], v[72:73]
	v_pk_add_f32 v[74:75], v[74:75], v[70:71]
	v_pk_add_f32 v[72:73], v[88:89], v[82:83]
	v_pk_add_f32 v[70:71], v[86:87], v[80:81]
	s_cbranch_scc1 .LBB0_495
	v_pk_add_f32 v[64:65], v[64:65], v[74:75]
	v_pk_add_f32 v[80:81], v[62:63], v[72:73]
	v_pk_add_f32 v[62:63], v[60:61], v[70:71]
	v_mul_f32_e32 v60, 0x3d372713, v64
	v_mul_f32_e32 v61, 0x3d372713, v65
	v_mul_f32_e32 v60, v64, v60
	v_mul_f32_e32 v61, v65, v61
	v_fma_f32 v60, v64, v60, v64
	v_fma_f32 v61, v65, v61, v65
	v_mul_f32_e32 v60, 0x3f4c422a, v60
	v_mul_f32_e32 v61, 0x3f4c422a, v61
	v_mul_f32_e32 v60, -2.0, v60
	v_mul_f32_e32 v61, -2.0, v61
	v_mul_f32_e32 v60, 0x3fb8aa3b, v60
	v_mul_f32_e32 v61, 0x3fb8aa3b, v61
	v_exp_f32_e32 v60, v60
	v_exp_f32_e32 v61, v61
	v_pk_add_f32 v[66:67], v[66:67], v[78:79]
	v_pk_add_f32 v[56:57], v[56:57], v[74:75]
	v_add_f32_e32 v60, 1.0, v60
	v_add_f32_e32 v61, 1.0, v61
	v_rcp_f32_e32 v60, v60
	v_rcp_f32_e32 v61, v61
	v_pk_add_f32 v[58:59], v[58:59], v[78:79]
	v_pk_add_f32 v[48:49], v[48:49], v[74:75]
	v_pk_add_f32 v[50:51], v[50:51], v[78:79]
	v_pk_mul_f32 v[60:61], v[64:65], v[60:61]
	v_pk_add_f32 v[40:41], v[40:41], v[74:75]
	v_cvt_pk_bf16_f32 v60, v60, v61
	v_mul_f32_e32 v61, 0x3d372713, v66
	v_mul_f32_e32 v61, v66, v61
	v_fma_f32 v61, v66, v61, v66
	v_mul_f32_e32 v61, 0x3f4c422a, v61
	v_mul_f32_e32 v61, -2.0, v61
	v_mul_f32_e32 v61, 0x3fb8aa3b, v61
	v_exp_f32_e32 v61, v61
	v_pk_add_f32 v[42:43], v[42:43], v[78:79]
	v_pk_add_f32 v[32:33], v[32:33], v[74:75]
	v_pk_add_f32 v[34:35], v[34:35], v[78:79]
	v_add_f32_e32 v61, 1.0, v61
	v_rcp_f32_e32 v64, v61
	v_mul_f32_e32 v61, 0x3d372713, v67
	v_mul_f32_e32 v61, v67, v61
	v_fma_f32 v61, v67, v61, v67
	v_mul_f32_e32 v61, 0x3f4c422a, v61
	v_mul_f32_e32 v61, -2.0, v61
	v_mul_f32_e32 v61, 0x3fb8aa3b, v61
	v_exp_f32_e32 v61, v61
	v_pk_add_f32 v[24:25], v[24:25], v[74:75]
	v_pk_add_f32 v[26:27], v[26:27], v[78:79]
	v_pk_add_f32 v[16:17], v[16:17], v[74:75]
	v_add_f32_e32 v61, 1.0, v61
	v_rcp_f32_e32 v65, v61
	v_pk_add_f32 v[18:19], v[18:19], v[78:79]
	v_pk_add_f32 v[8:9], v[8:9], v[74:75]
	v_pk_add_f32 v[10:11], v[10:11], v[78:79]
	v_pk_mul_f32 v[64:65], v[66:67], v[64:65]
	s_and_b64 vcc, exec, s[48:49]
	v_cvt_pk_bf16_f32 v61, v64, v65
	v_mul_f32_e32 v64, 0x3d372713, v62
	v_mul_f32_e32 v65, 0x3d372713, v63
	v_mul_f32_e32 v64, v62, v64
	v_mul_f32_e32 v65, v63, v65
	v_fma_f32 v64, v62, v64, v62
; __device__ __forceinline__ unsigned cvt_pk_bf16(float lo, float hi) { const f32x2 v = {lo, hi}; const bf16v2_ r = __builtin_convertvector(v, bf16v2_); return __builtin_bit_cast(unsigned, r); }
; __device__ __forceinline__ int opaque_tid() { int t = threadIdx.x; asm volatile("" : "+v"(t)); return t; }
; __device__ __forceinline__ float gelu_tanh(float x) { const float y = 0.7978845608028654f * (x + 0.044715f * x * x * x); return x * __builtin_amdgcn_rcpf(1.f + __expf(-2.f * y)); }
;     __device__ __forceinline__ void operator()(const f32x4 (&acc)[2][2][4][2], const Unit& u, int wr, int wc, int, int) const {
;         const int ol_ = opaque_tid() & 63, fr = ol_ & 15, fq = ol_ >> 4;
;         const int row0 = u.pm * BM + wr * 64 + fr, col0 = u.pn * BM + wc * 32 + 8 * fq;
; #pragma unroll
;         for (int bj = 0; bj < 2; ++bj) { f32x4 b0 = (f32x4){0.f, 0.f, 0.f, 0.f}, b1 = b0;
; #pragma unroll 8
;             for (int pp = 0; pp < 32; ++pp) { b0 += *(const f32x4*)(bias + pp * 256 + col0 + bj * HALF); b1 += *(const f32x4*)(bias + pp * 256 + col0 + bj * HALF + 4); }
; #pragma unroll
;             for (int ai = 0; ai < 2; ++ai)
; #pragma unroll
;                 for (int m = 0; m < 4; ++m) { const f32x4 v0 = acc[ai][bj][m][0] + b0, v1 = acc[ai][bj][m][1] + b1;
;                     u32x4 w; w.x = cvt_pk_bf16(gelu_tanh(v0[0]), gelu_tanh(v0[1])); w.y = cvt_pk_bf16(gelu_tanh(v0[2]), gelu_tanh(v0[3]));
;                     w.z = cvt_pk_bf16(gelu_tanh(v1[0]), gelu_tanh(v1[1])); w.w = cvt_pk_bf16(gelu_tanh(v1[2]), gelu_tanh(v1[3]));
;                     *(u32x4*)(O + (size_t)(row0 + ai * HALF + m * 16) * ldc + col0 + bj * HALF) = w; } }
	v_fma_f32 v65, v63, v65, v63
	v_mul_f32_e32 v64, 0x3f4c422a, v64
	v_mul_f32_e32 v65, 0x3f4c422a, v65
	v_mul_f32_e32 v64, -2.0, v64
	v_mul_f32_e32 v65, -2.0, v65
	v_mul_f32_e32 v64, 0x3fb8aa3b, v64
	v_mul_f32_e32 v65, 0x3fb8aa3b, v65
	v_exp_f32_e32 v64, v64
	v_exp_f32_e32 v65, v65
	s_mov_b32 s1, s50
	s_mov_b32 s0, s52
	v_add_f32_e32 v64, 1.0, v64
	v_add_f32_e32 v65, 1.0, v65
	v_rcp_f32_e32 v64, v64
	v_rcp_f32_e32 v65, v65
	s_mov_b64 s[6:7], s[56:57]
	s_mov_b64 s[4:5], s[54:55]
	v_pk_mul_f32 v[62:63], v[62:63], v[64:65]
	s_nop 0
	v_cvt_pk_bf16_f32 v62, v62, v63
	v_mul_f32_e32 v63, 0x3d372713, v80
	v_mul_f32_e32 v63, v80, v63
	v_fma_f32 v63, v80, v63, v80
	v_mul_f32_e32 v63, 0x3f4c422a, v63
	v_mul_f32_e32 v63, -2.0, v63
	v_mul_f32_e32 v63, 0x3fb8aa3b, v63
	v_exp_f32_e32 v63, v63
	s_nop 0
	v_add_f32_e32 v63, 1.0, v63
	v_rcp_f32_e32 v64, v63
	v_mul_f32_e32 v63, 0x3d372713, v81
	v_mul_f32_e32 v63, v81, v63
	v_fma_f32 v63, v81, v63, v81
	v_mul_f32_e32 v63, 0x3f4c422a, v63
	v_mul_f32_e32 v63, -2.0, v63
	v_mul_f32_e32 v63, 0x3fb8aa3b, v63
	v_exp_f32_e32 v63, v63
	s_nop 0
	v_add_f32_e32 v63, 1.0, v63
	v_rcp_f32_e32 v65, v63
	s_nop 0
	v_pk_mul_f32 v[64:65], v[80:81], v[64:65]
	s_nop 0
	v_cvt_pk_bf16_f32 v63, v64, v65
	global_store_dwordx4 v[124:125], v[60:63], off offset:256 sc1
	s_nop 1
	v_pk_add_f32 v[60:61], v[54:55], v[72:73]
	v_pk_add_f32 v[54:55], v[52:53], v[70:71]
	v_mul_f32_e32 v52, 0x3d372713, v56
	v_mul_f32_e32 v53, 0x3d372713, v57
	v_mul_f32_e32 v52, v56, v52
	v_mul_f32_e32 v53, v57, v53
	v_fma_f32 v52, v56, v52, v56
	v_fma_f32 v53, v57, v53, v57
	v_mul_f32_e32 v52, 0x3f4c422a, v52
	v_mul_f32_e32 v53, 0x3f4c422a, v53
	v_mul_f32_e32 v52, -2.0, v52
	v_mul_f32_e32 v53, -2.0, v53
	v_mul_f32_e32 v52, 0x3fb8aa3b, v52
	v_mul_f32_e32 v53, 0x3fb8aa3b, v53
	v_exp_f32_e32 v52, v52
	v_exp_f32_e32 v53, v53
	v_add_f32_e32 v52, 1.0, v52
	v_add_f32_e32 v53, 1.0, v53
	v_rcp_f32_e32 v52, v52
	v_rcp_f32_e32 v53, v53
	s_nop 0
	v_pk_mul_f32 v[52:53], v[56:57], v[52:53]
	s_nop 0
	v_cvt_pk_bf16_f32 v52, v52, v53
	v_mul_f32_e32 v53, 0x3d372713, v58
	v_mul_f32_e32 v53, v58, v53
	v_fma_f32 v53, v58, v53, v58
	v_mul_f32_e32 v53, 0x3f4c422a, v53
	v_mul_f32_e32 v53, -2.0, v53
	v_mul_f32_e32 v53, 0x3fb8aa3b, v53
	v_exp_f32_e32 v53, v53
	s_nop 0
	v_add_f32_e32 v53, 1.0, v53
	v_rcp_f32_e32 v56, v53
	v_mul_f32_e32 v53, 0x3d372713, v59
	v_mul_f32_e32 v53, v59, v53
	v_fma_f32 v53, v59, v53, v59
	v_mul_f32_e32 v53, 0x3f4c422a, v53
	v_mul_f32_e32 v53, -2.0, v53
	v_mul_f32_e32 v53, 0x3fb8aa3b, v53
	v_exp_f32_e32 v53, v53
	s_nop 0
	v_add_f32_e32 v53, 1.0, v53
	v_rcp_f32_e32 v57, v53
	s_nop 0
	v_pk_mul_f32 v[56:57], v[58:59], v[56:57]
	s_nop 0
	v_cvt_pk_bf16_f32 v53, v56, v57
	v_mul_f32_e32 v56, 0x3d372713, v54
	v_mul_f32_e32 v57, 0x3d372713, v55
	v_mul_f32_e32 v56, v54, v56
	v_mul_f32_e32 v57, v55, v57
	v_fma_f32 v56, v54, v56, v54
	v_fma_f32 v57, v55, v57, v55
	v_mul_f32_e32 v56, 0x3f4c422a, v56
	v_mul_f32_e32 v57, 0x3f4c422a, v57
	v_mul_f32_e32 v56, -2.0, v56
	v_mul_f32_e32 v57, -2.0, v57
	v_mul_f32_e32 v56, 0x3fb8aa3b, v56
	v_mul_f32_e32 v57, 0x3fb8aa3b, v57
	v_exp_f32_e32 v56, v56
	v_exp_f32_e32 v57, v57
	v_add_f32_e32 v56, 1.0, v56
	v_add_f32_e32 v57, 1.0, v57
	v_rcp_f32_e32 v56, v56
	v_rcp_f32_e32 v57, v57
	s_nop 0
	v_pk_mul_f32 v[54:55], v[54:55], v[56:57]
	s_nop 0
	v_cvt_pk_bf16_f32 v54, v54, v55
	v_mul_f32_e32 v55, 0x3d372713, v60
	v_mul_f32_e32 v55, v60, v55
	v_fma_f32 v55, v60, v55, v60
	v_mul_f32_e32 v55, 0x3f4c422a, v55
	v_mul_f32_e32 v55, -2.0, v55
	v_mul_f32_e32 v55, 0x3fb8aa3b, v55
	v_exp_f32_e32 v55, v55
	s_nop 0
	v_add_f32_e32 v55, 1.0, v55
	v_rcp_f32_e32 v56, v55
	v_mul_f32_e32 v55, 0x3d372713, v61
	v_mul_f32_e32 v55, v61, v55
	v_fma_f32 v55, v61, v55, v61
	v_mul_f32_e32 v55, 0x3f4c422a, v55
	v_mul_f32_e32 v55, -2.0, v55
	v_mul_f32_e32 v55, 0x3fb8aa3b, v55
	v_exp_f32_e32 v55, v55
	s_nop 0
	v_add_f32_e32 v55, 1.0, v55
	v_rcp_f32_e32 v57, v55
	s_nop 0
	v_pk_mul_f32 v[56:57], v[60:61], v[56:57]
	s_nop 0
	v_cvt_pk_bf16_f32 v55, v56, v57
	global_store_dwordx4 v[116:117], v[52:55], off offset:256 sc1
	s_nop 1
	v_pk_add_f32 v[52:53], v[46:47], v[72:73]
	v_pk_add_f32 v[46:47], v[44:45], v[70:71]
	v_mul_f32_e32 v44, 0x3d372713, v48
	v_mul_f32_e32 v45, 0x3d372713, v49
	v_mul_f32_e32 v44, v48, v44
	v_mul_f32_e32 v45, v49, v45
	v_fma_f32 v44, v48, v44, v48
	v_fma_f32 v45, v49, v45, v49
	v_mul_f32_e32 v44, 0x3f4c422a, v44
	v_mul_f32_e32 v45, 0x3f4c422a, v45
	v_mul_f32_e32 v44, -2.0, v44
	v_mul_f32_e32 v45, -2.0, v45
	v_mul_f32_e32 v44, 0x3fb8aa3b, v44
	v_mul_f32_e32 v45, 0x3fb8aa3b, v45
	v_exp_f32_e32 v44, v44
	v_exp_f32_e32 v45, v45
	v_add_f32_e32 v44, 1.0, v44
	v_add_f32_e32 v45, 1.0, v45
	v_rcp_f32_e32 v44, v44
	v_rcp_f32_e32 v45, v45
	s_nop 0
	v_pk_mul_f32 v[44:45], v[48:49], v[44:45]
	s_nop 0
	v_cvt_pk_bf16_f32 v44, v44, v45
	v_mul_f32_e32 v45, 0x3d372713, v50
	v_mul_f32_e32 v45, v50, v45
	v_fma_f32 v45, v50, v45, v50
	v_mul_f32_e32 v45, 0x3f4c422a, v45
	v_mul_f32_e32 v45, -2.0, v45
	v_mul_f32_e32 v45, 0x3fb8aa3b, v45
	v_exp_f32_e32 v45, v45
	s_nop 0
	v_add_f32_e32 v45, 1.0, v45
	v_rcp_f32_e32 v48, v45
	v_mul_f32_e32 v45, 0x3d372713, v51
	v_mul_f32_e32 v45, v51, v45
	v_fma_f32 v45, v51, v45, v51
	v_mul_f32_e32 v45, 0x3f4c422a, v45
	v_mul_f32_e32 v45, -2.0, v45
	v_mul_f32_e32 v45, 0x3fb8aa3b, v45
	v_exp_f32_e32 v45, v45
	s_nop 0
	v_add_f32_e32 v45, 1.0, v45
	v_rcp_f32_e32 v49, v45
	s_nop 0
	v_pk_mul_f32 v[48:49], v[50:51], v[48:49]
	s_nop 0
	v_cvt_pk_bf16_f32 v45, v48, v49
	v_mul_f32_e32 v48, 0x3d372713, v46
	v_mul_f32_e32 v49, 0x3d372713, v47
	v_mul_f32_e32 v48, v46, v48
	v_mul_f32_e32 v49, v47, v49
	v_fma_f32 v48, v46, v48, v46
	v_fma_f32 v49, v47, v49, v47
; __device__ __forceinline__ unsigned cvt_pk_bf16(float lo, float hi) { const f32x2 v = {lo, hi}; const bf16v2_ r = __builtin_convertvector(v, bf16v2_); return __builtin_bit_cast(unsigned, r); }
; __device__ __forceinline__ int opaque_tid() { int t = threadIdx.x; asm volatile("" : "+v"(t)); return t; }
; __device__ __forceinline__ float gelu_tanh(float x) { const float y = 0.7978845608028654f * (x + 0.044715f * x * x * x); return x * __builtin_amdgcn_rcpf(1.f + __expf(-2.f * y)); }
;     __device__ __forceinline__ void operator()(const f32x4 (&acc)[2][2][4][2], const Unit& u, int wr, int wc, int, int) const {
;         const int ol_ = opaque_tid() & 63, fr = ol_ & 15, fq = ol_ >> 4;
;         const int row0 = u.pm * BM + wr * 64 + fr, col0 = u.pn * BM + wc * 32 + 8 * fq;
; #pragma unroll
;         for (int bj = 0; bj < 2; ++bj) { f32x4 b0 = (f32x4){0.f, 0.f, 0.f, 0.f}, b1 = b0;
; #pragma unroll 8
;             for (int pp = 0; pp < 32; ++pp) { b0 += *(const f32x4*)(bias + pp * 256 + col0 + bj * HALF); b1 += *(const f32x4*)(bias + pp * 256 + col0 + bj * HALF + 4); }
; #pragma unroll
;             for (int ai = 0; ai < 2; ++ai)
; #pragma unroll
;                 for (int m = 0; m < 4; ++m) { const f32x4 v0 = acc[ai][bj][m][0] + b0, v1 = acc[ai][bj][m][1] + b1;
;                     u32x4 w; w.x = cvt_pk_bf16(gelu_tanh(v0[0]), gelu_tanh(v0[1])); w.y = cvt_pk_bf16(gelu_tanh(v0[2]), gelu_tanh(v0[3]));
;                     w.z = cvt_pk_bf16(gelu_tanh(v1[0]), gelu_tanh(v1[1])); w.w = cvt_pk_bf16(gelu_tanh(v1[2]), gelu_tanh(v1[3]));
;                     *(u32x4*)(O + (size_t)(row0 + ai * HALF + m * 16) * ldc + col0 + bj * HALF) = w; } }
	v_mul_f32_e32 v48, 0x3f4c422a, v48
	v_mul_f32_e32 v49, 0x3f4c422a, v49
	v_mul_f32_e32 v48, -2.0, v48
	v_mul_f32_e32 v49, -2.0, v49
	v_mul_f32_e32 v48, 0x3fb8aa3b, v48
	v_mul_f32_e32 v49, 0x3fb8aa3b, v49
	v_exp_f32_e32 v48, v48
	v_exp_f32_e32 v49, v49
	v_add_f32_e32 v48, 1.0, v48
	v_add_f32_e32 v49, 1.0, v49
	v_rcp_f32_e32 v48, v48
	v_rcp_f32_e32 v49, v49
	s_nop 0
	v_pk_mul_f32 v[46:47], v[46:47], v[48:49]
	s_nop 0
	v_cvt_pk_bf16_f32 v46, v46, v47
	v_mul_f32_e32 v47, 0x3d372713, v52
	v_mul_f32_e32 v47, v52, v47
	v_fma_f32 v47, v52, v47, v52
	v_mul_f32_e32 v47, 0x3f4c422a, v47
	v_mul_f32_e32 v47, -2.0, v47
	v_mul_f32_e32 v47, 0x3fb8aa3b, v47
	v_exp_f32_e32 v47, v47
	s_nop 0
	v_add_f32_e32 v47, 1.0, v47
	v_rcp_f32_e32 v48, v47
	v_mul_f32_e32 v47, 0x3d372713, v53
	v_mul_f32_e32 v47, v53, v47
	v_fma_f32 v47, v53, v47, v53
	v_mul_f32_e32 v47, 0x3f4c422a, v47
	v_mul_f32_e32 v47, -2.0, v47
	v_mul_f32_e32 v47, 0x3fb8aa3b, v47
	v_exp_f32_e32 v47, v47
	s_nop 0
	v_add_f32_e32 v47, 1.0, v47
	v_rcp_f32_e32 v49, v47
	s_nop 0
	v_pk_mul_f32 v[48:49], v[52:53], v[48:49]
	s_nop 0
	v_cvt_pk_bf16_f32 v47, v48, v49
	global_store_dwordx4 v[108:109], v[44:47], off offset:256
	s_nop 1
	v_pk_add_f32 v[44:45], v[38:39], v[72:73]
	v_pk_add_f32 v[38:39], v[36:37], v[70:71]
	v_mul_f32_e32 v36, 0x3d372713, v40
	v_mul_f32_e32 v37, 0x3d372713, v41
	v_mul_f32_e32 v36, v40, v36
	v_mul_f32_e32 v37, v41, v37
	v_fma_f32 v36, v40, v36, v40
	v_fma_f32 v37, v41, v37, v41
	v_mul_f32_e32 v36, 0x3f4c422a, v36
	v_mul_f32_e32 v37, 0x3f4c422a, v37
	v_mul_f32_e32 v36, -2.0, v36
	v_mul_f32_e32 v37, -2.0, v37
	v_mul_f32_e32 v36, 0x3fb8aa3b, v36
	v_mul_f32_e32 v37, 0x3fb8aa3b, v37
	v_exp_f32_e32 v36, v36
	v_exp_f32_e32 v37, v37
	v_add_f32_e32 v36, 1.0, v36
	v_add_f32_e32 v37, 1.0, v37
	v_rcp_f32_e32 v36, v36
	v_rcp_f32_e32 v37, v37
	s_nop 0
	v_pk_mul_f32 v[36:37], v[40:41], v[36:37]
	s_nop 0
	v_cvt_pk_bf16_f32 v36, v36, v37
	v_mul_f32_e32 v37, 0x3d372713, v42
	v_mul_f32_e32 v37, v42, v37
	v_fma_f32 v37, v42, v37, v42
	v_mul_f32_e32 v37, 0x3f4c422a, v37
	v_mul_f32_e32 v37, -2.0, v37
	v_mul_f32_e32 v37, 0x3fb8aa3b, v37
	v_exp_f32_e32 v37, v37
	s_nop 0
	v_add_f32_e32 v37, 1.0, v37
	v_rcp_f32_e32 v40, v37
	v_mul_f32_e32 v37, 0x3d372713, v43
	v_mul_f32_e32 v37, v43, v37
	v_fma_f32 v37, v43, v37, v43
	v_mul_f32_e32 v37, 0x3f4c422a, v37
	v_mul_f32_e32 v37, -2.0, v37
	v_mul_f32_e32 v37, 0x3fb8aa3b, v37
	v_exp_f32_e32 v37, v37
	s_nop 0
	v_add_f32_e32 v37, 1.0, v37
	v_rcp_f32_e32 v41, v37
	s_nop 0
	v_pk_mul_f32 v[40:41], v[42:43], v[40:41]
	s_nop 0
	v_cvt_pk_bf16_f32 v37, v40, v41
	v_mul_f32_e32 v40, 0x3d372713, v38
	v_mul_f32_e32 v41, 0x3d372713, v39
	v_mul_f32_e32 v40, v38, v40
	v_mul_f32_e32 v41, v39, v41
	v_fma_f32 v40, v38, v40, v38
	v_fma_f32 v41, v39, v41, v39
	v_mul_f32_e32 v40, 0x3f4c422a, v40
	v_mul_f32_e32 v41, 0x3f4c422a, v41
	v_mul_f32_e32 v40, -2.0, v40
	v_mul_f32_e32 v41, -2.0, v41
	v_mul_f32_e32 v40, 0x3fb8aa3b, v40
	v_mul_f32_e32 v41, 0x3fb8aa3b, v41
	v_exp_f32_e32 v40, v40
	v_exp_f32_e32 v41, v41
	v_add_f32_e32 v40, 1.0, v40
	v_add_f32_e32 v41, 1.0, v41
	v_rcp_f32_e32 v40, v40
	v_rcp_f32_e32 v41, v41
	s_nop 0
	v_pk_mul_f32 v[38:39], v[38:39], v[40:41]
	s_nop 0
	v_cvt_pk_bf16_f32 v38, v38, v39
	v_mul_f32_e32 v39, 0x3d372713, v44
	v_mul_f32_e32 v39, v44, v39
	v_fma_f32 v39, v44, v39, v44
	v_mul_f32_e32 v39, 0x3f4c422a, v39
	v_mul_f32_e32 v39, -2.0, v39
	v_mul_f32_e32 v39, 0x3fb8aa3b, v39
	v_exp_f32_e32 v39, v39
	s_nop 0
	v_add_f32_e32 v39, 1.0, v39
	v_rcp_f32_e32 v40, v39
	v_mul_f32_e32 v39, 0x3d372713, v45
	v_mul_f32_e32 v39, v45, v39
	v_fma_f32 v39, v45, v39, v45
	v_mul_f32_e32 v39, 0x3f4c422a, v39
	v_mul_f32_e32 v39, -2.0, v39
	v_mul_f32_e32 v39, 0x3fb8aa3b, v39
	v_exp_f32_e32 v39, v39
	s_nop 0
	v_add_f32_e32 v39, 1.0, v39
	v_rcp_f32_e32 v41, v39
	s_nop 0
	v_pk_mul_f32 v[40:41], v[44:45], v[40:41]
	s_nop 0
	v_cvt_pk_bf16_f32 v39, v40, v41
	global_store_dwordx4 v[100:101], v[36:39], off offset:256
	s_nop 1
	v_pk_add_f32 v[36:37], v[30:31], v[72:73]
	v_pk_add_f32 v[30:31], v[28:29], v[70:71]
	v_mul_f32_e32 v28, 0x3d372713, v32
	v_mul_f32_e32 v29, 0x3d372713, v33
	v_mul_f32_e32 v28, v32, v28
	v_mul_f32_e32 v29, v33, v29
	v_fma_f32 v28, v32, v28, v32
	v_fma_f32 v29, v33, v29, v33
	v_mul_f32_e32 v28, 0x3f4c422a, v28
	v_mul_f32_e32 v29, 0x3f4c422a, v29
	v_mul_f32_e32 v28, -2.0, v28
	v_mul_f32_e32 v29, -2.0, v29
	v_mul_f32_e32 v28, 0x3fb8aa3b, v28
	v_mul_f32_e32 v29, 0x3fb8aa3b, v29
	v_exp_f32_e32 v28, v28
	v_exp_f32_e32 v29, v29
	v_add_f32_e32 v28, 1.0, v28
	v_add_f32_e32 v29, 1.0, v29
	v_rcp_f32_e32 v28, v28
	v_rcp_f32_e32 v29, v29
	s_nop 0
	v_pk_mul_f32 v[28:29], v[32:33], v[28:29]
	s_nop 0
	v_cvt_pk_bf16_f32 v28, v28, v29
	v_mul_f32_e32 v29, 0x3d372713, v34
	v_mul_f32_e32 v29, v34, v29
	v_fma_f32 v29, v34, v29, v34
	v_mul_f32_e32 v29, 0x3f4c422a, v29
	v_mul_f32_e32 v29, -2.0, v29
	v_mul_f32_e32 v29, 0x3fb8aa3b, v29
	v_exp_f32_e32 v29, v29
	s_nop 0
	v_add_f32_e32 v29, 1.0, v29
	v_rcp_f32_e32 v32, v29
	v_mul_f32_e32 v29, 0x3d372713, v35
	v_mul_f32_e32 v29, v35, v29
	v_fma_f32 v29, v35, v29, v35
	v_mul_f32_e32 v29, 0x3f4c422a, v29
	v_mul_f32_e32 v29, -2.0, v29
	v_mul_f32_e32 v29, 0x3fb8aa3b, v29
	v_exp_f32_e32 v29, v29
	s_nop 0
	v_add_f32_e32 v29, 1.0, v29
	v_rcp_f32_e32 v33, v29
	s_nop 0
	v_pk_mul_f32 v[32:33], v[34:35], v[32:33]
	s_nop 0
	v_cvt_pk_bf16_f32 v29, v32, v33
	v_mul_f32_e32 v32, 0x3d372713, v30
	v_mul_f32_e32 v33, 0x3d372713, v31
	v_mul_f32_e32 v32, v30, v32
	v_mul_f32_e32 v33, v31, v33
	v_fma_f32 v32, v30, v32, v30
	v_fma_f32 v33, v31, v33, v31
	v_mul_f32_e32 v32, 0x3f4c422a, v32
	v_mul_f32_e32 v33, 0x3f4c422a, v33
	v_mul_f32_e32 v32, -2.0, v32
	v_mul_f32_e32 v33, -2.0, v33
; __device__ __forceinline__ unsigned cvt_pk_bf16(float lo, float hi) { const f32x2 v = {lo, hi}; const bf16v2_ r = __builtin_convertvector(v, bf16v2_); return __builtin_bit_cast(unsigned, r); }
; __device__ __forceinline__ int opaque_tid() { int t = threadIdx.x; asm volatile("" : "+v"(t)); return t; }
; __device__ __forceinline__ float gelu_tanh(float x) { const float y = 0.7978845608028654f * (x + 0.044715f * x * x * x); return x * __builtin_amdgcn_rcpf(1.f + __expf(-2.f * y)); }
;     __device__ __forceinline__ void operator()(const f32x4 (&acc)[2][2][4][2], const Unit& u, int wr, int wc, int, int) const {
;         const int ol_ = opaque_tid() & 63, fr = ol_ & 15, fq = ol_ >> 4;
;         const int row0 = u.pm * BM + wr * 64 + fr, col0 = u.pn * BM + wc * 32 + 8 * fq;
; #pragma unroll
;         for (int bj = 0; bj < 2; ++bj) { f32x4 b0 = (f32x4){0.f, 0.f, 0.f, 0.f}, b1 = b0;
; #pragma unroll 8
;             for (int pp = 0; pp < 32; ++pp) { b0 += *(const f32x4*)(bias + pp * 256 + col0 + bj * HALF); b1 += *(const f32x4*)(bias + pp * 256 + col0 + bj * HALF + 4); }
; #pragma unroll
;             for (int ai = 0; ai < 2; ++ai)
; #pragma unroll
;                 for (int m = 0; m < 4; ++m) { const f32x4 v0 = acc[ai][bj][m][0] + b0, v1 = acc[ai][bj][m][1] + b1;
;                     u32x4 w; w.x = cvt_pk_bf16(gelu_tanh(v0[0]), gelu_tanh(v0[1])); w.y = cvt_pk_bf16(gelu_tanh(v0[2]), gelu_tanh(v0[3]));
;                     w.z = cvt_pk_bf16(gelu_tanh(v1[0]), gelu_tanh(v1[1])); w.w = cvt_pk_bf16(gelu_tanh(v1[2]), gelu_tanh(v1[3]));
;                     *(u32x4*)(O + (size_t)(row0 + ai * HALF + m * 16) * ldc + col0 + bj * HALF) = w; } }
	v_mul_f32_e32 v32, 0x3fb8aa3b, v32
	v_mul_f32_e32 v33, 0x3fb8aa3b, v33
	v_exp_f32_e32 v32, v32
	v_exp_f32_e32 v33, v33
	v_add_f32_e32 v32, 1.0, v32
	v_add_f32_e32 v33, 1.0, v33
	v_rcp_f32_e32 v32, v32
	v_rcp_f32_e32 v33, v33
	s_nop 0
	v_pk_mul_f32 v[30:31], v[30:31], v[32:33]
	s_nop 0
	v_cvt_pk_bf16_f32 v30, v30, v31
	v_mul_f32_e32 v31, 0x3d372713, v36
	v_mul_f32_e32 v31, v36, v31
	v_fma_f32 v31, v36, v31, v36
	v_mul_f32_e32 v31, 0x3f4c422a, v31
	v_mul_f32_e32 v31, -2.0, v31
	v_mul_f32_e32 v31, 0x3fb8aa3b, v31
	v_exp_f32_e32 v31, v31
	s_nop 0
	v_add_f32_e32 v31, 1.0, v31
	v_rcp_f32_e32 v32, v31
	v_mul_f32_e32 v31, 0x3d372713, v37
	v_mul_f32_e32 v31, v37, v31
	v_fma_f32 v31, v37, v31, v37
	v_mul_f32_e32 v31, 0x3f4c422a, v31
	v_mul_f32_e32 v31, -2.0, v31
	v_mul_f32_e32 v31, 0x3fb8aa3b, v31
	v_exp_f32_e32 v31, v31
	s_nop 0
	v_add_f32_e32 v31, 1.0, v31
	v_rcp_f32_e32 v33, v31
	s_nop 0
	v_pk_mul_f32 v[32:33], v[36:37], v[32:33]
	s_nop 0
	v_cvt_pk_bf16_f32 v31, v32, v33
	global_store_dwordx4 v[92:93], v[28:31], off offset:256
	s_nop 1
	v_pk_add_f32 v[28:29], v[22:23], v[72:73]
	v_pk_add_f32 v[22:23], v[20:21], v[70:71]
	v_mul_f32_e32 v20, 0x3d372713, v24
	v_mul_f32_e32 v21, 0x3d372713, v25
	v_mul_f32_e32 v20, v24, v20
	v_mul_f32_e32 v21, v25, v21
	v_fma_f32 v20, v24, v20, v24
	v_fma_f32 v21, v25, v21, v25
	v_mul_f32_e32 v20, 0x3f4c422a, v20
	v_mul_f32_e32 v21, 0x3f4c422a, v21
	v_mul_f32_e32 v20, -2.0, v20
	v_mul_f32_e32 v21, -2.0, v21
	v_mul_f32_e32 v20, 0x3fb8aa3b, v20
	v_mul_f32_e32 v21, 0x3fb8aa3b, v21
	v_exp_f32_e32 v20, v20
	v_exp_f32_e32 v21, v21
	v_add_f32_e32 v20, 1.0, v20
	v_add_f32_e32 v21, 1.0, v21
	v_rcp_f32_e32 v20, v20
	v_rcp_f32_e32 v21, v21
	s_nop 0
	v_pk_mul_f32 v[20:21], v[24:25], v[20:21]
	s_nop 0
	v_cvt_pk_bf16_f32 v20, v20, v21
	v_mul_f32_e32 v21, 0x3d372713, v26
	v_mul_f32_e32 v21, v26, v21
	v_fma_f32 v21, v26, v21, v26
	v_mul_f32_e32 v21, 0x3f4c422a, v21
	v_mul_f32_e32 v21, -2.0, v21
	v_mul_f32_e32 v21, 0x3fb8aa3b, v21
	v_exp_f32_e32 v21, v21
	s_nop 0
	v_add_f32_e32 v21, 1.0, v21
	v_rcp_f32_e32 v24, v21
	v_mul_f32_e32 v21, 0x3d372713, v27
	v_mul_f32_e32 v21, v27, v21
	v_fma_f32 v21, v27, v21, v27
	v_mul_f32_e32 v21, 0x3f4c422a, v21
	v_mul_f32_e32 v21, -2.0, v21
	v_mul_f32_e32 v21, 0x3fb8aa3b, v21
	v_exp_f32_e32 v21, v21
	s_nop 0
	v_add_f32_e32 v21, 1.0, v21
	v_rcp_f32_e32 v25, v21
	s_nop 0
	v_pk_mul_f32 v[24:25], v[26:27], v[24:25]
	s_nop 0
	v_cvt_pk_bf16_f32 v21, v24, v25
	v_mul_f32_e32 v24, 0x3d372713, v22
	v_mul_f32_e32 v25, 0x3d372713, v23
	v_mul_f32_e32 v24, v22, v24
	v_mul_f32_e32 v25, v23, v25
	v_fma_f32 v24, v22, v24, v22
	v_fma_f32 v25, v23, v25, v23
	v_mul_f32_e32 v24, 0x3f4c422a, v24
	v_mul_f32_e32 v25, 0x3f4c422a, v25
	v_mul_f32_e32 v24, -2.0, v24
	v_mul_f32_e32 v25, -2.0, v25
	v_mul_f32_e32 v24, 0x3fb8aa3b, v24
	v_mul_f32_e32 v25, 0x3fb8aa3b, v25
	v_exp_f32_e32 v24, v24
	v_exp_f32_e32 v25, v25
	v_add_f32_e32 v24, 1.0, v24
	v_add_f32_e32 v25, 1.0, v25
	v_rcp_f32_e32 v24, v24
	v_rcp_f32_e32 v25, v25
	s_nop 0
	v_pk_mul_f32 v[22:23], v[22:23], v[24:25]
	s_nop 0
	v_cvt_pk_bf16_f32 v22, v22, v23
	v_mul_f32_e32 v23, 0x3d372713, v28
	v_mul_f32_e32 v23, v28, v23
	v_fma_f32 v23, v28, v23, v28
	v_mul_f32_e32 v23, 0x3f4c422a, v23
	v_mul_f32_e32 v23, -2.0, v23
	v_mul_f32_e32 v23, 0x3fb8aa3b, v23
	v_exp_f32_e32 v23, v23
	s_nop 0
	v_add_f32_e32 v23, 1.0, v23
	v_rcp_f32_e32 v24, v23
	v_mul_f32_e32 v23, 0x3d372713, v29
	v_mul_f32_e32 v23, v29, v23
	v_fma_f32 v23, v29, v23, v29
	v_mul_f32_e32 v23, 0x3f4c422a, v23
	v_mul_f32_e32 v23, -2.0, v23
	v_mul_f32_e32 v23, 0x3fb8aa3b, v23
	v_exp_f32_e32 v23, v23
	s_nop 0
	v_add_f32_e32 v23, 1.0, v23
	v_rcp_f32_e32 v25, v23
	s_nop 0
	v_pk_mul_f32 v[24:25], v[28:29], v[24:25]
	s_nop 0
	v_cvt_pk_bf16_f32 v23, v24, v25
	global_store_dwordx4 v[84:85], v[20:23], off offset:256
	s_nop 1
	v_pk_add_f32 v[20:21], v[14:15], v[72:73]
	v_pk_add_f32 v[14:15], v[12:13], v[70:71]
	v_mul_f32_e32 v12, 0x3d372713, v16
	v_mul_f32_e32 v13, 0x3d372713, v17
	v_mul_f32_e32 v12, v16, v12
	v_mul_f32_e32 v13, v17, v13
	v_fma_f32 v12, v16, v12, v16
	v_fma_f32 v13, v17, v13, v17
	v_mul_f32_e32 v12, 0x3f4c422a, v12
	v_mul_f32_e32 v13, 0x3f4c422a, v13
	v_mul_f32_e32 v12, -2.0, v12
	v_mul_f32_e32 v13, -2.0, v13
	v_mul_f32_e32 v12, 0x3fb8aa3b, v12
	v_mul_f32_e32 v13, 0x3fb8aa3b, v13
	v_exp_f32_e32 v12, v12
	v_exp_f32_e32 v13, v13
	v_add_f32_e32 v12, 1.0, v12
	v_add_f32_e32 v13, 1.0, v13
	v_rcp_f32_e32 v12, v12
	v_rcp_f32_e32 v13, v13
	s_nop 0
	v_pk_mul_f32 v[12:13], v[16:17], v[12:13]
	s_nop 0
	v_cvt_pk_bf16_f32 v12, v12, v13
	v_mul_f32_e32 v13, 0x3d372713, v18
	v_mul_f32_e32 v13, v18, v13
; __device__ __forceinline__ unsigned cvt_pk_bf16(float lo, float hi) { const f32x2 v = {lo, hi}; const bf16v2_ r = __builtin_convertvector(v, bf16v2_); return __builtin_bit_cast(unsigned, r); }
; __device__ __forceinline__ int opaque_tid() { int t = threadIdx.x; asm volatile("" : "+v"(t)); return t; }
; __device__ __forceinline__ float gelu_tanh(float x) { const float y = 0.7978845608028654f * (x + 0.044715f * x * x * x); return x * __builtin_amdgcn_rcpf(1.f + __expf(-2.f * y)); }
;     __device__ __forceinline__ void operator()(const f32x4 (&acc)[2][2][4][2], const Unit& u, int wr, int wc, int, int) const {
;         const int ol_ = opaque_tid() & 63, fr = ol_ & 15, fq = ol_ >> 4;
;         const int row0 = u.pm * BM + wr * 64 + fr, col0 = u.pn * BM + wc * 32 + 8 * fq;
; #pragma unroll
;         for (int bj = 0; bj < 2; ++bj) { f32x4 b0 = (f32x4){0.f, 0.f, 0.f, 0.f}, b1 = b0;
; #pragma unroll 8
;             for (int pp = 0; pp < 32; ++pp) { b0 += *(const f32x4*)(bias + pp * 256 + col0 + bj * HALF); b1 += *(const f32x4*)(bias + pp * 256 + col0 + bj * HALF + 4); }
; #pragma unroll
;             for (int ai = 0; ai < 2; ++ai)
; #pragma unroll
;                 for (int m = 0; m < 4; ++m) { const f32x4 v0 = acc[ai][bj][m][0] + b0, v1 = acc[ai][bj][m][1] + b1;
;                     u32x4 w; w.x = cvt_pk_bf16(gelu_tanh(v0[0]), gelu_tanh(v0[1])); w.y = cvt_pk_bf16(gelu_tanh(v0[2]), gelu_tanh(v0[3]));
;                     w.z = cvt_pk_bf16(gelu_tanh(v1[0]), gelu_tanh(v1[1])); w.w = cvt_pk_bf16(gelu_tanh(v1[2]), gelu_tanh(v1[3]));
;                     *(u32x4*)(O + (size_t)(row0 + ai * HALF + m * 16) * ldc + col0 + bj * HALF) = w; } }
	v_fma_f32 v13, v18, v13, v18
	v_mul_f32_e32 v13, 0x3f4c422a, v13
	v_mul_f32_e32 v13, -2.0, v13
	v_mul_f32_e32 v13, 0x3fb8aa3b, v13
	v_exp_f32_e32 v13, v13
	s_nop 0
	v_add_f32_e32 v13, 1.0, v13
	v_rcp_f32_e32 v16, v13
	v_mul_f32_e32 v13, 0x3d372713, v19
	v_mul_f32_e32 v13, v19, v13
	v_fma_f32 v13, v19, v13, v19
	v_mul_f32_e32 v13, 0x3f4c422a, v13
	v_mul_f32_e32 v13, -2.0, v13
	v_mul_f32_e32 v13, 0x3fb8aa3b, v13
	v_exp_f32_e32 v13, v13
	s_nop 0
	v_add_f32_e32 v13, 1.0, v13
	v_rcp_f32_e32 v17, v13
	s_nop 0
	v_pk_mul_f32 v[16:17], v[18:19], v[16:17]
	s_nop 0
	v_cvt_pk_bf16_f32 v13, v16, v17
	v_mul_f32_e32 v16, 0x3d372713, v14
	v_mul_f32_e32 v17, 0x3d372713, v15
	v_mul_f32_e32 v16, v14, v16
	v_mul_f32_e32 v17, v15, v17
	v_fma_f32 v16, v14, v16, v14
	v_fma_f32 v17, v15, v17, v15
	v_mul_f32_e32 v16, 0x3f4c422a, v16
	v_mul_f32_e32 v17, 0x3f4c422a, v17
	v_mul_f32_e32 v16, -2.0, v16
	v_mul_f32_e32 v17, -2.0, v17
	v_mul_f32_e32 v16, 0x3fb8aa3b, v16
	v_mul_f32_e32 v17, 0x3fb8aa3b, v17
	v_exp_f32_e32 v16, v16
	v_exp_f32_e32 v17, v17
	v_add_f32_e32 v16, 1.0, v16
	v_add_f32_e32 v17, 1.0, v17
	v_rcp_f32_e32 v16, v16
	v_rcp_f32_e32 v17, v17
	s_nop 0
	v_pk_mul_f32 v[14:15], v[14:15], v[16:17]
	s_nop 0
	v_cvt_pk_bf16_f32 v14, v14, v15
	v_mul_f32_e32 v15, 0x3d372713, v20
	v_mul_f32_e32 v15, v20, v15
	v_fma_f32 v15, v20, v15, v20
	v_mul_f32_e32 v15, 0x3f4c422a, v15
	v_mul_f32_e32 v15, -2.0, v15
	v_mul_f32_e32 v15, 0x3fb8aa3b, v15
	v_exp_f32_e32 v15, v15
	s_nop 0
	v_add_f32_e32 v15, 1.0, v15
	v_rcp_f32_e32 v16, v15
	v_mul_f32_e32 v15, 0x3d372713, v21
	v_mul_f32_e32 v15, v21, v15
	v_fma_f32 v15, v21, v15, v21
	v_mul_f32_e32 v15, 0x3f4c422a, v15
	v_mul_f32_e32 v15, -2.0, v15
	v_mul_f32_e32 v15, 0x3fb8aa3b, v15
	v_exp_f32_e32 v15, v15
	s_nop 0
	v_add_f32_e32 v15, 1.0, v15
	v_rcp_f32_e32 v17, v15
	s_nop 0
	v_pk_mul_f32 v[16:17], v[20:21], v[16:17]
	s_nop 0
	v_cvt_pk_bf16_f32 v15, v16, v17
	global_store_dwordx4 v[76:77], v[12:15], off offset:256
	s_nop 1
	v_pk_add_f32 v[12:13], v[6:7], v[72:73]
	v_pk_add_f32 v[6:7], v[4:5], v[70:71]
	v_mul_f32_e32 v4, 0x3d372713, v8
	v_mul_f32_e32 v5, 0x3d372713, v9
	v_mul_f32_e32 v4, v8, v4
	v_mul_f32_e32 v5, v9, v5
	v_fma_f32 v4, v8, v4, v8
	v_fma_f32 v5, v9, v5, v9
	v_mul_f32_e32 v4, 0x3f4c422a, v4
	v_mul_f32_e32 v5, 0x3f4c422a, v5
	v_mul_f32_e32 v4, -2.0, v4
	v_mul_f32_e32 v5, -2.0, v5
	v_mul_f32_e32 v4, 0x3fb8aa3b, v4
	v_mul_f32_e32 v5, 0x3fb8aa3b, v5
	v_exp_f32_e32 v4, v4
	v_exp_f32_e32 v5, v5
	v_add_f32_e32 v4, 1.0, v4
	v_add_f32_e32 v5, 1.0, v5
	v_rcp_f32_e32 v4, v4
	v_rcp_f32_e32 v5, v5
	s_nop 0
	v_pk_mul_f32 v[4:5], v[8:9], v[4:5]
	s_nop 0
	v_cvt_pk_bf16_f32 v4, v4, v5
	v_mul_f32_e32 v5, 0x3d372713, v10
	v_mul_f32_e32 v5, v10, v5
	v_fma_f32 v5, v10, v5, v10
	v_mul_f32_e32 v5, 0x3f4c422a, v5
	v_mul_f32_e32 v5, -2.0, v5
	v_mul_f32_e32 v5, 0x3fb8aa3b, v5
	v_exp_f32_e32 v5, v5
	s_nop 0
	v_add_f32_e32 v5, 1.0, v5
	v_rcp_f32_e32 v8, v5
	v_mul_f32_e32 v5, 0x3d372713, v11
	v_mul_f32_e32 v5, v11, v5
	v_fma_f32 v5, v11, v5, v11
	v_mul_f32_e32 v5, 0x3f4c422a, v5
	v_mul_f32_e32 v5, -2.0, v5
	v_mul_f32_e32 v5, 0x3fb8aa3b, v5
	v_exp_f32_e32 v5, v5
	s_nop 0
	v_add_f32_e32 v5, 1.0, v5
	v_rcp_f32_e32 v9, v5
	s_nop 0
	v_pk_mul_f32 v[8:9], v[10:11], v[8:9]
	s_nop 0
	v_cvt_pk_bf16_f32 v5, v8, v9
	v_mul_f32_e32 v8, 0x3d372713, v6
	v_mul_f32_e32 v9, 0x3d372713, v7
	v_mul_f32_e32 v8, v6, v8
	v_mul_f32_e32 v9, v7, v9
	v_fma_f32 v8, v6, v8, v6
	v_fma_f32 v9, v7, v9, v7
	v_mul_f32_e32 v8, 0x3f4c422a, v8
	v_mul_f32_e32 v9, 0x3f4c422a, v9
	v_mul_f32_e32 v8, -2.0, v8
	v_mul_f32_e32 v9, -2.0, v9
	v_mul_f32_e32 v8, 0x3fb8aa3b, v8
	v_mul_f32_e32 v9, 0x3fb8aa3b, v9
	v_exp_f32_e32 v8, v8
	v_exp_f32_e32 v9, v9
	v_add_f32_e32 v8, 1.0, v8
	v_add_f32_e32 v9, 1.0, v9
	v_rcp_f32_e32 v8, v8
	v_rcp_f32_e32 v9, v9
	s_nop 0
	v_pk_mul_f32 v[6:7], v[6:7], v[8:9]
	s_nop 0
	v_cvt_pk_bf16_f32 v6, v6, v7
	v_mul_f32_e32 v7, 0x3d372713, v12
	v_mul_f32_e32 v7, v12, v7
	v_fma_f32 v7, v12, v7, v12
	v_mul_f32_e32 v7, 0x3f4c422a, v7
	v_mul_f32_e32 v7, -2.0, v7
	v_mul_f32_e32 v7, 0x3fb8aa3b, v7
	v_exp_f32_e32 v7, v7
	s_nop 0
	v_add_f32_e32 v7, 1.0, v7
	v_rcp_f32_e32 v8, v7
	v_mul_f32_e32 v7, 0x3d372713, v13
	v_mul_f32_e32 v7, v13, v7
	v_fma_f32 v7, v13, v7, v13
	v_mul_f32_e32 v7, 0x3f4c422a, v7
	v_mul_f32_e32 v7, -2.0, v7
	v_mul_f32_e32 v7, 0x3fb8aa3b, v7
	v_exp_f32_e32 v7, v7
	s_nop 0
	v_add_f32_e32 v7, 1.0, v7
	v_rcp_f32_e32 v9, v7
	s_nop 0
	v_pk_mul_f32 v[8:9], v[12:13], v[8:9]
	s_nop 0
	v_cvt_pk_bf16_f32 v7, v8, v9
	global_store_dwordx4 v[68:69], v[4:7], off offset:256
	s_cbranch_vccz .LBB0_484
	s_waitcnt vmcnt(0)
	s_cmpk_gt_u32 s21, 0xff
	s_cbranch_scc1 .LBB0_499
	s_barrier

; #define PG8_STAGE(bufoff, gbase, voff) do { _Pragma("unroll") for (int _i = 0; _i < 2; ++_i) \
;         __builtin_amdgcn_global_load_lds((const unsigned*)((const char*)(gbase) + (voff)[_i]), (LAS unsigned*)(lds + (bufoff) + ldsw + _i * 8192), 16, 0, 0); } while (0)
; #define PG8_LDA(dst, b, h) do { _Pragma("unroll") for (int m = 0; m < 4; ++m) _Pragma("unroll") for (int k = 0; k < 2; ++k) dst[m][k] = *(const LAS bf16x8*)(lds + PG8_SA(b, h) + aoff + m * 2048 + k * 1024); } while (0)
; #define PG8_LDB(dst, b, h) do { _Pragma("unroll") for (int n = 0; n < 2; ++n) _Pragma("unroll") for (int k = 0; k < 2; ++k) dst[n][k] = *(const LAS bf16x8*)(lds + PG8_SB(b, h) + boff + n * 2048 + k * 1024); } while (0)
; #define PG8_MMA(ai, bj, At, Bt) do { __builtin_amdgcn_s_setprio(1); _Pragma("unroll") for (int m = 0; m < 4; ++m) _Pragma("unroll") for (int n = 0; n < 2; ++n) _Pragma("unroll") for (int k = 0; k < 2; ++k) \
;         acc[ai][bj][m][n] = __builtin_amdgcn_mfma_f32_16x16x32_bf16(Bt[n][k], At[m][k], acc[ai][bj][m][n], 0, 0, 0); __builtin_amdgcn_s_setprio(0); } while (0)
; #define PG8_WAIT_V(n) asm volatile("s_waitcnt vmcnt(" #n ")" ::: "memory")
; #define PG8_WAIT_L(n) asm volatile("s_waitcnt lgkmcnt(" #n ")" ::: "memory")
; #define PG8_BAR __builtin_amdgcn_s_barrier()
; #define PG8_SCHED __builtin_amdgcn_sched_barrier(0)
; template <class Epi, class Sched>
; __device__ __forceinline__ void gemm_phase(LAS unsigned char* lds, const Gemm g, const Sched& S, const Epi& E) {
;     ...
;             PG8_LDB(B0, 0, 0); PG8_SCHED; PG8_LDA(At, 0, 0); PG8_STAGE(PG8_SA(1, 1), a1 + hstepA, voffA);
;             PG8_WAIT_L(8); PG8_BAR; PG8_WAIT_L(0); PG8_MMA(0, 0, At, B0); PG8_BAR; PG8_SCHED;
;             PG8_LDB(B1, 0, 1); PG8_STAGE(PG8_SB(0, 0), b2, voffB);
;             PG8_BAR; PG8_WAIT_L(0); PG8_MMA(0, 1, At, B1); PG8_BAR;
;             PG8_LDA(At, 0, 1); PG8_STAGE(PG8_SA(0, 0), a2, voffA);
;             PG8_BAR; PG8_WAIT_L(0); PG8_MMA(1, 0, At, B0); PG8_BAR; PG8_SCHED;
;             PG8_STAGE(PG8_SB(0, 1), b2 + hstepB, voffB);
;             PG8_WAIT_V(6); PG8_BAR; PG8_MMA(1, 1, At, B1); PG8_BAR;
.LBB0_966:
	s_setprio 0
	s_add_u32 s20, s6, 0xfff80080
	s_addc_u32 s21, s7, -1
	s_add_i32 s52, 0, 0x10000
	v_add_u32_e32 v144, s52, v1
	ds_read_b128 v[132:135], v144
	ds_read_b128 v[136:139], v144 offset:1024
	ds_read_b128 v[140:143], v144 offset:2048
	ds_read_b128 v[144:147], v144 offset:3072
	s_cmp_eq_u32 s51, 28
	s_cselect_b32 s25, s15, s21
	s_cselect_b32 s24, s47, s20
	s_cselect_b32 s21, s1, s50
	s_cselect_b32 s20, s48, s49
	ds_read_b128 v[148:151], v224
	ds_read_b128 v[152:155], v224 offset:1024
	ds_read_b128 v[156:159], v224 offset:2048
	ds_read_b128 v[160:163], v224 offset:3072
	ds_read_b128 v[164:167], v224 offset:4096
	ds_read_b128 v[168:171], v224 offset:5120
	ds_read_b128 v[172:175], v224 offset:6144
	ds_read_b128 v[176:179], v224 offset:7168
	s_add_i32 s54, 0, 0x14000
	v_add_u32_e32 v202, s54, v1
	ds_read_b128 v[180:183], v202
	ds_read_b128 v[184:187], v202 offset:1024
	ds_read_b128 v[188:191], v202 offset:2048
	ds_read_b128 v[202:205], v202 offset:3072
	s_add_i32 m0, s31, 0xc000
	s_nop 0
	global_load_lds_dwordx4 v198, s[6:7]
	s_add_i32 m0, s31, 0xe000
	s_nop 0
	global_load_lds_dwordx4 v200, s[6:7]
	s_waitcnt lgkmcnt(0)
	s_setprio 1
	s_barrier
	v_mfma_f32_16x16x32_bf16 v[128:131], v[132:135], v[148:151], v[128:131]
	v_mfma_f32_16x16x32_bf16 v[124:127], v[140:143], v[148:151], v[124:127]
	v_mfma_f32_16x16x32_bf16 v[112:115], v[132:135], v[156:159], v[112:115]
	v_mfma_f32_16x16x32_bf16 v[108:111], v[140:143], v[156:159], v[108:111]
	v_mfma_f32_16x16x32_bf16 v[100:103], v[132:135], v[164:167], v[100:103]
	v_mfma_f32_16x16x32_bf16 v[92:95], v[140:143], v[164:167], v[92:95]
	v_mfma_f32_16x16x32_bf16 v[84:87], v[132:135], v[172:175], v[84:87]
	v_mfma_f32_16x16x32_bf16 v[76:79], v[140:143], v[172:175], v[76:79]
	v_mfma_f32_16x16x32_bf16 v[128:131], v[136:139], v[152:155], v[128:131]
	v_mfma_f32_16x16x32_bf16 v[124:127], v[144:147], v[152:155], v[124:127]
	v_mfma_f32_16x16x32_bf16 v[112:115], v[136:139], v[160:163], v[112:115]
	v_mfma_f32_16x16x32_bf16 v[108:111], v[144:147], v[160:163], v[108:111]
	v_mfma_f32_16x16x32_bf16 v[100:103], v[136:139], v[168:171], v[100:103]
	v_mfma_f32_16x16x32_bf16 v[92:95], v[144:147], v[168:171], v[92:95]
	v_mfma_f32_16x16x32_bf16 v[84:87], v[136:139], v[176:179], v[84:87]
	v_mfma_f32_16x16x32_bf16 v[76:79], v[144:147], v[176:179], v[76:79]
	v_mfma_f32_16x16x32_bf16 v[120:123], v[180:183], v[148:151], v[120:123]
	v_mfma_f32_16x16x32_bf16 v[116:119], v[188:191], v[148:151], v[116:119]
	v_mfma_f32_16x16x32_bf16 v[104:107], v[180:183], v[156:159], v[104:107]
	v_mfma_f32_16x16x32_bf16 v[96:99], v[188:191], v[156:159], v[96:99]
	v_mfma_f32_16x16x32_bf16 v[88:91], v[180:183], v[164:167], v[88:91]
	v_mfma_f32_16x16x32_bf16 v[80:83], v[188:191], v[164:167], v[80:83]
	v_mfma_f32_16x16x32_bf16 v[72:75], v[180:183], v[172:175], v[72:75]
	v_mfma_f32_16x16x32_bf16 v[68:71], v[188:191], v[172:175], v[68:71]
	v_mfma_f32_16x16x32_bf16 v[120:123], v[184:187], v[152:155], v[120:123]
	v_mfma_f32_16x16x32_bf16 v[116:119], v[202:205], v[152:155], v[116:119]
	v_mfma_f32_16x16x32_bf16 v[104:107], v[184:187], v[160:163], v[104:107]
	v_mfma_f32_16x16x32_bf16 v[96:99], v[202:205], v[160:163], v[96:99]
	v_mfma_f32_16x16x32_bf16 v[88:91], v[184:187], v[168:171], v[88:91]
	v_mfma_f32_16x16x32_bf16 v[80:83], v[202:205], v[168:171], v[80:83]
	v_mfma_f32_16x16x32_bf16 v[72:75], v[184:187], v[176:179], v[72:75]
	v_mfma_f32_16x16x32_bf16 v[68:71], v[202:205], v[176:179], v[68:71]
	s_barrier
	s_setprio 0
	ds_read_b128 v[148:151], v224 offset:16384
	ds_read_b128 v[152:155], v224 offset:17408
	ds_read_b128 v[156:159], v224 offset:18432
	ds_read_b128 v[160:163], v224 offset:19456
	ds_read_b128 v[164:167], v224 offset:20480
	ds_read_b128 v[168:171], v224 offset:21504
	ds_read_b128 v[172:175], v224 offset:22528
	ds_read_b128 v[176:179], v224 offset:23552
	s_add_i32 s52, s52, s30
	v_lshl_add_u64 v[206:207], s[20:21], 0, v[2:3]
	s_mov_b32 m0, s52
	s_nop 0
	global_load_lds_dwordx4 v[206:207], off
	v_lshl_add_u64 v[208:209], s[20:21], 0, v[192:193]
	s_add_i32 m0, s52, 0x2000
	s_nop 0
	global_load_lds_dwordx4 v[208:209], off
	s_mov_b32 m0, s31
	v_lshl_add_u64 v[210:211], s[24:25], 0, v[196:197]
	global_load_lds_dwordx4 v[210:211], off
	v_lshl_add_u64 v[212:213], s[24:25], 0, v[194:195]
	s_mov_b32 m0, s35
	s_nop 0
	global_load_lds_dwordx4 v[212:213], off
	s_add_u32 s52, s20, 0x80000
	s_addc_u32 s53, s21, 0
	s_add_i32 s54, s54, s30
	s_mov_b32 m0, s54
	s_nop 0
	global_load_lds_dwordx4 v2, s[52:53]
	s_add_i32 m0, s54, 0x2000
	s_nop 0
	global_load_lds_dwordx4 v192, s[52:53]
	s_waitcnt lgkmcnt(0)
	s_waitcnt vmcnt(6)
	s_setprio 1
	s_barrier
; #define PG8_STAGE(bufoff, gbase, voff) do { _Pragma("unroll") for (int _i = 0; _i < 2; ++_i) \
;         __builtin_amdgcn_global_load_lds((const unsigned*)((const char*)(gbase) + (voff)[_i]), (LAS unsigned*)(lds + (bufoff) + ldsw + _i * 8192), 16, 0, 0); } while (0)
; #define PG8_LDA(dst, b, h) do { _Pragma("unroll") for (int m = 0; m < 4; ++m) _Pragma("unroll") for (int k = 0; k < 2; ++k) dst[m][k] = *(const LAS bf16x8*)(lds + PG8_SA(b, h) + aoff + m * 2048 + k * 1024); } while (0)
; #define PG8_LDB(dst, b, h) do { _Pragma("unroll") for (int n = 0; n < 2; ++n) _Pragma("unroll") for (int k = 0; k < 2; ++k) dst[n][k] = *(const LAS bf16x8*)(lds + PG8_SB(b, h) + boff + n * 2048 + k * 1024); } while (0)
; #define PG8_MMA(ai, bj, At, Bt) do { __builtin_amdgcn_s_setprio(1); _Pragma("unroll") for (int m = 0; m < 4; ++m) _Pragma("unroll") for (int n = 0; n < 2; ++n) _Pragma("unroll") for (int k = 0; k < 2; ++k) \
;         acc[ai][bj][m][n] = __builtin_amdgcn_mfma_f32_16x16x32_bf16(Bt[n][k], At[m][k], acc[ai][bj][m][n], 0, 0, 0); __builtin_amdgcn_s_setprio(0); } while (0)
; #define PG8_WAIT_V(n) asm volatile("s_waitcnt vmcnt(" #n ")" ::: "memory")
; #define PG8_WAIT_L(n) asm volatile("s_waitcnt lgkmcnt(" #n ")" ::: "memory")
; #define PG8_BAR __builtin_amdgcn_s_barrier()
; #define PG8_SCHED __builtin_amdgcn_sched_barrier(0)
; template <class Epi, class Sched>
; __device__ __forceinline__ void gemm_phase(LAS unsigned char* lds, const Gemm g, const Sched& S, const Epi& E) {
;     ...
;             PG8_WAIT_V(6); PG8_BAR; PG8_MMA(1, 1, At, B1); PG8_BAR;
;             PG8_LDB(B0, 1, 0); PG8_SCHED; PG8_LDA(At, 1, 0); PG8_STAGE(PG8_SA(0, 1), a2 + hstepA, voffA);
;             PG8_WAIT_L(8); PG8_BAR; PG8_WAIT_L(0); PG8_MMA(0, 0, At, B0); PG8_BAR; PG8_SCHED;
;             PG8_LDB(B1, 1, 1); PG8_STAGE(PG8_SB(1, 0), b3, voffB);
;             PG8_BAR; PG8_WAIT_L(0); PG8_MMA(0, 1, At, B1); PG8_BAR;
;             PG8_LDA(At, 1, 1); PG8_STAGE(PG8_SA(1, 0), a3, voffA);
;             PG8_BAR; PG8_WAIT_L(0); PG8_MMA(1, 0, At, B0); PG8_BAR; PG8_SCHED;
	v_mfma_f32_16x16x32_bf16 v[64:67], v[132:135], v[148:151], v[64:67]
	v_mfma_f32_16x16x32_bf16 v[60:63], v[140:143], v[148:151], v[60:63]
	v_mfma_f32_16x16x32_bf16 v[52:55], v[132:135], v[156:159], v[52:55]
	v_mfma_f32_16x16x32_bf16 v[44:47], v[140:143], v[156:159], v[44:47]
	v_mfma_f32_16x16x32_bf16 v[36:39], v[132:135], v[164:167], v[36:39]
	v_mfma_f32_16x16x32_bf16 v[28:31], v[140:143], v[164:167], v[28:31]
	v_mfma_f32_16x16x32_bf16 v[20:23], v[132:135], v[172:175], v[20:23]
	v_mfma_f32_16x16x32_bf16 v[12:15], v[140:143], v[172:175], v[12:15]
	v_mfma_f32_16x16x32_bf16 v[64:67], v[136:139], v[152:155], v[64:67]
	v_mfma_f32_16x16x32_bf16 v[60:63], v[144:147], v[152:155], v[60:63]
	v_mfma_f32_16x16x32_bf16 v[52:55], v[136:139], v[160:163], v[52:55]
	v_mfma_f32_16x16x32_bf16 v[44:47], v[144:147], v[160:163], v[44:47]
	v_mfma_f32_16x16x32_bf16 v[36:39], v[136:139], v[168:171], v[36:39]
	v_mfma_f32_16x16x32_bf16 v[28:31], v[144:147], v[168:171], v[28:31]
	v_mfma_f32_16x16x32_bf16 v[20:23], v[136:139], v[176:179], v[20:23]
	v_mfma_f32_16x16x32_bf16 v[12:15], v[144:147], v[176:179], v[12:15]
	v_mfma_f32_16x16x32_bf16 v[56:59], v[180:183], v[148:151], v[56:59]
	v_mfma_f32_16x16x32_bf16 v[48:51], v[188:191], v[148:151], v[48:51]
	v_mfma_f32_16x16x32_bf16 v[40:43], v[180:183], v[156:159], v[40:43]
	v_mfma_f32_16x16x32_bf16 v[32:35], v[188:191], v[156:159], v[32:35]
	v_mfma_f32_16x16x32_bf16 v[24:27], v[180:183], v[164:167], v[24:27]
	v_mfma_f32_16x16x32_bf16 v[16:19], v[188:191], v[164:167], v[16:19]
	v_mfma_f32_16x16x32_bf16 v[8:11], v[180:183], v[172:175], v[8:11]
	v_mfma_f32_16x16x32_bf16 v[4:7], v[188:191], v[172:175], v[4:7]
	v_mfma_f32_16x16x32_bf16 v[56:59], v[184:187], v[152:155], v[56:59]
	v_mfma_f32_16x16x32_bf16 v[48:51], v[202:205], v[152:155], v[48:51]
	v_mfma_f32_16x16x32_bf16 v[40:43], v[184:187], v[160:163], v[40:43]
	v_mfma_f32_16x16x32_bf16 v[32:35], v[202:205], v[160:163], v[32:35]
	v_mfma_f32_16x16x32_bf16 v[24:27], v[184:187], v[168:171], v[24:27]
	v_mfma_f32_16x16x32_bf16 v[16:19], v[202:205], v[168:171], v[16:19]
	v_mfma_f32_16x16x32_bf16 v[8:11], v[184:187], v[176:179], v[8:11]
	v_mfma_f32_16x16x32_bf16 v[4:7], v[202:205], v[176:179], v[4:7]
	s_barrier
	s_setprio 0
	s_add_i32 s52, 0, 0x18000
	v_add_u32_e32 v144, s52, v1
	ds_read_b128 v[132:135], v144
	ds_read_b128 v[136:139], v144 offset:1024
	ds_read_b128 v[140:143], v144 offset:2048
	ds_read_b128 v[144:147], v144 offset:3072
	s_add_u32 s24, s24, 0x80000
	s_addc_u32 s25, s25, 0
	ds_read_b128 v[148:151], v224 offset:32768
	ds_read_b128 v[152:155], v224 offset:33792
	ds_read_b128 v[156:159], v224 offset:34816
	ds_read_b128 v[160:163], v224 offset:35840
	ds_read_b128 v[164:167], v224 offset:36864
	ds_read_b128 v[168:171], v224 offset:37888
	ds_read_b128 v[172:175], v224 offset:38912
	ds_read_b128 v[176:179], v224 offset:39936
	s_mov_b32 m0, s36
	s_nop 0
	global_load_lds_dwordx4 v196, s[24:25]
	s_mov_b32 m0, s37
	s_nop 0
	global_load_lds_dwordx4 v194, s[24:25]
	s_add_i32 s24, 0, 0x1c000
	v_add_u32_e32 v202, s24, v1
	ds_read_b128 v[180:183], v202
	ds_read_b128 v[184:187], v202 offset:1024
	ds_read_b128 v[188:191], v202 offset:2048
	ds_read_b128 v[202:205], v202 offset:3072
	s_waitcnt lgkmcnt(0)
	s_setprio 1
	s_barrier
	v_mfma_f32_16x16x32_bf16 v[128:131], v[132:135], v[148:151], v[128:131]
	v_mfma_f32_16x16x32_bf16 v[124:127], v[140:143], v[148:151], v[124:127]
	v_mfma_f32_16x16x32_bf16 v[112:115], v[132:135], v[156:159], v[112:115]
	v_mfma_f32_16x16x32_bf16 v[108:111], v[140:143], v[156:159], v[108:111]
	v_mfma_f32_16x16x32_bf16 v[100:103], v[132:135], v[164:167], v[100:103]
	v_mfma_f32_16x16x32_bf16 v[92:95], v[140:143], v[164:167], v[92:95]
	v_mfma_f32_16x16x32_bf16 v[84:87], v[132:135], v[172:175], v[84:87]
	v_mfma_f32_16x16x32_bf16 v[76:79], v[140:143], v[172:175], v[76:79]
	v_mfma_f32_16x16x32_bf16 v[128:131], v[136:139], v[152:155], v[128:131]
	v_mfma_f32_16x16x32_bf16 v[124:127], v[144:147], v[152:155], v[124:127]
	v_mfma_f32_16x16x32_bf16 v[112:115], v[136:139], v[160:163], v[112:115]
	v_mfma_f32_16x16x32_bf16 v[108:111], v[144:147], v[160:163], v[108:111]
	v_mfma_f32_16x16x32_bf16 v[100:103], v[136:139], v[168:171], v[100:103]
	v_mfma_f32_16x16x32_bf16 v[92:95], v[144:147], v[168:171], v[92:95]
	v_mfma_f32_16x16x32_bf16 v[84:87], v[136:139], v[176:179], v[84:87]
	v_mfma_f32_16x16x32_bf16 v[76:79], v[144:147], v[176:179], v[76:79]
	v_mfma_f32_16x16x32_bf16 v[120:123], v[180:183], v[148:151], v[120:123]
	v_mfma_f32_16x16x32_bf16 v[116:119], v[188:191], v[148:151], v[116:119]
	v_mfma_f32_16x16x32_bf16 v[104:107], v[180:183], v[156:159], v[104:107]
	v_mfma_f32_16x16x32_bf16 v[96:99], v[188:191], v[156:159], v[96:99]
	v_mfma_f32_16x16x32_bf16 v[88:91], v[180:183], v[164:167], v[88:91]
	v_mfma_f32_16x16x32_bf16 v[80:83], v[188:191], v[164:167], v[80:83]
	v_mfma_f32_16x16x32_bf16 v[72:75], v[180:183], v[172:175], v[72:75]
	v_mfma_f32_16x16x32_bf16 v[68:71], v[188:191], v[172:175], v[68:71]
	v_mfma_f32_16x16x32_bf16 v[120:123], v[184:187], v[152:155], v[120:123]
	v_mfma_f32_16x16x32_bf16 v[116:119], v[202:205], v[152:155], v[116:119]
	v_mfma_f32_16x16x32_bf16 v[104:107], v[184:187], v[160:163], v[104:107]
	v_mfma_f32_16x16x32_bf16 v[96:99], v[202:205], v[160:163], v[96:99]
	v_mfma_f32_16x16x32_bf16 v[88:91], v[184:187], v[168:171], v[88:91]
	v_mfma_f32_16x16x32_bf16 v[80:83], v[202:205], v[168:171], v[80:83]
	v_mfma_f32_16x16x32_bf16 v[72:75], v[184:187], v[176:179], v[72:75]
	v_mfma_f32_16x16x32_bf16 v[68:71], v[202:205], v[176:179], v[68:71]
	s_barrier
; __device__ __forceinline__ int opaque_tid() { int t = threadIdx.x; asm volatile("" : "+v"(t)); return t; }
; #define PG8_STAGE(bufoff, gbase, voff) do { _Pragma("unroll") for (int _i = 0; _i < 2; ++_i) \
;         __builtin_amdgcn_global_load_lds((const unsigned*)((const char*)(gbase) + (voff)[_i]), (LAS unsigned*)(lds + (bufoff) + ldsw + _i * 8192), 16, 0, 0); } while (0)
; #define PG8_LDA(dst, b, h) do { _Pragma("unroll") for (int m = 0; m < 4; ++m) _Pragma("unroll") for (int k = 0; k < 2; ++k) dst[m][k] = *(const LAS bf16x8*)(lds + PG8_SA(b, h) + aoff + m * 2048 + k * 1024); } while (0)
; #define PG8_LDB(dst, b, h) do { _Pragma("unroll") for (int n = 0; n < 2; ++n) _Pragma("unroll") for (int k = 0; k < 2; ++k) dst[n][k] = *(const LAS bf16x8*)(lds + PG8_SB(b, h) + boff + n * 2048 + k * 1024); } while (0)
; #define PG8_WAIT_V(n) asm volatile("s_waitcnt vmcnt(" #n ")" ::: "memory")
; #define PG8_WAIT_L(n) asm volatile("s_waitcnt lgkmcnt(" #n ")" ::: "memory")
;     __device__ __forceinline__ void operator()(const f32x4 (&acc)[2][2][4][2], const Unit& u, int wr, int wc, int, int) const {
;         const int ol_ = opaque_tid() & 63, fr = ol_ & 15, fq = ol_ >> 4;
;         const int row0 = u.pm * BM + wr * 64 + fr, col0 = u.pn * BM + wc * 32 + 8 * fq;
;         u32x4 cin[2][4][2];
; #pragma unroll
;         for (int ai = 0; ai < 2; ++ai)
; #pragma unroll
;             for (int m = 0; m < 4; ++m)
; #pragma unroll
;                 for (int bj = 0; bj < 2; ++bj) cin[ai][m][bj] = *(const u32x4*)(C + (size_t)(row0 + ai * HALF + m * 16) * ldc + col0 + bj * HALF);
; template <class Epi, class Sched>
; __device__ __forceinline__ void gemm_phase(LAS unsigned char* lds, const Gemm g, const Sched& S, const Epi& E) {
;     ...
;             PG8_LDB(B0, 1, 0); PG8_SCHED; PG8_LDA(At, 1, 0); PG8_STAGE(PG8_SA(0, 1), a2 + hstepA, voffA);
;             PG8_WAIT_L(8); PG8_BAR; PG8_WAIT_L(0); PG8_MMA(0, 0, At, B0); PG8_BAR; PG8_SCHED;
;             PG8_LDB(B1, 1, 1); PG8_STAGE(PG8_SB(1, 0), b3, voffB);
;             PG8_BAR; PG8_WAIT_L(0); PG8_MMA(0, 1, At, B1); PG8_BAR;
;             PG8_LDA(At, 1, 1); PG8_STAGE(PG8_SA(1, 0), a3, voffA);
;             PG8_BAR; PG8_WAIT_L(0); PG8_MMA(1, 0, At, B0); PG8_BAR; PG8_SCHED;
;             PG8_STAGE(PG8_SB(1, 1), b3 + hstepB, voffB);
;             PG8_WAIT_V(6); PG8_BAR; PG8_MMA(1, 1, At, B1); PG8_BAR;
;         }
	s_setprio 0
	ds_read_b128 v[148:151], v224 offset:49152
	ds_read_b128 v[152:155], v224 offset:50176
	ds_read_b128 v[156:159], v224 offset:51200
	ds_read_b128 v[160:163], v224 offset:52224
	ds_read_b128 v[164:167], v224 offset:53248
	ds_read_b128 v[168:171], v224 offset:54272
	ds_read_b128 v[172:175], v224 offset:55296
	ds_read_b128 v[176:179], v224 offset:56320
	s_add_i32 s25, s52, s30
	v_lshl_add_u64 v[206:207], v[206:207], 0, s[8:9]
	s_mov_b32 m0, s25
	s_nop 0
	global_load_lds_dwordx4 v[206:207], off
	v_lshl_add_u64 v[206:207], v[208:209], 0, s[8:9]
	s_add_i32 m0, s25, 0x2000
	s_nop 0
	global_load_lds_dwordx4 v[206:207], off
	s_mov_b32 m0, s40
	v_lshl_add_u64 v[206:207], v[210:211], 0, s[8:9]
	global_load_lds_dwordx4 v[206:207], off
	v_lshl_add_u64 v[206:207], v[212:213], 0, s[8:9]
	s_mov_b32 m0, s41
	s_nop 0
	global_load_lds_dwordx4 v[206:207], off
	s_add_u32 s20, s20, 0x80080
	s_addc_u32 s21, s21, 0
	s_add_i32 s24, s24, s30
	s_mov_b32 m0, s24
	s_nop 0
	global_load_lds_dwordx4 v2, s[20:21]
	s_add_i32 m0, s24, 0x2000
	s_nop 0
	global_load_lds_dwordx4 v192, s[20:21]
	s_add_i32 s51, s51, 2
	s_add_u32 s6, s6, 0x100
	s_addc_u32 s7, s7, 0
	s_add_u32 s49, s49, 0x100
	s_addc_u32 s50, s50, 0
	s_cmp_gt_u32 s51, 29
	s_waitcnt lgkmcnt(0)
	s_waitcnt vmcnt(6)
	s_setprio 1
	s_barrier
	v_mfma_f32_16x16x32_bf16 v[64:67], v[132:135], v[148:151], v[64:67]
	v_mfma_f32_16x16x32_bf16 v[60:63], v[140:143], v[148:151], v[60:63]
	v_mfma_f32_16x16x32_bf16 v[52:55], v[132:135], v[156:159], v[52:55]
	v_mfma_f32_16x16x32_bf16 v[44:47], v[140:143], v[156:159], v[44:47]
	v_mfma_f32_16x16x32_bf16 v[36:39], v[132:135], v[164:167], v[36:39]
	v_mfma_f32_16x16x32_bf16 v[28:31], v[140:143], v[164:167], v[28:31]
	v_mfma_f32_16x16x32_bf16 v[20:23], v[132:135], v[172:175], v[20:23]
	v_mfma_f32_16x16x32_bf16 v[12:15], v[140:143], v[172:175], v[12:15]
	v_mfma_f32_16x16x32_bf16 v[64:67], v[136:139], v[152:155], v[64:67]
	v_mfma_f32_16x16x32_bf16 v[60:63], v[144:147], v[152:155], v[60:63]
	v_mfma_f32_16x16x32_bf16 v[52:55], v[136:139], v[160:163], v[52:55]
	v_mfma_f32_16x16x32_bf16 v[44:47], v[144:147], v[160:163], v[44:47]
	v_mfma_f32_16x16x32_bf16 v[36:39], v[136:139], v[168:171], v[36:39]
	v_mfma_f32_16x16x32_bf16 v[28:31], v[144:147], v[168:171], v[28:31]
	v_mfma_f32_16x16x32_bf16 v[20:23], v[136:139], v[176:179], v[20:23]
	v_mfma_f32_16x16x32_bf16 v[12:15], v[144:147], v[176:179], v[12:15]
	v_mfma_f32_16x16x32_bf16 v[56:59], v[180:183], v[148:151], v[56:59]
	v_mfma_f32_16x16x32_bf16 v[48:51], v[188:191], v[148:151], v[48:51]
	v_mfma_f32_16x16x32_bf16 v[40:43], v[180:183], v[156:159], v[40:43]
	v_mfma_f32_16x16x32_bf16 v[32:35], v[188:191], v[156:159], v[32:35]
	v_mfma_f32_16x16x32_bf16 v[24:27], v[180:183], v[164:167], v[24:27]
	v_mfma_f32_16x16x32_bf16 v[16:19], v[188:191], v[164:167], v[16:19]
	v_mfma_f32_16x16x32_bf16 v[8:11], v[180:183], v[172:175], v[8:11]
	v_mfma_f32_16x16x32_bf16 v[4:7], v[188:191], v[172:175], v[4:7]
	v_mfma_f32_16x16x32_bf16 v[56:59], v[184:187], v[152:155], v[56:59]
	v_mfma_f32_16x16x32_bf16 v[48:51], v[202:205], v[152:155], v[48:51]
	v_mfma_f32_16x16x32_bf16 v[40:43], v[184:187], v[160:163], v[40:43]
	v_mfma_f32_16x16x32_bf16 v[32:35], v[202:205], v[160:163], v[32:35]
	v_mfma_f32_16x16x32_bf16 v[24:27], v[184:187], v[168:171], v[24:27]
	v_mfma_f32_16x16x32_bf16 v[16:19], v[202:205], v[168:171], v[16:19]
	v_mfma_f32_16x16x32_bf16 v[8:11], v[184:187], v[176:179], v[8:11]
	v_mfma_f32_16x16x32_bf16 v[4:7], v[202:205], v[176:179], v[4:7]
	s_barrier
	s_cbranch_scc0 .LBB0_966
	s_setprio 0
	v_mov_b32_e32 v133, v0
	s_lshl_b32 s1, s46, 8
	s_add_i32 s1, s1, s38
	v_and_or_b32 v132, v133, 15, s1
	s_lshl_b32 s1, s45, 8
	v_lshrrev_b32_e32 v133, 1, v133
	v_and_or_b32 v133, v133, 24, s1
	v_or_b32_e32 v134, s39, v133
	v_ashrrev_i32_e32 v135, 31, v134
	v_lshlrev_b64 v[202:203], 1, v[134:135]
	v_ashrrev_i32_e32 v133, 31, v132
	v_lshl_add_u64 v[134:135], s[88:89], 0, v[202:203]
	v_lshlrev_b64 v[226:227], 12, v[132:133]
	v_lshl_add_u64 v[136:137], v[134:135], 0, v[226:227]
	global_load_dwordx4 v[216:219], v[136:137], off
	global_load_dwordx4 v[188:191], v[136:137], off offset:256
	v_or_b32_e32 v136, 16, v132
	v_ashrrev_i32_e32 v137, 31, v136
	v_lshlrev_b64 v[222:223], 12, v[136:137]
	v_lshl_add_u64 v[136:137], v[134:135], 0, v[222:223]
	global_load_dwordx4 v[184:187], v[136:137], off
	global_load_dwordx4 v[180:183], v[136:137], off offset:256
	v_or_b32_e32 v136, 32, v132
	v_ashrrev_i32_e32 v137, 31, v136
	v_lshlrev_b64 v[220:221], 12, v[136:137]
	v_lshl_add_u64 v[136:137], v[134:135], 0, v[220:221]
	global_load_dwordx4 v[176:179], v[136:137], off
	global_load_dwordx4 v[168:171], v[136:137], off offset:256
	v_or_b32_e32 v132, 48, v132
	v_ashrrev_i32_e32 v133, 31, v132
	v_lshlrev_b64 v[212:213], 12, v[132:133]
	v_lshl_add_u64 v[132:133], v[134:135], 0, v[212:213]
	global_load_dwordx4 v[172:175], v[132:133], off
	global_load_dwordx4 v[164:167], v[132:133], off offset:256
	s_mov_b64 s[6:7], 0x80000
	v_lshl_add_u64 v[210:211], v[226:227], 0, s[6:7]
	v_lshl_add_u64 v[132:133], v[134:135], 0, v[210:211]
	global_load_dwordx4 v[160:163], v[132:133], off
	global_load_dwordx4 v[156:159], v[132:133], off offset:256
	s_mov_b64 s[6:7], 0x90000
	v_lshl_add_u64 v[208:209], v[226:227], 0, s[6:7]
	v_lshl_add_u64 v[132:133], v[134:135], 0, v[208:209]
	global_load_dwordx4 v[152:155], v[132:133], off
	global_load_dwordx4 v[148:151], v[132:133], off offset:256
	s_mov_b64 s[6:7], 0xa0000
	v_lshl_add_u64 v[206:207], v[226:227], 0, s[6:7]
	v_lshl_add_u64 v[132:133], v[134:135], 0, v[206:207]
	global_load_dwordx4 v[144:147], v[132:133], off
	global_load_dwordx4 v[140:143], v[132:133], off offset:256
	s_mov_b64 s[6:7], 0xb0000
	v_lshl_add_u64 v[204:205], v[226:227], 0, s[6:7]
	v_lshl_add_u64 v[132:133], v[134:135], 0, v[204:205]
	global_load_dwordx4 v[136:139], v[132:133], off
	s_nop 0
	global_load_dwordx4 v[132:135], v[132:133], off offset:256
	s_and_b64 vcc, exec, s[42:43]
	s_mov_b32 s45, s0
	s_mov_b32 s46, s14
	s_mov_b64 s[20:21], s[18:19]
	s_mov_b64 s[6:7], s[4:5]
	s_waitcnt vmcnt(15)
; __device__ __forceinline__ unsigned cvt_pk_bf16(float lo, float hi) { const f32x2 v = {lo, hi}; const bf16v2_ r = __builtin_convertvector(v, bf16v2_); return __builtin_bit_cast(unsigned, r); }
; __device__ __forceinline__ float bflo(unsigned w) { return __uint_as_float(w << 16); }
; __device__ __forceinline__ float bfhi(unsigned w) { return __uint_as_float(w & 0xffff0000u); }
;     __device__ __forceinline__ void operator()(const f32x4 (&acc)[2][2][4][2], const Unit& u, int wr, int wc, int, int) const {
;     ...
; #pragma unroll
;         for (int ai = 0; ai < 2; ++ai)
; #pragma unroll
;             for (int m = 0; m < 4; ++m)
; #pragma unroll
;                 for (int bj = 0; bj < 2; ++bj) { const u32x4 c = cin[ai][m][bj]; const f32x4 v0 = acc[ai][bj][m][0], v1 = acc[ai][bj][m][1];
;                     u32x4 w; w.x = cvt_pk_bf16(bflo(c.x) + v0[0], bfhi(c.x) + v0[1]); w.y = cvt_pk_bf16(bflo(c.y) + v0[2], bfhi(c.y) + v0[3]);
;                     w.z = cvt_pk_bf16(bflo(c.z) + v1[0], bfhi(c.z) + v1[1]); w.w = cvt_pk_bf16(bflo(c.w) + v1[2], bfhi(c.w) + v1[3]);
;                     *(u32x4*)(C + (size_t)(row0 + ai * HALF + m * 16) * ldc + col0 + bj * HALF) = w; }
	v_lshlrev_b32_e32 v228, 16, v216
	v_and_b32_e32 v229, 0xffff0000, v216
	v_lshlrev_b32_e32 v216, 16, v217
	v_and_b32_e32 v217, 0xffff0000, v217
	v_pk_add_f32 v[128:129], v[128:129], v[228:229]
	v_pk_add_f32 v[130:131], v[130:131], v[216:217]
	v_cvt_pk_bf16_f32 v128, v128, v129
	v_cvt_pk_bf16_f32 v129, v130, v131
	v_lshlrev_b32_e32 v130, 16, v218
	v_and_b32_e32 v131, 0xffff0000, v218
	v_pk_add_f32 v[124:125], v[124:125], v[130:131]
	s_nop 0
	v_cvt_pk_bf16_f32 v130, v124, v125
	v_lshlrev_b32_e32 v124, 16, v219
	v_and_b32_e32 v125, 0xffff0000, v219
	v_pk_add_f32 v[124:125], v[126:127], v[124:125]
	s_waitcnt vmcnt(14)
	v_lshlrev_b32_e32 v126, 16, v188
	v_and_b32_e32 v127, 0xffff0000, v188
	v_pk_add_f32 v[120:121], v[120:121], v[126:127]
	v_lshlrev_b32_e32 v126, 16, v189
	v_and_b32_e32 v127, 0xffff0000, v189
	v_pk_add_f32 v[122:123], v[122:123], v[126:127]
	v_cvt_pk_bf16_f32 v120, v120, v121
	v_cvt_pk_bf16_f32 v121, v122, v123
	v_lshlrev_b32_e32 v122, 16, v190
	v_and_b32_e32 v123, 0xffff0000, v190
	v_pk_add_f32 v[116:117], v[116:117], v[122:123]
	v_cvt_pk_bf16_f32 v131, v124, v125
	v_cvt_pk_bf16_f32 v122, v116, v117
	v_lshlrev_b32_e32 v116, 16, v191
	v_and_b32_e32 v117, 0xffff0000, v191
	v_pk_add_f32 v[116:117], v[118:119], v[116:117]
	v_lshl_add_u64 v[124:125], s[88:89], 0, v[226:227]
	v_cvt_pk_bf16_f32 v123, v116, v117
	s_waitcnt vmcnt(13)
	v_lshlrev_b32_e32 v116, 16, v184
	v_and_b32_e32 v117, 0xffff0000, v184
	v_pk_add_f32 v[112:113], v[112:113], v[116:117]
	v_lshlrev_b32_e32 v116, 16, v185
	v_and_b32_e32 v117, 0xffff0000, v185
	v_pk_add_f32 v[114:115], v[114:115], v[116:117]
	v_cvt_pk_bf16_f32 v112, v112, v113
	v_cvt_pk_bf16_f32 v113, v114, v115
	v_lshlrev_b32_e32 v114, 16, v186
	v_and_b32_e32 v115, 0xffff0000, v186
	v_pk_add_f32 v[108:109], v[108:109], v[114:115]
	v_lshl_add_u64 v[124:125], v[124:125], 0, v[202:203]
	v_cvt_pk_bf16_f32 v114, v108, v109
	v_lshlrev_b32_e32 v108, 16, v187
	v_and_b32_e32 v109, 0xffff0000, v187
	v_pk_add_f32 v[108:109], v[110:111], v[108:109]
	s_waitcnt vmcnt(12)
	v_lshlrev_b32_e32 v110, 16, v180
	v_and_b32_e32 v111, 0xffff0000, v180
	v_pk_add_f32 v[104:105], v[104:105], v[110:111]
	v_lshlrev_b32_e32 v110, 16, v181
	v_and_b32_e32 v111, 0xffff0000, v181
	v_pk_add_f32 v[106:107], v[106:107], v[110:111]
	v_cvt_pk_bf16_f32 v104, v104, v105
	v_cvt_pk_bf16_f32 v105, v106, v107
	v_lshlrev_b32_e32 v106, 16, v182
	v_and_b32_e32 v107, 0xffff0000, v182
	v_pk_add_f32 v[96:97], v[96:97], v[106:107]
	v_cvt_pk_bf16_f32 v115, v108, v109
	v_cvt_pk_bf16_f32 v106, v96, v97
	v_lshlrev_b32_e32 v96, 16, v183
	v_and_b32_e32 v97, 0xffff0000, v183
	v_pk_add_f32 v[96:97], v[98:99], v[96:97]
	s_waitcnt vmcnt(11)
	v_lshlrev_b32_e32 v98, 16, v177
	v_cvt_pk_bf16_f32 v107, v96, v97
	v_lshlrev_b32_e32 v96, 16, v176
	v_and_b32_e32 v97, 0xffff0000, v176
	v_and_b32_e32 v99, 0xffff0000, v177
	v_pk_add_f32 v[96:97], v[100:101], v[96:97]
	v_pk_add_f32 v[98:99], v[102:103], v[98:99]
	v_cvt_pk_bf16_f32 v96, v96, v97
	v_cvt_pk_bf16_f32 v97, v98, v99
	v_lshlrev_b32_e32 v98, 16, v178
	v_and_b32_e32 v99, 0xffff0000, v178
	v_pk_add_f32 v[92:93], v[92:93], v[98:99]
	v_lshl_add_u64 v[108:109], s[88:89], 0, v[222:223]
	v_cvt_pk_bf16_f32 v98, v92, v93
	v_lshlrev_b32_e32 v92, 16, v179
	v_and_b32_e32 v93, 0xffff0000, v179
	v_pk_add_f32 v[92:93], v[94:95], v[92:93]
	s_waitcnt vmcnt(10)
	v_lshlrev_b32_e32 v94, 16, v168
	v_and_b32_e32 v95, 0xffff0000, v168
	v_pk_add_f32 v[88:89], v[88:89], v[94:95]
	v_lshlrev_b32_e32 v94, 16, v169
	v_and_b32_e32 v95, 0xffff0000, v169
	v_pk_add_f32 v[90:91], v[90:91], v[94:95]
	v_cvt_pk_bf16_f32 v88, v88, v89
	v_cvt_pk_bf16_f32 v89, v90, v91
	v_lshlrev_b32_e32 v90, 16, v170
	v_and_b32_e32 v91, 0xffff0000, v170
	v_pk_add_f32 v[80:81], v[80:81], v[90:91]
	v_cvt_pk_bf16_f32 v99, v92, v93
	v_cvt_pk_bf16_f32 v90, v80, v81
	v_lshlrev_b32_e32 v80, 16, v171
	v_and_b32_e32 v81, 0xffff0000, v171
	v_pk_add_f32 v[80:81], v[82:83], v[80:81]
	s_waitcnt vmcnt(9)
	v_lshlrev_b32_e32 v82, 16, v173
	v_cvt_pk_bf16_f32 v91, v80, v81
	v_lshlrev_b32_e32 v80, 16, v172
	v_and_b32_e32 v81, 0xffff0000, v172
	v_and_b32_e32 v83, 0xffff0000, v173
	v_pk_add_f32 v[80:81], v[84:85], v[80:81]
	v_pk_add_f32 v[82:83], v[86:87], v[82:83]
	v_cvt_pk_bf16_f32 v80, v80, v81
	v_cvt_pk_bf16_f32 v81, v82, v83
	v_lshlrev_b32_e32 v82, 16, v174
	v_and_b32_e32 v83, 0xffff0000, v174
	v_pk_add_f32 v[76:77], v[76:77], v[82:83]
	v_lshl_add_u64 v[92:93], s[88:89], 0, v[220:221]
	v_cvt_pk_bf16_f32 v82, v76, v77
	v_lshlrev_b32_e32 v76, 16, v175
	v_and_b32_e32 v77, 0xffff0000, v175
	v_pk_add_f32 v[76:77], v[78:79], v[76:77]
	s_waitcnt vmcnt(8)
	v_lshlrev_b32_e32 v78, 16, v164
	v_and_b32_e32 v79, 0xffff0000, v164
	v_pk_add_f32 v[72:73], v[72:73], v[78:79]
	v_lshlrev_b32_e32 v78, 16, v165
	v_and_b32_e32 v79, 0xffff0000, v165
	v_pk_add_f32 v[74:75], v[74:75], v[78:79]
	v_cvt_pk_bf16_f32 v72, v72, v73
	v_cvt_pk_bf16_f32 v73, v74, v75
	v_lshlrev_b32_e32 v74, 16, v166
	v_and_b32_e32 v75, 0xffff0000, v166
	v_pk_add_f32 v[68:69], v[68:69], v[74:75]
	v_cvt_pk_bf16_f32 v83, v76, v77
	v_cvt_pk_bf16_f32 v74, v68, v69
	v_lshlrev_b32_e32 v68, 16, v167
	v_and_b32_e32 v69, 0xffff0000, v167
	v_pk_add_f32 v[68:69], v[70:71], v[68:69]
	v_lshl_add_u64 v[76:77], s[88:89], 0, v[212:213]
	v_cvt_pk_bf16_f32 v75, v68, v69
	s_waitcnt vmcnt(7)
	v_lshlrev_b32_e32 v68, 16, v160
	v_and_b32_e32 v69, 0xffff0000, v160
	v_pk_add_f32 v[64:65], v[64:65], v[68:69]
	v_lshlrev_b32_e32 v68, 16, v161
	v_and_b32_e32 v69, 0xffff0000, v161
	v_pk_add_f32 v[66:67], v[66:67], v[68:69]
	v_cvt_pk_bf16_f32 v64, v64, v65
	v_cvt_pk_bf16_f32 v65, v66, v67
	v_lshlrev_b32_e32 v66, 16, v162
	v_and_b32_e32 v67, 0xffff0000, v162
	v_pk_add_f32 v[60:61], v[60:61], v[66:67]
	v_lshl_add_u64 v[108:109], v[108:109], 0, v[202:203]
	v_cvt_pk_bf16_f32 v66, v60, v61
	v_lshlrev_b32_e32 v60, 16, v163
	v_and_b32_e32 v61, 0xffff0000, v163
	v_pk_add_f32 v[60:61], v[62:63], v[60:61]
	s_waitcnt vmcnt(6)
; __device__ __forceinline__ unsigned cvt_pk_bf16(float lo, float hi) { const f32x2 v = {lo, hi}; const bf16v2_ r = __builtin_convertvector(v, bf16v2_); return __builtin_bit_cast(unsigned, r); }
; __device__ __forceinline__ float bflo(unsigned w) { return __uint_as_float(w << 16); }
; __device__ __forceinline__ float bfhi(unsigned w) { return __uint_as_float(w & 0xffff0000u); }
;     __device__ __forceinline__ void operator()(const f32x4 (&acc)[2][2][4][2], const Unit& u, int wr, int wc, int, int) const {
;     ...
; #pragma unroll
;         for (int ai = 0; ai < 2; ++ai)
; #pragma unroll
;             for (int m = 0; m < 4; ++m)
; #pragma unroll
;                 for (int bj = 0; bj < 2; ++bj) { const u32x4 c = cin[ai][m][bj]; const f32x4 v0 = acc[ai][bj][m][0], v1 = acc[ai][bj][m][1];
;                     u32x4 w; w.x = cvt_pk_bf16(bflo(c.x) + v0[0], bfhi(c.x) + v0[1]); w.y = cvt_pk_bf16(bflo(c.y) + v0[2], bfhi(c.y) + v0[3]);
;                     w.z = cvt_pk_bf16(bflo(c.z) + v1[0], bfhi(c.z) + v1[1]); w.w = cvt_pk_bf16(bflo(c.w) + v1[2], bfhi(c.w) + v1[3]);
;                     *(u32x4*)(C + (size_t)(row0 + ai * HALF + m * 16) * ldc + col0 + bj * HALF) = w; }
	v_lshlrev_b32_e32 v62, 16, v156
	v_and_b32_e32 v63, 0xffff0000, v156
	v_pk_add_f32 v[56:57], v[56:57], v[62:63]
	v_lshlrev_b32_e32 v62, 16, v157
	v_and_b32_e32 v63, 0xffff0000, v157
	v_pk_add_f32 v[58:59], v[58:59], v[62:63]
	v_cvt_pk_bf16_f32 v56, v56, v57
	v_cvt_pk_bf16_f32 v57, v58, v59
	v_lshlrev_b32_e32 v58, 16, v158
	v_and_b32_e32 v59, 0xffff0000, v158
	v_pk_add_f32 v[48:49], v[48:49], v[58:59]
	v_cvt_pk_bf16_f32 v67, v60, v61
	v_cvt_pk_bf16_f32 v58, v48, v49
	v_lshlrev_b32_e32 v48, 16, v159
	v_and_b32_e32 v49, 0xffff0000, v159
	v_pk_add_f32 v[48:49], v[50:51], v[48:49]
	s_waitcnt vmcnt(5)
	v_lshlrev_b32_e32 v50, 16, v153
	v_cvt_pk_bf16_f32 v59, v48, v49
	v_lshlrev_b32_e32 v48, 16, v152
	v_and_b32_e32 v49, 0xffff0000, v152
	v_and_b32_e32 v51, 0xffff0000, v153
	v_pk_add_f32 v[48:49], v[52:53], v[48:49]
	v_pk_add_f32 v[50:51], v[54:55], v[50:51]
	v_cvt_pk_bf16_f32 v48, v48, v49
	v_cvt_pk_bf16_f32 v49, v50, v51
	v_lshlrev_b32_e32 v50, 16, v154
	v_and_b32_e32 v51, 0xffff0000, v154
	v_pk_add_f32 v[44:45], v[44:45], v[50:51]
	v_lshl_add_u64 v[60:61], s[88:89], 0, v[210:211]
	v_cvt_pk_bf16_f32 v50, v44, v45
	v_lshlrev_b32_e32 v44, 16, v155
	v_and_b32_e32 v45, 0xffff0000, v155
	v_pk_add_f32 v[44:45], v[46:47], v[44:45]
	s_waitcnt vmcnt(4)
	v_lshlrev_b32_e32 v46, 16, v148
	v_and_b32_e32 v47, 0xffff0000, v148
	v_pk_add_f32 v[40:41], v[40:41], v[46:47]
	v_lshlrev_b32_e32 v46, 16, v149
	v_and_b32_e32 v47, 0xffff0000, v149
	v_pk_add_f32 v[42:43], v[42:43], v[46:47]
	v_cvt_pk_bf16_f32 v40, v40, v41
	v_cvt_pk_bf16_f32 v41, v42, v43
	v_lshlrev_b32_e32 v42, 16, v150
	v_and_b32_e32 v43, 0xffff0000, v150
	v_pk_add_f32 v[32:33], v[32:33], v[42:43]
	v_cvt_pk_bf16_f32 v51, v44, v45
	v_cvt_pk_bf16_f32 v42, v32, v33
	v_lshlrev_b32_e32 v32, 16, v151
	v_and_b32_e32 v33, 0xffff0000, v151
	v_pk_add_f32 v[32:33], v[34:35], v[32:33]
	s_waitcnt vmcnt(3)
	v_lshlrev_b32_e32 v34, 16, v145
	v_cvt_pk_bf16_f32 v43, v32, v33
	v_lshlrev_b32_e32 v32, 16, v144
	v_and_b32_e32 v33, 0xffff0000, v144
	v_and_b32_e32 v35, 0xffff0000, v145
	v_pk_add_f32 v[32:33], v[36:37], v[32:33]
	v_pk_add_f32 v[34:35], v[38:39], v[34:35]
	v_cvt_pk_bf16_f32 v32, v32, v33
	v_cvt_pk_bf16_f32 v33, v34, v35
	v_lshlrev_b32_e32 v34, 16, v146
	v_and_b32_e32 v35, 0xffff0000, v146
	v_pk_add_f32 v[28:29], v[28:29], v[34:35]
	v_lshl_add_u64 v[44:45], s[88:89], 0, v[208:209]
	v_cvt_pk_bf16_f32 v34, v28, v29
	v_lshlrev_b32_e32 v28, 16, v147
	v_and_b32_e32 v29, 0xffff0000, v147
	v_pk_add_f32 v[28:29], v[30:31], v[28:29]
	s_waitcnt vmcnt(2)
	v_lshlrev_b32_e32 v30, 16, v140
	v_and_b32_e32 v31, 0xffff0000, v140
	v_pk_add_f32 v[24:25], v[24:25], v[30:31]
	v_lshlrev_b32_e32 v30, 16, v141
	v_and_b32_e32 v31, 0xffff0000, v141
	v_pk_add_f32 v[26:27], v[26:27], v[30:31]
	v_cvt_pk_bf16_f32 v24, v24, v25
	v_cvt_pk_bf16_f32 v25, v26, v27
	v_lshlrev_b32_e32 v26, 16, v142
	v_and_b32_e32 v27, 0xffff0000, v142
	v_pk_add_f32 v[16:17], v[16:17], v[26:27]
	v_cvt_pk_bf16_f32 v35, v28, v29
	v_cvt_pk_bf16_f32 v26, v16, v17
	v_lshlrev_b32_e32 v16, 16, v143
	v_and_b32_e32 v17, 0xffff0000, v143
	v_pk_add_f32 v[16:17], v[18:19], v[16:17]
	s_waitcnt vmcnt(1)
	v_lshlrev_b32_e32 v18, 16, v137
	v_cvt_pk_bf16_f32 v27, v16, v17
	v_lshlrev_b32_e32 v16, 16, v136
	v_and_b32_e32 v17, 0xffff0000, v136
	v_and_b32_e32 v19, 0xffff0000, v137
	v_pk_add_f32 v[16:17], v[20:21], v[16:17]
	v_pk_add_f32 v[18:19], v[22:23], v[18:19]
	v_cvt_pk_bf16_f32 v16, v16, v17
	v_cvt_pk_bf16_f32 v17, v18, v19
	v_lshlrev_b32_e32 v18, 16, v138
	v_and_b32_e32 v19, 0xffff0000, v138
	v_pk_add_f32 v[12:13], v[12:13], v[18:19]
	v_lshl_add_u64 v[28:29], s[88:89], 0, v[206:207]
	v_cvt_pk_bf16_f32 v18, v12, v13
	v_lshlrev_b32_e32 v12, 16, v139
	v_and_b32_e32 v13, 0xffff0000, v139
	v_pk_add_f32 v[12:13], v[14:15], v[12:13]
	s_waitcnt vmcnt(0)
	v_lshlrev_b32_e32 v14, 16, v132
	v_and_b32_e32 v15, 0xffff0000, v132
	v_pk_add_f32 v[8:9], v[8:9], v[14:15]
	v_lshlrev_b32_e32 v14, 16, v133
	v_and_b32_e32 v15, 0xffff0000, v133
	v_pk_add_f32 v[10:11], v[10:11], v[14:15]
	v_cvt_pk_bf16_f32 v8, v8, v9
	v_cvt_pk_bf16_f32 v9, v10, v11
	v_lshlrev_b32_e32 v10, 16, v134
	v_and_b32_e32 v11, 0xffff0000, v134
	v_pk_add_f32 v[4:5], v[4:5], v[10:11]
	v_cvt_pk_bf16_f32 v19, v12, v13
	v_cvt_pk_bf16_f32 v10, v4, v5
	v_lshlrev_b32_e32 v4, 16, v135
	v_and_b32_e32 v5, 0xffff0000, v135
	v_lshl_add_u64 v[12:13], s[88:89], 0, v[204:205]
	v_pk_add_f32 v[4:5], v[6:7], v[4:5]
	v_lshl_add_u64 v[92:93], v[92:93], 0, v[202:203]
	v_lshl_add_u64 v[76:77], v[76:77], 0, v[202:203]
	v_lshl_add_u64 v[60:61], v[60:61], 0, v[202:203]
	v_lshl_add_u64 v[44:45], v[44:45], 0, v[202:203]
	v_lshl_add_u64 v[28:29], v[28:29], 0, v[202:203]
	v_lshl_add_u64 v[12:13], v[12:13], 0, v[202:203]
	v_cvt_pk_bf16_f32 v11, v4, v5
	global_store_dwordx4 v[124:125], v[128:131], off sc1
	global_store_dwordx4 v[124:125], v[120:123], off offset:256 sc1
	global_store_dwordx4 v[108:109], v[112:115], off sc1
	global_store_dwordx4 v[108:109], v[104:107], off offset:256 sc1
	global_store_dwordx4 v[92:93], v[96:99], off sc1
	global_store_dwordx4 v[92:93], v[88:91], off offset:256 sc1
	global_store_dwordx4 v[76:77], v[80:83], off sc1
	global_store_dwordx4 v[76:77], v[72:75], off offset:256 sc1
	global_store_dwordx4 v[60:61], v[64:67], off sc1
	global_store_dwordx4 v[60:61], v[56:59], off offset:256 sc1
	global_store_dwordx4 v[44:45], v[48:51], off sc1
	global_store_dwordx4 v[44:45], v[40:43], off offset:256 sc1
	global_store_dwordx4 v[28:29], v[32:35], off sc1
	global_store_dwordx4 v[28:29], v[24:27], off offset:256 sc1
	global_store_dwordx4 v[12:13], v[16:19], off sc1
	global_store_dwordx4 v[12:13], v[8:11], off offset:256 sc1
	s_cbranch_vccz .LBB0_959
	s_waitcnt vmcnt(0)
	s_cmpk_gt_u32 s2, 0xff
	s_cbranch_scc1 .LBB0_970
	s_barrier

; #define PG8_STAGE(bufoff, gbase, voff) do { _Pragma("unroll") for (int _i = 0; _i < 2; ++_i) \
;         __builtin_amdgcn_global_load_lds((const unsigned*)((const char*)(gbase) + (voff)[_i]), (LAS unsigned*)(lds + (bufoff) + ldsw + _i * 8192), 16, 0, 0); } while (0)
; #define PG8_LDA(dst, b, h) do { _Pragma("unroll") for (int m = 0; m < 4; ++m) _Pragma("unroll") for (int k = 0; k < 2; ++k) dst[m][k] = *(const LAS bf16x8*)(lds + PG8_SA(b, h) + aoff + m * 2048 + k * 1024); } while (0)
; #define PG8_LDB(dst, b, h) do { _Pragma("unroll") for (int n = 0; n < 2; ++n) _Pragma("unroll") for (int k = 0; k < 2; ++k) dst[n][k] = *(const LAS bf16x8*)(lds + PG8_SB(b, h) + boff + n * 2048 + k * 1024); } while (0)
; #define PG8_MMA(ai, bj, At, Bt) do { __builtin_amdgcn_s_setprio(1); _Pragma("unroll") for (int m = 0; m < 4; ++m) _Pragma("unroll") for (int n = 0; n < 2; ++n) _Pragma("unroll") for (int k = 0; k < 2; ++k) \
;         acc[ai][bj][m][n] = __builtin_amdgcn_mfma_f32_16x16x32_bf16(Bt[n][k], At[m][k], acc[ai][bj][m][n], 0, 0, 0); __builtin_amdgcn_s_setprio(0); } while (0)
; #define PG8_WAIT_V(n) asm volatile("s_waitcnt vmcnt(" #n ")" ::: "memory")
; #define PG8_WAIT_L(n) asm volatile("s_waitcnt lgkmcnt(" #n ")" ::: "memory")
; #define PG8_BAR __builtin_amdgcn_s_barrier()
; #define PG8_SCHED __builtin_amdgcn_sched_barrier(0)
; template <class Epi, class Sched>
; __device__ __forceinline__ void gemm_phase(LAS unsigned char* lds, const Gemm g, const Sched& S, const Epi& E) {
;     ...
;             PG8_LDB(B0, 0, 0); PG8_SCHED; PG8_LDA(At, 0, 0); PG8_STAGE(PG8_SA(1, 1), a1 + hstepA, voffA);
;             PG8_WAIT_L(8); PG8_BAR; PG8_WAIT_L(0); PG8_MMA(0, 0, At, B0); PG8_BAR; PG8_SCHED;
;             PG8_LDB(B1, 0, 1); PG8_STAGE(PG8_SB(0, 0), b2, voffB);
;             PG8_BAR; PG8_WAIT_L(0); PG8_MMA(0, 1, At, B1); PG8_BAR;
;             PG8_LDA(At, 0, 1); PG8_STAGE(PG8_SA(0, 0), a2, voffA);
;             PG8_BAR; PG8_WAIT_L(0); PG8_MMA(1, 0, At, B0); PG8_BAR; PG8_SCHED;
;             PG8_STAGE(PG8_SB(0, 1), b2 + hstepB, voffB);
;             PG8_WAIT_V(6); PG8_BAR; PG8_MMA(1, 1, At, B1); PG8_BAR;
.LBB0_1094:
	s_setprio 0
	s_add_u32 s20, s18, 0xfff80080
	s_addc_u32 s21, s19, -1
	s_add_i32 s54, 0, 0x10000
	v_add_u32_e32 v146, s54, v1
	ds_read_b128 v[142:145], v146
	ds_read_b128 v[150:153], v146 offset:1024
	ds_read_b128 v[154:157], v146 offset:2048
	ds_read_b128 v[158:161], v146 offset:3072
	s_cmp_eq_u32 s53, 28
	s_cselect_b32 s25, s5, s21
	s_cselect_b32 s24, s49, s20
	s_cselect_b32 s21, s1, s52
	s_cselect_b32 s20, s50, s51
	ds_read_b128 v[162:165], v148
	ds_read_b128 v[166:169], v148 offset:1024
	ds_read_b128 v[170:173], v148 offset:2048
	ds_read_b128 v[174:177], v148 offset:3072
	ds_read_b128 v[178:181], v148 offset:4096
	ds_read_b128 v[182:185], v148 offset:5120
	ds_read_b128 v[186:189], v148 offset:6144
	ds_read_b128 v[190:193], v148 offset:7168
	s_add_i32 s56, 0, 0x14000
	v_add_u32_e32 v146, s56, v1
	ds_read_b128 v[194:197], v146
	ds_read_b128 v[198:201], v146 offset:1024
	ds_read_b128 v[202:205], v146 offset:2048
	ds_read_b128 v[206:209], v146 offset:3072
	s_add_i32 m0, s31, 0xc000
	s_nop 0
	global_load_lds_dwordx4 v138, s[18:19]
	s_add_i32 m0, s31, 0xe000
	s_nop 0
	global_load_lds_dwordx4 v140, s[18:19]
	s_waitcnt lgkmcnt(0)
	s_setprio 1
	s_barrier
	v_mfma_f32_16x16x32_bf16 v[128:131], v[142:145], v[162:165], v[128:131]
	v_mfma_f32_16x16x32_bf16 v[124:127], v[154:157], v[162:165], v[124:127]
	v_mfma_f32_16x16x32_bf16 v[120:123], v[142:145], v[170:173], v[120:123]
	v_mfma_f32_16x16x32_bf16 v[112:115], v[154:157], v[170:173], v[112:115]
	v_mfma_f32_16x16x32_bf16 v[104:107], v[142:145], v[178:181], v[104:107]
	v_mfma_f32_16x16x32_bf16 v[96:99], v[154:157], v[178:181], v[96:99]
	v_mfma_f32_16x16x32_bf16 v[88:91], v[142:145], v[186:189], v[88:91]
	v_mfma_f32_16x16x32_bf16 v[80:83], v[154:157], v[186:189], v[80:83]
	v_mfma_f32_16x16x32_bf16 v[128:131], v[150:153], v[166:169], v[128:131]
	v_mfma_f32_16x16x32_bf16 v[124:127], v[158:161], v[166:169], v[124:127]
	v_mfma_f32_16x16x32_bf16 v[120:123], v[150:153], v[174:177], v[120:123]
	v_mfma_f32_16x16x32_bf16 v[112:115], v[158:161], v[174:177], v[112:115]
	v_mfma_f32_16x16x32_bf16 v[104:107], v[150:153], v[182:185], v[104:107]
	v_mfma_f32_16x16x32_bf16 v[96:99], v[158:161], v[182:185], v[96:99]
	v_mfma_f32_16x16x32_bf16 v[88:91], v[150:153], v[190:193], v[88:91]
	v_mfma_f32_16x16x32_bf16 v[80:83], v[158:161], v[190:193], v[80:83]
	v_mfma_f32_16x16x32_bf16 v[116:119], v[194:197], v[162:165], v[116:119]
	v_mfma_f32_16x16x32_bf16 v[108:111], v[202:205], v[162:165], v[108:111]
	v_mfma_f32_16x16x32_bf16 v[100:103], v[194:197], v[170:173], v[100:103]
	v_mfma_f32_16x16x32_bf16 v[92:95], v[202:205], v[170:173], v[92:95]
	v_mfma_f32_16x16x32_bf16 v[84:87], v[194:197], v[178:181], v[84:87]
	v_mfma_f32_16x16x32_bf16 v[76:79], v[202:205], v[178:181], v[76:79]
	v_mfma_f32_16x16x32_bf16 v[72:75], v[194:197], v[186:189], v[72:75]
	v_mfma_f32_16x16x32_bf16 v[68:71], v[202:205], v[186:189], v[68:71]
	v_mfma_f32_16x16x32_bf16 v[116:119], v[198:201], v[166:169], v[116:119]
	v_mfma_f32_16x16x32_bf16 v[108:111], v[206:209], v[166:169], v[108:111]
	v_mfma_f32_16x16x32_bf16 v[100:103], v[198:201], v[174:177], v[100:103]
	v_mfma_f32_16x16x32_bf16 v[92:95], v[206:209], v[174:177], v[92:95]
	v_mfma_f32_16x16x32_bf16 v[84:87], v[198:201], v[182:185], v[84:87]
	v_mfma_f32_16x16x32_bf16 v[76:79], v[206:209], v[182:185], v[76:79]
	v_mfma_f32_16x16x32_bf16 v[72:75], v[198:201], v[190:193], v[72:75]
	v_mfma_f32_16x16x32_bf16 v[68:71], v[206:209], v[190:193], v[68:71]
	s_barrier
	s_setprio 0
	ds_read_b128 v[162:165], v148 offset:16384
	ds_read_b128 v[166:169], v148 offset:17408
	ds_read_b128 v[170:173], v148 offset:18432
	ds_read_b128 v[174:177], v148 offset:19456
	ds_read_b128 v[178:181], v148 offset:20480
	ds_read_b128 v[182:185], v148 offset:21504
	ds_read_b128 v[186:189], v148 offset:22528
	ds_read_b128 v[190:193], v148 offset:23552
	s_add_i32 s54, s54, s30
	v_lshl_add_u64 v[146:147], s[20:21], 0, v[2:3]
	s_mov_b32 m0, s54
	v_lshl_add_u64 v[210:211], s[20:21], 0, v[132:133]
	global_load_lds_dwordx4 v[146:147], off
	s_add_i32 m0, s54, 0x2000
	s_nop 0
	global_load_lds_dwordx4 v[210:211], off
	s_mov_b32 m0, s31
	v_lshl_add_u64 v[212:213], s[24:25], 0, v[136:137]
	global_load_lds_dwordx4 v[212:213], off
	v_lshl_add_u64 v[216:217], s[24:25], 0, v[134:135]
	s_mov_b32 m0, s35
	s_nop 0
	global_load_lds_dwordx4 v[216:217], off
	s_add_u32 s54, s20, 0x80000
	s_addc_u32 s55, s21, 0
	s_add_i32 s56, s56, s30
	s_mov_b32 m0, s56
	s_nop 0
	global_load_lds_dwordx4 v2, s[54:55]
	s_add_i32 m0, s56, 0x2000
	s_nop 0
	global_load_lds_dwordx4 v132, s[54:55]
	s_waitcnt lgkmcnt(0)
	s_waitcnt vmcnt(6)
	s_setprio 1
	s_barrier
; #define PG8_STAGE(bufoff, gbase, voff) do { _Pragma("unroll") for (int _i = 0; _i < 2; ++_i) \
;         __builtin_amdgcn_global_load_lds((const unsigned*)((const char*)(gbase) + (voff)[_i]), (LAS unsigned*)(lds + (bufoff) + ldsw + _i * 8192), 16, 0, 0); } while (0)
; #define PG8_LDA(dst, b, h) do { _Pragma("unroll") for (int m = 0; m < 4; ++m) _Pragma("unroll") for (int k = 0; k < 2; ++k) dst[m][k] = *(const LAS bf16x8*)(lds + PG8_SA(b, h) + aoff + m * 2048 + k * 1024); } while (0)
; #define PG8_LDB(dst, b, h) do { _Pragma("unroll") for (int n = 0; n < 2; ++n) _Pragma("unroll") for (int k = 0; k < 2; ++k) dst[n][k] = *(const LAS bf16x8*)(lds + PG8_SB(b, h) + boff + n * 2048 + k * 1024); } while (0)
; #define PG8_MMA(ai, bj, At, Bt) do { __builtin_amdgcn_s_setprio(1); _Pragma("unroll") for (int m = 0; m < 4; ++m) _Pragma("unroll") for (int n = 0; n < 2; ++n) _Pragma("unroll") for (int k = 0; k < 2; ++k) \
;         acc[ai][bj][m][n] = __builtin_amdgcn_mfma_f32_16x16x32_bf16(Bt[n][k], At[m][k], acc[ai][bj][m][n], 0, 0, 0); __builtin_amdgcn_s_setprio(0); } while (0)
; #define PG8_WAIT_V(n) asm volatile("s_waitcnt vmcnt(" #n ")" ::: "memory")
; #define PG8_WAIT_L(n) asm volatile("s_waitcnt lgkmcnt(" #n ")" ::: "memory")
; #define PG8_BAR __builtin_amdgcn_s_barrier()
; #define PG8_SCHED __builtin_amdgcn_sched_barrier(0)
; template <class Epi, class Sched>
; __device__ __forceinline__ void gemm_phase(LAS unsigned char* lds, const Gemm g, const Sched& S, const Epi& E) {
;     ...
;             PG8_WAIT_V(6); PG8_BAR; PG8_MMA(1, 1, At, B1); PG8_BAR;
;             PG8_LDB(B0, 1, 0); PG8_SCHED; PG8_LDA(At, 1, 0); PG8_STAGE(PG8_SA(0, 1), a2 + hstepA, voffA);
;             PG8_WAIT_L(8); PG8_BAR; PG8_WAIT_L(0); PG8_MMA(0, 0, At, B0); PG8_BAR; PG8_SCHED;
;             PG8_LDB(B1, 1, 1); PG8_STAGE(PG8_SB(1, 0), b3, voffB);
;             PG8_BAR; PG8_WAIT_L(0); PG8_MMA(0, 1, At, B1); PG8_BAR;
;             PG8_LDA(At, 1, 1); PG8_STAGE(PG8_SA(1, 0), a3, voffA);
;             PG8_BAR; PG8_WAIT_L(0); PG8_MMA(1, 0, At, B0); PG8_BAR; PG8_SCHED;
	v_mfma_f32_16x16x32_bf16 v[64:67], v[142:145], v[162:165], v[64:67]
	v_mfma_f32_16x16x32_bf16 v[60:63], v[154:157], v[162:165], v[60:63]
	v_mfma_f32_16x16x32_bf16 v[56:59], v[142:145], v[170:173], v[56:59]
	v_mfma_f32_16x16x32_bf16 v[48:51], v[154:157], v[170:173], v[48:51]
	v_mfma_f32_16x16x32_bf16 v[40:43], v[142:145], v[178:181], v[40:43]
	v_mfma_f32_16x16x32_bf16 v[32:35], v[154:157], v[178:181], v[32:35]
	v_mfma_f32_16x16x32_bf16 v[24:27], v[142:145], v[186:189], v[24:27]
	v_mfma_f32_16x16x32_bf16 v[16:19], v[154:157], v[186:189], v[16:19]
	v_mfma_f32_16x16x32_bf16 v[64:67], v[150:153], v[166:169], v[64:67]
	v_mfma_f32_16x16x32_bf16 v[60:63], v[158:161], v[166:169], v[60:63]
	v_mfma_f32_16x16x32_bf16 v[56:59], v[150:153], v[174:177], v[56:59]
	v_mfma_f32_16x16x32_bf16 v[48:51], v[158:161], v[174:177], v[48:51]
	v_mfma_f32_16x16x32_bf16 v[40:43], v[150:153], v[182:185], v[40:43]
	v_mfma_f32_16x16x32_bf16 v[32:35], v[158:161], v[182:185], v[32:35]
	v_mfma_f32_16x16x32_bf16 v[24:27], v[150:153], v[190:193], v[24:27]
	v_mfma_f32_16x16x32_bf16 v[16:19], v[158:161], v[190:193], v[16:19]
	v_mfma_f32_16x16x32_bf16 v[52:55], v[194:197], v[162:165], v[52:55]
	v_mfma_f32_16x16x32_bf16 v[44:47], v[202:205], v[162:165], v[44:47]
	v_mfma_f32_16x16x32_bf16 v[36:39], v[194:197], v[170:173], v[36:39]
	v_mfma_f32_16x16x32_bf16 v[28:31], v[202:205], v[170:173], v[28:31]
	v_mfma_f32_16x16x32_bf16 v[20:23], v[194:197], v[178:181], v[20:23]
	v_mfma_f32_16x16x32_bf16 v[12:15], v[202:205], v[178:181], v[12:15]
	v_mfma_f32_16x16x32_bf16 v[8:11], v[194:197], v[186:189], v[8:11]
	v_mfma_f32_16x16x32_bf16 v[4:7], v[202:205], v[186:189], v[4:7]
	v_mfma_f32_16x16x32_bf16 v[52:55], v[198:201], v[166:169], v[52:55]
	v_mfma_f32_16x16x32_bf16 v[44:47], v[206:209], v[166:169], v[44:47]
	v_mfma_f32_16x16x32_bf16 v[36:39], v[198:201], v[174:177], v[36:39]
	v_mfma_f32_16x16x32_bf16 v[28:31], v[206:209], v[174:177], v[28:31]
	v_mfma_f32_16x16x32_bf16 v[20:23], v[198:201], v[182:185], v[20:23]
	v_mfma_f32_16x16x32_bf16 v[12:15], v[206:209], v[182:185], v[12:15]
	v_mfma_f32_16x16x32_bf16 v[8:11], v[198:201], v[190:193], v[8:11]
	v_mfma_f32_16x16x32_bf16 v[4:7], v[206:209], v[190:193], v[4:7]
	s_barrier
	s_setprio 0
	s_add_i32 s54, 0, 0x18000
	v_add_u32_e32 v149, s54, v1
	ds_read_b128 v[142:145], v149
	ds_read_b128 v[150:153], v149 offset:1024
	ds_read_b128 v[154:157], v149 offset:2048
	ds_read_b128 v[158:161], v149 offset:3072
	s_add_u32 s24, s24, 0x80000
	s_addc_u32 s25, s25, 0
	ds_read_b128 v[162:165], v148 offset:32768
	ds_read_b128 v[166:169], v148 offset:33792
	ds_read_b128 v[170:173], v148 offset:34816
	ds_read_b128 v[174:177], v148 offset:35840
	ds_read_b128 v[178:181], v148 offset:36864
	ds_read_b128 v[182:185], v148 offset:37888
	ds_read_b128 v[186:189], v148 offset:38912
	ds_read_b128 v[190:193], v148 offset:39936
	s_mov_b32 m0, s36
	s_nop 0
	global_load_lds_dwordx4 v136, s[24:25]
	s_mov_b32 m0, s37
	s_nop 0
	global_load_lds_dwordx4 v134, s[24:25]
	s_add_i32 s24, 0, 0x1c000
	v_add_u32_e32 v149, s24, v1
	ds_read_b128 v[194:197], v149
	ds_read_b128 v[198:201], v149 offset:1024
	ds_read_b128 v[202:205], v149 offset:2048
	ds_read_b128 v[206:209], v149 offset:3072
	s_waitcnt lgkmcnt(0)
	s_setprio 1
	s_barrier
	v_mfma_f32_16x16x32_bf16 v[128:131], v[142:145], v[162:165], v[128:131]
	v_mfma_f32_16x16x32_bf16 v[124:127], v[154:157], v[162:165], v[124:127]
	v_mfma_f32_16x16x32_bf16 v[120:123], v[142:145], v[170:173], v[120:123]
	v_mfma_f32_16x16x32_bf16 v[112:115], v[154:157], v[170:173], v[112:115]
	v_mfma_f32_16x16x32_bf16 v[104:107], v[142:145], v[178:181], v[104:107]
	v_mfma_f32_16x16x32_bf16 v[96:99], v[154:157], v[178:181], v[96:99]
	v_mfma_f32_16x16x32_bf16 v[88:91], v[142:145], v[186:189], v[88:91]
	v_mfma_f32_16x16x32_bf16 v[80:83], v[154:157], v[186:189], v[80:83]
	v_mfma_f32_16x16x32_bf16 v[128:131], v[150:153], v[166:169], v[128:131]
	v_mfma_f32_16x16x32_bf16 v[124:127], v[158:161], v[166:169], v[124:127]
	v_mfma_f32_16x16x32_bf16 v[120:123], v[150:153], v[174:177], v[120:123]
	v_mfma_f32_16x16x32_bf16 v[112:115], v[158:161], v[174:177], v[112:115]
	v_mfma_f32_16x16x32_bf16 v[104:107], v[150:153], v[182:185], v[104:107]
	v_mfma_f32_16x16x32_bf16 v[96:99], v[158:161], v[182:185], v[96:99]
	v_mfma_f32_16x16x32_bf16 v[88:91], v[150:153], v[190:193], v[88:91]
	v_mfma_f32_16x16x32_bf16 v[80:83], v[158:161], v[190:193], v[80:83]
	v_mfma_f32_16x16x32_bf16 v[116:119], v[194:197], v[162:165], v[116:119]
	v_mfma_f32_16x16x32_bf16 v[108:111], v[202:205], v[162:165], v[108:111]
	v_mfma_f32_16x16x32_bf16 v[100:103], v[194:197], v[170:173], v[100:103]
	v_mfma_f32_16x16x32_bf16 v[92:95], v[202:205], v[170:173], v[92:95]
	v_mfma_f32_16x16x32_bf16 v[84:87], v[194:197], v[178:181], v[84:87]
	v_mfma_f32_16x16x32_bf16 v[76:79], v[202:205], v[178:181], v[76:79]
	v_mfma_f32_16x16x32_bf16 v[72:75], v[194:197], v[186:189], v[72:75]
	v_mfma_f32_16x16x32_bf16 v[68:71], v[202:205], v[186:189], v[68:71]
	v_mfma_f32_16x16x32_bf16 v[116:119], v[198:201], v[166:169], v[116:119]
	v_mfma_f32_16x16x32_bf16 v[108:111], v[206:209], v[166:169], v[108:111]
	v_mfma_f32_16x16x32_bf16 v[100:103], v[198:201], v[174:177], v[100:103]
	v_mfma_f32_16x16x32_bf16 v[92:95], v[206:209], v[174:177], v[92:95]
	v_mfma_f32_16x16x32_bf16 v[84:87], v[198:201], v[182:185], v[84:87]
	v_mfma_f32_16x16x32_bf16 v[76:79], v[206:209], v[182:185], v[76:79]
	v_mfma_f32_16x16x32_bf16 v[72:75], v[198:201], v[190:193], v[72:75]
	v_mfma_f32_16x16x32_bf16 v[68:71], v[206:209], v[190:193], v[68:71]
	s_barrier
; #define LAS __attribute__((address_space(3)))
; __device__ __forceinline__ int opaque_tid() { int t = threadIdx.x; asm volatile("" : "+v"(t)); return t; }
;     __device__ __forceinline__ void prefetch(const Unit& u, int ui) const { rs_prefetch(rs, u.pm, ui); }
; #define PG8_STAGE(bufoff, gbase, voff) do { _Pragma("unroll") for (int _i = 0; _i < 2; ++_i) \
;         __builtin_amdgcn_global_load_lds((const unsigned*)((const char*)(gbase) + (voff)[_i]), (LAS unsigned*)(lds + (bufoff) + ldsw + _i * 8192), 16, 0, 0); } while (0)
; #define PG8_LDA(dst, b, h) do { _Pragma("unroll") for (int m = 0; m < 4; ++m) _Pragma("unroll") for (int k = 0; k < 2; ++k) dst[m][k] = *(const LAS bf16x8*)(lds + PG8_SA(b, h) + aoff + m * 2048 + k * 1024); } while (0)
; #define PG8_WAIT_V(n) asm volatile("s_waitcnt vmcnt(" #n ")" ::: "memory")
; #define PG8_WAIT_L(n) asm volatile("s_waitcnt lgkmcnt(" #n ")" ::: "memory")
; #define PG8_BAR __builtin_amdgcn_s_barrier()
; #define PG8_SCHED __builtin_amdgcn_sched_barrier(0)
; __device__ __forceinline__ void rs_read(float (&r_)[2][4], int ui, int wr, int fr) {
;     extern __shared__ __attribute__((aligned(16))) unsigned char lds_dyn_[];
;     const LAS float* rl = (const LAS float*)((LAS unsigned char*)lds_dyn_ + L_RSPF + (ui & 1) * 1024) + wr * 64 + fr;
; #pragma unroll
;     for (int ai = 0; ai < 2; ++ai)
; #pragma unroll
;         for (int m = 0; m < 4; ++m) r_[ai][m] = rl[ai * HALF + m * 16];
; }
;     __device__ __forceinline__ void prefetch(const Unit& u, int ui) const { if (rs) rs_prefetch(rs, u.pm, ui); }
;     __device__ __forceinline__ void operator()(const f32x4 (&acc)[2][2][4][2], const Unit& u, int wr, int wc, int ui, int) const {
;         const int ol_ = opaque_tid() & 63, fr = ol_ & 15, fq = ol_ >> 4;
;         const int row0 = u.pm * BM + wr * 64 + fr, col0 = u.pn * BM + wc * 32 + 8 * fq;
;         float r_[2][4];
;         if (rs) rs_read(r_, ui, wr, fr);
; template <class Epi, class Sched>
; __device__ __forceinline__ void gemm_phase(LAS unsigned char* lds, const Gemm g, const Sched& S, const Epi& E) {
;     ...
;             PG8_LDA(At, 1, 1); PG8_STAGE(PG8_SA(1, 0), a3, voffA);
;             PG8_BAR; PG8_WAIT_L(0); PG8_MMA(1, 0, At, B0); PG8_BAR; PG8_SCHED;
;             PG8_STAGE(PG8_SB(1, 1), b3 + hstepB, voffB);
;             PG8_WAIT_V(6); PG8_BAR; PG8_MMA(1, 1, At, B1); PG8_BAR;
;         }
	s_setprio 0
	ds_read_b128 v[162:165], v148 offset:49152
	ds_read_b128 v[166:169], v148 offset:50176
	ds_read_b128 v[170:173], v148 offset:51200
	ds_read_b128 v[174:177], v148 offset:52224
	ds_read_b128 v[178:181], v148 offset:53248
	ds_read_b128 v[182:185], v148 offset:54272
	ds_read_b128 v[186:189], v148 offset:55296
	ds_read_b128 v[190:193], v148 offset:56320
	s_add_i32 s25, s54, s30
	v_lshl_add_u64 v[146:147], v[146:147], 0, s[8:9]
	s_mov_b32 m0, s25
	s_nop 0
	global_load_lds_dwordx4 v[146:147], off
	v_lshl_add_u64 v[146:147], v[210:211], 0, s[8:9]
	s_add_i32 m0, s25, 0x2000
	s_nop 0
	global_load_lds_dwordx4 v[146:147], off
	s_mov_b32 m0, s42
	v_lshl_add_u64 v[146:147], v[212:213], 0, s[8:9]
	global_load_lds_dwordx4 v[146:147], off
	v_lshl_add_u64 v[146:147], v[216:217], 0, s[8:9]
	s_mov_b32 m0, s43
	s_nop 0
	global_load_lds_dwordx4 v[146:147], off
	s_add_u32 s20, s20, 0x80080
	s_addc_u32 s21, s21, 0
	s_add_i32 s24, s24, s30
	s_mov_b32 m0, s24
	s_nop 0
	global_load_lds_dwordx4 v2, s[20:21]
	s_add_i32 m0, s24, 0x2000
	s_nop 0
	global_load_lds_dwordx4 v132, s[20:21]
	s_add_i32 s53, s53, 2
	s_add_u32 s18, s18, 0x100
	s_addc_u32 s19, s19, 0
	s_add_u32 s51, s51, 0x100
	s_addc_u32 s52, s52, 0
	s_cmp_gt_u32 s53, 29
	s_waitcnt lgkmcnt(0)
	s_waitcnt vmcnt(6)
	s_setprio 1
	s_barrier
	v_mfma_f32_16x16x32_bf16 v[64:67], v[142:145], v[162:165], v[64:67]
	v_mfma_f32_16x16x32_bf16 v[60:63], v[154:157], v[162:165], v[60:63]
	v_mfma_f32_16x16x32_bf16 v[56:59], v[142:145], v[170:173], v[56:59]
	v_mfma_f32_16x16x32_bf16 v[48:51], v[154:157], v[170:173], v[48:51]
	v_mfma_f32_16x16x32_bf16 v[40:43], v[142:145], v[178:181], v[40:43]
	v_mfma_f32_16x16x32_bf16 v[32:35], v[154:157], v[178:181], v[32:35]
	v_mfma_f32_16x16x32_bf16 v[24:27], v[142:145], v[186:189], v[24:27]
	v_mfma_f32_16x16x32_bf16 v[16:19], v[154:157], v[186:189], v[16:19]
	v_mfma_f32_16x16x32_bf16 v[64:67], v[150:153], v[166:169], v[64:67]
	v_mfma_f32_16x16x32_bf16 v[60:63], v[158:161], v[166:169], v[60:63]
	v_mfma_f32_16x16x32_bf16 v[56:59], v[150:153], v[174:177], v[56:59]
	v_mfma_f32_16x16x32_bf16 v[48:51], v[158:161], v[174:177], v[48:51]
	v_mfma_f32_16x16x32_bf16 v[40:43], v[150:153], v[182:185], v[40:43]
	v_mfma_f32_16x16x32_bf16 v[32:35], v[158:161], v[182:185], v[32:35]
	v_mfma_f32_16x16x32_bf16 v[24:27], v[150:153], v[190:193], v[24:27]
	v_mfma_f32_16x16x32_bf16 v[16:19], v[158:161], v[190:193], v[16:19]
	v_mfma_f32_16x16x32_bf16 v[52:55], v[194:197], v[162:165], v[52:55]
	v_mfma_f32_16x16x32_bf16 v[44:47], v[202:205], v[162:165], v[44:47]
	v_mfma_f32_16x16x32_bf16 v[36:39], v[194:197], v[170:173], v[36:39]
	v_mfma_f32_16x16x32_bf16 v[28:31], v[202:205], v[170:173], v[28:31]
	v_mfma_f32_16x16x32_bf16 v[20:23], v[194:197], v[178:181], v[20:23]
	v_mfma_f32_16x16x32_bf16 v[12:15], v[202:205], v[178:181], v[12:15]
	v_mfma_f32_16x16x32_bf16 v[8:11], v[194:197], v[186:189], v[8:11]
	v_mfma_f32_16x16x32_bf16 v[4:7], v[202:205], v[186:189], v[4:7]
	v_mfma_f32_16x16x32_bf16 v[52:55], v[198:201], v[166:169], v[52:55]
	v_mfma_f32_16x16x32_bf16 v[44:47], v[206:209], v[166:169], v[44:47]
	v_mfma_f32_16x16x32_bf16 v[36:39], v[198:201], v[174:177], v[36:39]
	v_mfma_f32_16x16x32_bf16 v[28:31], v[206:209], v[174:177], v[28:31]
	v_mfma_f32_16x16x32_bf16 v[20:23], v[198:201], v[182:185], v[20:23]
	v_mfma_f32_16x16x32_bf16 v[12:15], v[206:209], v[182:185], v[12:15]
	v_mfma_f32_16x16x32_bf16 v[8:11], v[198:201], v[190:193], v[8:11]
	v_mfma_f32_16x16x32_bf16 v[4:7], v[206:209], v[190:193], v[4:7]
	s_barrier
	s_cbranch_scc0 .LBB0_1094
	s_setprio 0
	s_lshl_b32 s1, s48, 10
	v_mov_b32_e32 v144, v0
	s_and_b32 s1, s1, 0x400
	s_add_i32 s1, s44, s1
	v_and_b32_e32 v145, 15, v144
	v_lshl_add_u32 v142, v145, 2, s1
	s_lshl_b32 s1, s47, 8
	v_lshrrev_b32_e32 v144, 1, v144
	v_and_or_b32 v144, v144, 24, s1
	ds_read2_b32 v[150:151], v142 offset1:16
	ds_read2_b32 v[152:153], v142 offset0:32 offset1:48
	ds_read2_b32 v[154:155], v142 offset0:128 offset1:144
	ds_read2_b32 v[142:143], v142 offset0:160 offset1:176
	v_or_b32_e32 v146, s39, v144
	v_or_b32_e32 v144, s38, v145
	v_lshl_add_u32 v149, s46, 8, v144
	v_ashrrev_i32_e32 v147, 31, v146
	v_mov_b64_e32 v[144:145], s[92:93]
	v_mad_i64_i32 v[156:157], s[18:19], v149, s11, v[144:145]
	v_lshlrev_b64 v[146:147], 1, v[146:147]
	s_waitcnt lgkmcnt(0)
; __device__ __forceinline__ unsigned cvt_pk_bf16(float lo, float hi) { const f32x2 v = {lo, hi}; const bf16v2_ r = __builtin_convertvector(v, bf16v2_); return __builtin_bit_cast(unsigned, r); }
;     __device__ __forceinline__ void operator()(const f32x4 (&acc)[2][2][4][2], const Unit& u, int wr, int wc, int ui, int) const {
;     ...
; #pragma unroll
;         for (int ai = 0; ai < 2; ++ai)
; #pragma unroll
;             for (int m = 0; m < 4; ++m) { bf16_t* rowp = O + (size_t)(row0 + ai * HALF + m * 16) * ldc + col0; const float r = r_[ai][m];
; #pragma unroll
;                 for (int bj = 0; bj < 2; ++bj) { const f32x4 v0 = acc[ai][bj][m][0] * r, v1 = acc[ai][bj][m][1] * r;
;                     u32x4 w; w.x = cvt_pk_bf16(v0[0], v0[1]); w.y = cvt_pk_bf16(v0[2], v0[3]); w.z = cvt_pk_bf16(v1[0], v1[1]); w.w = cvt_pk_bf16(v1[2], v1[3]);
;                     *(u32x4*)(rowp + bj * HALF) = w; } }
	v_pk_mul_f32 v[130:131], v[130:131], v[150:151] op_sel_hi:[1,0]
	v_pk_mul_f32 v[128:129], v[128:129], v[150:151] op_sel_hi:[1,0]
	v_pk_mul_f32 v[158:159], v[126:127], v[150:151] op_sel_hi:[1,0]
	v_pk_mul_f32 v[126:127], v[124:125], v[150:151] op_sel_hi:[1,0]
	v_lshl_add_u64 v[156:157], v[156:157], 0, v[146:147]
	v_cvt_pk_bf16_f32 v124, v128, v129
	v_cvt_pk_bf16_f32 v125, v130, v131
	v_cvt_pk_bf16_f32 v126, v126, v127
	v_cvt_pk_bf16_f32 v127, v158, v159
	global_store_dwordx4 v[156:157], v[124:127], off sc1
	v_pk_mul_f32 v[118:119], v[118:119], v[150:151] op_sel_hi:[1,0]
	v_pk_mul_f32 v[116:117], v[116:117], v[150:151] op_sel_hi:[1,0]
	v_pk_mul_f32 v[124:125], v[110:111], v[150:151] op_sel_hi:[1,0]
	v_pk_mul_f32 v[110:111], v[108:109], v[150:151] op_sel_hi:[1,0]
	v_cvt_pk_bf16_f32 v108, v116, v117
	v_cvt_pk_bf16_f32 v109, v118, v119
	v_cvt_pk_bf16_f32 v110, v110, v111
	v_cvt_pk_bf16_f32 v111, v124, v125
	global_store_dwordx4 v[156:157], v[108:111], off offset:256 sc1
	v_mov_b32_e32 v118, v151
	v_pk_mul_f32 v[114:115], v[114:115], v[118:119] op_sel_hi:[1,0]
	v_or_b32_e32 v108, 16, v149
	v_mad_i64_i32 v[108:109], s[18:19], v108, s11, v[144:145]
	v_lshl_add_u64 v[116:117], v[108:109], 0, v[146:147]
	v_pk_mul_f32 v[110:111], v[122:123], v[118:119] op_sel_hi:[1,0]
	v_pk_mul_f32 v[108:109], v[120:121], v[118:119] op_sel_hi:[1,0]
	v_pk_mul_f32 v[112:113], v[112:113], v[118:119] op_sel_hi:[1,0]
	v_cvt_pk_bf16_f32 v108, v108, v109
	v_cvt_pk_bf16_f32 v109, v110, v111
	v_cvt_pk_bf16_f32 v110, v112, v113
	v_cvt_pk_bf16_f32 v111, v114, v115
	global_store_dwordx4 v[116:117], v[108:111], off sc1
	v_pk_mul_f32 v[102:103], v[102:103], v[118:119] op_sel_hi:[1,0]
	v_pk_mul_f32 v[100:101], v[100:101], v[118:119] op_sel_hi:[1,0]
	v_pk_mul_f32 v[108:109], v[94:95], v[118:119] op_sel_hi:[1,0]
	v_pk_mul_f32 v[94:95], v[92:93], v[118:119] op_sel_hi:[1,0]
	v_cvt_pk_bf16_f32 v92, v100, v101
	v_cvt_pk_bf16_f32 v93, v102, v103
	v_cvt_pk_bf16_f32 v94, v94, v95
	v_cvt_pk_bf16_f32 v95, v108, v109
	global_store_dwordx4 v[116:117], v[92:95], off offset:256 sc1
	v_pk_mul_f32 v[98:99], v[98:99], v[152:153] op_sel_hi:[1,0]
	v_pk_mul_f32 v[96:97], v[96:97], v[152:153] op_sel_hi:[1,0]
	v_or_b32_e32 v92, 32, v149
	v_mad_i64_i32 v[92:93], s[18:19], v92, s11, v[144:145]
	v_lshl_add_u64 v[100:101], v[92:93], 0, v[146:147]
	v_pk_mul_f32 v[94:95], v[106:107], v[152:153] op_sel_hi:[1,0]
	v_pk_mul_f32 v[92:93], v[104:105], v[152:153] op_sel_hi:[1,0]
	v_pk_mul_f32 v[86:87], v[86:87], v[152:153] op_sel_hi:[1,0]
	v_cvt_pk_bf16_f32 v92, v92, v93
	v_cvt_pk_bf16_f32 v93, v94, v95
	v_cvt_pk_bf16_f32 v94, v96, v97
	v_cvt_pk_bf16_f32 v95, v98, v99
	global_store_dwordx4 v[100:101], v[92:95], off sc1
	v_pk_mul_f32 v[84:85], v[84:85], v[152:153] op_sel_hi:[1,0]
	v_pk_mul_f32 v[66:67], v[66:67], v[154:155] op_sel_hi:[1,0]
	v_pk_mul_f32 v[92:93], v[78:79], v[152:153] op_sel_hi:[1,0]
	v_pk_mul_f32 v[78:79], v[76:77], v[152:153] op_sel_hi:[1,0]
	v_cvt_pk_bf16_f32 v76, v84, v85
	v_cvt_pk_bf16_f32 v77, v86, v87
	v_cvt_pk_bf16_f32 v78, v78, v79
	v_cvt_pk_bf16_f32 v79, v92, v93
	global_store_dwordx4 v[100:101], v[76:79], off offset:256 sc1
	v_mov_b32_e32 v86, v153
	v_pk_mul_f32 v[82:83], v[82:83], v[86:87] op_sel_hi:[1,0]
	v_or_b32_e32 v76, 48, v149
	v_mad_i64_i32 v[76:77], s[18:19], v76, s11, v[144:145]
	v_lshl_add_u64 v[84:85], v[76:77], 0, v[146:147]
	v_pk_mul_f32 v[78:79], v[90:91], v[86:87] op_sel_hi:[1,0]
	v_pk_mul_f32 v[76:77], v[88:89], v[86:87] op_sel_hi:[1,0]
	v_pk_mul_f32 v[80:81], v[80:81], v[86:87] op_sel_hi:[1,0]
	v_cvt_pk_bf16_f32 v76, v76, v77
	v_cvt_pk_bf16_f32 v77, v78, v79
	v_cvt_pk_bf16_f32 v78, v80, v81
	v_cvt_pk_bf16_f32 v79, v82, v83
	global_store_dwordx4 v[84:85], v[76:79], off sc1
	v_pk_mul_f32 v[74:75], v[74:75], v[86:87] op_sel_hi:[1,0]
	v_pk_mul_f32 v[72:73], v[72:73], v[86:87] op_sel_hi:[1,0]
	v_pk_mul_f32 v[76:77], v[70:71], v[86:87] op_sel_hi:[1,0]
	v_pk_mul_f32 v[70:71], v[68:69], v[86:87] op_sel_hi:[1,0]
	v_cvt_pk_bf16_f32 v68, v72, v73
	v_cvt_pk_bf16_f32 v69, v74, v75
	v_cvt_pk_bf16_f32 v70, v70, v71
	v_cvt_pk_bf16_f32 v71, v76, v77
	global_store_dwordx4 v[84:85], v[68:71], off offset:256 sc1
; __device__ __forceinline__ unsigned cvt_pk_bf16(float lo, float hi) { const f32x2 v = {lo, hi}; const bf16v2_ r = __builtin_convertvector(v, bf16v2_); return __builtin_bit_cast(unsigned, r); }
;     __device__ __forceinline__ void operator()(const f32x4 (&acc)[2][2][4][2], const Unit& u, int wr, int wc, int ui, int) const {
;     ...
; #pragma unroll
;         for (int ai = 0; ai < 2; ++ai)
; #pragma unroll
;             for (int m = 0; m < 4; ++m) { bf16_t* rowp = O + (size_t)(row0 + ai * HALF + m * 16) * ldc + col0; const float r = r_[ai][m];
; #pragma unroll
;                 for (int bj = 0; bj < 2; ++bj) { const f32x4 v0 = acc[ai][bj][m][0] * r, v1 = acc[ai][bj][m][1] * r;
;                     u32x4 w; w.x = cvt_pk_bf16(v0[0], v0[1]); w.y = cvt_pk_bf16(v0[2], v0[3]); w.z = cvt_pk_bf16(v1[0], v1[1]); w.w = cvt_pk_bf16(v1[2], v1[3]);
;                     *(u32x4*)(rowp + bj * HALF) = w; } }
	v_pk_mul_f32 v[64:65], v[64:65], v[154:155] op_sel_hi:[1,0]
	v_pk_mul_f32 v[54:55], v[54:55], v[154:155] op_sel_hi:[1,0]
	v_add_u32_e32 v68, 0x80, v149
	v_mad_i64_i32 v[68:69], s[18:19], v68, s11, v[144:145]
	v_pk_mul_f32 v[70:71], v[62:63], v[154:155] op_sel_hi:[1,0]
	v_pk_mul_f32 v[62:63], v[60:61], v[154:155] op_sel_hi:[1,0]
	v_lshl_add_u64 v[68:69], v[68:69], 0, v[146:147]
	v_cvt_pk_bf16_f32 v60, v64, v65
	v_cvt_pk_bf16_f32 v61, v66, v67
	v_cvt_pk_bf16_f32 v62, v62, v63
	v_cvt_pk_bf16_f32 v63, v70, v71
	global_store_dwordx4 v[68:69], v[60:63], off sc1
	v_pk_mul_f32 v[52:53], v[52:53], v[154:155] op_sel_hi:[1,0]
	v_pk_mul_f32 v[34:35], v[34:35], v[142:143] op_sel_hi:[1,0]
	v_pk_mul_f32 v[60:61], v[46:47], v[154:155] op_sel_hi:[1,0]
	v_pk_mul_f32 v[46:47], v[44:45], v[154:155] op_sel_hi:[1,0]
	v_cvt_pk_bf16_f32 v44, v52, v53
	v_cvt_pk_bf16_f32 v45, v54, v55
	v_cvt_pk_bf16_f32 v46, v46, v47
	v_cvt_pk_bf16_f32 v47, v60, v61
	global_store_dwordx4 v[68:69], v[44:47], off offset:256 sc1
	v_mov_b32_e32 v54, v155
	v_pk_mul_f32 v[50:51], v[50:51], v[54:55] op_sel_hi:[1,0]
	v_add_u32_e32 v44, 0x90, v149
	v_mad_i64_i32 v[44:45], s[18:19], v44, s11, v[144:145]
	v_lshl_add_u64 v[52:53], v[44:45], 0, v[146:147]
	v_pk_mul_f32 v[46:47], v[58:59], v[54:55] op_sel_hi:[1,0]
	v_pk_mul_f32 v[44:45], v[56:57], v[54:55] op_sel_hi:[1,0]
	v_pk_mul_f32 v[48:49], v[48:49], v[54:55] op_sel_hi:[1,0]
	v_cvt_pk_bf16_f32 v44, v44, v45
	v_cvt_pk_bf16_f32 v45, v46, v47
	v_cvt_pk_bf16_f32 v46, v48, v49
	v_cvt_pk_bf16_f32 v47, v50, v51
	global_store_dwordx4 v[52:53], v[44:47], off sc1
	v_pk_mul_f32 v[38:39], v[38:39], v[54:55] op_sel_hi:[1,0]
	v_pk_mul_f32 v[36:37], v[36:37], v[54:55] op_sel_hi:[1,0]
	v_pk_mul_f32 v[44:45], v[30:31], v[54:55] op_sel_hi:[1,0]
	v_pk_mul_f32 v[30:31], v[28:29], v[54:55] op_sel_hi:[1,0]
	v_cvt_pk_bf16_f32 v28, v36, v37
	v_cvt_pk_bf16_f32 v29, v38, v39
	v_cvt_pk_bf16_f32 v30, v30, v31
	v_cvt_pk_bf16_f32 v31, v44, v45
	global_store_dwordx4 v[52:53], v[28:31], off offset:256 sc1
	v_pk_mul_f32 v[32:33], v[32:33], v[142:143] op_sel_hi:[1,0]
	v_pk_mul_f32 v[22:23], v[22:23], v[142:143] op_sel_hi:[1,0]
	v_add_u32_e32 v28, 0xa0, v149
	v_mad_i64_i32 v[28:29], s[18:19], v28, s11, v[144:145]
	v_lshl_add_u64 v[36:37], v[28:29], 0, v[146:147]
	v_pk_mul_f32 v[30:31], v[42:43], v[142:143] op_sel_hi:[1,0]
	v_pk_mul_f32 v[28:29], v[40:41], v[142:143] op_sel_hi:[1,0]
	v_pk_mul_f32 v[20:21], v[20:21], v[142:143] op_sel_hi:[1,0]
	v_cvt_pk_bf16_f32 v28, v28, v29
	v_cvt_pk_bf16_f32 v29, v30, v31
	v_cvt_pk_bf16_f32 v30, v32, v33
	v_cvt_pk_bf16_f32 v31, v34, v35
	global_store_dwordx4 v[36:37], v[28:31], off sc1
	s_and_b64 vcc, exec, s[40:41]
	s_mov_b32 s47, s0
	v_pk_mul_f32 v[28:29], v[14:15], v[142:143] op_sel_hi:[1,0]
	v_pk_mul_f32 v[14:15], v[12:13], v[142:143] op_sel_hi:[1,0]
	v_cvt_pk_bf16_f32 v12, v20, v21
	v_cvt_pk_bf16_f32 v13, v22, v23
	v_cvt_pk_bf16_f32 v14, v14, v15
	v_cvt_pk_bf16_f32 v15, v28, v29
	global_store_dwordx4 v[36:37], v[12:15], off offset:256 sc1
	v_mov_b32_e32 v22, v143
	v_pk_mul_f32 v[18:19], v[18:19], v[22:23] op_sel_hi:[1,0]
	v_add_u32_e32 v12, 0xb0, v149
	v_mad_i64_i32 v[12:13], s[18:19], v12, s11, v[144:145]
	v_lshl_add_u64 v[20:21], v[12:13], 0, v[146:147]
	v_pk_mul_f32 v[14:15], v[26:27], v[22:23] op_sel_hi:[1,0]
	v_pk_mul_f32 v[12:13], v[24:25], v[22:23] op_sel_hi:[1,0]
	v_pk_mul_f32 v[16:17], v[16:17], v[22:23] op_sel_hi:[1,0]
	v_cvt_pk_bf16_f32 v12, v12, v13
	v_cvt_pk_bf16_f32 v13, v14, v15
	v_cvt_pk_bf16_f32 v14, v16, v17
	v_cvt_pk_bf16_f32 v15, v18, v19
	global_store_dwordx4 v[20:21], v[12:15], off sc1
	v_pk_mul_f32 v[10:11], v[10:11], v[22:23] op_sel_hi:[1,0]
	v_pk_mul_f32 v[8:9], v[8:9], v[22:23] op_sel_hi:[1,0]
	v_pk_mul_f32 v[12:13], v[6:7], v[22:23] op_sel_hi:[1,0]
	v_pk_mul_f32 v[6:7], v[4:5], v[22:23] op_sel_hi:[1,0]
	v_cvt_pk_bf16_f32 v4, v8, v9
	v_cvt_pk_bf16_f32 v5, v10, v11
	v_cvt_pk_bf16_f32 v6, v6, v7
	v_cvt_pk_bf16_f32 v7, v12, v13
	s_mov_b32 s46, s4
	s_mov_b64 s[20:21], s[14:15]
	s_mov_b64 s[18:19], s[6:7]
	s_mov_b32 s48, s45
	global_store_dwordx4 v[20:21], v[4:7], off offset:256 sc1
	s_cbranch_vccz .LBB0_1089
	s_waitcnt vmcnt(0)
	s_cmpk_gt_u32 s2, 0xff
	s_cbranch_scc1 .LBB0_1098
	s_barrier

; #define PG8_STAGE(bufoff, gbase, voff) do { _Pragma("unroll") for (int _i = 0; _i < 2; ++_i) \
;         __builtin_amdgcn_global_load_lds((const unsigned*)((const char*)(gbase) + (voff)[_i]), (LAS unsigned*)(lds + (bufoff) + ldsw + _i * 8192), 16, 0, 0); } while (0)
; #define PG8_LDA(dst, b, h) do { _Pragma("unroll") for (int m = 0; m < 4; ++m) _Pragma("unroll") for (int k = 0; k < 2; ++k) dst[m][k] = *(const LAS bf16x8*)(lds + PG8_SA(b, h) + aoff + m * 2048 + k * 1024); } while (0)
; #define PG8_LDB(dst, b, h) do { _Pragma("unroll") for (int n = 0; n < 2; ++n) _Pragma("unroll") for (int k = 0; k < 2; ++k) dst[n][k] = *(const LAS bf16x8*)(lds + PG8_SB(b, h) + boff + n * 2048 + k * 1024); } while (0)
; #define PG8_MMA(ai, bj, At, Bt) do { __builtin_amdgcn_s_setprio(1); _Pragma("unroll") for (int m = 0; m < 4; ++m) _Pragma("unroll") for (int n = 0; n < 2; ++n) _Pragma("unroll") for (int k = 0; k < 2; ++k) \
;         acc[ai][bj][m][n] = __builtin_amdgcn_mfma_f32_16x16x32_bf16(Bt[n][k], At[m][k], acc[ai][bj][m][n], 0, 0, 0); __builtin_amdgcn_s_setprio(0); } while (0)
; #define PG8_WAIT_V(n) asm volatile("s_waitcnt vmcnt(" #n ")" ::: "memory")
; #define PG8_WAIT_L(n) asm volatile("s_waitcnt lgkmcnt(" #n ")" ::: "memory")
; #define PG8_BAR __builtin_amdgcn_s_barrier()
; #define PG8_SCHED __builtin_amdgcn_sched_barrier(0)
; template <class Epi, class Sched>
; __device__ __forceinline__ void gemm_phase(LAS unsigned char* lds, const Gemm g, const Sched& S, const Epi& E) {
;     ...
;             PG8_LDB(B0, 0, 0); PG8_SCHED; PG8_LDA(At, 0, 0); PG8_STAGE(PG8_SA(1, 1), a1 + hstepA, voffA);
;             PG8_WAIT_L(8); PG8_BAR; PG8_WAIT_L(0); PG8_MMA(0, 0, At, B0); PG8_BAR; PG8_SCHED;
;             PG8_LDB(B1, 0, 1); PG8_STAGE(PG8_SB(0, 0), b2, voffB);
;             PG8_BAR; PG8_WAIT_L(0); PG8_MMA(0, 1, At, B1); PG8_BAR;
;             PG8_LDA(At, 0, 1); PG8_STAGE(PG8_SA(0, 0), a2, voffA);
;             PG8_BAR; PG8_WAIT_L(0); PG8_MMA(1, 0, At, B0); PG8_BAR; PG8_SCHED;
;             PG8_STAGE(PG8_SB(0, 1), b2 + hstepB, voffB);
;             PG8_WAIT_V(6); PG8_BAR; PG8_MMA(1, 1, At, B1); PG8_BAR;
.LBB0_1396:
	s_setprio 0
	s_add_u32 s20, s6, 0xfff80080
	s_addc_u32 s21, s7, -1
	s_add_i32 s52, 0, 0x10000
	v_add_u32_e32 v144, s52, v1
	ds_read_b128 v[132:135], v144
	ds_read_b128 v[136:139], v144 offset:1024
	ds_read_b128 v[140:143], v144 offset:2048
	ds_read_b128 v[144:147], v144 offset:3072
	s_cmp_eq_u32 s51, 28
	s_cselect_b32 s25, s15, s21
	s_cselect_b32 s24, s47, s20
	s_cselect_b32 s21, s1, s50
	s_cselect_b32 s20, s48, s49
	ds_read_b128 v[148:151], v224
	ds_read_b128 v[152:155], v224 offset:1024
	ds_read_b128 v[156:159], v224 offset:2048
	ds_read_b128 v[160:163], v224 offset:3072
	ds_read_b128 v[164:167], v224 offset:4096
	ds_read_b128 v[168:171], v224 offset:5120
	ds_read_b128 v[172:175], v224 offset:6144
	ds_read_b128 v[176:179], v224 offset:7168
	s_add_i32 s54, 0, 0x14000
	v_add_u32_e32 v202, s54, v1
	ds_read_b128 v[180:183], v202
	ds_read_b128 v[184:187], v202 offset:1024
	ds_read_b128 v[188:191], v202 offset:2048
	ds_read_b128 v[202:205], v202 offset:3072
	s_add_i32 m0, s31, 0xc000
	s_nop 0
	global_load_lds_dwordx4 v198, s[6:7]
	s_add_i32 m0, s31, 0xe000
	s_nop 0
	global_load_lds_dwordx4 v200, s[6:7]
	s_waitcnt lgkmcnt(0)
	s_setprio 1
	s_barrier
	v_mfma_f32_16x16x32_bf16 v[128:131], v[132:135], v[148:151], v[128:131]
	v_mfma_f32_16x16x32_bf16 v[124:127], v[140:143], v[148:151], v[124:127]
	v_mfma_f32_16x16x32_bf16 v[112:115], v[132:135], v[156:159], v[112:115]
	v_mfma_f32_16x16x32_bf16 v[108:111], v[140:143], v[156:159], v[108:111]
	v_mfma_f32_16x16x32_bf16 v[100:103], v[132:135], v[164:167], v[100:103]
	v_mfma_f32_16x16x32_bf16 v[92:95], v[140:143], v[164:167], v[92:95]
	v_mfma_f32_16x16x32_bf16 v[84:87], v[132:135], v[172:175], v[84:87]
	v_mfma_f32_16x16x32_bf16 v[76:79], v[140:143], v[172:175], v[76:79]
	v_mfma_f32_16x16x32_bf16 v[128:131], v[136:139], v[152:155], v[128:131]
	v_mfma_f32_16x16x32_bf16 v[124:127], v[144:147], v[152:155], v[124:127]
	v_mfma_f32_16x16x32_bf16 v[112:115], v[136:139], v[160:163], v[112:115]
	v_mfma_f32_16x16x32_bf16 v[108:111], v[144:147], v[160:163], v[108:111]
	v_mfma_f32_16x16x32_bf16 v[100:103], v[136:139], v[168:171], v[100:103]
	v_mfma_f32_16x16x32_bf16 v[92:95], v[144:147], v[168:171], v[92:95]
	v_mfma_f32_16x16x32_bf16 v[84:87], v[136:139], v[176:179], v[84:87]
	v_mfma_f32_16x16x32_bf16 v[76:79], v[144:147], v[176:179], v[76:79]
	v_mfma_f32_16x16x32_bf16 v[120:123], v[180:183], v[148:151], v[120:123]
	v_mfma_f32_16x16x32_bf16 v[116:119], v[188:191], v[148:151], v[116:119]
	v_mfma_f32_16x16x32_bf16 v[104:107], v[180:183], v[156:159], v[104:107]
	v_mfma_f32_16x16x32_bf16 v[96:99], v[188:191], v[156:159], v[96:99]
	v_mfma_f32_16x16x32_bf16 v[88:91], v[180:183], v[164:167], v[88:91]
	v_mfma_f32_16x16x32_bf16 v[80:83], v[188:191], v[164:167], v[80:83]
	v_mfma_f32_16x16x32_bf16 v[72:75], v[180:183], v[172:175], v[72:75]
	v_mfma_f32_16x16x32_bf16 v[68:71], v[188:191], v[172:175], v[68:71]
	v_mfma_f32_16x16x32_bf16 v[120:123], v[184:187], v[152:155], v[120:123]
	v_mfma_f32_16x16x32_bf16 v[116:119], v[202:205], v[152:155], v[116:119]
	v_mfma_f32_16x16x32_bf16 v[104:107], v[184:187], v[160:163], v[104:107]
	v_mfma_f32_16x16x32_bf16 v[96:99], v[202:205], v[160:163], v[96:99]
	v_mfma_f32_16x16x32_bf16 v[88:91], v[184:187], v[168:171], v[88:91]
	v_mfma_f32_16x16x32_bf16 v[80:83], v[202:205], v[168:171], v[80:83]
	v_mfma_f32_16x16x32_bf16 v[72:75], v[184:187], v[176:179], v[72:75]
	v_mfma_f32_16x16x32_bf16 v[68:71], v[202:205], v[176:179], v[68:71]
	s_barrier
	s_setprio 0
	ds_read_b128 v[148:151], v224 offset:16384
	ds_read_b128 v[152:155], v224 offset:17408
	ds_read_b128 v[156:159], v224 offset:18432
	ds_read_b128 v[160:163], v224 offset:19456
	ds_read_b128 v[164:167], v224 offset:20480
	ds_read_b128 v[168:171], v224 offset:21504
	ds_read_b128 v[172:175], v224 offset:22528
	ds_read_b128 v[176:179], v224 offset:23552
	s_add_i32 s52, s52, s30
	v_lshl_add_u64 v[206:207], s[20:21], 0, v[2:3]
	s_mov_b32 m0, s52
	s_nop 0
	global_load_lds_dwordx4 v[206:207], off
	v_lshl_add_u64 v[208:209], s[20:21], 0, v[192:193]
	s_add_i32 m0, s52, 0x2000
	s_nop 0
	global_load_lds_dwordx4 v[208:209], off
	s_mov_b32 m0, s31
	v_lshl_add_u64 v[210:211], s[24:25], 0, v[196:197]
	global_load_lds_dwordx4 v[210:211], off
	v_lshl_add_u64 v[212:213], s[24:25], 0, v[194:195]
	s_mov_b32 m0, s35
	s_nop 0
	global_load_lds_dwordx4 v[212:213], off
	s_add_u32 s52, s20, 0x80000
	s_addc_u32 s53, s21, 0
	s_add_i32 s54, s54, s30
	s_mov_b32 m0, s54
	s_nop 0
	global_load_lds_dwordx4 v2, s[52:53]
	s_add_i32 m0, s54, 0x2000
	s_nop 0
	global_load_lds_dwordx4 v192, s[52:53]
	s_waitcnt lgkmcnt(0)
	s_waitcnt vmcnt(6)
	s_setprio 1
	s_barrier
; #define PG8_STAGE(bufoff, gbase, voff) do { _Pragma("unroll") for (int _i = 0; _i < 2; ++_i) \
;         __builtin_amdgcn_global_load_lds((const unsigned*)((const char*)(gbase) + (voff)[_i]), (LAS unsigned*)(lds + (bufoff) + ldsw + _i * 8192), 16, 0, 0); } while (0)
; #define PG8_LDA(dst, b, h) do { _Pragma("unroll") for (int m = 0; m < 4; ++m) _Pragma("unroll") for (int k = 0; k < 2; ++k) dst[m][k] = *(const LAS bf16x8*)(lds + PG8_SA(b, h) + aoff + m * 2048 + k * 1024); } while (0)
; #define PG8_LDB(dst, b, h) do { _Pragma("unroll") for (int n = 0; n < 2; ++n) _Pragma("unroll") for (int k = 0; k < 2; ++k) dst[n][k] = *(const LAS bf16x8*)(lds + PG8_SB(b, h) + boff + n * 2048 + k * 1024); } while (0)
; #define PG8_MMA(ai, bj, At, Bt) do { __builtin_amdgcn_s_setprio(1); _Pragma("unroll") for (int m = 0; m < 4; ++m) _Pragma("unroll") for (int n = 0; n < 2; ++n) _Pragma("unroll") for (int k = 0; k < 2; ++k) \
;         acc[ai][bj][m][n] = __builtin_amdgcn_mfma_f32_16x16x32_bf16(Bt[n][k], At[m][k], acc[ai][bj][m][n], 0, 0, 0); __builtin_amdgcn_s_setprio(0); } while (0)
; #define PG8_WAIT_V(n) asm volatile("s_waitcnt vmcnt(" #n ")" ::: "memory")
; #define PG8_WAIT_L(n) asm volatile("s_waitcnt lgkmcnt(" #n ")" ::: "memory")
; #define PG8_BAR __builtin_amdgcn_s_barrier()
; #define PG8_SCHED __builtin_amdgcn_sched_barrier(0)
; template <class Epi, class Sched>
; __device__ __forceinline__ void gemm_phase(LAS unsigned char* lds, const Gemm g, const Sched& S, const Epi& E) {
;     ...
;             PG8_WAIT_V(6); PG8_BAR; PG8_MMA(1, 1, At, B1); PG8_BAR;
;             PG8_LDB(B0, 1, 0); PG8_SCHED; PG8_LDA(At, 1, 0); PG8_STAGE(PG8_SA(0, 1), a2 + hstepA, voffA);
;             PG8_WAIT_L(8); PG8_BAR; PG8_WAIT_L(0); PG8_MMA(0, 0, At, B0); PG8_BAR; PG8_SCHED;
;             PG8_LDB(B1, 1, 1); PG8_STAGE(PG8_SB(1, 0), b3, voffB);
;             PG8_BAR; PG8_WAIT_L(0); PG8_MMA(0, 1, At, B1); PG8_BAR;
;             PG8_LDA(At, 1, 1); PG8_STAGE(PG8_SA(1, 0), a3, voffA);
;             PG8_BAR; PG8_WAIT_L(0); PG8_MMA(1, 0, At, B0); PG8_BAR; PG8_SCHED;
	v_mfma_f32_16x16x32_bf16 v[64:67], v[132:135], v[148:151], v[64:67]
	v_mfma_f32_16x16x32_bf16 v[60:63], v[140:143], v[148:151], v[60:63]
	v_mfma_f32_16x16x32_bf16 v[52:55], v[132:135], v[156:159], v[52:55]
	v_mfma_f32_16x16x32_bf16 v[44:47], v[140:143], v[156:159], v[44:47]
	v_mfma_f32_16x16x32_bf16 v[36:39], v[132:135], v[164:167], v[36:39]
	v_mfma_f32_16x16x32_bf16 v[28:31], v[140:143], v[164:167], v[28:31]
	v_mfma_f32_16x16x32_bf16 v[20:23], v[132:135], v[172:175], v[20:23]
	v_mfma_f32_16x16x32_bf16 v[12:15], v[140:143], v[172:175], v[12:15]
	v_mfma_f32_16x16x32_bf16 v[64:67], v[136:139], v[152:155], v[64:67]
	v_mfma_f32_16x16x32_bf16 v[60:63], v[144:147], v[152:155], v[60:63]
	v_mfma_f32_16x16x32_bf16 v[52:55], v[136:139], v[160:163], v[52:55]
	v_mfma_f32_16x16x32_bf16 v[44:47], v[144:147], v[160:163], v[44:47]
	v_mfma_f32_16x16x32_bf16 v[36:39], v[136:139], v[168:171], v[36:39]
	v_mfma_f32_16x16x32_bf16 v[28:31], v[144:147], v[168:171], v[28:31]
	v_mfma_f32_16x16x32_bf16 v[20:23], v[136:139], v[176:179], v[20:23]
	v_mfma_f32_16x16x32_bf16 v[12:15], v[144:147], v[176:179], v[12:15]
	v_mfma_f32_16x16x32_bf16 v[56:59], v[180:183], v[148:151], v[56:59]
	v_mfma_f32_16x16x32_bf16 v[48:51], v[188:191], v[148:151], v[48:51]
	v_mfma_f32_16x16x32_bf16 v[40:43], v[180:183], v[156:159], v[40:43]
	v_mfma_f32_16x16x32_bf16 v[32:35], v[188:191], v[156:159], v[32:35]
	v_mfma_f32_16x16x32_bf16 v[24:27], v[180:183], v[164:167], v[24:27]
	v_mfma_f32_16x16x32_bf16 v[16:19], v[188:191], v[164:167], v[16:19]
	v_mfma_f32_16x16x32_bf16 v[8:11], v[180:183], v[172:175], v[8:11]
	v_mfma_f32_16x16x32_bf16 v[4:7], v[188:191], v[172:175], v[4:7]
	v_mfma_f32_16x16x32_bf16 v[56:59], v[184:187], v[152:155], v[56:59]
	v_mfma_f32_16x16x32_bf16 v[48:51], v[202:205], v[152:155], v[48:51]
	v_mfma_f32_16x16x32_bf16 v[40:43], v[184:187], v[160:163], v[40:43]
	v_mfma_f32_16x16x32_bf16 v[32:35], v[202:205], v[160:163], v[32:35]
	v_mfma_f32_16x16x32_bf16 v[24:27], v[184:187], v[168:171], v[24:27]
	v_mfma_f32_16x16x32_bf16 v[16:19], v[202:205], v[168:171], v[16:19]
	v_mfma_f32_16x16x32_bf16 v[8:11], v[184:187], v[176:179], v[8:11]
	v_mfma_f32_16x16x32_bf16 v[4:7], v[202:205], v[176:179], v[4:7]
	s_barrier
	s_setprio 0
	s_add_i32 s52, 0, 0x18000
	v_add_u32_e32 v144, s52, v1
	ds_read_b128 v[132:135], v144
	ds_read_b128 v[136:139], v144 offset:1024
	ds_read_b128 v[140:143], v144 offset:2048
	ds_read_b128 v[144:147], v144 offset:3072
	s_add_u32 s24, s24, 0x80000
	s_addc_u32 s25, s25, 0
	ds_read_b128 v[148:151], v224 offset:32768
	ds_read_b128 v[152:155], v224 offset:33792
	ds_read_b128 v[156:159], v224 offset:34816
	ds_read_b128 v[160:163], v224 offset:35840
	ds_read_b128 v[164:167], v224 offset:36864
	ds_read_b128 v[168:171], v224 offset:37888
	ds_read_b128 v[172:175], v224 offset:38912
	ds_read_b128 v[176:179], v224 offset:39936
	s_mov_b32 m0, s36
	s_nop 0
	global_load_lds_dwordx4 v196, s[24:25]
	s_mov_b32 m0, s37
	s_nop 0
	global_load_lds_dwordx4 v194, s[24:25]
	s_add_i32 s24, 0, 0x1c000
	v_add_u32_e32 v202, s24, v1
	ds_read_b128 v[180:183], v202
	ds_read_b128 v[184:187], v202 offset:1024
	ds_read_b128 v[188:191], v202 offset:2048
	ds_read_b128 v[202:205], v202 offset:3072
	s_waitcnt lgkmcnt(0)
	s_setprio 1
	s_barrier
	v_mfma_f32_16x16x32_bf16 v[128:131], v[132:135], v[148:151], v[128:131]
	v_mfma_f32_16x16x32_bf16 v[124:127], v[140:143], v[148:151], v[124:127]
	v_mfma_f32_16x16x32_bf16 v[112:115], v[132:135], v[156:159], v[112:115]
	v_mfma_f32_16x16x32_bf16 v[108:111], v[140:143], v[156:159], v[108:111]
	v_mfma_f32_16x16x32_bf16 v[100:103], v[132:135], v[164:167], v[100:103]
	v_mfma_f32_16x16x32_bf16 v[92:95], v[140:143], v[164:167], v[92:95]
	v_mfma_f32_16x16x32_bf16 v[84:87], v[132:135], v[172:175], v[84:87]
	v_mfma_f32_16x16x32_bf16 v[76:79], v[140:143], v[172:175], v[76:79]
	v_mfma_f32_16x16x32_bf16 v[128:131], v[136:139], v[152:155], v[128:131]
	v_mfma_f32_16x16x32_bf16 v[124:127], v[144:147], v[152:155], v[124:127]
	v_mfma_f32_16x16x32_bf16 v[112:115], v[136:139], v[160:163], v[112:115]
	v_mfma_f32_16x16x32_bf16 v[108:111], v[144:147], v[160:163], v[108:111]
	v_mfma_f32_16x16x32_bf16 v[100:103], v[136:139], v[168:171], v[100:103]
	v_mfma_f32_16x16x32_bf16 v[92:95], v[144:147], v[168:171], v[92:95]
	v_mfma_f32_16x16x32_bf16 v[84:87], v[136:139], v[176:179], v[84:87]
	v_mfma_f32_16x16x32_bf16 v[76:79], v[144:147], v[176:179], v[76:79]
	v_mfma_f32_16x16x32_bf16 v[120:123], v[180:183], v[148:151], v[120:123]
	v_mfma_f32_16x16x32_bf16 v[116:119], v[188:191], v[148:151], v[116:119]
	v_mfma_f32_16x16x32_bf16 v[104:107], v[180:183], v[156:159], v[104:107]
	v_mfma_f32_16x16x32_bf16 v[96:99], v[188:191], v[156:159], v[96:99]
	v_mfma_f32_16x16x32_bf16 v[88:91], v[180:183], v[164:167], v[88:91]
	v_mfma_f32_16x16x32_bf16 v[80:83], v[188:191], v[164:167], v[80:83]
	v_mfma_f32_16x16x32_bf16 v[72:75], v[180:183], v[172:175], v[72:75]
	v_mfma_f32_16x16x32_bf16 v[68:71], v[188:191], v[172:175], v[68:71]
	v_mfma_f32_16x16x32_bf16 v[120:123], v[184:187], v[152:155], v[120:123]
	v_mfma_f32_16x16x32_bf16 v[116:119], v[202:205], v[152:155], v[116:119]
	v_mfma_f32_16x16x32_bf16 v[104:107], v[184:187], v[160:163], v[104:107]
	v_mfma_f32_16x16x32_bf16 v[96:99], v[202:205], v[160:163], v[96:99]
	v_mfma_f32_16x16x32_bf16 v[88:91], v[184:187], v[168:171], v[88:91]
	v_mfma_f32_16x16x32_bf16 v[80:83], v[202:205], v[168:171], v[80:83]
	v_mfma_f32_16x16x32_bf16 v[72:75], v[184:187], v[176:179], v[72:75]
	v_mfma_f32_16x16x32_bf16 v[68:71], v[202:205], v[176:179], v[68:71]
	s_barrier
; __device__ __forceinline__ int opaque_tid() { int t = threadIdx.x; asm volatile("" : "+v"(t)); return t; }
; #define PG8_STAGE(bufoff, gbase, voff) do { _Pragma("unroll") for (int _i = 0; _i < 2; ++_i) \
;         __builtin_amdgcn_global_load_lds((const unsigned*)((const char*)(gbase) + (voff)[_i]), (LAS unsigned*)(lds + (bufoff) + ldsw + _i * 8192), 16, 0, 0); } while (0)
; #define PG8_LDA(dst, b, h) do { _Pragma("unroll") for (int m = 0; m < 4; ++m) _Pragma("unroll") for (int k = 0; k < 2; ++k) dst[m][k] = *(const LAS bf16x8*)(lds + PG8_SA(b, h) + aoff + m * 2048 + k * 1024); } while (0)
; #define PG8_LDB(dst, b, h) do { _Pragma("unroll") for (int n = 0; n < 2; ++n) _Pragma("unroll") for (int k = 0; k < 2; ++k) dst[n][k] = *(const LAS bf16x8*)(lds + PG8_SB(b, h) + boff + n * 2048 + k * 1024); } while (0)
; #define PG8_WAIT_V(n) asm volatile("s_waitcnt vmcnt(" #n ")" ::: "memory")
; #define PG8_WAIT_L(n) asm volatile("s_waitcnt lgkmcnt(" #n ")" ::: "memory")
;     __device__ __forceinline__ void operator()(const f32x4 (&acc)[2][2][4][2], const Unit& u, int wr, int wc, int, int) const {
;         const int ol_ = opaque_tid() & 63, fr = ol_ & 15, fq = ol_ >> 4;
;         const int row0 = u.pm * BM + wr * 64 + fr, col0 = u.pn * BM + wc * 32 + 8 * fq;
;         u32x4 cin[2][4][2];
; #pragma unroll
;         for (int ai = 0; ai < 2; ++ai)
; #pragma unroll
;             for (int m = 0; m < 4; ++m)
; #pragma unroll
;                 for (int bj = 0; bj < 2; ++bj) cin[ai][m][bj] = *(const u32x4*)(C + (size_t)(row0 + ai * HALF + m * 16) * ldc + col0 + bj * HALF);
; template <class Epi, class Sched>
; __device__ __forceinline__ void gemm_phase(LAS unsigned char* lds, const Gemm g, const Sched& S, const Epi& E) {
;     ...
;             PG8_LDB(B0, 1, 0); PG8_SCHED; PG8_LDA(At, 1, 0); PG8_STAGE(PG8_SA(0, 1), a2 + hstepA, voffA);
;             PG8_WAIT_L(8); PG8_BAR; PG8_WAIT_L(0); PG8_MMA(0, 0, At, B0); PG8_BAR; PG8_SCHED;
;             PG8_LDB(B1, 1, 1); PG8_STAGE(PG8_SB(1, 0), b3, voffB);
;             PG8_BAR; PG8_WAIT_L(0); PG8_MMA(0, 1, At, B1); PG8_BAR;
;             PG8_LDA(At, 1, 1); PG8_STAGE(PG8_SA(1, 0), a3, voffA);
;             PG8_BAR; PG8_WAIT_L(0); PG8_MMA(1, 0, At, B0); PG8_BAR; PG8_SCHED;
;             PG8_STAGE(PG8_SB(1, 1), b3 + hstepB, voffB);
;             PG8_WAIT_V(6); PG8_BAR; PG8_MMA(1, 1, At, B1); PG8_BAR;
;         }
	s_setprio 0
	ds_read_b128 v[148:151], v224 offset:49152
	ds_read_b128 v[152:155], v224 offset:50176
	ds_read_b128 v[156:159], v224 offset:51200
	ds_read_b128 v[160:163], v224 offset:52224
	ds_read_b128 v[164:167], v224 offset:53248
	ds_read_b128 v[168:171], v224 offset:54272
	ds_read_b128 v[172:175], v224 offset:55296
	ds_read_b128 v[176:179], v224 offset:56320
	s_add_i32 s25, s52, s30
	v_lshl_add_u64 v[206:207], v[206:207], 0, s[8:9]
	s_mov_b32 m0, s25
	s_nop 0
	global_load_lds_dwordx4 v[206:207], off
	v_lshl_add_u64 v[206:207], v[208:209], 0, s[8:9]
	s_add_i32 m0, s25, 0x2000
	s_nop 0
	global_load_lds_dwordx4 v[206:207], off
	s_mov_b32 m0, s42
	v_lshl_add_u64 v[206:207], v[210:211], 0, s[8:9]
	global_load_lds_dwordx4 v[206:207], off
	v_lshl_add_u64 v[206:207], v[212:213], 0, s[8:9]
	s_mov_b32 m0, s43
	s_nop 0
	global_load_lds_dwordx4 v[206:207], off
	s_add_u32 s20, s20, 0x80080
	s_addc_u32 s21, s21, 0
	s_add_i32 s24, s24, s30
	s_mov_b32 m0, s24
	s_nop 0
	global_load_lds_dwordx4 v2, s[20:21]
	s_add_i32 m0, s24, 0x2000
	s_nop 0
	global_load_lds_dwordx4 v192, s[20:21]
	s_add_i32 s51, s51, 2
	s_add_u32 s6, s6, 0x100
	s_addc_u32 s7, s7, 0
	s_add_u32 s49, s49, 0x100
	s_addc_u32 s50, s50, 0
	s_cmp_gt_u32 s51, 29
	s_waitcnt lgkmcnt(0)
	s_waitcnt vmcnt(6)
	s_setprio 1
	s_barrier
	v_mfma_f32_16x16x32_bf16 v[64:67], v[132:135], v[148:151], v[64:67]
	v_mfma_f32_16x16x32_bf16 v[60:63], v[140:143], v[148:151], v[60:63]
	v_mfma_f32_16x16x32_bf16 v[52:55], v[132:135], v[156:159], v[52:55]
	v_mfma_f32_16x16x32_bf16 v[44:47], v[140:143], v[156:159], v[44:47]
	v_mfma_f32_16x16x32_bf16 v[36:39], v[132:135], v[164:167], v[36:39]
	v_mfma_f32_16x16x32_bf16 v[28:31], v[140:143], v[164:167], v[28:31]
	v_mfma_f32_16x16x32_bf16 v[20:23], v[132:135], v[172:175], v[20:23]
	v_mfma_f32_16x16x32_bf16 v[12:15], v[140:143], v[172:175], v[12:15]
	v_mfma_f32_16x16x32_bf16 v[64:67], v[136:139], v[152:155], v[64:67]
	v_mfma_f32_16x16x32_bf16 v[60:63], v[144:147], v[152:155], v[60:63]
	v_mfma_f32_16x16x32_bf16 v[52:55], v[136:139], v[160:163], v[52:55]
	v_mfma_f32_16x16x32_bf16 v[44:47], v[144:147], v[160:163], v[44:47]
	v_mfma_f32_16x16x32_bf16 v[36:39], v[136:139], v[168:171], v[36:39]
	v_mfma_f32_16x16x32_bf16 v[28:31], v[144:147], v[168:171], v[28:31]
	v_mfma_f32_16x16x32_bf16 v[20:23], v[136:139], v[176:179], v[20:23]
	v_mfma_f32_16x16x32_bf16 v[12:15], v[144:147], v[176:179], v[12:15]
	v_mfma_f32_16x16x32_bf16 v[56:59], v[180:183], v[148:151], v[56:59]
	v_mfma_f32_16x16x32_bf16 v[48:51], v[188:191], v[148:151], v[48:51]
	v_mfma_f32_16x16x32_bf16 v[40:43], v[180:183], v[156:159], v[40:43]
	v_mfma_f32_16x16x32_bf16 v[32:35], v[188:191], v[156:159], v[32:35]
	v_mfma_f32_16x16x32_bf16 v[24:27], v[180:183], v[164:167], v[24:27]
	v_mfma_f32_16x16x32_bf16 v[16:19], v[188:191], v[164:167], v[16:19]
	v_mfma_f32_16x16x32_bf16 v[8:11], v[180:183], v[172:175], v[8:11]
	v_mfma_f32_16x16x32_bf16 v[4:7], v[188:191], v[172:175], v[4:7]
	v_mfma_f32_16x16x32_bf16 v[56:59], v[184:187], v[152:155], v[56:59]
	v_mfma_f32_16x16x32_bf16 v[48:51], v[202:205], v[152:155], v[48:51]
	v_mfma_f32_16x16x32_bf16 v[40:43], v[184:187], v[160:163], v[40:43]
	v_mfma_f32_16x16x32_bf16 v[32:35], v[202:205], v[160:163], v[32:35]
	v_mfma_f32_16x16x32_bf16 v[24:27], v[184:187], v[168:171], v[24:27]
	v_mfma_f32_16x16x32_bf16 v[16:19], v[202:205], v[168:171], v[16:19]
	v_mfma_f32_16x16x32_bf16 v[8:11], v[184:187], v[176:179], v[8:11]
	v_mfma_f32_16x16x32_bf16 v[4:7], v[202:205], v[176:179], v[4:7]
	s_barrier
	s_cbranch_scc0 .LBB0_1396
	s_setprio 0
	v_mov_b32_e32 v133, v0
	s_lshl_b32 s1, s46, 8
	s_add_i32 s1, s1, s38
	v_and_or_b32 v132, v133, 15, s1
	s_lshl_b32 s1, s45, 8
	v_lshrrev_b32_e32 v133, 1, v133
	v_and_or_b32 v133, v133, 24, s1
	v_or_b32_e32 v134, s39, v133
	v_ashrrev_i32_e32 v135, 31, v134
	v_lshlrev_b64 v[202:203], 1, v[134:135]
	v_ashrrev_i32_e32 v133, 31, v132
	v_lshl_add_u64 v[134:135], s[88:89], 0, v[202:203]
	v_lshlrev_b64 v[216:217], 12, v[132:133]
	v_lshl_add_u64 v[136:137], v[134:135], 0, v[216:217]
	global_load_dwordx4 v[226:229], v[136:137], off
	global_load_dwordx4 v[188:191], v[136:137], off offset:256
	v_or_b32_e32 v136, 16, v132
	v_ashrrev_i32_e32 v137, 31, v136
	v_lshlrev_b64 v[222:223], 12, v[136:137]
	v_lshl_add_u64 v[136:137], v[134:135], 0, v[222:223]
	global_load_dwordx4 v[184:187], v[136:137], off
	global_load_dwordx4 v[180:183], v[136:137], off offset:256
	v_or_b32_e32 v136, 32, v132
	v_ashrrev_i32_e32 v137, 31, v136
	v_lshlrev_b64 v[220:221], 12, v[136:137]
	v_lshl_add_u64 v[136:137], v[134:135], 0, v[220:221]
	global_load_dwordx4 v[176:179], v[136:137], off
	global_load_dwordx4 v[168:171], v[136:137], off offset:256
	v_or_b32_e32 v132, 48, v132
	v_ashrrev_i32_e32 v133, 31, v132
	v_lshlrev_b64 v[212:213], 12, v[132:133]
	v_lshl_add_u64 v[132:133], v[134:135], 0, v[212:213]
	global_load_dwordx4 v[172:175], v[132:133], off
	global_load_dwordx4 v[164:167], v[132:133], off offset:256
	s_mov_b64 s[6:7], 0x80000
	v_lshl_add_u64 v[210:211], v[216:217], 0, s[6:7]
	v_lshl_add_u64 v[132:133], v[134:135], 0, v[210:211]
	global_load_dwordx4 v[160:163], v[132:133], off
	global_load_dwordx4 v[156:159], v[132:133], off offset:256
	s_mov_b64 s[6:7], 0x90000
	v_lshl_add_u64 v[208:209], v[216:217], 0, s[6:7]
	v_lshl_add_u64 v[132:133], v[134:135], 0, v[208:209]
	global_load_dwordx4 v[152:155], v[132:133], off
	global_load_dwordx4 v[148:151], v[132:133], off offset:256
	s_mov_b64 s[6:7], 0xa0000
	v_lshl_add_u64 v[206:207], v[216:217], 0, s[6:7]
	v_lshl_add_u64 v[132:133], v[134:135], 0, v[206:207]
	global_load_dwordx4 v[144:147], v[132:133], off
	global_load_dwordx4 v[140:143], v[132:133], off offset:256
	s_mov_b64 s[6:7], 0xb0000
	v_lshl_add_u64 v[204:205], v[216:217], 0, s[6:7]
	v_lshl_add_u64 v[132:133], v[134:135], 0, v[204:205]
	global_load_dwordx4 v[136:139], v[132:133], off
	s_nop 0
	global_load_dwordx4 v[132:135], v[132:133], off offset:256
	s_and_b64 vcc, exec, s[40:41]
	s_mov_b32 s45, s0
	s_mov_b32 s46, s14
	s_mov_b64 s[20:21], s[18:19]
	s_mov_b64 s[6:7], s[4:5]
	s_waitcnt vmcnt(15)
; __device__ __forceinline__ unsigned cvt_pk_bf16(float lo, float hi) { const f32x2 v = {lo, hi}; const bf16v2_ r = __builtin_convertvector(v, bf16v2_); return __builtin_bit_cast(unsigned, r); }
; __device__ __forceinline__ float bflo(unsigned w) { return __uint_as_float(w << 16); }
; __device__ __forceinline__ float bfhi(unsigned w) { return __uint_as_float(w & 0xffff0000u); }
;     __device__ __forceinline__ void operator()(const f32x4 (&acc)[2][2][4][2], const Unit& u, int wr, int wc, int, int) const {
;     ...
; #pragma unroll
;         for (int ai = 0; ai < 2; ++ai)
; #pragma unroll
;             for (int m = 0; m < 4; ++m)
; #pragma unroll
;                 for (int bj = 0; bj < 2; ++bj) { const u32x4 c = cin[ai][m][bj]; const f32x4 v0 = acc[ai][bj][m][0], v1 = acc[ai][bj][m][1];
;                     u32x4 w; w.x = cvt_pk_bf16(bflo(c.x) + v0[0], bfhi(c.x) + v0[1]); w.y = cvt_pk_bf16(bflo(c.y) + v0[2], bfhi(c.y) + v0[3]);
;                     w.z = cvt_pk_bf16(bflo(c.z) + v1[0], bfhi(c.z) + v1[1]); w.w = cvt_pk_bf16(bflo(c.w) + v1[2], bfhi(c.w) + v1[3]);
;                     *(u32x4*)(C + (size_t)(row0 + ai * HALF + m * 16) * ldc + col0 + bj * HALF) = w; }
	v_lshlrev_b32_e32 v218, 16, v226
	v_and_b32_e32 v219, 0xffff0000, v226
	v_pk_add_f32 v[128:129], v[128:129], v[218:219]
	v_lshlrev_b32_e32 v218, 16, v227
	v_and_b32_e32 v219, 0xffff0000, v227
	v_pk_add_f32 v[130:131], v[130:131], v[218:219]
	v_cvt_pk_bf16_f32 v128, v128, v129
	v_cvt_pk_bf16_f32 v129, v130, v131
	v_lshlrev_b32_e32 v130, 16, v228
	v_and_b32_e32 v131, 0xffff0000, v228
	v_pk_add_f32 v[124:125], v[124:125], v[130:131]
	s_nop 0
	v_cvt_pk_bf16_f32 v130, v124, v125
	v_lshlrev_b32_e32 v124, 16, v229
	v_and_b32_e32 v125, 0xffff0000, v229
	v_pk_add_f32 v[124:125], v[126:127], v[124:125]
	s_waitcnt vmcnt(14)
	v_lshlrev_b32_e32 v126, 16, v188
	v_and_b32_e32 v127, 0xffff0000, v188
	v_pk_add_f32 v[120:121], v[120:121], v[126:127]
	v_lshlrev_b32_e32 v126, 16, v189
	v_and_b32_e32 v127, 0xffff0000, v189
	v_pk_add_f32 v[122:123], v[122:123], v[126:127]
	v_cvt_pk_bf16_f32 v120, v120, v121
	v_cvt_pk_bf16_f32 v121, v122, v123
	v_lshlrev_b32_e32 v122, 16, v190
	v_and_b32_e32 v123, 0xffff0000, v190
	v_pk_add_f32 v[116:117], v[116:117], v[122:123]
	v_cvt_pk_bf16_f32 v131, v124, v125
	v_cvt_pk_bf16_f32 v122, v116, v117
	v_lshlrev_b32_e32 v116, 16, v191
	v_and_b32_e32 v117, 0xffff0000, v191
	v_pk_add_f32 v[116:117], v[118:119], v[116:117]
	v_lshl_add_u64 v[124:125], s[88:89], 0, v[216:217]
	v_cvt_pk_bf16_f32 v123, v116, v117
	s_waitcnt vmcnt(13)
	v_lshlrev_b32_e32 v116, 16, v184
	v_and_b32_e32 v117, 0xffff0000, v184
	v_pk_add_f32 v[112:113], v[112:113], v[116:117]
	v_lshlrev_b32_e32 v116, 16, v185
	v_and_b32_e32 v117, 0xffff0000, v185
	v_pk_add_f32 v[114:115], v[114:115], v[116:117]
	v_cvt_pk_bf16_f32 v112, v112, v113
	v_cvt_pk_bf16_f32 v113, v114, v115
	v_lshlrev_b32_e32 v114, 16, v186
	v_and_b32_e32 v115, 0xffff0000, v186
	v_pk_add_f32 v[108:109], v[108:109], v[114:115]
	v_lshl_add_u64 v[124:125], v[124:125], 0, v[202:203]
	v_cvt_pk_bf16_f32 v114, v108, v109
	v_lshlrev_b32_e32 v108, 16, v187
	v_and_b32_e32 v109, 0xffff0000, v187
	v_pk_add_f32 v[108:109], v[110:111], v[108:109]
	s_waitcnt vmcnt(12)
	v_lshlrev_b32_e32 v110, 16, v180
	v_and_b32_e32 v111, 0xffff0000, v180
	v_pk_add_f32 v[104:105], v[104:105], v[110:111]
	v_lshlrev_b32_e32 v110, 16, v181
	v_and_b32_e32 v111, 0xffff0000, v181
	v_pk_add_f32 v[106:107], v[106:107], v[110:111]
	v_cvt_pk_bf16_f32 v104, v104, v105
	v_cvt_pk_bf16_f32 v105, v106, v107
	v_lshlrev_b32_e32 v106, 16, v182
	v_and_b32_e32 v107, 0xffff0000, v182
	v_pk_add_f32 v[96:97], v[96:97], v[106:107]
	v_cvt_pk_bf16_f32 v115, v108, v109
	v_cvt_pk_bf16_f32 v106, v96, v97
	v_lshlrev_b32_e32 v96, 16, v183
	v_and_b32_e32 v97, 0xffff0000, v183
	v_pk_add_f32 v[96:97], v[98:99], v[96:97]
	s_waitcnt vmcnt(11)
	v_lshlrev_b32_e32 v98, 16, v177
	v_cvt_pk_bf16_f32 v107, v96, v97
	v_lshlrev_b32_e32 v96, 16, v176
	v_and_b32_e32 v97, 0xffff0000, v176
	v_and_b32_e32 v99, 0xffff0000, v177
	v_pk_add_f32 v[96:97], v[100:101], v[96:97]
	v_pk_add_f32 v[98:99], v[102:103], v[98:99]
	v_cvt_pk_bf16_f32 v96, v96, v97
	v_cvt_pk_bf16_f32 v97, v98, v99
	v_lshlrev_b32_e32 v98, 16, v178
	v_and_b32_e32 v99, 0xffff0000, v178
	v_pk_add_f32 v[92:93], v[92:93], v[98:99]
	v_lshl_add_u64 v[108:109], s[88:89], 0, v[222:223]
	v_cvt_pk_bf16_f32 v98, v92, v93
	v_lshlrev_b32_e32 v92, 16, v179
	v_and_b32_e32 v93, 0xffff0000, v179
	v_pk_add_f32 v[92:93], v[94:95], v[92:93]
	s_waitcnt vmcnt(10)
	v_lshlrev_b32_e32 v94, 16, v168
	v_and_b32_e32 v95, 0xffff0000, v168
	v_pk_add_f32 v[88:89], v[88:89], v[94:95]
	v_lshlrev_b32_e32 v94, 16, v169
	v_and_b32_e32 v95, 0xffff0000, v169
	v_pk_add_f32 v[90:91], v[90:91], v[94:95]
	v_cvt_pk_bf16_f32 v88, v88, v89
	v_cvt_pk_bf16_f32 v89, v90, v91
	v_lshlrev_b32_e32 v90, 16, v170
	v_and_b32_e32 v91, 0xffff0000, v170
	v_pk_add_f32 v[80:81], v[80:81], v[90:91]
	v_cvt_pk_bf16_f32 v99, v92, v93
	v_cvt_pk_bf16_f32 v90, v80, v81
	v_lshlrev_b32_e32 v80, 16, v171
	v_and_b32_e32 v81, 0xffff0000, v171
	v_pk_add_f32 v[80:81], v[82:83], v[80:81]
	s_waitcnt vmcnt(9)
	v_lshlrev_b32_e32 v82, 16, v173
	v_cvt_pk_bf16_f32 v91, v80, v81
	v_lshlrev_b32_e32 v80, 16, v172
	v_and_b32_e32 v81, 0xffff0000, v172
	v_and_b32_e32 v83, 0xffff0000, v173
	v_pk_add_f32 v[80:81], v[84:85], v[80:81]
	v_pk_add_f32 v[82:83], v[86:87], v[82:83]
	v_cvt_pk_bf16_f32 v80, v80, v81
	v_cvt_pk_bf16_f32 v81, v82, v83
	v_lshlrev_b32_e32 v82, 16, v174
	v_and_b32_e32 v83, 0xffff0000, v174
	v_pk_add_f32 v[76:77], v[76:77], v[82:83]
	v_lshl_add_u64 v[92:93], s[88:89], 0, v[220:221]
	v_cvt_pk_bf16_f32 v82, v76, v77
	v_lshlrev_b32_e32 v76, 16, v175
	v_and_b32_e32 v77, 0xffff0000, v175
	v_pk_add_f32 v[76:77], v[78:79], v[76:77]
	s_waitcnt vmcnt(8)
	v_lshlrev_b32_e32 v78, 16, v164
	v_and_b32_e32 v79, 0xffff0000, v164
	v_pk_add_f32 v[72:73], v[72:73], v[78:79]
	v_lshlrev_b32_e32 v78, 16, v165
	v_and_b32_e32 v79, 0xffff0000, v165
	v_pk_add_f32 v[74:75], v[74:75], v[78:79]
	v_cvt_pk_bf16_f32 v72, v72, v73
	v_cvt_pk_bf16_f32 v73, v74, v75
	v_lshlrev_b32_e32 v74, 16, v166
	v_and_b32_e32 v75, 0xffff0000, v166
	v_pk_add_f32 v[68:69], v[68:69], v[74:75]
	v_cvt_pk_bf16_f32 v83, v76, v77
	v_cvt_pk_bf16_f32 v74, v68, v69
	v_lshlrev_b32_e32 v68, 16, v167
	v_and_b32_e32 v69, 0xffff0000, v167
	v_pk_add_f32 v[68:69], v[70:71], v[68:69]
	v_lshl_add_u64 v[76:77], s[88:89], 0, v[212:213]
	v_cvt_pk_bf16_f32 v75, v68, v69
	s_waitcnt vmcnt(7)
	v_lshlrev_b32_e32 v68, 16, v160
	v_and_b32_e32 v69, 0xffff0000, v160
	v_pk_add_f32 v[64:65], v[64:65], v[68:69]
	v_lshlrev_b32_e32 v68, 16, v161
	v_and_b32_e32 v69, 0xffff0000, v161
	v_pk_add_f32 v[66:67], v[66:67], v[68:69]
	v_cvt_pk_bf16_f32 v64, v64, v65
	v_cvt_pk_bf16_f32 v65, v66, v67
	v_lshlrev_b32_e32 v66, 16, v162
	v_and_b32_e32 v67, 0xffff0000, v162
	v_pk_add_f32 v[60:61], v[60:61], v[66:67]
	v_lshl_add_u64 v[108:109], v[108:109], 0, v[202:203]
	v_cvt_pk_bf16_f32 v66, v60, v61
	v_lshlrev_b32_e32 v60, 16, v163
	v_and_b32_e32 v61, 0xffff0000, v163
	v_pk_add_f32 v[60:61], v[62:63], v[60:61]
	s_waitcnt vmcnt(6)
; __device__ __forceinline__ unsigned cvt_pk_bf16(float lo, float hi) { const f32x2 v = {lo, hi}; const bf16v2_ r = __builtin_convertvector(v, bf16v2_); return __builtin_bit_cast(unsigned, r); }
; __device__ __forceinline__ float bflo(unsigned w) { return __uint_as_float(w << 16); }
; __device__ __forceinline__ float bfhi(unsigned w) { return __uint_as_float(w & 0xffff0000u); }
;     __device__ __forceinline__ void operator()(const f32x4 (&acc)[2][2][4][2], const Unit& u, int wr, int wc, int, int) const {
;     ...
; #pragma unroll
;         for (int ai = 0; ai < 2; ++ai)
; #pragma unroll
;             for (int m = 0; m < 4; ++m)
; #pragma unroll
;                 for (int bj = 0; bj < 2; ++bj) { const u32x4 c = cin[ai][m][bj]; const f32x4 v0 = acc[ai][bj][m][0], v1 = acc[ai][bj][m][1];
;                     u32x4 w; w.x = cvt_pk_bf16(bflo(c.x) + v0[0], bfhi(c.x) + v0[1]); w.y = cvt_pk_bf16(bflo(c.y) + v0[2], bfhi(c.y) + v0[3]);
;                     w.z = cvt_pk_bf16(bflo(c.z) + v1[0], bfhi(c.z) + v1[1]); w.w = cvt_pk_bf16(bflo(c.w) + v1[2], bfhi(c.w) + v1[3]);
;                     *(u32x4*)(C + (size_t)(row0 + ai * HALF + m * 16) * ldc + col0 + bj * HALF) = w; }
	v_lshlrev_b32_e32 v62, 16, v156
	v_and_b32_e32 v63, 0xffff0000, v156
	v_pk_add_f32 v[56:57], v[56:57], v[62:63]
	v_lshlrev_b32_e32 v62, 16, v157
	v_and_b32_e32 v63, 0xffff0000, v157
	v_pk_add_f32 v[58:59], v[58:59], v[62:63]
	v_cvt_pk_bf16_f32 v56, v56, v57
	v_cvt_pk_bf16_f32 v57, v58, v59
	v_lshlrev_b32_e32 v58, 16, v158
	v_and_b32_e32 v59, 0xffff0000, v158
	v_pk_add_f32 v[48:49], v[48:49], v[58:59]
	v_cvt_pk_bf16_f32 v67, v60, v61
	v_cvt_pk_bf16_f32 v58, v48, v49
	v_lshlrev_b32_e32 v48, 16, v159
	v_and_b32_e32 v49, 0xffff0000, v159
	v_pk_add_f32 v[48:49], v[50:51], v[48:49]
	s_waitcnt vmcnt(5)
	v_lshlrev_b32_e32 v50, 16, v153
	v_cvt_pk_bf16_f32 v59, v48, v49
	v_lshlrev_b32_e32 v48, 16, v152
	v_and_b32_e32 v49, 0xffff0000, v152
	v_and_b32_e32 v51, 0xffff0000, v153
	v_pk_add_f32 v[48:49], v[52:53], v[48:49]
	v_pk_add_f32 v[50:51], v[54:55], v[50:51]
	v_cvt_pk_bf16_f32 v48, v48, v49
	v_cvt_pk_bf16_f32 v49, v50, v51
	v_lshlrev_b32_e32 v50, 16, v154
	v_and_b32_e32 v51, 0xffff0000, v154
	v_pk_add_f32 v[44:45], v[44:45], v[50:51]
	v_lshl_add_u64 v[60:61], s[88:89], 0, v[210:211]
	v_cvt_pk_bf16_f32 v50, v44, v45
	v_lshlrev_b32_e32 v44, 16, v155
	v_and_b32_e32 v45, 0xffff0000, v155
	v_pk_add_f32 v[44:45], v[46:47], v[44:45]
	s_waitcnt vmcnt(4)
	v_lshlrev_b32_e32 v46, 16, v148
	v_and_b32_e32 v47, 0xffff0000, v148
	v_pk_add_f32 v[40:41], v[40:41], v[46:47]
	v_lshlrev_b32_e32 v46, 16, v149
	v_and_b32_e32 v47, 0xffff0000, v149
	v_pk_add_f32 v[42:43], v[42:43], v[46:47]
	v_cvt_pk_bf16_f32 v40, v40, v41
	v_cvt_pk_bf16_f32 v41, v42, v43
	v_lshlrev_b32_e32 v42, 16, v150
	v_and_b32_e32 v43, 0xffff0000, v150
	v_pk_add_f32 v[32:33], v[32:33], v[42:43]
	v_cvt_pk_bf16_f32 v51, v44, v45
	v_cvt_pk_bf16_f32 v42, v32, v33
	v_lshlrev_b32_e32 v32, 16, v151
	v_and_b32_e32 v33, 0xffff0000, v151
	v_pk_add_f32 v[32:33], v[34:35], v[32:33]
	s_waitcnt vmcnt(3)
	v_lshlrev_b32_e32 v34, 16, v145
	v_cvt_pk_bf16_f32 v43, v32, v33
	v_lshlrev_b32_e32 v32, 16, v144
	v_and_b32_e32 v33, 0xffff0000, v144
	v_and_b32_e32 v35, 0xffff0000, v145
	v_pk_add_f32 v[32:33], v[36:37], v[32:33]
	v_pk_add_f32 v[34:35], v[38:39], v[34:35]
	v_cvt_pk_bf16_f32 v32, v32, v33
	v_cvt_pk_bf16_f32 v33, v34, v35
	v_lshlrev_b32_e32 v34, 16, v146
	v_and_b32_e32 v35, 0xffff0000, v146
	v_pk_add_f32 v[28:29], v[28:29], v[34:35]
	v_lshl_add_u64 v[44:45], s[88:89], 0, v[208:209]
	v_cvt_pk_bf16_f32 v34, v28, v29
	v_lshlrev_b32_e32 v28, 16, v147
	v_and_b32_e32 v29, 0xffff0000, v147
	v_pk_add_f32 v[28:29], v[30:31], v[28:29]
	s_waitcnt vmcnt(2)
	v_lshlrev_b32_e32 v30, 16, v140
	v_and_b32_e32 v31, 0xffff0000, v140
	v_pk_add_f32 v[24:25], v[24:25], v[30:31]
	v_lshlrev_b32_e32 v30, 16, v141
	v_and_b32_e32 v31, 0xffff0000, v141
	v_pk_add_f32 v[26:27], v[26:27], v[30:31]
	v_cvt_pk_bf16_f32 v24, v24, v25
	v_cvt_pk_bf16_f32 v25, v26, v27
	v_lshlrev_b32_e32 v26, 16, v142
	v_and_b32_e32 v27, 0xffff0000, v142
	v_pk_add_f32 v[16:17], v[16:17], v[26:27]
	v_cvt_pk_bf16_f32 v35, v28, v29
	v_cvt_pk_bf16_f32 v26, v16, v17
	v_lshlrev_b32_e32 v16, 16, v143
	v_and_b32_e32 v17, 0xffff0000, v143
	v_pk_add_f32 v[16:17], v[18:19], v[16:17]
	s_waitcnt vmcnt(1)
	v_lshlrev_b32_e32 v18, 16, v137
	v_cvt_pk_bf16_f32 v27, v16, v17
	v_lshlrev_b32_e32 v16, 16, v136
	v_and_b32_e32 v17, 0xffff0000, v136
	v_and_b32_e32 v19, 0xffff0000, v137
	v_pk_add_f32 v[16:17], v[20:21], v[16:17]
	v_pk_add_f32 v[18:19], v[22:23], v[18:19]
	v_cvt_pk_bf16_f32 v16, v16, v17
	v_cvt_pk_bf16_f32 v17, v18, v19
	v_lshlrev_b32_e32 v18, 16, v138
	v_and_b32_e32 v19, 0xffff0000, v138
	v_pk_add_f32 v[12:13], v[12:13], v[18:19]
	v_lshl_add_u64 v[28:29], s[88:89], 0, v[206:207]
	v_cvt_pk_bf16_f32 v18, v12, v13
	v_lshlrev_b32_e32 v12, 16, v139
	v_and_b32_e32 v13, 0xffff0000, v139
	v_pk_add_f32 v[12:13], v[14:15], v[12:13]
	s_waitcnt vmcnt(0)
	v_lshlrev_b32_e32 v14, 16, v132
	v_and_b32_e32 v15, 0xffff0000, v132
	v_pk_add_f32 v[8:9], v[8:9], v[14:15]
	v_lshlrev_b32_e32 v14, 16, v133
	v_and_b32_e32 v15, 0xffff0000, v133
	v_pk_add_f32 v[10:11], v[10:11], v[14:15]
	v_cvt_pk_bf16_f32 v8, v8, v9
	v_cvt_pk_bf16_f32 v9, v10, v11
	v_lshlrev_b32_e32 v10, 16, v134
	v_and_b32_e32 v11, 0xffff0000, v134
	v_pk_add_f32 v[4:5], v[4:5], v[10:11]
	v_cvt_pk_bf16_f32 v19, v12, v13
	v_cvt_pk_bf16_f32 v10, v4, v5
	v_lshlrev_b32_e32 v4, 16, v135
	v_and_b32_e32 v5, 0xffff0000, v135
	v_lshl_add_u64 v[12:13], s[88:89], 0, v[204:205]
	v_pk_add_f32 v[4:5], v[6:7], v[4:5]
	v_lshl_add_u64 v[92:93], v[92:93], 0, v[202:203]
	v_lshl_add_u64 v[76:77], v[76:77], 0, v[202:203]
	v_lshl_add_u64 v[60:61], v[60:61], 0, v[202:203]
	v_lshl_add_u64 v[44:45], v[44:45], 0, v[202:203]
	v_lshl_add_u64 v[28:29], v[28:29], 0, v[202:203]
	v_lshl_add_u64 v[12:13], v[12:13], 0, v[202:203]
	v_cvt_pk_bf16_f32 v11, v4, v5
	global_store_dwordx4 v[124:125], v[128:131], off sc1
	global_store_dwordx4 v[124:125], v[120:123], off offset:256 sc1
	global_store_dwordx4 v[108:109], v[112:115], off sc1
	global_store_dwordx4 v[108:109], v[104:107], off offset:256 sc1
	global_store_dwordx4 v[92:93], v[96:99], off sc1
	global_store_dwordx4 v[92:93], v[88:91], off offset:256 sc1
	global_store_dwordx4 v[76:77], v[80:83], off sc1
	global_store_dwordx4 v[76:77], v[72:75], off offset:256 sc1
	global_store_dwordx4 v[60:61], v[64:67], off sc1
	global_store_dwordx4 v[60:61], v[56:59], off offset:256 sc1
	global_store_dwordx4 v[44:45], v[48:51], off sc1
	global_store_dwordx4 v[44:45], v[40:43], off offset:256 sc1
	global_store_dwordx4 v[28:29], v[32:35], off sc1
	global_store_dwordx4 v[28:29], v[24:27], off offset:256 sc1
	global_store_dwordx4 v[12:13], v[16:19], off sc1
	global_store_dwordx4 v[12:13], v[8:11], off offset:256 sc1
	s_cbranch_vccz .LBB0_1389
	s_waitcnt vmcnt(0)
	s_cmpk_gt_u32 s2, 0xff
	s_cbranch_scc1 .LBB0_1400
	s_barrier

;     __device__ __forceinline__ void operator()(f32x4 (&acc)[2][2][4][2], const Unit& u, int wr, int wc, int ui, int) const {
;         const int ol_ = opaque_tid() & 63, fr = ol_ & 15, fq = ol_ >> 4;
;         { float r_[2][4];
;           rs_read(r_, ui, wr, fr);
; #pragma unroll
;           for (int ai = 0; ai < 2; ++ai)
; #pragma unroll
;               for (int bj = 0; bj < 2; ++bj)
; #pragma unroll
;                   for (int m = 0; m < 4; ++m) { acc[ai][bj][m][0] *= r_[ai][m]; acc[ai][bj][m][1] *= r_[ai][m]; } }
;         const int col = u.pn * 128 + wc * 32 + 8 * fq;
;         if (fr >= 14) {
; #pragma unroll
;             for (int ai = 0; ai < 2; ++ai) { LAS f32x4* s = (LAS f32x4*)(hl + ((((ai * 2 + wr) * 4 + wc) * 8 + fq * 2 + (fr - 14)) * 32));
;                 s[0] = acc[ai][1][3][0]; s[1] = acc[ai][1][3][1]; }
;         }
;         asm volatile("s_waitcnt lgkmcnt(0)" ::: "memory"); __builtin_amdgcn_s_barrier(); asm volatile("" ::: "memory");
;         __builtin_amdgcn_s_barrier(); asm volatile("" ::: "memory");
;         float w0[8], w1[8], w2[8], bb[8];
;         { const f32x4 a0 = *(const f32x4*)(cw + col), a1 = *(const f32x4*)(cw + col + 4), b0 = *(const f32x4*)(cw + FF + col), b1 = *(const f32x4*)(cw + FF + col + 4),
;                       c0 = *(const f32x4*)(cw + 2 * FF + col), c1 = *(const f32x4*)(cw + 2 * FF + col + 4), d0 = *(const f32x4*)(cb + col), d1 = *(const f32x4*)(cb + col + 4);
; #pragma unroll
;           for (int e = 0; e < 4; ++e) { w0[e] = a0[e] * -LOG2E; w0[4 + e] = a1[e] * -LOG2E; w1[e] = b0[e] * -LOG2E; w1[4 + e] = b1[e] * -LOG2E; w2[e] = c0[e] * -LOG2E; w2[4 + e] = c1[e] * -LOG2E; bb[e] = d0[e] * -LOG2E; bb[4 + e] = d1[e] * -LOG2E; } }
; #pragma unroll
;         for (int ai = 0; ai < 2; ++ai) {
;             f32x4 hal[2] = {(f32x4){0.f, 0.f, 0.f, 0.f}, (f32x4){0.f, 0.f, 0.f, 0.f}};
;             if (!(ai == 0 && wr == 0) && fr >= 14) {
;                 const int sai = (wr == 1) ? ai : 0, swr = (wr == 1) ? 0 : 1;
;                 const LAS f32x4* s = (const LAS f32x4*)(hl + ((((sai * 2 + swr) * 4 + wc) * 8 + fq * 2 + (fr - 14)) * 32));
;                 hal[0] = s[0]; hal[1] = s[1];
;             }
; #pragma unroll
;             for (int m = 0; m < 4; ++m) {
;                 const int row = u.pm * BM + ai * HALF + wr * 64 + m * 16 + fr;
;                 float o[8], z[8], g1[8], g2[8];
; #pragma unroll
.LBB0_1531:
	s_or_b64 exec, exec, s[4:5]
	s_mov_b32 s4, 0xbfb8aa3b
	s_waitcnt vmcnt(0)
	v_pk_mul_f32 v[192:193], v[158:159], s[4:5] op_sel_hi:[1,0]
	v_pk_mul_f32 v[158:159], v[146:147], s[4:5] op_sel_hi:[1,0]
	v_pk_mul_f32 v[194:195], v[150:151], s[4:5] op_sel_hi:[1,0]
	v_pk_mul_f32 v[150:151], v[142:143], s[4:5] op_sel_hi:[1,0]
	v_pk_mul_f32 v[142:143], v[164:165], s[4:5] op_sel_hi:[1,0]
	v_pk_mul_f32 v[164:165], v[168:169], s[4:5] op_sel_hi:[1,0]
	v_pk_mul_f32 v[146:147], v[156:157], s[4:5] op_sel_hi:[1,0]
	v_pk_mul_f32 v[156:157], v[160:161], s[4:5] op_sel_hi:[1,0]
	v_pk_mul_f32 v[160:161], v[122:123], v[206:207] op_sel_hi:[1,0]
	v_pk_mul_f32 v[168:169], v[120:121], v[206:207] op_sel_hi:[1,0]
	v_pk_mul_f32 v[120:121], v[116:117], v[206:207] op_sel_hi:[1,0]
	v_mov_b32_e32 v116, v208
	v_mov_b32_e32 v117, v208
	v_pk_mul_f32 v[76:77], v[76:77], v[204:205] op_sel_hi:[1,0]
	v_pk_mul_f32 v[122:123], v[96:97], v[206:207] op_sel_hi:[1,0]
	v_pk_mul_f32 v[96:97], v[94:95], v[206:207] op_sel_hi:[1,0]
	s_waitcnt lgkmcnt(1)
	v_mov_b32_dpp v94, v138 row_ror:2 row_mask:0xf bank_mask:0xf bound_ctrl:1
	v_mov_b32_dpp v95, v139 row_ror:2 row_mask:0xf bank_mask:0xf bound_ctrl:1
	v_pk_mul_f32 v[170:171], v[170:171], s[4:5] op_sel_hi:[1,0]
	v_pk_mul_f32 v[106:107], v[106:107], v[116:117]
	v_pk_mul_f32 v[102:103], v[102:103], v[116:117]
	v_pk_mul_f32 v[116:117], v[98:99], v[206:207] op_sel_hi:[1,0]
	v_pk_mul_f32 v[98:99], v[92:93], v[206:207] op_sel_hi:[1,0]
	v_pk_mul_f32 v[92:93], v[88:89], v[202:203] op_sel_hi:[1,0]
	v_mov_b32_dpp v88, v138 row_ror:1 row_mask:0xf bank_mask:0xf bound_ctrl:1
	v_mov_b32_dpp v94, v76 row_shr:2 row_mask:0xf bank_mask:0xf
	v_mov_b32_dpp v89, v139 row_ror:1 row_mask:0xf bank_mask:0xf bound_ctrl:1
	v_mov_b32_dpp v95, v77 row_shr:2 row_mask:0xf bank_mask:0xf
	v_pk_mul_f32 v[190:191], v[166:167], s[4:5] op_sel_hi:[1,0]
	v_mov_b32_dpp v88, v76 row_shr:1 row_mask:0xf bank_mask:0xf
	v_mov_b32_dpp v89, v77 row_shr:1 row_mask:0xf bank_mask:0xf
	v_pk_fma_f32 v[94:95], v[170:171], v[94:95], v[194:195]
	v_pk_mul_f32 v[78:79], v[78:79], v[204:205] op_sel_hi:[1,0]
	v_pk_fma_f32 v[88:89], v[190:191], v[88:89], v[94:95]
	v_mov_b32_dpp v138, v140 row_ror:1 row_mask:0xf bank_mask:0xf bound_ctrl:1
	v_pk_fma_f32 v[88:89], v[76:77], v[192:193], v[88:89]
	v_mov_b32_dpp v140, v140 row_ror:2 row_mask:0xf bank_mask:0xf bound_ctrl:1
	v_mov_b32_dpp v139, v141 row_ror:1 row_mask:0xf bank_mask:0xf bound_ctrl:1
	v_mov_b32_dpp v141, v141 row_ror:2 row_mask:0xf bank_mask:0xf bound_ctrl:1
	v_exp_f32_e32 v94, v88
	v_exp_f32_e32 v95, v89
	v_pk_mul_f32 v[166:167], v[172:173], s[4:5] op_sel_hi:[1,0]
	v_pk_mul_f32 v[152:153], v[152:153], s[4:5] op_sel_hi:[1,0]
	v_mov_b32_dpp v140, v78 row_shr:2 row_mask:0xf bank_mask:0xf
	v_mov_b32_dpp v141, v79 row_shr:2 row_mask:0xf bank_mask:0xf
	v_mov_b32_dpp v138, v78 row_shr:1 row_mask:0xf bank_mask:0xf
	v_mov_b32_dpp v139, v79 row_shr:1 row_mask:0xf bank_mask:0xf
	v_pk_fma_f32 v[140:141], v[166:167], v[140:141], v[152:153]
	v_add_f32_e32 v94, 1.0, v94
	v_pk_fma_f32 v[138:139], v[164:165], v[138:139], v[140:141]
	v_add_f32_e32 v95, 1.0, v95
	v_pk_fma_f32 v[138:139], v[78:79], v[156:157], v[138:139]
	v_pk_mul_f32 v[114:115], v[114:115], v[202:203] op_sel_hi:[1,0]
	v_pk_mul_f32 v[112:113], v[112:113], v[202:203] op_sel_hi:[1,0]
	v_pk_mul_f32 v[110:111], v[110:111], v[202:203] op_sel_hi:[1,0]
	v_pk_mul_f32 v[108:109], v[108:109], v[202:203] op_sel_hi:[1,0]
	v_pk_mul_f32 v[80:81], v[80:81], v[204:205] op_sel_hi:[1,0]
	v_pk_mul_f32 v[90:91], v[90:91], v[202:203] op_sel_hi:[1,0]
	v_pk_mul_f32 v[86:87], v[86:87], v[202:203] op_sel_hi:[1,0]
	v_pk_mul_f32 v[84:85], v[84:85], v[202:203] op_sel_hi:[1,0]
	s_waitcnt lgkmcnt(0)
	v_mov_b32_dpp v202, v134 row_ror:1 row_mask:0xf bank_mask:0xf bound_ctrl:1
	v_mov_b32_dpp v134, v134 row_ror:2 row_mask:0xf bank_mask:0xf bound_ctrl:1
	v_mov_b32_dpp v203, v135 row_ror:1 row_mask:0xf bank_mask:0xf bound_ctrl:1
	v_mov_b32_dpp v135, v135 row_ror:2 row_mask:0xf bank_mask:0xf bound_ctrl:1
	v_rcp_f32_e32 v94, v94
	v_rcp_f32_e32 v95, v95
	v_exp_f32_e32 v125, v138
	v_exp_f32_e32 v140, v139
	v_pk_mul_f32 v[162:163], v[162:163], s[4:5] op_sel_hi:[1,0]
	v_mov_b32_dpp v134, v80 row_shr:2 row_mask:0xf bank_mask:0xf
	v_mov_b32_dpp v135, v81 row_shr:2 row_mask:0xf bank_mask:0xf
	v_pk_mul_f32 v[154:155], v[154:155], s[4:5] op_sel_hi:[1,0]
	v_pk_mul_f32 v[68:69], v[68:69], v[204:205] op_sel_hi:[1,0]
	v_mov_b32_dpp v202, v80 row_shr:1 row_mask:0xf bank_mask:0xf
	v_mov_b32_dpp v203, v81 row_shr:1 row_mask:0xf bank_mask:0xf
	v_pk_fma_f32 v[134:135], v[162:163], v[134:135], v[150:151]
	v_pk_mul_f32 v[88:89], v[68:69], v[88:89]
	v_pk_fma_f32 v[134:135], v[154:155], v[202:203], v[134:135]
	v_pk_mul_f32 v[70:71], v[70:71], v[204:205] op_sel_hi:[1,0]
	v_pk_mul_f32 v[74:75], v[74:75], v[204:205] op_sel_hi:[1,0]
	v_pk_mul_f32 v[72:73], v[72:73], v[204:205] op_sel_hi:[1,0]
	v_pk_mul_f32 v[82:83], v[82:83], v[204:205] op_sel_hi:[1,0]
	v_mov_b32_dpp v204, v136 row_ror:1 row_mask:0xf bank_mask:0xf bound_ctrl:1
	v_mov_b32_dpp v136, v136 row_ror:2 row_mask:0xf bank_mask:0xf bound_ctrl:1
	v_mov_b32_dpp v205, v137 row_ror:1 row_mask:0xf bank_mask:0xf bound_ctrl:1
	v_mov_b32_dpp v137, v137 row_ror:2 row_mask:0xf bank_mask:0xf bound_ctrl:1
	v_pk_mul_f32 v[88:89], v[88:89], v[94:95]
	v_add_f32_e32 v94, 1.0, v125
	v_add_f32_e32 v95, 1.0, v140
	v_pk_fma_f32 v[134:135], v[80:81], v[158:159], v[134:135]
	v_pk_mul_f32 v[144:145], v[144:145], s[4:5] op_sel_hi:[1,0]
	v_mov_b32_dpp v136, v82 row_shr:2 row_mask:0xf bank_mask:0xf
	v_mov_b32_dpp v137, v83 row_shr:2 row_mask:0xf bank_mask:0xf
	v_rcp_f32_e32 v94, v94
	v_rcp_f32_e32 v95, v95
; __device__ __forceinline__ unsigned cvt_pk_bf16(float lo, float hi) { const f32x2 v = {lo, hi}; const bf16v2_ r = __builtin_convertvector(v, bf16v2_); return __builtin_bit_cast(unsigned, r); }
;     __device__ __forceinline__ void operator()(f32x4 (&acc)[2][2][4][2], const Unit& u, int wr, int wc, int ui, int) const {
;     ...
;             for (int m = 0; m < 4; ++m) {
;                 const int row = u.pm * BM + ai * HALF + wr * 64 + m * 16 + fr;
;                 float o[8], z[8], g1[8], g2[8];
; #pragma unroll
;                 for (int k = 0; k < 8; ++k) { const int n = k >> 2, e = k & 3;
;                     const float gc = acc[ai][1][m][n][e], gp = (m == 0) ? hal[n][e] : acc[ai][1][m - 1][n][e];
;                     const int gci = __builtin_bit_cast(int, gc), gpi = __builtin_bit_cast(int, gp);
;                     const int r1 = __builtin_amdgcn_update_dpp(0, gpi, 0x121, 0xf, 0xf, true), r2 = __builtin_amdgcn_update_dpp(0, gpi, 0x122, 0xf, 0xf, true);
;                     g1[k] = __builtin_bit_cast(float, __builtin_amdgcn_update_dpp(r1, gci, 0x111, 0xf, 0xf, false));
;                     g2[k] = __builtin_bit_cast(float, __builtin_amdgcn_update_dpp(r2, gci, 0x112, 0xf, 0xf, false)); }
; #pragma unroll
;                 for (int k = 0; k < 8; ++k) z[k] = w0[k] * g2[k] + bb[k];
; #pragma unroll
;                 for (int k = 0; k < 8; ++k) z[k] += w1[k] * g1[k];
; #pragma unroll
;                 for (int k = 0; k < 8; ++k) z[k] += w2[k] * acc[ai][1][m][k >> 2][k & 3];
; #pragma unroll
;                 for (int k = 0; k < 8; ++k) o[k] = __builtin_amdgcn_exp2f(z[k]);
; #pragma unroll
;                 for (int k = 0; k < 8; ++k) o[k] += 1.f;
; #pragma unroll
;                 for (int k = 0; k < 8; ++k) o[k] = __builtin_amdgcn_rcpf(o[k]);
; #pragma unroll
;                 for (int k = 0; k < 8; ++k) z[k] *= acc[ai][0][m][k >> 2][k & 3];
; #pragma unroll
;                 for (int k = 0; k < 8; ++k) o[k] *= z[k];
;                 u32x4 w; w.x = cvt_pk_bf16(o[0], o[1]); w.y = cvt_pk_bf16(o[2], o[3]); w.z = cvt_pk_bf16(o[4], o[5]); w.w = cvt_pk_bf16(o[6], o[7]);
;                 *(u32x4*)(act + (size_t)row * FF + col) = w;
	v_exp_f32_e32 v140, v135
	v_mov_b32_dpp v204, v82 row_shr:1 row_mask:0xf bank_mask:0xf
	v_mov_b32_dpp v205, v83 row_shr:1 row_mask:0xf bank_mask:0xf
	v_pk_fma_f32 v[136:137], v[142:143], v[136:137], v[144:145]
	v_pk_mul_f32 v[148:149], v[148:149], s[4:5] op_sel_hi:[1,0]
	v_pk_fma_f32 v[136:137], v[146:147], v[204:205], v[136:137]
	v_exp_f32_e32 v125, v134
	v_pk_mul_f32 v[138:139], v[70:71], v[138:139]
	v_pk_fma_f32 v[136:137], v[82:83], v[148:149], v[136:137]
	v_pk_mul_f32 v[94:95], v[138:139], v[94:95]
	v_add_f32_e32 v139, 1.0, v140
	v_exp_f32_e32 v140, v136
	v_exp_f32_e32 v141, v137
	v_add_f32_e32 v125, 1.0, v125
	v_rcp_f32_e32 v138, v125
	v_rcp_f32_e32 v139, v139
	v_add_f32_e32 v125, 1.0, v140
	v_add_f32_e32 v141, 1.0, v141
	v_rcp_f32_e32 v140, v125
	v_rcp_f32_e32 v141, v141
	s_lshl_b32 s4, s52, 8
	v_pk_mul_f32 v[134:135], v[72:73], v[134:135]
	s_add_i32 s4, s4, s28
	v_pk_mul_f32 v[138:139], v[134:135], v[138:139]
	v_pk_mul_f32 v[134:135], v[74:75], v[136:137]
	v_or_b32_e32 v172, s4, v210
	v_pk_mul_f32 v[140:141], v[134:135], v[140:141]
	v_cvt_pk_bf16_f32 v135, v94, v95
	v_mov_b64_e32 v[94:95], s[92:93]
	s_movk_i32 s6, 0x2c00
	v_cvt_pk_bf16_f32 v134, v88, v89
	v_cvt_pk_bf16_f32 v136, v138, v139
	v_mad_i64_i32 v[138:139], s[4:5], v172, s6, v[94:95]
	v_lshlrev_b64 v[88:89], 1, v[188:189]
	v_cvt_pk_bf16_f32 v137, v140, v141
	v_lshl_add_u64 v[138:139], v[138:139], 0, v[88:89]
	global_store_dwordx4 v[138:139], v[134:137], off sc1
	v_mov_b32_dpp v140, v78 row_ror:2 row_mask:0xf bank_mask:0xf bound_ctrl:1
	v_mov_b32_dpp v141, v79 row_ror:2 row_mask:0xf bank_mask:0xf bound_ctrl:1
	v_mov_b32_dpp v136, v76 row_ror:2 row_mask:0xf bank_mask:0xf bound_ctrl:1
	v_mov_b32_dpp v137, v77 row_ror:2 row_mask:0xf bank_mask:0xf bound_ctrl:1
	v_mov_b32_dpp v134, v76 row_ror:1 row_mask:0xf bank_mask:0xf bound_ctrl:1
	v_mov_b32_dpp v136, v122 row_shr:2 row_mask:0xf bank_mask:0xf
	v_mov_b32_dpp v135, v77 row_ror:1 row_mask:0xf bank_mask:0xf bound_ctrl:1
	v_mov_b32_dpp v137, v123 row_shr:2 row_mask:0xf bank_mask:0xf
	v_mov_b32_dpp v134, v122 row_shr:1 row_mask:0xf bank_mask:0xf
	v_mov_b32_dpp v135, v123 row_shr:1 row_mask:0xf bank_mask:0xf
	v_pk_fma_f32 v[136:137], v[170:171], v[136:137], v[194:195]
	v_mov_b32_dpp v138, v78 row_ror:1 row_mask:0xf bank_mask:0xf bound_ctrl:1
	v_pk_fma_f32 v[134:135], v[190:191], v[134:135], v[136:137]
	v_mov_b32_dpp v140, v116 row_shr:2 row_mask:0xf bank_mask:0xf
	v_pk_fma_f32 v[134:135], v[122:123], v[192:193], v[134:135]
	v_mov_b32_dpp v139, v79 row_ror:1 row_mask:0xf bank_mask:0xf bound_ctrl:1
	v_exp_f32_e32 v125, v134
	v_exp_f32_e32 v136, v135
	v_mov_b32_dpp v141, v117 row_shr:2 row_mask:0xf bank_mask:0xf
	v_mov_b32_dpp v138, v116 row_shr:1 row_mask:0xf bank_mask:0xf
	v_mov_b32_dpp v139, v117 row_shr:1 row_mask:0xf bank_mask:0xf
	v_pk_fma_f32 v[140:141], v[166:167], v[140:141], v[152:153]
	v_add_f32_e32 v125, 1.0, v125
	v_pk_fma_f32 v[138:139], v[164:165], v[138:139], v[140:141]
	v_add_f32_e32 v137, 1.0, v136
	v_pk_fma_f32 v[138:139], v[116:117], v[156:157], v[138:139]
	v_rcp_f32_e32 v136, v125
	v_rcp_f32_e32 v137, v137
	v_exp_f32_e32 v125, v138
	v_exp_f32_e32 v140, v139
	v_mov_b32_dpp v204, v80 row_ror:2 row_mask:0xf bank_mask:0xf bound_ctrl:1
	v_mov_b32_dpp v205, v81 row_ror:2 row_mask:0xf bank_mask:0xf bound_ctrl:1
	v_pk_mul_f32 v[134:135], v[168:169], v[134:135]
	v_mov_b32_dpp v202, v80 row_ror:1 row_mask:0xf bank_mask:0xf bound_ctrl:1
	v_mov_b32_dpp v204, v98 row_shr:2 row_mask:0xf bank_mask:0xf
	v_mov_b32_dpp v203, v81 row_ror:1 row_mask:0xf bank_mask:0xf bound_ctrl:1
	v_mov_b32_dpp v205, v99 row_shr:2 row_mask:0xf bank_mask:0xf
	v_pk_mul_f32 v[134:135], v[134:135], v[136:137]
	v_add_f32_e32 v125, 1.0, v125
	v_add_f32_e32 v137, 1.0, v140
	v_mov_b32_dpp v202, v98 row_shr:1 row_mask:0xf bank_mask:0xf
	v_mov_b32_dpp v203, v99 row_shr:1 row_mask:0xf bank_mask:0xf
	v_rcp_f32_e32 v136, v125
	v_rcp_f32_e32 v137, v137
	v_pk_fma_f32 v[140:141], v[162:163], v[204:205], v[150:151]
	v_mov_b32_e32 v209, v208
	v_pk_fma_f32 v[140:141], v[154:155], v[202:203], v[140:141]
	v_mov_b32_dpp v212, v82 row_ror:2 row_mask:0xf bank_mask:0xf bound_ctrl:1
	v_mov_b32_dpp v213, v83 row_ror:2 row_mask:0xf bank_mask:0xf bound_ctrl:1
	v_pk_fma_f32 v[140:141], v[98:99], v[158:159], v[140:141]
	v_pk_mul_f32 v[104:105], v[104:105], v[208:209]
	v_pk_mul_f32 v[100:101], v[100:101], v[208:209]
	v_mov_b32_dpp v208, v82 row_ror:1 row_mask:0xf bank_mask:0xf bound_ctrl:1
	v_mov_b32_dpp v212, v96 row_shr:2 row_mask:0xf bank_mask:0xf
	v_mov_b32_dpp v209, v83 row_ror:1 row_mask:0xf bank_mask:0xf bound_ctrl:1
	v_mov_b32_dpp v213, v97 row_shr:2 row_mask:0xf bank_mask:0xf
	v_exp_f32_e32 v168, v141
	v_pk_mul_f32 v[138:139], v[160:161], v[138:139]
	v_mov_b32_dpp v208, v96 row_shr:1 row_mask:0xf bank_mask:0xf
	v_mov_b32_dpp v209, v97 row_shr:1 row_mask:0xf bank_mask:0xf
	v_pk_mul_f32 v[136:137], v[138:139], v[136:137]
	v_pk_fma_f32 v[138:139], v[142:143], v[212:213], v[144:145]
	v_exp_f32_e32 v125, v140
	v_pk_fma_f32 v[138:139], v[146:147], v[208:209], v[138:139]
	v_add_f32_e32 v161, 1.0, v168
	v_pk_fma_f32 v[138:139], v[96:97], v[148:149], v[138:139]
	v_add_f32_e32 v125, 1.0, v125
	v_exp_f32_e32 v168, v138
	v_exp_f32_e32 v169, v139
	v_rcp_f32_e32 v160, v125
	v_rcp_f32_e32 v161, v161
	v_add_f32_e32 v125, 1.0, v168
	v_add_f32_e32 v169, 1.0, v169
	v_rcp_f32_e32 v168, v125
	v_rcp_f32_e32 v169, v169
	v_pk_mul_f32 v[118:119], v[118:119], v[206:207] op_sel_hi:[1,0]
	v_pk_mul_f32 v[120:121], v[120:121], v[140:141]
	v_pk_mul_f32 v[118:119], v[118:119], v[138:139]
	v_or_b32_e32 v125, 16, v172
	v_pk_mul_f32 v[120:121], v[120:121], v[160:161]
	v_pk_mul_f32 v[138:139], v[118:119], v[168:169]
; __device__ __forceinline__ unsigned cvt_pk_bf16(float lo, float hi) { const f32x2 v = {lo, hi}; const bf16v2_ r = __builtin_convertvector(v, bf16v2_); return __builtin_bit_cast(unsigned, r); }
;     __device__ __forceinline__ void operator()(f32x4 (&acc)[2][2][4][2], const Unit& u, int wr, int wc, int ui, int) const {
;     ...
;             for (int m = 0; m < 4; ++m) {
;                 const int row = u.pm * BM + ai * HALF + wr * 64 + m * 16 + fr;
;                 float o[8], z[8], g1[8], g2[8];
; #pragma unroll
;                 for (int k = 0; k < 8; ++k) { const int n = k >> 2, e = k & 3;
;                     const float gc = acc[ai][1][m][n][e], gp = (m == 0) ? hal[n][e] : acc[ai][1][m - 1][n][e];
;                     const int gci = __builtin_bit_cast(int, gc), gpi = __builtin_bit_cast(int, gp);
;                     const int r1 = __builtin_amdgcn_update_dpp(0, gpi, 0x121, 0xf, 0xf, true), r2 = __builtin_amdgcn_update_dpp(0, gpi, 0x122, 0xf, 0xf, true);
;                     g1[k] = __builtin_bit_cast(float, __builtin_amdgcn_update_dpp(r1, gci, 0x111, 0xf, 0xf, false));
;                     g2[k] = __builtin_bit_cast(float, __builtin_amdgcn_update_dpp(r2, gci, 0x112, 0xf, 0xf, false)); }
; #pragma unroll
;                 for (int k = 0; k < 8; ++k) z[k] = w0[k] * g2[k] + bb[k];
; #pragma unroll
;                 for (int k = 0; k < 8; ++k) z[k] += w1[k] * g1[k];
; #pragma unroll
;                 for (int k = 0; k < 8; ++k) z[k] += w2[k] * acc[ai][1][m][k >> 2][k & 3];
; #pragma unroll
;                 for (int k = 0; k < 8; ++k) o[k] = __builtin_amdgcn_exp2f(z[k]);
; #pragma unroll
;                 for (int k = 0; k < 8; ++k) o[k] += 1.f;
; #pragma unroll
;                 for (int k = 0; k < 8; ++k) o[k] = __builtin_amdgcn_rcpf(o[k]);
; #pragma unroll
;                 for (int k = 0; k < 8; ++k) z[k] *= acc[ai][0][m][k >> 2][k & 3];
; #pragma unroll
;                 for (int k = 0; k < 8; ++k) o[k] *= z[k];
;                 u32x4 w; w.x = cvt_pk_bf16(o[0], o[1]); w.y = cvt_pk_bf16(o[2], o[3]); w.z = cvt_pk_bf16(o[4], o[5]); w.w = cvt_pk_bf16(o[6], o[7]);
;                 *(u32x4*)(act + (size_t)row * FF + col) = w;
	v_cvt_pk_bf16_f32 v118, v134, v135
	v_mad_i64_i32 v[134:135], s[4:5], v125, s6, v[94:95]
	v_cvt_pk_bf16_f32 v119, v136, v137
	v_cvt_pk_bf16_f32 v120, v120, v121
	v_cvt_pk_bf16_f32 v121, v138, v139
	v_lshl_add_u64 v[134:135], v[134:135], 0, v[88:89]
	global_store_dwordx4 v[134:135], v[118:121], off sc1
	v_mov_b32_dpp v136, v96 row_ror:1 row_mask:0xf bank_mask:0xf bound_ctrl:1
	v_mov_b32_dpp v134, v98 row_ror:1 row_mask:0xf bank_mask:0xf bound_ctrl:1
	v_mov_b32_dpp v118, v122 row_ror:1 row_mask:0xf bank_mask:0xf bound_ctrl:1
	v_mov_b32_dpp v120, v122 row_ror:2 row_mask:0xf bank_mask:0xf bound_ctrl:1
	v_mov_b32_dpp v119, v123 row_ror:1 row_mask:0xf bank_mask:0xf bound_ctrl:1
	v_mov_b32_dpp v121, v123 row_ror:2 row_mask:0xf bank_mask:0xf bound_ctrl:1
	v_mov_b32_dpp v122, v116 row_ror:1 row_mask:0xf bank_mask:0xf bound_ctrl:1
	v_mov_b32_dpp v116, v116 row_ror:2 row_mask:0xf bank_mask:0xf bound_ctrl:1
	v_mov_b32_dpp v123, v117 row_ror:1 row_mask:0xf bank_mask:0xf bound_ctrl:1
	v_mov_b32_dpp v117, v117 row_ror:2 row_mask:0xf bank_mask:0xf bound_ctrl:1
	v_mov_b32_dpp v120, v92 row_shr:2 row_mask:0xf bank_mask:0xf
	v_mov_b32_dpp v121, v93 row_shr:2 row_mask:0xf bank_mask:0xf
	v_mov_b32_dpp v116, v90 row_shr:2 row_mask:0xf bank_mask:0xf
	v_mov_b32_dpp v117, v91 row_shr:2 row_mask:0xf bank_mask:0xf
	v_mov_b32_dpp v118, v92 row_shr:1 row_mask:0xf bank_mask:0xf
	v_mov_b32_dpp v119, v93 row_shr:1 row_mask:0xf bank_mask:0xf
	v_mov_b32_dpp v122, v90 row_shr:1 row_mask:0xf bank_mask:0xf
	v_mov_b32_dpp v123, v91 row_shr:1 row_mask:0xf bank_mask:0xf
	v_pk_fma_f32 v[120:121], v[170:171], v[120:121], v[194:195]
	v_pk_fma_f32 v[116:117], v[166:167], v[116:117], v[152:153]
	v_pk_fma_f32 v[118:119], v[190:191], v[118:119], v[120:121]
	v_pk_fma_f32 v[116:117], v[164:165], v[122:123], v[116:117]
	v_pk_fma_f32 v[118:119], v[92:93], v[192:193], v[118:119]
	v_pk_fma_f32 v[116:117], v[90:91], v[156:157], v[116:117]
	v_exp_f32_e32 v120, v118
	v_exp_f32_e32 v121, v119
	v_exp_f32_e32 v122, v116
	v_exp_f32_e32 v123, v117
	v_mov_b32_dpp v98, v98 row_ror:2 row_mask:0xf bank_mask:0xf bound_ctrl:1
	v_mov_b32_dpp v135, v99 row_ror:1 row_mask:0xf bank_mask:0xf bound_ctrl:1
	v_mov_b32_dpp v99, v99 row_ror:2 row_mask:0xf bank_mask:0xf bound_ctrl:1
	v_mov_b32_dpp v96, v96 row_ror:2 row_mask:0xf bank_mask:0xf bound_ctrl:1
	v_mov_b32_dpp v137, v97 row_ror:1 row_mask:0xf bank_mask:0xf bound_ctrl:1
	v_mov_b32_dpp v97, v97 row_ror:2 row_mask:0xf bank_mask:0xf bound_ctrl:1
	v_add_f32_e32 v120, 1.0, v120
	v_add_f32_e32 v121, 1.0, v121
	v_pk_mul_f32 v[112:113], v[112:113], v[118:119]
	v_add_f32_e32 v118, 1.0, v122
	v_add_f32_e32 v119, 1.0, v123
	v_mov_b32_dpp v98, v84 row_shr:2 row_mask:0xf bank_mask:0xf
	v_mov_b32_dpp v99, v85 row_shr:2 row_mask:0xf bank_mask:0xf
	v_mov_b32_dpp v96, v86 row_shr:2 row_mask:0xf bank_mask:0xf
	v_mov_b32_dpp v97, v87 row_shr:2 row_mask:0xf bank_mask:0xf
	v_rcp_f32_e32 v120, v120
	v_rcp_f32_e32 v121, v121
	v_rcp_f32_e32 v118, v118
	v_rcp_f32_e32 v119, v119
	v_mov_b32_dpp v134, v84 row_shr:1 row_mask:0xf bank_mask:0xf
	v_mov_b32_dpp v135, v85 row_shr:1 row_mask:0xf bank_mask:0xf
	v_mov_b32_dpp v136, v86 row_shr:1 row_mask:0xf bank_mask:0xf
	v_mov_b32_dpp v137, v87 row_shr:1 row_mask:0xf bank_mask:0xf
	v_pk_fma_f32 v[98:99], v[162:163], v[98:99], v[150:151]
	v_pk_fma_f32 v[96:97], v[142:143], v[96:97], v[144:145]
	v_pk_fma_f32 v[98:99], v[154:155], v[134:135], v[98:99]
	v_pk_fma_f32 v[96:97], v[146:147], v[136:137], v[96:97]
	v_pk_fma_f32 v[98:99], v[84:85], v[158:159], v[98:99]
	v_pk_mul_f32 v[114:115], v[114:115], v[116:117]
	v_pk_fma_f32 v[96:97], v[86:87], v[148:149], v[96:97]
	v_pk_mul_f32 v[112:113], v[112:113], v[120:121]
	v_exp_f32_e32 v120, v98
	v_exp_f32_e32 v121, v99
	v_pk_mul_f32 v[114:115], v[114:115], v[118:119]
	v_exp_f32_e32 v118, v96
	v_exp_f32_e32 v119, v97
	v_add_f32_e32 v116, 1.0, v120
	v_add_f32_e32 v117, 1.0, v121
	v_add_f32_e32 v118, 1.0, v118
	v_add_f32_e32 v119, 1.0, v119
	v_rcp_f32_e32 v116, v116
	v_rcp_f32_e32 v117, v117
	v_rcp_f32_e32 v118, v118
	v_rcp_f32_e32 v119, v119
	v_pk_mul_f32 v[98:99], v[108:109], v[98:99]
	v_pk_mul_f32 v[96:97], v[110:111], v[96:97]
	v_pk_mul_f32 v[98:99], v[98:99], v[116:117]
	v_pk_mul_f32 v[108:109], v[96:97], v[118:119]
	v_or_b32_e32 v110, 32, v172
	v_cvt_pk_bf16_f32 v98, v98, v99
	v_cvt_pk_bf16_f32 v99, v108, v109
	v_mad_i64_i32 v[108:109], s[4:5], v110, s6, v[94:95]
	v_cvt_pk_bf16_f32 v96, v112, v113
	v_cvt_pk_bf16_f32 v97, v114, v115
	v_lshl_add_u64 v[108:109], v[108:109], 0, v[88:89]
	global_store_dwordx4 v[108:109], v[96:99], off sc1
	v_mov_b32_dpp v110, v86 row_ror:1 row_mask:0xf bank_mask:0xf bound_ctrl:1
	v_mov_b32_dpp v108, v84 row_ror:1 row_mask:0xf bank_mask:0xf bound_ctrl:1
	v_mov_b32_dpp v96, v92 row_ror:1 row_mask:0xf bank_mask:0xf bound_ctrl:1
	v_mov_b32_dpp v92, v92 row_ror:2 row_mask:0xf bank_mask:0xf bound_ctrl:1
	v_mov_b32_dpp v97, v93 row_ror:1 row_mask:0xf bank_mask:0xf bound_ctrl:1
	v_mov_b32_dpp v93, v93 row_ror:2 row_mask:0xf bank_mask:0xf bound_ctrl:1
	v_mov_b32_dpp v92, v130 row_shr:2 row_mask:0xf bank_mask:0xf
	v_mov_b32_dpp v96, v130 row_shr:1 row_mask:0xf bank_mask:0xf
	v_mov_b32_dpp v93, v131 row_shr:2 row_mask:0xf bank_mask:0xf
	v_mov_b32_dpp v97, v131 row_shr:1 row_mask:0xf bank_mask:0xf
	v_pk_fma_f32 v[92:93], v[170:171], v[92:93], v[194:195]
	v_mov_b32_dpp v98, v90 row_ror:1 row_mask:0xf bank_mask:0xf bound_ctrl:1
	v_pk_fma_f32 v[92:93], v[190:191], v[96:97], v[92:93]
	v_mov_b32_dpp v90, v90 row_ror:2 row_mask:0xf bank_mask:0xf bound_ctrl:1
	v_pk_fma_f32 v[92:93], v[130:131], v[192:193], v[92:93]
	v_mov_b32_dpp v99, v91 row_ror:1 row_mask:0xf bank_mask:0xf bound_ctrl:1
;     __device__ __forceinline__ void operator()(f32x4 (&acc)[2][2][4][2], const Unit& u, int wr, int wc, int ui, int) const {
;     ...
;           for (int ai = 0; ai < 2; ++ai)
; #pragma unroll
;               for (int bj = 0; bj < 2; ++bj)
; #pragma unroll
;                   for (int m = 0; m < 4; ++m) { acc[ai][bj][m][0] *= r_[ai][m]; acc[ai][bj][m][1] *= r_[ai][m]; } }
;     ...
;             for (int m = 0; m < 4; ++m) {
;                 const int row = u.pm * BM + ai * HALF + wr * 64 + m * 16 + fr;
;                 float o[8], z[8], g1[8], g2[8];
; #pragma unroll
;                 for (int k = 0; k < 8; ++k) { const int n = k >> 2, e = k & 3;
;                     const float gc = acc[ai][1][m][n][e], gp = (m == 0) ? hal[n][e] : acc[ai][1][m - 1][n][e];
;                     const int gci = __builtin_bit_cast(int, gc), gpi = __builtin_bit_cast(int, gp);
;                     const int r1 = __builtin_amdgcn_update_dpp(0, gpi, 0x121, 0xf, 0xf, true), r2 = __builtin_amdgcn_update_dpp(0, gpi, 0x122, 0xf, 0xf, true);
;                     g1[k] = __builtin_bit_cast(float, __builtin_amdgcn_update_dpp(r1, gci, 0x111, 0xf, 0xf, false));
;                     g2[k] = __builtin_bit_cast(float, __builtin_amdgcn_update_dpp(r2, gci, 0x112, 0xf, 0xf, false)); }
; #pragma unroll
;                 for (int k = 0; k < 8; ++k) z[k] = w0[k] * g2[k] + bb[k];
; #pragma unroll
;                 for (int k = 0; k < 8; ++k) z[k] += w1[k] * g1[k];
; #pragma unroll
;                 for (int k = 0; k < 8; ++k) z[k] += w2[k] * acc[ai][1][m][k >> 2][k & 3];
; #pragma unroll
;                 for (int k = 0; k < 8; ++k) o[k] = __builtin_amdgcn_exp2f(z[k]);
; #pragma unroll
;                 for (int k = 0; k < 8; ++k) o[k] += 1.f;
; #pragma unroll
;                 for (int k = 0; k < 8; ++k) o[k] = __builtin_amdgcn_rcpf(o[k]);
; #pragma unroll
;                 for (int k = 0; k < 8; ++k) z[k] *= acc[ai][0][m][k >> 2][k & 3];
; #pragma unroll
;                 for (int k = 0; k < 8; ++k) o[k] *= z[k];
;                 u32x4 w; w.x = cvt_pk_bf16(o[0], o[1]); w.y = cvt_pk_bf16(o[2], o[3]); w.z = cvt_pk_bf16(o[4], o[5]); w.w = cvt_pk_bf16(o[6], o[7]);
;                 *(u32x4*)(act + (size_t)row * FF + col) = w;
	v_mov_b32_dpp v91, v91 row_ror:2 row_mask:0xf bank_mask:0xf bound_ctrl:1
	v_exp_f32_e32 v96, v92
	v_exp_f32_e32 v97, v93
	v_mov_b32_dpp v90, v132 row_shr:2 row_mask:0xf bank_mask:0xf
	v_mov_b32_dpp v91, v133 row_shr:2 row_mask:0xf bank_mask:0xf
	v_mov_b32_dpp v98, v132 row_shr:1 row_mask:0xf bank_mask:0xf
	v_mov_b32_dpp v99, v133 row_shr:1 row_mask:0xf bank_mask:0xf
	v_pk_fma_f32 v[90:91], v[166:167], v[90:91], v[152:153]
	v_add_f32_e32 v96, 1.0, v96
	v_pk_fma_f32 v[90:91], v[164:165], v[98:99], v[90:91]
	v_add_f32_e32 v97, 1.0, v97
	v_pk_fma_f32 v[90:91], v[132:133], v[156:157], v[90:91]
	v_mov_b32_dpp v84, v84 row_ror:2 row_mask:0xf bank_mask:0xf bound_ctrl:1
	v_mov_b32_dpp v109, v85 row_ror:1 row_mask:0xf bank_mask:0xf bound_ctrl:1
	v_mov_b32_dpp v85, v85 row_ror:2 row_mask:0xf bank_mask:0xf bound_ctrl:1
	v_rcp_f32_e32 v96, v96
	v_rcp_f32_e32 v97, v97
	v_exp_f32_e32 v98, v90
	v_exp_f32_e32 v99, v91
	v_mov_b32_dpp v84, v126 row_shr:2 row_mask:0xf bank_mask:0xf
	v_mov_b32_dpp v85, v127 row_shr:2 row_mask:0xf bank_mask:0xf
	v_mov_b32_dpp v108, v126 row_shr:1 row_mask:0xf bank_mask:0xf
	v_mov_b32_dpp v109, v127 row_shr:1 row_mask:0xf bank_mask:0xf
	v_pk_fma_f32 v[84:85], v[162:163], v[84:85], v[150:151]
	v_pk_mul_f32 v[92:93], v[104:105], v[92:93]
	v_pk_fma_f32 v[84:85], v[154:155], v[108:109], v[84:85]
	v_mov_b32_dpp v86, v86 row_ror:2 row_mask:0xf bank_mask:0xf bound_ctrl:1
	v_mov_b32_dpp v111, v87 row_ror:1 row_mask:0xf bank_mask:0xf bound_ctrl:1
	v_mov_b32_dpp v87, v87 row_ror:2 row_mask:0xf bank_mask:0xf bound_ctrl:1
	v_pk_mul_f32 v[92:93], v[92:93], v[96:97]
	v_add_f32_e32 v96, 1.0, v98
	v_add_f32_e32 v97, 1.0, v99
	v_pk_fma_f32 v[84:85], v[126:127], v[158:159], v[84:85]
	v_mov_b32_dpp v86, v128 row_shr:2 row_mask:0xf bank_mask:0xf
	v_mov_b32_dpp v87, v129 row_shr:2 row_mask:0xf bank_mask:0xf
	v_rcp_f32_e32 v96, v96
	v_rcp_f32_e32 v97, v97
	v_exp_f32_e32 v98, v84
	v_exp_f32_e32 v99, v85
	v_mov_b32_dpp v110, v128 row_shr:1 row_mask:0xf bank_mask:0xf
	v_mov_b32_dpp v111, v129 row_shr:1 row_mask:0xf bank_mask:0xf
	v_pk_fma_f32 v[86:87], v[142:143], v[86:87], v[144:145]
	v_pk_mul_f32 v[90:91], v[106:107], v[90:91]
	v_pk_fma_f32 v[86:87], v[146:147], v[110:111], v[86:87]
	v_pk_mul_f32 v[90:91], v[90:91], v[96:97]
	v_pk_fma_f32 v[86:87], v[128:129], v[148:149], v[86:87]
	v_add_f32_e32 v96, 1.0, v98
	v_add_f32_e32 v97, 1.0, v99
	v_exp_f32_e32 v98, v86
	v_exp_f32_e32 v99, v87
	v_rcp_f32_e32 v96, v96
	v_rcp_f32_e32 v97, v97
	v_add_f32_e32 v98, 1.0, v98
	v_add_f32_e32 v99, 1.0, v99
	v_rcp_f32_e32 v98, v98
	v_rcp_f32_e32 v99, v99
	v_pk_mul_f32 v[84:85], v[100:101], v[84:85]
	v_or_b32_e32 v100, 48, v172
	v_pk_mul_f32 v[96:97], v[84:85], v[96:97]
	v_pk_mul_f32 v[84:85], v[102:103], v[86:87]
	v_cvt_pk_bf16_f32 v86, v96, v97
	v_pk_mul_f32 v[98:99], v[84:85], v[98:99]
	v_cvt_pk_bf16_f32 v85, v90, v91
	v_mad_i64_i32 v[90:91], s[4:5], v100, s6, v[94:95]
	v_cvt_pk_bf16_f32 v84, v92, v93
	v_cvt_pk_bf16_f32 v87, v98, v99
	v_lshl_add_u64 v[90:91], v[90:91], 0, v[88:89]
	global_store_dwordx4 v[90:91], v[84:87], off sc1
	v_mov_b32_e32 v125, 0
	v_mov_b32_e32 v126, 0
	v_mov_b32_e32 v127, 0
	v_mov_b32_e32 v84, 0
	v_mov_b32_e32 v85, 0
	v_mov_b32_e32 v86, 0
	v_mov_b32_e32 v87, 0
	s_and_saveexec_b64 s[4:5], vcc
	s_mov_b32 s72, s16
	s_mov_b32 s73, s17
	s_cbranch_execz .LBB0_1533
	v_add3_u32 v84, s64, v197, v199
	v_add_u32_e32 v90, 0xfffffe50, v84
	v_add_u32_e32 v84, 0xfffffe40, v84
	ds_read_b128 v[84:87], v84
	ds_read_b128 v[124:127], v90
.LBB0_1533:
	s_or_b64 exec, exec, s[4:5]
	v_mov_b32_e32 v90, v200
	v_mov_b32_e32 v91, v200
	v_pk_mul_f32 v[34:35], v[34:35], v[90:91]
	v_pk_mul_f32 v[30:31], v[30:31], v[90:91]
	v_pk_mul_f32 v[90:91], v[24:25], v[198:199] op_sel_hi:[1,0]
	v_pk_mul_f32 v[92:93], v[22:23], v[198:199] op_sel_hi:[1,0]
	s_waitcnt lgkmcnt(1)
	v_mov_b32_dpp v22, v84 row_ror:2 row_mask:0xf bank_mask:0xf bound_ctrl:1
	v_mov_b32_dpp v23, v85 row_ror:2 row_mask:0xf bank_mask:0xf bound_ctrl:1
	v_pk_mul_f32 v[94:95], v[20:21], v[198:199] op_sel_hi:[1,0]
	v_pk_mul_f32 v[20:21], v[16:17], v[2:3] op_sel_hi:[1,0]
	v_pk_mul_f32 v[16:17], v[12:13], v[2:3] op_sel_hi:[1,0]
	v_mov_b32_dpp v12, v84 row_ror:1 row_mask:0xf bank_mask:0xf bound_ctrl:1
	v_mov_b32_dpp v22, v90 row_shr:2 row_mask:0xf bank_mask:0xf
	v_mov_b32_dpp v13, v85 row_ror:1 row_mask:0xf bank_mask:0xf bound_ctrl:1
	v_mov_b32_dpp v23, v91 row_shr:2 row_mask:0xf bank_mask:0xf
	v_mov_b32_dpp v12, v90 row_shr:1 row_mask:0xf bank_mask:0xf
	v_mov_b32_dpp v13, v91 row_shr:1 row_mask:0xf bank_mask:0xf
	v_pk_fma_f32 v[22:23], v[170:171], v[22:23], v[194:195]
	v_pk_mul_f32 v[26:27], v[26:27], v[198:199] op_sel_hi:[1,0]
	v_pk_fma_f32 v[12:13], v[190:191], v[12:13], v[22:23]
	v_mov_b32_dpp v84, v86 row_ror:2 row_mask:0xf bank_mask:0xf bound_ctrl:1
	v_pk_fma_f32 v[12:13], v[90:91], v[192:193], v[12:13]
	v_mov_b32_dpp v85, v87 row_ror:2 row_mask:0xf bank_mask:0xf bound_ctrl:1
	v_exp_f32_e32 v22, v12
	v_exp_f32_e32 v23, v13
	v_mov_b32_dpp v24, v86 row_ror:1 row_mask:0xf bank_mask:0xf bound_ctrl:1
	v_mov_b32_dpp v84, v26 row_shr:2 row_mask:0xf bank_mask:0xf
	v_mov_b32_dpp v25, v87 row_ror:1 row_mask:0xf bank_mask:0xf bound_ctrl:1
	v_mov_b32_dpp v85, v27 row_shr:2 row_mask:0xf bank_mask:0xf
	v_mov_b32_dpp v24, v26 row_shr:1 row_mask:0xf bank_mask:0xf
	v_mov_b32_dpp v25, v27 row_shr:1 row_mask:0xf bank_mask:0xf
	v_pk_fma_f32 v[84:85], v[166:167], v[84:85], v[152:153]
	v_add_f32_e32 v22, 1.0, v22
	v_pk_fma_f32 v[24:25], v[164:165], v[24:25], v[84:85]
	v_add_f32_e32 v23, 1.0, v23
	v_pk_fma_f32 v[24:25], v[26:27], v[156:157], v[24:25]
	v_rcp_f32_e32 v22, v22
	v_rcp_f32_e32 v23, v23
	v_exp_f32_e32 v84, v24
	v_exp_f32_e32 v85, v25
	v_pk_mul_f32 v[56:57], v[56:57], v[198:199] op_sel_hi:[1,0]
	s_waitcnt lgkmcnt(0)
; __device__ __forceinline__ unsigned cvt_pk_bf16(float lo, float hi) { const f32x2 v = {lo, hi}; const bf16v2_ r = __builtin_convertvector(v, bf16v2_); return __builtin_bit_cast(unsigned, r); }
;     __device__ __forceinline__ void operator()(f32x4 (&acc)[2][2][4][2], const Unit& u, int wr, int wc, int ui, int) const {
;     ...
;             for (int m = 0; m < 4; ++m) {
;                 const int row = u.pm * BM + ai * HALF + wr * 64 + m * 16 + fr;
;                 float o[8], z[8], g1[8], g2[8];
; #pragma unroll
;                 for (int k = 0; k < 8; ++k) { const int n = k >> 2, e = k & 3;
;                     const float gc = acc[ai][1][m][n][e], gp = (m == 0) ? hal[n][e] : acc[ai][1][m - 1][n][e];
;                     const int gci = __builtin_bit_cast(int, gc), gpi = __builtin_bit_cast(int, gp);
;                     const int r1 = __builtin_amdgcn_update_dpp(0, gpi, 0x121, 0xf, 0xf, true), r2 = __builtin_amdgcn_update_dpp(0, gpi, 0x122, 0xf, 0xf, true);
;                     g1[k] = __builtin_bit_cast(float, __builtin_amdgcn_update_dpp(r1, gci, 0x111, 0xf, 0xf, false));
;                     g2[k] = __builtin_bit_cast(float, __builtin_amdgcn_update_dpp(r2, gci, 0x112, 0xf, 0xf, false)); }
; #pragma unroll
;                 for (int k = 0; k < 8; ++k) z[k] = w0[k] * g2[k] + bb[k];
; #pragma unroll
;                 for (int k = 0; k < 8; ++k) z[k] += w1[k] * g1[k];
; #pragma unroll
;                 for (int k = 0; k < 8; ++k) z[k] += w2[k] * acc[ai][1][m][k >> 2][k & 3];
; #pragma unroll
;                 for (int k = 0; k < 8; ++k) o[k] = __builtin_amdgcn_exp2f(z[k]);
; #pragma unroll
;                 for (int k = 0; k < 8; ++k) o[k] += 1.f;
; #pragma unroll
;                 for (int k = 0; k < 8; ++k) o[k] = __builtin_amdgcn_rcpf(o[k]);
; #pragma unroll
;                 for (int k = 0; k < 8; ++k) z[k] *= acc[ai][0][m][k >> 2][k & 3];
; #pragma unroll
;                 for (int k = 0; k < 8; ++k) o[k] *= z[k];
;                 u32x4 w; w.x = cvt_pk_bf16(o[0], o[1]); w.y = cvt_pk_bf16(o[2], o[3]); w.z = cvt_pk_bf16(o[4], o[5]); w.w = cvt_pk_bf16(o[6], o[7]);
;                 *(u32x4*)(act + (size_t)row * FF + col) = w;
	v_mov_b32_dpp v96, v124 row_ror:2 row_mask:0xf bank_mask:0xf bound_ctrl:1
	v_mov_b32_dpp v97, v125 row_ror:2 row_mask:0xf bank_mask:0xf bound_ctrl:1
	v_pk_mul_f32 v[12:13], v[56:57], v[12:13]
	v_mov_b32_dpp v86, v124 row_ror:1 row_mask:0xf bank_mask:0xf bound_ctrl:1
	v_mov_b32_dpp v96, v94 row_shr:2 row_mask:0xf bank_mask:0xf
	v_mov_b32_dpp v87, v125 row_ror:1 row_mask:0xf bank_mask:0xf bound_ctrl:1
	v_mov_b32_dpp v97, v95 row_shr:2 row_mask:0xf bank_mask:0xf
	v_pk_mul_f32 v[12:13], v[12:13], v[22:23]
	v_add_f32_e32 v22, 1.0, v84
	v_add_f32_e32 v23, 1.0, v85
	v_mov_b32_dpp v86, v94 row_shr:1 row_mask:0xf bank_mask:0xf
	v_mov_b32_dpp v87, v95 row_shr:1 row_mask:0xf bank_mask:0xf
	v_rcp_f32_e32 v22, v22
	v_rcp_f32_e32 v23, v23
	v_pk_fma_f32 v[56:57], v[162:163], v[96:97], v[150:151]
	v_pk_mul_f32 v[58:59], v[58:59], v[198:199] op_sel_hi:[1,0]
	v_pk_fma_f32 v[56:57], v[154:155], v[86:87], v[56:57]
	v_mov_b32_dpp v100, v126 row_ror:2 row_mask:0xf bank_mask:0xf bound_ctrl:1
	v_mov_b32_dpp v101, v127 row_ror:2 row_mask:0xf bank_mask:0xf bound_ctrl:1
	v_pk_fma_f32 v[56:57], v[94:95], v[158:159], v[56:57]
	v_mov_b32_dpp v98, v126 row_ror:1 row_mask:0xf bank_mask:0xf bound_ctrl:1
	v_mov_b32_dpp v100, v92 row_shr:2 row_mask:0xf bank_mask:0xf
	v_mov_b32_dpp v99, v127 row_ror:1 row_mask:0xf bank_mask:0xf bound_ctrl:1
	v_mov_b32_dpp v101, v93 row_shr:2 row_mask:0xf bank_mask:0xf
	v_exp_f32_e32 v84, v56
	v_exp_f32_e32 v85, v57
	v_pk_mul_f32 v[24:25], v[58:59], v[24:25]
	v_mov_b32_dpp v98, v92 row_shr:1 row_mask:0xf bank_mask:0xf
	v_mov_b32_dpp v99, v93 row_shr:1 row_mask:0xf bank_mask:0xf
	v_pk_mul_f32 v[24:25], v[24:25], v[22:23]
	v_pk_fma_f32 v[22:23], v[142:143], v[100:101], v[144:145]
	v_add_f32_e32 v58, 1.0, v84
	v_pk_fma_f32 v[22:23], v[146:147], v[98:99], v[22:23]
	v_add_f32_e32 v59, 1.0, v85
	v_pk_fma_f32 v[22:23], v[92:93], v[148:149], v[22:23]
	v_rcp_f32_e32 v58, v58
	v_exp_f32_e32 v84, v22
	v_exp_f32_e32 v85, v23
	v_rcp_f32_e32 v59, v59
	v_pk_mul_f32 v[54:55], v[54:55], v[198:199] op_sel_hi:[1,0]
	v_add_f32_e32 v84, 1.0, v84
	v_add_f32_e32 v85, 1.0, v85
	v_rcp_f32_e32 v84, v84
	v_rcp_f32_e32 v85, v85
	v_pk_mul_f32 v[52:53], v[52:53], v[198:199] op_sel_hi:[1,0]
	v_pk_mul_f32 v[22:23], v[54:55], v[22:23]
	v_pk_mul_f32 v[52:53], v[52:53], v[56:57]
	v_pk_mul_f32 v[50:51], v[50:51], v[2:3] op_sel_hi:[1,0]
	v_pk_mul_f32 v[48:49], v[48:49], v[2:3] op_sel_hi:[1,0]
	v_pk_mul_f32 v[46:47], v[46:47], v[2:3] op_sel_hi:[1,0]
	v_pk_mul_f32 v[44:45], v[44:45], v[2:3] op_sel_hi:[1,0]
	v_pk_mul_f32 v[18:19], v[18:19], v[2:3] op_sel_hi:[1,0]
	v_pk_mul_f32 v[14:15], v[14:15], v[2:3] op_sel_hi:[1,0]
	v_add_u32_e32 v2, 0x80, v172
	v_pk_mul_f32 v[52:53], v[52:53], v[58:59]
	v_pk_mul_f32 v[54:55], v[22:23], v[84:85]
	v_cvt_pk_bf16_f32 v22, v12, v13
	v_mov_b64_e32 v[12:13], s[92:93]
	v_cvt_pk_bf16_f32 v23, v24, v25
	v_cvt_pk_bf16_f32 v24, v52, v53
	v_mad_i64_i32 v[52:53], s[4:5], v2, s6, v[12:13]
	v_cvt_pk_bf16_f32 v25, v54, v55
	v_lshl_add_u64 v[52:53], v[52:53], 0, v[88:89]
	global_store_dwordx4 v[52:53], v[22:25], off sc1
	v_mov_b32_dpp v56, v94 row_ror:2 row_mask:0xf bank_mask:0xf bound_ctrl:1
	v_mov_b32_dpp v52, v26 row_ror:1 row_mask:0xf bank_mask:0xf bound_ctrl:1
	v_mov_b32_dpp v24, v90 row_ror:2 row_mask:0xf bank_mask:0xf bound_ctrl:1
	v_mov_b32_dpp v25, v91 row_ror:2 row_mask:0xf bank_mask:0xf bound_ctrl:1
	v_mov_b32_dpp v22, v90 row_ror:1 row_mask:0xf bank_mask:0xf bound_ctrl:1
	v_mov_b32_dpp v24, v20 row_shr:2 row_mask:0xf bank_mask:0xf
	v_mov_b32_dpp v23, v91 row_ror:1 row_mask:0xf bank_mask:0xf bound_ctrl:1
	v_mov_b32_dpp v25, v21 row_shr:2 row_mask:0xf bank_mask:0xf
	v_mov_b32_dpp v22, v20 row_shr:1 row_mask:0xf bank_mask:0xf
	v_mov_b32_dpp v23, v21 row_shr:1 row_mask:0xf bank_mask:0xf
	v_pk_fma_f32 v[24:25], v[170:171], v[24:25], v[194:195]
	v_mov_b32_dpp v26, v26 row_ror:2 row_mask:0xf bank_mask:0xf bound_ctrl:1
	v_pk_fma_f32 v[22:23], v[190:191], v[22:23], v[24:25]
	v_mov_b32_dpp v53, v27 row_ror:1 row_mask:0xf bank_mask:0xf bound_ctrl:1
	v_pk_fma_f32 v[22:23], v[20:21], v[192:193], v[22:23]
	v_mov_b32_dpp v27, v27 row_ror:2 row_mask:0xf bank_mask:0xf bound_ctrl:1
	v_exp_f32_e32 v2, v22
	v_exp_f32_e32 v24, v23
	v_mov_b32_dpp v26, v18 row_shr:2 row_mask:0xf bank_mask:0xf
	v_mov_b32_dpp v27, v19 row_shr:2 row_mask:0xf bank_mask:0xf
	v_mov_b32_dpp v52, v18 row_shr:1 row_mask:0xf bank_mask:0xf
	v_mov_b32_dpp v53, v19 row_shr:1 row_mask:0xf bank_mask:0xf
	v_pk_fma_f32 v[26:27], v[166:167], v[26:27], v[152:153]
	v_add_f32_e32 v2, 1.0, v2
	v_pk_fma_f32 v[26:27], v[164:165], v[52:53], v[26:27]
	v_add_f32_e32 v25, 1.0, v24
	v_pk_fma_f32 v[26:27], v[18:19], v[156:157], v[26:27]
	v_rcp_f32_e32 v24, v2
	v_rcp_f32_e32 v25, v25
	v_exp_f32_e32 v2, v26
	v_exp_f32_e32 v52, v27
	v_mov_b32_dpp v57, v95 row_ror:2 row_mask:0xf bank_mask:0xf bound_ctrl:1
	v_pk_mul_f32 v[22:23], v[48:49], v[22:23]
	v_mov_b32_dpp v54, v94 row_ror:1 row_mask:0xf bank_mask:0xf bound_ctrl:1
	v_mov_b32_dpp v56, v16 row_shr:2 row_mask:0xf bank_mask:0xf
	v_mov_b32_dpp v55, v95 row_ror:1 row_mask:0xf bank_mask:0xf bound_ctrl:1
	v_mov_b32_dpp v57, v17 row_shr:2 row_mask:0xf bank_mask:0xf
	v_pk_mul_f32 v[22:23], v[22:23], v[24:25]
	v_add_f32_e32 v2, 1.0, v2
	v_add_f32_e32 v25, 1.0, v52
	v_mov_b32_dpp v54, v16 row_shr:1 row_mask:0xf bank_mask:0xf
	v_mov_b32_dpp v55, v17 row_shr:1 row_mask:0xf bank_mask:0xf
	v_rcp_f32_e32 v24, v2
	v_rcp_f32_e32 v25, v25
	v_pk_fma_f32 v[48:49], v[162:163], v[56:57], v[150:151]
	v_mov_b32_dpp v84, v92 row_ror:2 row_mask:0xf bank_mask:0xf bound_ctrl:1
	v_pk_fma_f32 v[48:49], v[154:155], v[54:55], v[48:49]
	v_mov_b32_dpp v85, v93 row_ror:2 row_mask:0xf bank_mask:0xf bound_ctrl:1
; __device__ __forceinline__ unsigned cvt_pk_bf16(float lo, float hi) { const f32x2 v = {lo, hi}; const bf16v2_ r = __builtin_convertvector(v, bf16v2_); return __builtin_bit_cast(unsigned, r); }
;     __device__ __forceinline__ void operator()(f32x4 (&acc)[2][2][4][2], const Unit& u, int wr, int wc, int ui, int) const {
;     ...
;             for (int m = 0; m < 4; ++m) {
;                 const int row = u.pm * BM + ai * HALF + wr * 64 + m * 16 + fr;
;                 float o[8], z[8], g1[8], g2[8];
; #pragma unroll
;                 for (int k = 0; k < 8; ++k) { const int n = k >> 2, e = k & 3;
;                     const float gc = acc[ai][1][m][n][e], gp = (m == 0) ? hal[n][e] : acc[ai][1][m - 1][n][e];
;                     const int gci = __builtin_bit_cast(int, gc), gpi = __builtin_bit_cast(int, gp);
;                     const int r1 = __builtin_amdgcn_update_dpp(0, gpi, 0x121, 0xf, 0xf, true), r2 = __builtin_amdgcn_update_dpp(0, gpi, 0x122, 0xf, 0xf, true);
;                     g1[k] = __builtin_bit_cast(float, __builtin_amdgcn_update_dpp(r1, gci, 0x111, 0xf, 0xf, false));
;                     g2[k] = __builtin_bit_cast(float, __builtin_amdgcn_update_dpp(r2, gci, 0x112, 0xf, 0xf, false)); }
; #pragma unroll
;                 for (int k = 0; k < 8; ++k) z[k] = w0[k] * g2[k] + bb[k];
; #pragma unroll
;                 for (int k = 0; k < 8; ++k) z[k] += w1[k] * g1[k];
; #pragma unroll
;                 for (int k = 0; k < 8; ++k) z[k] += w2[k] * acc[ai][1][m][k >> 2][k & 3];
; #pragma unroll
;                 for (int k = 0; k < 8; ++k) o[k] = __builtin_amdgcn_exp2f(z[k]);
; #pragma unroll
;                 for (int k = 0; k < 8; ++k) o[k] += 1.f;
; #pragma unroll
;                 for (int k = 0; k < 8; ++k) o[k] = __builtin_amdgcn_rcpf(o[k]);
; #pragma unroll
;                 for (int k = 0; k < 8; ++k) z[k] *= acc[ai][0][m][k >> 2][k & 3];
; #pragma unroll
;                 for (int k = 0; k < 8; ++k) o[k] *= z[k];
;                 u32x4 w; w.x = cvt_pk_bf16(o[0], o[1]); w.y = cvt_pk_bf16(o[2], o[3]); w.z = cvt_pk_bf16(o[4], o[5]); w.w = cvt_pk_bf16(o[6], o[7]);
;                 *(u32x4*)(act + (size_t)row * FF + col) = w;
	v_pk_fma_f32 v[48:49], v[16:17], v[158:159], v[48:49]
	v_mov_b32_dpp v58, v92 row_ror:1 row_mask:0xf bank_mask:0xf bound_ctrl:1
	v_mov_b32_dpp v84, v14 row_shr:2 row_mask:0xf bank_mask:0xf
	v_mov_b32_dpp v59, v93 row_ror:1 row_mask:0xf bank_mask:0xf bound_ctrl:1
	v_mov_b32_dpp v85, v15 row_shr:2 row_mask:0xf bank_mask:0xf
	v_exp_f32_e32 v52, v49
	v_pk_mul_f32 v[26:27], v[50:51], v[26:27]
	v_mov_b32_dpp v58, v14 row_shr:1 row_mask:0xf bank_mask:0xf
	v_mov_b32_dpp v59, v15 row_shr:1 row_mask:0xf bank_mask:0xf
	v_pk_mul_f32 v[24:25], v[26:27], v[24:25]
	v_pk_fma_f32 v[26:27], v[142:143], v[84:85], v[144:145]
	v_exp_f32_e32 v2, v48
	v_pk_fma_f32 v[26:27], v[146:147], v[58:59], v[26:27]
	v_add_f32_e32 v51, 1.0, v52
	v_pk_fma_f32 v[26:27], v[14:15], v[148:149], v[26:27]
	v_add_f32_e32 v2, 1.0, v2
	v_exp_f32_e32 v52, v26
	v_exp_f32_e32 v53, v27
	v_rcp_f32_e32 v50, v2
	v_rcp_f32_e32 v51, v51
	v_add_f32_e32 v2, 1.0, v52
	v_add_f32_e32 v53, 1.0, v53
	v_rcp_f32_e32 v52, v2
	v_rcp_f32_e32 v53, v53
	v_pk_mul_f32 v[26:27], v[46:47], v[26:27]
	v_pk_mul_f32 v[44:45], v[44:45], v[48:49]
	v_add_u32_e32 v2, 0x90, v172
	v_pk_mul_f32 v[26:27], v[26:27], v[52:53]
	v_pk_mul_f32 v[44:45], v[44:45], v[50:51]
	v_cvt_pk_bf16_f32 v22, v22, v23
	v_cvt_pk_bf16_f32 v23, v24, v25
	v_cvt_pk_bf16_f32 v25, v26, v27
	v_mad_i64_i32 v[26:27], s[4:5], v2, s6, v[12:13]
	v_cvt_pk_bf16_f32 v24, v44, v45
	v_lshl_add_u64 v[26:27], v[26:27], 0, v[88:89]
	v_pk_mul_f32 v[8:9], v[8:9], v[196:197] op_sel_hi:[1,0]
	global_store_dwordx4 v[26:27], v[22:25], off sc1
	v_pk_mul_f32 v[10:11], v[10:11], v[196:197] op_sel_hi:[1,0]
	v_pk_mul_f32 v[4:5], v[4:5], v[196:197] op_sel_hi:[1,0]
	v_mov_b32_dpp v22, v20 row_ror:1 row_mask:0xf bank_mask:0xf bound_ctrl:1
	v_mov_b32_dpp v20, v20 row_ror:2 row_mask:0xf bank_mask:0xf bound_ctrl:1
	v_mov_b32_dpp v23, v21 row_ror:1 row_mask:0xf bank_mask:0xf bound_ctrl:1
	v_mov_b32_dpp v21, v21 row_ror:2 row_mask:0xf bank_mask:0xf bound_ctrl:1
	v_mov_b32_dpp v20, v8 row_shr:2 row_mask:0xf bank_mask:0xf
	v_mov_b32_dpp v22, v8 row_shr:1 row_mask:0xf bank_mask:0xf
	v_mov_b32_dpp v21, v9 row_shr:2 row_mask:0xf bank_mask:0xf
	v_mov_b32_dpp v23, v9 row_shr:1 row_mask:0xf bank_mask:0xf
	v_pk_fma_f32 v[20:21], v[170:171], v[20:21], v[194:195]
	v_mov_b32_dpp v24, v18 row_ror:1 row_mask:0xf bank_mask:0xf bound_ctrl:1
	v_pk_fma_f32 v[20:21], v[190:191], v[22:23], v[20:21]
	v_mov_b32_dpp v18, v18 row_ror:2 row_mask:0xf bank_mask:0xf bound_ctrl:1
	v_pk_fma_f32 v[20:21], v[8:9], v[192:193], v[20:21]
	v_mov_b32_dpp v25, v19 row_ror:1 row_mask:0xf bank_mask:0xf bound_ctrl:1
	v_mov_b32_dpp v19, v19 row_ror:2 row_mask:0xf bank_mask:0xf bound_ctrl:1
	v_exp_f32_e32 v2, v20
	v_exp_f32_e32 v22, v21
	v_mov_b32_dpp v18, v10 row_shr:2 row_mask:0xf bank_mask:0xf
	v_mov_b32_dpp v19, v11 row_shr:2 row_mask:0xf bank_mask:0xf
	v_mov_b32_dpp v24, v10 row_shr:1 row_mask:0xf bank_mask:0xf
	v_mov_b32_dpp v25, v11 row_shr:1 row_mask:0xf bank_mask:0xf
	v_pk_fma_f32 v[18:19], v[166:167], v[18:19], v[152:153]
	v_add_f32_e32 v2, 1.0, v2
	v_pk_fma_f32 v[18:19], v[164:165], v[24:25], v[18:19]
	v_add_f32_e32 v23, 1.0, v22
	v_pk_fma_f32 v[18:19], v[10:11], v[156:157], v[18:19]
	v_mov_b32_dpp v26, v16 row_ror:1 row_mask:0xf bank_mask:0xf bound_ctrl:1
	v_mov_b32_dpp v16, v16 row_ror:2 row_mask:0xf bank_mask:0xf bound_ctrl:1
	v_mov_b32_dpp v27, v17 row_ror:1 row_mask:0xf bank_mask:0xf bound_ctrl:1
	v_mov_b32_dpp v17, v17 row_ror:2 row_mask:0xf bank_mask:0xf bound_ctrl:1
	v_rcp_f32_e32 v22, v2
	v_rcp_f32_e32 v23, v23
	v_exp_f32_e32 v2, v18
	v_exp_f32_e32 v24, v19
	v_mov_b32_dpp v16, v4 row_shr:2 row_mask:0xf bank_mask:0xf
	v_mov_b32_dpp v17, v5 row_shr:2 row_mask:0xf bank_mask:0xf
	v_pk_mul_f32 v[40:41], v[40:41], v[196:197] op_sel_hi:[1,0]
	v_mov_b32_dpp v26, v4 row_shr:1 row_mask:0xf bank_mask:0xf
	v_mov_b32_dpp v27, v5 row_shr:1 row_mask:0xf bank_mask:0xf
	v_pk_fma_f32 v[16:17], v[162:163], v[16:17], v[150:151]
	v_pk_mul_f32 v[20:21], v[40:41], v[20:21]
	v_pk_fma_f32 v[16:17], v[154:155], v[26:27], v[16:17]
	v_pk_mul_f32 v[6:7], v[6:7], v[196:197] op_sel_hi:[1,0]
	v_mov_b32_dpp v44, v14 row_ror:1 row_mask:0xf bank_mask:0xf bound_ctrl:1
	v_mov_b32_dpp v14, v14 row_ror:2 row_mask:0xf bank_mask:0xf bound_ctrl:1
	v_mov_b32_dpp v45, v15 row_ror:1 row_mask:0xf bank_mask:0xf bound_ctrl:1
	v_mov_b32_dpp v15, v15 row_ror:2 row_mask:0xf bank_mask:0xf bound_ctrl:1
	v_pk_mul_f32 v[20:21], v[20:21], v[22:23]
	v_add_f32_e32 v2, 1.0, v2
	v_add_f32_e32 v23, 1.0, v24
	v_pk_fma_f32 v[16:17], v[4:5], v[158:159], v[16:17]
	v_mov_b32_dpp v14, v6 row_shr:2 row_mask:0xf bank_mask:0xf
	v_mov_b32_dpp v15, v7 row_shr:2 row_mask:0xf bank_mask:0xf
	v_rcp_f32_e32 v22, v2
	v_rcp_f32_e32 v23, v23
	v_exp_f32_e32 v24, v17
	v_mov_b32_dpp v44, v6 row_shr:1 row_mask:0xf bank_mask:0xf
	v_mov_b32_dpp v45, v7 row_shr:1 row_mask:0xf bank_mask:0xf
	v_pk_fma_f32 v[14:15], v[142:143], v[14:15], v[144:145]
	v_pk_mul_f32 v[42:43], v[42:43], v[196:197] op_sel_hi:[1,0]
	v_pk_fma_f32 v[14:15], v[146:147], v[44:45], v[14:15]
	v_exp_f32_e32 v2, v16
	v_pk_mul_f32 v[18:19], v[42:43], v[18:19]
	v_pk_fma_f32 v[14:15], v[6:7], v[148:149], v[14:15]
	v_pk_mul_f32 v[18:19], v[18:19], v[22:23]
	v_add_f32_e32 v23, 1.0, v24
	v_exp_f32_e32 v24, v14
	v_exp_f32_e32 v25, v15
	v_add_f32_e32 v2, 1.0, v2
	v_rcp_f32_e32 v22, v2
	v_add_f32_e32 v2, 1.0, v24
	v_add_f32_e32 v25, 1.0, v25
	v_rcp_f32_e32 v23, v23
	v_rcp_f32_e32 v24, v2
	v_rcp_f32_e32 v25, v25
	v_pk_mul_f32 v[38:39], v[38:39], v[196:197] op_sel_hi:[1,0]
	v_pk_mul_f32 v[36:37], v[36:37], v[196:197] op_sel_hi:[1,0]
	v_pk_mul_f32 v[14:15], v[38:39], v[14:15]
	v_pk_mul_f32 v[16:17], v[36:37], v[16:17]
;     __device__ __forceinline__ void operator()(f32x4 (&acc)[2][2][4][2], const Unit& u, int wr, int wc, int ui, int) const {
;     ...
;             for (int m = 0; m < 4; ++m) {
;                 const int row = u.pm * BM + ai * HALF + wr * 64 + m * 16 + fr;
;                 float o[8], z[8], g1[8], g2[8];
; #pragma unroll
;                 for (int k = 0; k < 8; ++k) { const int n = k >> 2, e = k & 3;
;                     const float gc = acc[ai][1][m][n][e], gp = (m == 0) ? hal[n][e] : acc[ai][1][m - 1][n][e];
;                     const int gci = __builtin_bit_cast(int, gc), gpi = __builtin_bit_cast(int, gp);
;                     const int r1 = __builtin_amdgcn_update_dpp(0, gpi, 0x121, 0xf, 0xf, true), r2 = __builtin_amdgcn_update_dpp(0, gpi, 0x122, 0xf, 0xf, true);
;                     g1[k] = __builtin_bit_cast(float, __builtin_amdgcn_update_dpp(r1, gci, 0x111, 0xf, 0xf, false));
;                     g2[k] = __builtin_bit_cast(float, __builtin_amdgcn_update_dpp(r2, gci, 0x112, 0xf, 0xf, false)); }
; #pragma unroll
;                 for (int k = 0; k < 8; ++k) z[k] = w0[k] * g2[k] + bb[k];
; #pragma unroll
;                 for (int k = 0; k < 8; ++k) z[k] += w1[k] * g1[k];
; #pragma unroll
;                 for (int k = 0; k < 8; ++k) z[k] += w2[k] * acc[ai][1][m][k >> 2][k & 3];
; #pragma unroll
;                 for (int k = 0; k < 8; ++k) o[k] = __builtin_amdgcn_exp2f(z[k]);
; #pragma unroll
;                 for (int k = 0; k < 8; ++k) o[k] += 1.f;
; #pragma unroll
;                 for (int k = 0; k < 8; ++k) o[k] = __builtin_amdgcn_rcpf(o[k]);
; #pragma unroll
;                 for (int k = 0; k < 8; ++k) z[k] *= acc[ai][0][m][k >> 2][k & 3];
; #pragma unroll
;                 for (int k = 0; k < 8; ++k) o[k] *= z[k];
;                 u32x4 w; w.x = cvt_pk_bf16(o[0], o[1]); w.y = cvt_pk_bf16(o[2], o[3]); w.z = cvt_pk_bf16(o[4], o[5]); w.w = cvt_pk_bf16(o[6], o[7]);
;                 *(u32x4*)(act + (size_t)row * FF + col) = w;
;             }
;         }
;         if (wr == 1 && fr >= 14) { float* t = tail + ((size_t)u.pm * 2 + (fr - 14)) * FF + col; *(f32x4*)t = acc[1][1][3][0]; *(f32x4*)(t + 4) = acc[1][1][3][1]; }
;         if (wr == 0 && fr < 2) { float* hg = headg + ((size_t)u.pm * 2 + fr) * FF + col; *(f32x4*)hg = acc[0][1][0][0]; *(f32x4*)(hg + 4) = acc[0][1][0][1];
	v_add_u32_e32 v2, 0xa0, v172
	v_pk_mul_f32 v[16:17], v[16:17], v[22:23]
	v_pk_mul_f32 v[22:23], v[14:15], v[24:25]
	v_cvt_pk_bf16_f32 v15, v18, v19
	v_mad_i64_i32 v[18:19], s[4:5], v2, s6, v[12:13]
	v_cvt_pk_bf16_f32 v14, v20, v21
	v_cvt_pk_bf16_f32 v16, v16, v17
	v_cvt_pk_bf16_f32 v17, v22, v23
	v_lshl_add_u64 v[18:19], v[18:19], 0, v[88:89]
	global_store_dwordx4 v[18:19], v[14:17], off sc1
	v_mov_b32_e32 v201, v200
	v_mov_b32_dpp v18, v4 row_ror:1 row_mask:0xf bank_mask:0xf bound_ctrl:1
	v_mov_b32_dpp v14, v8 row_ror:1 row_mask:0xf bank_mask:0xf bound_ctrl:1
	v_mov_b32_dpp v8, v8 row_ror:2 row_mask:0xf bank_mask:0xf bound_ctrl:1
	v_mov_b32_dpp v15, v9 row_ror:1 row_mask:0xf bank_mask:0xf bound_ctrl:1
	v_mov_b32_dpp v9, v9 row_ror:2 row_mask:0xf bank_mask:0xf bound_ctrl:1
	v_mov_b32_dpp v8, v60 row_shr:2 row_mask:0xf bank_mask:0xf
	v_mov_b32_dpp v14, v60 row_shr:1 row_mask:0xf bank_mask:0xf
	v_mov_b32_dpp v9, v61 row_shr:2 row_mask:0xf bank_mask:0xf
	v_mov_b32_dpp v15, v61 row_shr:1 row_mask:0xf bank_mask:0xf
	v_pk_fma_f32 v[8:9], v[170:171], v[8:9], v[194:195]
	v_mov_b32_dpp v16, v10 row_ror:1 row_mask:0xf bank_mask:0xf bound_ctrl:1
	v_pk_fma_f32 v[8:9], v[190:191], v[14:15], v[8:9]
	v_mov_b32_dpp v10, v10 row_ror:2 row_mask:0xf bank_mask:0xf bound_ctrl:1
	v_pk_fma_f32 v[8:9], v[60:61], v[192:193], v[8:9]
	v_mov_b32_dpp v17, v11 row_ror:1 row_mask:0xf bank_mask:0xf bound_ctrl:1
	v_mov_b32_dpp v11, v11 row_ror:2 row_mask:0xf bank_mask:0xf bound_ctrl:1
	v_exp_f32_e32 v2, v8
	v_exp_f32_e32 v14, v9
	v_mov_b32_dpp v10, v62 row_shr:2 row_mask:0xf bank_mask:0xf
	v_mov_b32_dpp v11, v63 row_shr:2 row_mask:0xf bank_mask:0xf
	v_mov_b32_dpp v16, v62 row_shr:1 row_mask:0xf bank_mask:0xf
	v_mov_b32_dpp v17, v63 row_shr:1 row_mask:0xf bank_mask:0xf
	v_pk_fma_f32 v[10:11], v[166:167], v[10:11], v[152:153]
	v_add_f32_e32 v2, 1.0, v2
	v_pk_fma_f32 v[10:11], v[164:165], v[16:17], v[10:11]
	v_add_f32_e32 v15, 1.0, v14
	v_pk_fma_f32 v[10:11], v[62:63], v[156:157], v[10:11]
	v_mov_b32_dpp v4, v4 row_ror:2 row_mask:0xf bank_mask:0xf bound_ctrl:1
	v_mov_b32_dpp v19, v5 row_ror:1 row_mask:0xf bank_mask:0xf bound_ctrl:1
	v_mov_b32_dpp v5, v5 row_ror:2 row_mask:0xf bank_mask:0xf bound_ctrl:1
	v_rcp_f32_e32 v14, v2
	v_rcp_f32_e32 v15, v15
	v_exp_f32_e32 v2, v10
	v_exp_f32_e32 v16, v11
	v_mov_b32_dpp v4, v64 row_shr:2 row_mask:0xf bank_mask:0xf
	v_mov_b32_dpp v5, v65 row_shr:2 row_mask:0xf bank_mask:0xf
	v_pk_mul_f32 v[32:33], v[32:33], v[200:201]
	v_mov_b32_dpp v18, v64 row_shr:1 row_mask:0xf bank_mask:0xf
	v_mov_b32_dpp v19, v65 row_shr:1 row_mask:0xf bank_mask:0xf
	v_pk_fma_f32 v[4:5], v[162:163], v[4:5], v[150:151]
	v_pk_mul_f32 v[8:9], v[32:33], v[8:9]
	v_pk_fma_f32 v[4:5], v[154:155], v[18:19], v[4:5]
	v_mov_b32_dpp v20, v6 row_ror:1 row_mask:0xf bank_mask:0xf bound_ctrl:1
	v_mov_b32_dpp v6, v6 row_ror:2 row_mask:0xf bank_mask:0xf bound_ctrl:1
	v_mov_b32_dpp v21, v7 row_ror:1 row_mask:0xf bank_mask:0xf bound_ctrl:1
	v_mov_b32_dpp v7, v7 row_ror:2 row_mask:0xf bank_mask:0xf bound_ctrl:1
	v_pk_mul_f32 v[8:9], v[8:9], v[14:15]
	v_add_f32_e32 v2, 1.0, v2
	v_add_f32_e32 v15, 1.0, v16
	v_pk_fma_f32 v[4:5], v[64:65], v[158:159], v[4:5]
	v_mov_b32_dpp v6, v66 row_shr:2 row_mask:0xf bank_mask:0xf
	v_mov_b32_dpp v7, v67 row_shr:2 row_mask:0xf bank_mask:0xf
	v_rcp_f32_e32 v14, v2
	v_rcp_f32_e32 v15, v15
	v_exp_f32_e32 v16, v5
	v_mov_b32_dpp v20, v66 row_shr:1 row_mask:0xf bank_mask:0xf
	v_mov_b32_dpp v21, v67 row_shr:1 row_mask:0xf bank_mask:0xf
	v_pk_fma_f32 v[6:7], v[142:143], v[6:7], v[144:145]
	v_exp_f32_e32 v2, v4
	v_pk_fma_f32 v[6:7], v[146:147], v[20:21], v[6:7]
	v_pk_mul_f32 v[10:11], v[34:35], v[10:11]
	v_pk_fma_f32 v[6:7], v[66:67], v[148:149], v[6:7]
	v_pk_mul_f32 v[10:11], v[10:11], v[14:15]
	v_add_f32_e32 v15, 1.0, v16
	v_exp_f32_e32 v16, v6
	v_exp_f32_e32 v17, v7
	v_add_f32_e32 v2, 1.0, v2
	v_rcp_f32_e32 v14, v2
	v_rcp_f32_e32 v15, v15
	v_add_f32_e32 v2, 1.0, v16
	v_add_f32_e32 v17, 1.0, v17
	v_rcp_f32_e32 v16, v2
	v_rcp_f32_e32 v17, v17
	v_pk_mul_f32 v[28:29], v[28:29], v[200:201]
	v_add_u32_e32 v2, 0xb0, v172
	v_pk_mul_f32 v[4:5], v[28:29], v[4:5]
	s_nop 0
	v_pk_mul_f32 v[14:15], v[4:5], v[14:15]
	v_pk_mul_f32 v[4:5], v[30:31], v[6:7]
	v_cvt_pk_bf16_f32 v6, v14, v15
	v_pk_mul_f32 v[16:17], v[4:5], v[16:17]
	v_cvt_pk_bf16_f32 v4, v8, v9
	v_mad_i64_i32 v[8:9], s[4:5], v2, s6, v[12:13]
	v_cvt_pk_bf16_f32 v5, v10, v11
	v_cvt_pk_bf16_f32 v7, v16, v17
	v_lshl_add_u64 v[8:9], v[8:9], 0, v[88:89]
	s_and_b64 s[6:7], s[0:1], vcc
	global_store_dwordx4 v[8:9], v[4:7], off sc1
	s_and_saveexec_b64 s[4:5], s[6:7]
	s_cbranch_execz .LBB0_1535
	v_readlane_b32 s6, v253, 51
	s_ashr_i32 s53, s52, 31
	v_add_u32_e32 v2, -14, v210
	v_readlane_b32 s7, v253, 52
	v_lshl_add_u64 v[4:5], s[52:53], 1, v[2:3]
	s_movk_i32 s14, 0x5800
	v_mov_b64_e32 v[6:7], s[6:7]
	v_mad_u64_u32 v[6:7], s[6:7], v4, s14, v[6:7]
	v_mad_i32_i24 v7, v5, s14, v7
	v_lshl_add_u64 v[4:5], v[188:189], 2, v[6:7]
	global_store_dwordx4 v[4:5], v[60:63], off sc1
	global_store_dwordx4 v[4:5], v[64:67], off offset:16 sc1
.LBB0_1535:
	s_or_b64 exec, exec, s[4:5]
	v_cmp_gt_u32_e32 vcc, 2, v210
	s_and_b64 s[6:7], s[46:47], vcc
	s_and_saveexec_b64 s[4:5], s[6:7]
	s_cbranch_execz .LBB0_1520
	v_readlane_b32 s6, v253, 53
	v_readlane_b32 s7, v253, 54
	v_lshl_or_b32 v2, s52, 1, v210
	s_movk_i32 s15, 0x5800
	v_mov_b64_e32 v[4:5], s[6:7]
	s_ashr_i32 s14, s52, 31
	v_mad_u64_u32 v[4:5], s[6:7], v2, s15, v[4:5]
	v_mov_b32_e32 v6, 0x5800
	v_mad_i32_i24 v5, s14, v6, v5
	v_readlane_b32 s6, v253, 55
	v_lshl_add_u64 v[4:5], v[4:5], 0, v[186:187]
	v_readlane_b32 s7, v253, 56
	global_store_dwordx4 v[4:5], v[76:79], off sc1
	global_store_dwordx4 v[4:5], v[80:83], off offset:16 sc1
	v_mov_b64_e32 v[4:5], s[6:7]
	v_mad_u64_u32 v[4:5], s[6:7], v2, s15, v[4:5]
	v_mad_i32_i24 v5, s14, v6, v5
	v_lshl_add_u64 v[4:5], v[4:5], 0, v[186:187]
	global_store_dwordx4 v[4:5], v[68:71], off sc1
	global_store_dwordx4 v[4:5], v[72:75], off offset:16 sc1
	s_branch .LBB0_1520

; #define PG8_STAGE(bufoff, gbase, voff) do { _Pragma("unroll") for (int _i = 0; _i < 2; ++_i) \
;         __builtin_amdgcn_global_load_lds((const unsigned*)((const char*)(gbase) + (voff)[_i]), (LAS unsigned*)(lds + (bufoff) + ldsw + _i * 8192), 16, 0, 0); } while (0)
; #define PG8_LDA(dst, b, h) do { _Pragma("unroll") for (int m = 0; m < 4; ++m) _Pragma("unroll") for (int k = 0; k < 2; ++k) dst[m][k] = *(const LAS bf16x8*)(lds + PG8_SA(b, h) + aoff + m * 2048 + k * 1024); } while (0)
; #define PG8_LDB(dst, b, h) do { _Pragma("unroll") for (int n = 0; n < 2; ++n) _Pragma("unroll") for (int k = 0; k < 2; ++k) dst[n][k] = *(const LAS bf16x8*)(lds + PG8_SB(b, h) + boff + n * 2048 + k * 1024); } while (0)
; #define PG8_WAIT_V(n) asm volatile("s_waitcnt vmcnt(" #n ")" ::: "memory")
; #define PG8_WAIT_L(n) asm volatile("s_waitcnt lgkmcnt(" #n ")" ::: "memory")
; #define PG8_BAR __builtin_amdgcn_s_barrier()
; #define PG8_SCHED __builtin_amdgcn_sched_barrier(0)
; template <class Epi, class Sched>
; __device__ __forceinline__ void gemm_phase(LAS unsigned char* lds, const Gemm g, const Sched& S, const Epi& E) {
;     ...
;             PG8_LDB(B0, 0, 0); PG8_SCHED; PG8_LDA(At, 0, 0); PG8_STAGE(PG8_SA(1, 1), a1 + hstepA, voffA);
;             PG8_WAIT_L(8); PG8_BAR; PG8_WAIT_L(0); PG8_MMA(0, 0, At, B0); PG8_BAR; PG8_SCHED;
;             PG8_LDB(B1, 0, 1); PG8_STAGE(PG8_SB(0, 0), b2, voffB);
;             PG8_BAR; PG8_WAIT_L(0); PG8_MMA(0, 1, At, B1); PG8_BAR;
;             PG8_LDA(At, 0, 1); PG8_STAGE(PG8_SA(0, 0), a2, voffA);
;             PG8_BAR; PG8_WAIT_L(0); PG8_MMA(1, 0, At, B0); PG8_BAR; PG8_SCHED;
;             PG8_STAGE(PG8_SB(0, 1), b2 + hstepB, voffB);
;             PG8_WAIT_V(6); PG8_BAR; PG8_MMA(1, 1, At, B1); PG8_BAR;
;             PG8_LDB(B0, 1, 0); PG8_SCHED; PG8_LDA(At, 1, 0); PG8_STAGE(PG8_SA(0, 1), a2 + hstepA, voffA);
;             PG8_WAIT_L(8); PG8_BAR; PG8_WAIT_L(0); PG8_MMA(0, 0, At, B0); PG8_BAR; PG8_SCHED;
;             PG8_LDB(B1, 1, 1); PG8_STAGE(PG8_SB(1, 0), b3, voffB);
;             PG8_BAR; PG8_WAIT_L(0); PG8_MMA(0, 1, At, B1); PG8_BAR;
;             PG8_LDA(At, 1, 1); PG8_STAGE(PG8_SA(1, 0), a3, voffA);
;             PG8_BAR; PG8_WAIT_L(0); PG8_MMA(1, 0, At, B0); PG8_BAR; PG8_SCHED;
;             PG8_STAGE(PG8_SB(1, 1), b3 + hstepB, voffB);
;             PG8_WAIT_V(6); PG8_BAR; PG8_MMA(1, 1, At, B1); PG8_BAR;
.LBB0_1666:
	s_setprio 0
	s_add_u32 s14, s6, 0x100
	s_addc_u32 s15, s7, 0
	s_add_i32 s45, 0, 0x10000
	v_add_u32_e32 v144, s45, v1
	ds_read_b128 v[132:135], v144
	ds_read_b128 v[136:139], v144 offset:1024
	ds_read_b128 v[140:143], v144 offset:2048
	ds_read_b128 v[144:147], v144 offset:3072
	s_cmpk_eq_i32 s44, 0x54
	s_cselect_b32 s21, s1, s15
	s_cselect_b32 s20, s0, s14
	s_cselect_b32 s19, s5, s43
	s_cselect_b32 s18, s4, s42
	ds_read_b128 v[148:151], v224
	ds_read_b128 v[152:155], v224 offset:1024
	ds_read_b128 v[156:159], v224 offset:2048
	ds_read_b128 v[160:163], v224 offset:3072
	ds_read_b128 v[164:167], v224 offset:4096
	ds_read_b128 v[168:171], v224 offset:5120
	ds_read_b128 v[172:175], v224 offset:6144
	ds_read_b128 v[176:179], v224 offset:7168
	s_add_i32 s51, 0, 0x14000
	v_add_u32_e32 v202, s51, v1
	ds_read_b128 v[180:183], v202
	ds_read_b128 v[184:187], v202 offset:1024
	ds_read_b128 v[188:191], v202 offset:2048
	ds_read_b128 v[202:205], v202 offset:3072
	s_add_i32 m0, s29, 0xc000
	s_nop 0
	global_load_lds_dwordx4 v198, s[6:7]
	s_add_i32 m0, s29, 0xe000
	s_nop 0
	global_load_lds_dwordx4 v200, s[6:7]
	s_waitcnt lgkmcnt(0)
	s_setprio 1
	s_barrier
	v_mfma_f32_16x16x32_bf16 v[128:131], v[132:135], v[148:151], v[128:131]
	v_mfma_f32_16x16x32_bf16 v[124:127], v[140:143], v[148:151], v[124:127]
	v_mfma_f32_16x16x32_bf16 v[112:115], v[132:135], v[156:159], v[112:115]
	v_mfma_f32_16x16x32_bf16 v[108:111], v[140:143], v[156:159], v[108:111]
	v_mfma_f32_16x16x32_bf16 v[100:103], v[132:135], v[164:167], v[100:103]
	v_mfma_f32_16x16x32_bf16 v[92:95], v[140:143], v[164:167], v[92:95]
	v_mfma_f32_16x16x32_bf16 v[84:87], v[132:135], v[172:175], v[84:87]
	v_mfma_f32_16x16x32_bf16 v[76:79], v[140:143], v[172:175], v[76:79]
	v_mfma_f32_16x16x32_bf16 v[128:131], v[136:139], v[152:155], v[128:131]
	v_mfma_f32_16x16x32_bf16 v[124:127], v[144:147], v[152:155], v[124:127]
	v_mfma_f32_16x16x32_bf16 v[112:115], v[136:139], v[160:163], v[112:115]
	v_mfma_f32_16x16x32_bf16 v[108:111], v[144:147], v[160:163], v[108:111]
	v_mfma_f32_16x16x32_bf16 v[100:103], v[136:139], v[168:171], v[100:103]
	v_mfma_f32_16x16x32_bf16 v[92:95], v[144:147], v[168:171], v[92:95]
	v_mfma_f32_16x16x32_bf16 v[84:87], v[136:139], v[176:179], v[84:87]
	v_mfma_f32_16x16x32_bf16 v[76:79], v[144:147], v[176:179], v[76:79]
	v_mfma_f32_16x16x32_bf16 v[120:123], v[180:183], v[148:151], v[120:123]
	v_mfma_f32_16x16x32_bf16 v[116:119], v[188:191], v[148:151], v[116:119]
	v_mfma_f32_16x16x32_bf16 v[104:107], v[180:183], v[156:159], v[104:107]
	v_mfma_f32_16x16x32_bf16 v[96:99], v[188:191], v[156:159], v[96:99]
	v_mfma_f32_16x16x32_bf16 v[88:91], v[180:183], v[164:167], v[88:91]
	v_mfma_f32_16x16x32_bf16 v[80:83], v[188:191], v[164:167], v[80:83]
	v_mfma_f32_16x16x32_bf16 v[72:75], v[180:183], v[172:175], v[72:75]
	v_mfma_f32_16x16x32_bf16 v[68:71], v[188:191], v[172:175], v[68:71]
	v_mfma_f32_16x16x32_bf16 v[120:123], v[184:187], v[152:155], v[120:123]
	v_mfma_f32_16x16x32_bf16 v[116:119], v[202:205], v[152:155], v[116:119]
	v_mfma_f32_16x16x32_bf16 v[104:107], v[184:187], v[160:163], v[104:107]
	v_mfma_f32_16x16x32_bf16 v[96:99], v[202:205], v[160:163], v[96:99]
	v_mfma_f32_16x16x32_bf16 v[88:91], v[184:187], v[168:171], v[88:91]
	v_mfma_f32_16x16x32_bf16 v[80:83], v[202:205], v[168:171], v[80:83]
	v_mfma_f32_16x16x32_bf16 v[72:75], v[184:187], v[176:179], v[72:75]
	v_mfma_f32_16x16x32_bf16 v[68:71], v[202:205], v[176:179], v[68:71]
	s_barrier
	s_setprio 0
	ds_read_b128 v[148:151], v224 offset:16384
	ds_read_b128 v[152:155], v224 offset:17408
	ds_read_b128 v[156:159], v224 offset:18432
	ds_read_b128 v[160:163], v224 offset:19456
	ds_read_b128 v[164:167], v224 offset:20480
	ds_read_b128 v[168:171], v224 offset:21504
	ds_read_b128 v[172:175], v224 offset:22528
	ds_read_b128 v[176:179], v224 offset:23552
	s_add_i32 s6, s45, s28
	v_lshl_add_u64 v[206:207], s[18:19], 0, v[2:3]
	s_mov_b32 m0, s6
	s_nop 0
	global_load_lds_dwordx4 v[206:207], off
	v_lshl_add_u64 v[208:209], s[18:19], 0, v[192:193]
	s_add_i32 m0, s6, 0x2000
	s_nop 0
	global_load_lds_dwordx4 v[208:209], off
	s_mov_b32 m0, s29
	v_lshl_add_u64 v[210:211], s[20:21], 0, v[196:197]
	global_load_lds_dwordx4 v[210:211], off
	v_lshl_add_u64 v[212:213], s[20:21], 0, v[194:195]
	s_mov_b32 m0, s30
	s_nop 0
	global_load_lds_dwordx4 v[212:213], off
	s_add_u32 s6, s18, 0x160000
	s_addc_u32 s7, s19, 0
	s_add_i32 s45, s51, s28
	s_mov_b32 m0, s45
	s_nop 0
	global_load_lds_dwordx4 v2, s[6:7]
	s_add_i32 m0, s45, 0x2000
	s_nop 0
	global_load_lds_dwordx4 v192, s[6:7]
	s_waitcnt lgkmcnt(0)
	s_waitcnt vmcnt(6)
	s_setprio 1
	s_barrier
; #define PG8_STAGE(bufoff, gbase, voff) do { _Pragma("unroll") for (int _i = 0; _i < 2; ++_i) \
;         __builtin_amdgcn_global_load_lds((const unsigned*)((const char*)(gbase) + (voff)[_i]), (LAS unsigned*)(lds + (bufoff) + ldsw + _i * 8192), 16, 0, 0); } while (0)
; #define PG8_LDA(dst, b, h) do { _Pragma("unroll") for (int m = 0; m < 4; ++m) _Pragma("unroll") for (int k = 0; k < 2; ++k) dst[m][k] = *(const LAS bf16x8*)(lds + PG8_SA(b, h) + aoff + m * 2048 + k * 1024); } while (0)
; #define PG8_LDB(dst, b, h) do { _Pragma("unroll") for (int n = 0; n < 2; ++n) _Pragma("unroll") for (int k = 0; k < 2; ++k) dst[n][k] = *(const LAS bf16x8*)(lds + PG8_SB(b, h) + boff + n * 2048 + k * 1024); } while (0)
; #define PG8_MMA(ai, bj, At, Bt) do { __builtin_amdgcn_s_setprio(1); _Pragma("unroll") for (int m = 0; m < 4; ++m) _Pragma("unroll") for (int n = 0; n < 2; ++n) _Pragma("unroll") for (int k = 0; k < 2; ++k) \
;         acc[ai][bj][m][n] = __builtin_amdgcn_mfma_f32_16x16x32_bf16(Bt[n][k], At[m][k], acc[ai][bj][m][n], 0, 0, 0); __builtin_amdgcn_s_setprio(0); } while (0)
; #define PG8_WAIT_V(n) asm volatile("s_waitcnt vmcnt(" #n ")" ::: "memory")
; #define PG8_WAIT_L(n) asm volatile("s_waitcnt lgkmcnt(" #n ")" ::: "memory")
; #define PG8_BAR __builtin_amdgcn_s_barrier()
; #define PG8_SCHED __builtin_amdgcn_sched_barrier(0)
; template <class Epi, class Sched>
; __device__ __forceinline__ void gemm_phase(LAS unsigned char* lds, const Gemm g, const Sched& S, const Epi& E) {
;     ...
;             PG8_BAR; PG8_WAIT_L(0); PG8_MMA(1, 0, At, B0); PG8_BAR; PG8_SCHED;
;             PG8_STAGE(PG8_SB(0, 1), b2 + hstepB, voffB);
;             PG8_WAIT_V(6); PG8_BAR; PG8_MMA(1, 1, At, B1); PG8_BAR;
;             PG8_LDB(B0, 1, 0); PG8_SCHED; PG8_LDA(At, 1, 0); PG8_STAGE(PG8_SA(0, 1), a2 + hstepA, voffA);
;             PG8_WAIT_L(8); PG8_BAR; PG8_WAIT_L(0); PG8_MMA(0, 0, At, B0); PG8_BAR; PG8_SCHED;
;             PG8_LDB(B1, 1, 1); PG8_STAGE(PG8_SB(1, 0), b3, voffB);
;             PG8_BAR; PG8_WAIT_L(0); PG8_MMA(0, 1, At, B1); PG8_BAR;
;             PG8_LDA(At, 1, 1); PG8_STAGE(PG8_SA(1, 0), a3, voffA);
;             PG8_BAR; PG8_WAIT_L(0); PG8_MMA(1, 0, At, B0); PG8_BAR; PG8_SCHED;
	v_mfma_f32_16x16x32_bf16 v[64:67], v[132:135], v[148:151], v[64:67]
	v_mfma_f32_16x16x32_bf16 v[60:63], v[140:143], v[148:151], v[60:63]
	v_mfma_f32_16x16x32_bf16 v[52:55], v[132:135], v[156:159], v[52:55]
	v_mfma_f32_16x16x32_bf16 v[44:47], v[140:143], v[156:159], v[44:47]
	v_mfma_f32_16x16x32_bf16 v[36:39], v[132:135], v[164:167], v[36:39]
	v_mfma_f32_16x16x32_bf16 v[28:31], v[140:143], v[164:167], v[28:31]
	v_mfma_f32_16x16x32_bf16 v[20:23], v[132:135], v[172:175], v[20:23]
	v_mfma_f32_16x16x32_bf16 v[12:15], v[140:143], v[172:175], v[12:15]
	v_mfma_f32_16x16x32_bf16 v[64:67], v[136:139], v[152:155], v[64:67]
	v_mfma_f32_16x16x32_bf16 v[60:63], v[144:147], v[152:155], v[60:63]
	v_mfma_f32_16x16x32_bf16 v[52:55], v[136:139], v[160:163], v[52:55]
	v_mfma_f32_16x16x32_bf16 v[44:47], v[144:147], v[160:163], v[44:47]
	v_mfma_f32_16x16x32_bf16 v[36:39], v[136:139], v[168:171], v[36:39]
	v_mfma_f32_16x16x32_bf16 v[28:31], v[144:147], v[168:171], v[28:31]
	v_mfma_f32_16x16x32_bf16 v[20:23], v[136:139], v[176:179], v[20:23]
	v_mfma_f32_16x16x32_bf16 v[12:15], v[144:147], v[176:179], v[12:15]
	v_mfma_f32_16x16x32_bf16 v[56:59], v[180:183], v[148:151], v[56:59]
	v_mfma_f32_16x16x32_bf16 v[48:51], v[188:191], v[148:151], v[48:51]
	v_mfma_f32_16x16x32_bf16 v[40:43], v[180:183], v[156:159], v[40:43]
	v_mfma_f32_16x16x32_bf16 v[32:35], v[188:191], v[156:159], v[32:35]
	v_mfma_f32_16x16x32_bf16 v[24:27], v[180:183], v[164:167], v[24:27]
	v_mfma_f32_16x16x32_bf16 v[16:19], v[188:191], v[164:167], v[16:19]
	v_mfma_f32_16x16x32_bf16 v[8:11], v[180:183], v[172:175], v[8:11]
	v_mfma_f32_16x16x32_bf16 v[4:7], v[188:191], v[172:175], v[4:7]
	v_mfma_f32_16x16x32_bf16 v[56:59], v[184:187], v[152:155], v[56:59]
	v_mfma_f32_16x16x32_bf16 v[48:51], v[202:205], v[152:155], v[48:51]
	v_mfma_f32_16x16x32_bf16 v[40:43], v[184:187], v[160:163], v[40:43]
	v_mfma_f32_16x16x32_bf16 v[32:35], v[202:205], v[160:163], v[32:35]
	v_mfma_f32_16x16x32_bf16 v[24:27], v[184:187], v[168:171], v[24:27]
	v_mfma_f32_16x16x32_bf16 v[16:19], v[202:205], v[168:171], v[16:19]
	v_mfma_f32_16x16x32_bf16 v[8:11], v[184:187], v[176:179], v[8:11]
	v_mfma_f32_16x16x32_bf16 v[4:7], v[202:205], v[176:179], v[4:7]
	s_barrier
	s_setprio 0
	s_add_i32 s45, 0, 0x18000
	v_add_u32_e32 v144, s45, v1
	ds_read_b128 v[132:135], v144
	ds_read_b128 v[136:139], v144 offset:1024
	ds_read_b128 v[140:143], v144 offset:2048
	ds_read_b128 v[144:147], v144 offset:3072
	s_add_u32 s6, s20, 0x160000
	s_addc_u32 s7, s21, 0
	ds_read_b128 v[148:151], v224 offset:32768
	ds_read_b128 v[152:155], v224 offset:33792
	ds_read_b128 v[156:159], v224 offset:34816
	ds_read_b128 v[160:163], v224 offset:35840
	ds_read_b128 v[164:167], v224 offset:36864
	ds_read_b128 v[168:171], v224 offset:37888
	ds_read_b128 v[172:175], v224 offset:38912
	ds_read_b128 v[176:179], v224 offset:39936
	s_mov_b32 m0, s31
	s_nop 0
	global_load_lds_dwordx4 v196, s[6:7]
	s_mov_b32 m0, s35
	s_nop 0
	global_load_lds_dwordx4 v194, s[6:7]
	s_add_i32 s20, 0, 0x1c000
	v_add_u32_e32 v202, s20, v1
	ds_read_b128 v[180:183], v202
	ds_read_b128 v[184:187], v202 offset:1024
	ds_read_b128 v[188:191], v202 offset:2048
	ds_read_b128 v[202:205], v202 offset:3072
	s_waitcnt lgkmcnt(0)
	s_setprio 1
	s_barrier
	v_mfma_f32_16x16x32_bf16 v[128:131], v[132:135], v[148:151], v[128:131]
	v_mfma_f32_16x16x32_bf16 v[124:127], v[140:143], v[148:151], v[124:127]
	v_mfma_f32_16x16x32_bf16 v[112:115], v[132:135], v[156:159], v[112:115]
	v_mfma_f32_16x16x32_bf16 v[108:111], v[140:143], v[156:159], v[108:111]
	v_mfma_f32_16x16x32_bf16 v[100:103], v[132:135], v[164:167], v[100:103]
	v_mfma_f32_16x16x32_bf16 v[92:95], v[140:143], v[164:167], v[92:95]
	v_mfma_f32_16x16x32_bf16 v[84:87], v[132:135], v[172:175], v[84:87]
	v_mfma_f32_16x16x32_bf16 v[76:79], v[140:143], v[172:175], v[76:79]
	v_mfma_f32_16x16x32_bf16 v[128:131], v[136:139], v[152:155], v[128:131]
	v_mfma_f32_16x16x32_bf16 v[124:127], v[144:147], v[152:155], v[124:127]
	v_mfma_f32_16x16x32_bf16 v[112:115], v[136:139], v[160:163], v[112:115]
	v_mfma_f32_16x16x32_bf16 v[108:111], v[144:147], v[160:163], v[108:111]
	v_mfma_f32_16x16x32_bf16 v[100:103], v[136:139], v[168:171], v[100:103]
	v_mfma_f32_16x16x32_bf16 v[92:95], v[144:147], v[168:171], v[92:95]
	v_mfma_f32_16x16x32_bf16 v[84:87], v[136:139], v[176:179], v[84:87]
	v_mfma_f32_16x16x32_bf16 v[76:79], v[144:147], v[176:179], v[76:79]
	v_mfma_f32_16x16x32_bf16 v[120:123], v[180:183], v[148:151], v[120:123]
	v_mfma_f32_16x16x32_bf16 v[116:119], v[188:191], v[148:151], v[116:119]
	v_mfma_f32_16x16x32_bf16 v[104:107], v[180:183], v[156:159], v[104:107]
	v_mfma_f32_16x16x32_bf16 v[96:99], v[188:191], v[156:159], v[96:99]
	v_mfma_f32_16x16x32_bf16 v[88:91], v[180:183], v[164:167], v[88:91]
	v_mfma_f32_16x16x32_bf16 v[80:83], v[188:191], v[164:167], v[80:83]
	v_mfma_f32_16x16x32_bf16 v[72:75], v[180:183], v[172:175], v[72:75]
	v_mfma_f32_16x16x32_bf16 v[68:71], v[188:191], v[172:175], v[68:71]
	v_mfma_f32_16x16x32_bf16 v[120:123], v[184:187], v[152:155], v[120:123]
	v_mfma_f32_16x16x32_bf16 v[116:119], v[202:205], v[152:155], v[116:119]
	v_mfma_f32_16x16x32_bf16 v[104:107], v[184:187], v[160:163], v[104:107]
	v_mfma_f32_16x16x32_bf16 v[96:99], v[202:205], v[160:163], v[96:99]
	v_mfma_f32_16x16x32_bf16 v[88:91], v[184:187], v[168:171], v[88:91]
	v_mfma_f32_16x16x32_bf16 v[80:83], v[202:205], v[168:171], v[80:83]
	v_mfma_f32_16x16x32_bf16 v[72:75], v[184:187], v[176:179], v[72:75]
	v_mfma_f32_16x16x32_bf16 v[68:71], v[202:205], v[176:179], v[68:71]
	s_barrier
; __device__ __forceinline__ int opaque_tid() { int t = threadIdx.x; asm volatile("" : "+v"(t)); return t; }
; #define PG8_STAGE(bufoff, gbase, voff) do { _Pragma("unroll") for (int _i = 0; _i < 2; ++_i) \
;         __builtin_amdgcn_global_load_lds((const unsigned*)((const char*)(gbase) + (voff)[_i]), (LAS unsigned*)(lds + (bufoff) + ldsw + _i * 8192), 16, 0, 0); } while (0)
; #define PG8_MMA(ai, bj, At, Bt) do { __builtin_amdgcn_s_setprio(1); _Pragma("unroll") for (int m = 0; m < 4; ++m) _Pragma("unroll") for (int n = 0; n < 2; ++n) _Pragma("unroll") for (int k = 0; k < 2; ++k) \
;         acc[ai][bj][m][n] = __builtin_amdgcn_mfma_f32_16x16x32_bf16(Bt[n][k], At[m][k], acc[ai][bj][m][n], 0, 0, 0); __builtin_amdgcn_s_setprio(0); } while (0)
; #define PG8_WAIT_V(n) asm volatile("s_waitcnt vmcnt(" #n ")" ::: "memory")
; #define PG8_WAIT_L(n) asm volatile("s_waitcnt lgkmcnt(" #n ")" ::: "memory")
; #define PG8_BAR __builtin_amdgcn_s_barrier()
; #define PG8_SCHED __builtin_amdgcn_sched_barrier(0)
;     __device__ __forceinline__ void operator()(const f32x4 (&acc)[2][2][4][2], const Unit& u, int wr, int wc, int, int) const {
;         const int ol_ = opaque_tid() & 63, fr = ol_ & 15, fq = ol_ >> 4;
;         const int row0 = u.pm * BM + wr * 64 + fr, col0 = u.pn * BM + wc * 32 + 8 * fq;
;         u32x4 cin[2][4][2];
; #pragma unroll
;         for (int ai = 0; ai < 2; ++ai)
; #pragma unroll
;             for (int m = 0; m < 4; ++m)
; #pragma unroll
;                 for (int bj = 0; bj < 2; ++bj) cin[ai][m][bj] = *(const u32x4*)(C + (size_t)(row0 + ai * HALF + m * 16) * ldc + col0 + bj * HALF);
; template <class Epi, class Sched>
; __device__ __forceinline__ void gemm_phase(LAS unsigned char* lds, const Gemm g, const Sched& S, const Epi& E) {
;     ...
;             PG8_BAR; PG8_WAIT_L(0); PG8_MMA(1, 0, At, B0); PG8_BAR; PG8_SCHED;
;             PG8_STAGE(PG8_SB(1, 1), b3 + hstepB, voffB);
;             PG8_WAIT_V(6); PG8_BAR; PG8_MMA(1, 1, At, B1); PG8_BAR;
	s_setprio 0
	ds_read_b128 v[148:151], v224 offset:49152
	ds_read_b128 v[152:155], v224 offset:50176
	ds_read_b128 v[156:159], v224 offset:51200
	ds_read_b128 v[160:163], v224 offset:52224
	ds_read_b128 v[164:167], v224 offset:53248
	ds_read_b128 v[168:171], v224 offset:54272
	ds_read_b128 v[172:175], v224 offset:55296
	ds_read_b128 v[176:179], v224 offset:56320
	s_add_i32 s6, s45, s28
	v_lshl_add_u64 v[206:207], v[206:207], 0, s[8:9]
	s_mov_b32 m0, s6
	s_nop 0
	global_load_lds_dwordx4 v[206:207], off
	v_lshl_add_u64 v[206:207], v[208:209], 0, s[8:9]
	s_add_i32 m0, s6, 0x2000
	s_nop 0
	global_load_lds_dwordx4 v[206:207], off
	s_mov_b32 m0, s38
	v_lshl_add_u64 v[206:207], v[210:211], 0, s[8:9]
	global_load_lds_dwordx4 v[206:207], off
	v_lshl_add_u64 v[206:207], v[212:213], 0, s[8:9]
	s_mov_b32 m0, s39
	s_nop 0
	global_load_lds_dwordx4 v[206:207], off
	s_add_u32 s6, s18, 0x160080
	s_addc_u32 s7, s19, 0
	s_add_i32 s18, s20, s28
	s_mov_b32 m0, s18
	s_nop 0
	global_load_lds_dwordx4 v2, s[6:7]
	s_add_i32 m0, s18, 0x2000
	s_nop 0
	global_load_lds_dwordx4 v192, s[6:7]
	s_add_i32 s44, s44, 2
	s_add_u32 s42, s42, 0x100
	s_addc_u32 s43, s43, 0
	s_cmpk_gt_u32 s44, 0x55
	s_mov_b64 s[6:7], s[14:15]
	s_waitcnt lgkmcnt(0)
	s_waitcnt vmcnt(6)
	s_setprio 1
	s_barrier
	v_mfma_f32_16x16x32_bf16 v[64:67], v[132:135], v[148:151], v[64:67]
	v_mfma_f32_16x16x32_bf16 v[60:63], v[140:143], v[148:151], v[60:63]
	v_mfma_f32_16x16x32_bf16 v[52:55], v[132:135], v[156:159], v[52:55]
	v_mfma_f32_16x16x32_bf16 v[44:47], v[140:143], v[156:159], v[44:47]
	v_mfma_f32_16x16x32_bf16 v[36:39], v[132:135], v[164:167], v[36:39]
	v_mfma_f32_16x16x32_bf16 v[28:31], v[140:143], v[164:167], v[28:31]
	v_mfma_f32_16x16x32_bf16 v[20:23], v[132:135], v[172:175], v[20:23]
	v_mfma_f32_16x16x32_bf16 v[12:15], v[140:143], v[172:175], v[12:15]
	v_mfma_f32_16x16x32_bf16 v[64:67], v[136:139], v[152:155], v[64:67]
	v_mfma_f32_16x16x32_bf16 v[60:63], v[144:147], v[152:155], v[60:63]
	v_mfma_f32_16x16x32_bf16 v[52:55], v[136:139], v[160:163], v[52:55]
	v_mfma_f32_16x16x32_bf16 v[44:47], v[144:147], v[160:163], v[44:47]
	v_mfma_f32_16x16x32_bf16 v[36:39], v[136:139], v[168:171], v[36:39]
	v_mfma_f32_16x16x32_bf16 v[28:31], v[144:147], v[168:171], v[28:31]
	v_mfma_f32_16x16x32_bf16 v[20:23], v[136:139], v[176:179], v[20:23]
	v_mfma_f32_16x16x32_bf16 v[12:15], v[144:147], v[176:179], v[12:15]
	v_mfma_f32_16x16x32_bf16 v[56:59], v[180:183], v[148:151], v[56:59]
	v_mfma_f32_16x16x32_bf16 v[48:51], v[188:191], v[148:151], v[48:51]
	v_mfma_f32_16x16x32_bf16 v[40:43], v[180:183], v[156:159], v[40:43]
	v_mfma_f32_16x16x32_bf16 v[32:35], v[188:191], v[156:159], v[32:35]
	v_mfma_f32_16x16x32_bf16 v[24:27], v[180:183], v[164:167], v[24:27]
	v_mfma_f32_16x16x32_bf16 v[16:19], v[188:191], v[164:167], v[16:19]
	v_mfma_f32_16x16x32_bf16 v[8:11], v[180:183], v[172:175], v[8:11]
	v_mfma_f32_16x16x32_bf16 v[4:7], v[188:191], v[172:175], v[4:7]
	v_mfma_f32_16x16x32_bf16 v[56:59], v[184:187], v[152:155], v[56:59]
	v_mfma_f32_16x16x32_bf16 v[48:51], v[202:205], v[152:155], v[48:51]
	v_mfma_f32_16x16x32_bf16 v[40:43], v[184:187], v[160:163], v[40:43]
	v_mfma_f32_16x16x32_bf16 v[32:35], v[202:205], v[160:163], v[32:35]
	v_mfma_f32_16x16x32_bf16 v[24:27], v[184:187], v[168:171], v[24:27]
	v_mfma_f32_16x16x32_bf16 v[16:19], v[202:205], v[168:171], v[16:19]
	v_mfma_f32_16x16x32_bf16 v[8:11], v[184:187], v[176:179], v[8:11]
	v_mfma_f32_16x16x32_bf16 v[4:7], v[202:205], v[176:179], v[4:7]
	s_barrier
	s_cbranch_scc0 .LBB0_1666
	s_setprio 0
	v_mov_b32_e32 v133, v0
	s_lshl_b32 s6, s50, 8
	s_add_i32 s6, s6, s36
	v_and_or_b32 v132, v133, 15, s6
	s_lshl_b32 s6, s49, 8
	v_lshrrev_b32_e32 v133, 1, v133
	v_and_or_b32 v133, v133, 24, s6
	v_or_b32_e32 v134, s37, v133
	v_ashrrev_i32_e32 v135, 31, v134
	v_lshlrev_b64 v[202:203], 1, v[134:135]
	v_ashrrev_i32_e32 v133, 31, v132
	v_lshl_add_u64 v[134:135], s[88:89], 0, v[202:203]
	v_lshlrev_b64 v[226:227], 12, v[132:133]
	v_lshl_add_u64 v[136:137], v[134:135], 0, v[226:227]
	global_load_dwordx4 v[216:219], v[136:137], off
	global_load_dwordx4 v[188:191], v[136:137], off offset:256
	v_or_b32_e32 v136, 16, v132
	v_ashrrev_i32_e32 v137, 31, v136
	v_lshlrev_b64 v[222:223], 12, v[136:137]
	v_lshl_add_u64 v[136:137], v[134:135], 0, v[222:223]
	global_load_dwordx4 v[184:187], v[136:137], off
	global_load_dwordx4 v[180:183], v[136:137], off offset:256
	v_or_b32_e32 v136, 32, v132
	v_ashrrev_i32_e32 v137, 31, v136
	v_lshlrev_b64 v[220:221], 12, v[136:137]
	v_lshl_add_u64 v[136:137], v[134:135], 0, v[220:221]
	global_load_dwordx4 v[176:179], v[136:137], off
	global_load_dwordx4 v[168:171], v[136:137], off offset:256
	v_or_b32_e32 v132, 48, v132
	v_ashrrev_i32_e32 v133, 31, v132
	v_lshlrev_b64 v[212:213], 12, v[132:133]
	v_lshl_add_u64 v[132:133], v[134:135], 0, v[212:213]
	global_load_dwordx4 v[172:175], v[132:133], off
	global_load_dwordx4 v[164:167], v[132:133], off offset:256
	s_mov_b64 s[6:7], 0x80000
	v_lshl_add_u64 v[210:211], v[226:227], 0, s[6:7]
	v_lshl_add_u64 v[132:133], v[134:135], 0, v[210:211]
	global_load_dwordx4 v[160:163], v[132:133], off
	global_load_dwordx4 v[156:159], v[132:133], off offset:256
	s_mov_b64 s[6:7], 0x90000
	v_lshl_add_u64 v[208:209], v[226:227], 0, s[6:7]
	v_lshl_add_u64 v[132:133], v[134:135], 0, v[208:209]
	global_load_dwordx4 v[152:155], v[132:133], off
	global_load_dwordx4 v[148:151], v[132:133], off offset:256
	s_mov_b64 s[6:7], 0xa0000
	v_lshl_add_u64 v[206:207], v[226:227], 0, s[6:7]
	v_lshl_add_u64 v[132:133], v[134:135], 0, v[206:207]
	global_load_dwordx4 v[144:147], v[132:133], off
	global_load_dwordx4 v[140:143], v[132:133], off offset:256
	s_mov_b64 s[6:7], 0xb0000
	v_lshl_add_u64 v[204:205], v[226:227], 0, s[6:7]
	v_lshl_add_u64 v[132:133], v[134:135], 0, v[204:205]
	global_load_dwordx4 v[136:139], v[132:133], off
	s_nop 0
	global_load_dwordx4 v[132:135], v[132:133], off offset:256
	s_and_b64 vcc, exec, s[40:41]
	s_mov_b32 s49, s47
	s_mov_b32 s50, s48
	s_mov_b64 s[14:15], s[4:5]
	s_mov_b64 s[6:7], s[0:1]
	s_waitcnt vmcnt(15)
; __device__ __forceinline__ unsigned cvt_pk_bf16(float lo, float hi) { const f32x2 v = {lo, hi}; const bf16v2_ r = __builtin_convertvector(v, bf16v2_); return __builtin_bit_cast(unsigned, r); }
; __device__ __forceinline__ float bflo(unsigned w) { return __uint_as_float(w << 16); }
; __device__ __forceinline__ float bfhi(unsigned w) { return __uint_as_float(w & 0xffff0000u); }
;     __device__ __forceinline__ void operator()(const f32x4 (&acc)[2][2][4][2], const Unit& u, int wr, int wc, int, int) const {
;     ...
; #pragma unroll
;         for (int ai = 0; ai < 2; ++ai)
; #pragma unroll
;             for (int m = 0; m < 4; ++m)
; #pragma unroll
;                 for (int bj = 0; bj < 2; ++bj) { const u32x4 c = cin[ai][m][bj]; const f32x4 v0 = acc[ai][bj][m][0], v1 = acc[ai][bj][m][1];
;                     u32x4 w; w.x = cvt_pk_bf16(bflo(c.x) + v0[0], bfhi(c.x) + v0[1]); w.y = cvt_pk_bf16(bflo(c.y) + v0[2], bfhi(c.y) + v0[3]);
;                     w.z = cvt_pk_bf16(bflo(c.z) + v1[0], bfhi(c.z) + v1[1]); w.w = cvt_pk_bf16(bflo(c.w) + v1[2], bfhi(c.w) + v1[3]);
;                     *(u32x4*)(C + (size_t)(row0 + ai * HALF + m * 16) * ldc + col0 + bj * HALF) = w; }
	v_lshlrev_b32_e32 v228, 16, v216
	v_and_b32_e32 v229, 0xffff0000, v216
	v_lshlrev_b32_e32 v216, 16, v217
	v_and_b32_e32 v217, 0xffff0000, v217
	v_pk_add_f32 v[128:129], v[128:129], v[228:229]
	v_pk_add_f32 v[130:131], v[130:131], v[216:217]
	v_cvt_pk_bf16_f32 v128, v128, v129
	v_cvt_pk_bf16_f32 v129, v130, v131
	v_lshlrev_b32_e32 v130, 16, v218
	v_and_b32_e32 v131, 0xffff0000, v218
	v_pk_add_f32 v[124:125], v[124:125], v[130:131]
	s_nop 0
	v_cvt_pk_bf16_f32 v130, v124, v125
	v_lshlrev_b32_e32 v124, 16, v219
	v_and_b32_e32 v125, 0xffff0000, v219
	v_pk_add_f32 v[124:125], v[126:127], v[124:125]
	s_waitcnt vmcnt(14)
	v_lshlrev_b32_e32 v126, 16, v188
	v_and_b32_e32 v127, 0xffff0000, v188
	v_pk_add_f32 v[120:121], v[120:121], v[126:127]
	v_lshlrev_b32_e32 v126, 16, v189
	v_and_b32_e32 v127, 0xffff0000, v189
	v_pk_add_f32 v[122:123], v[122:123], v[126:127]
	v_cvt_pk_bf16_f32 v120, v120, v121
	v_cvt_pk_bf16_f32 v121, v122, v123
	v_lshlrev_b32_e32 v122, 16, v190
	v_and_b32_e32 v123, 0xffff0000, v190
	v_pk_add_f32 v[116:117], v[116:117], v[122:123]
	v_cvt_pk_bf16_f32 v131, v124, v125
	v_cvt_pk_bf16_f32 v122, v116, v117
	v_lshlrev_b32_e32 v116, 16, v191
	v_and_b32_e32 v117, 0xffff0000, v191
	v_pk_add_f32 v[116:117], v[118:119], v[116:117]
	v_lshl_add_u64 v[124:125], s[88:89], 0, v[226:227]
	v_cvt_pk_bf16_f32 v123, v116, v117
	s_waitcnt vmcnt(13)
	v_lshlrev_b32_e32 v116, 16, v184
	v_and_b32_e32 v117, 0xffff0000, v184
	v_pk_add_f32 v[112:113], v[112:113], v[116:117]
	v_lshlrev_b32_e32 v116, 16, v185
	v_and_b32_e32 v117, 0xffff0000, v185
	v_pk_add_f32 v[114:115], v[114:115], v[116:117]
	v_cvt_pk_bf16_f32 v112, v112, v113
	v_cvt_pk_bf16_f32 v113, v114, v115
	v_lshlrev_b32_e32 v114, 16, v186
	v_and_b32_e32 v115, 0xffff0000, v186
	v_pk_add_f32 v[108:109], v[108:109], v[114:115]
	v_lshl_add_u64 v[124:125], v[124:125], 0, v[202:203]
	v_cvt_pk_bf16_f32 v114, v108, v109
	v_lshlrev_b32_e32 v108, 16, v187
	v_and_b32_e32 v109, 0xffff0000, v187
	v_pk_add_f32 v[108:109], v[110:111], v[108:109]
	s_waitcnt vmcnt(12)
	v_lshlrev_b32_e32 v110, 16, v180
	v_and_b32_e32 v111, 0xffff0000, v180
	v_pk_add_f32 v[104:105], v[104:105], v[110:111]
	v_lshlrev_b32_e32 v110, 16, v181
	v_and_b32_e32 v111, 0xffff0000, v181
	v_pk_add_f32 v[106:107], v[106:107], v[110:111]
	v_cvt_pk_bf16_f32 v104, v104, v105
	v_cvt_pk_bf16_f32 v105, v106, v107
	v_lshlrev_b32_e32 v106, 16, v182
	v_and_b32_e32 v107, 0xffff0000, v182
	v_pk_add_f32 v[96:97], v[96:97], v[106:107]
	v_cvt_pk_bf16_f32 v115, v108, v109
	v_cvt_pk_bf16_f32 v106, v96, v97
	v_lshlrev_b32_e32 v96, 16, v183
	v_and_b32_e32 v97, 0xffff0000, v183
	v_pk_add_f32 v[96:97], v[98:99], v[96:97]
	s_waitcnt vmcnt(11)
	v_lshlrev_b32_e32 v98, 16, v177
	v_cvt_pk_bf16_f32 v107, v96, v97
	v_lshlrev_b32_e32 v96, 16, v176
	v_and_b32_e32 v97, 0xffff0000, v176
	v_and_b32_e32 v99, 0xffff0000, v177
	v_pk_add_f32 v[96:97], v[100:101], v[96:97]
	v_pk_add_f32 v[98:99], v[102:103], v[98:99]
	v_cvt_pk_bf16_f32 v96, v96, v97
	v_cvt_pk_bf16_f32 v97, v98, v99
	v_lshlrev_b32_e32 v98, 16, v178
	v_and_b32_e32 v99, 0xffff0000, v178
	v_pk_add_f32 v[92:93], v[92:93], v[98:99]
	v_lshl_add_u64 v[108:109], s[88:89], 0, v[222:223]
	v_cvt_pk_bf16_f32 v98, v92, v93
	v_lshlrev_b32_e32 v92, 16, v179
	v_and_b32_e32 v93, 0xffff0000, v179
	v_pk_add_f32 v[92:93], v[94:95], v[92:93]
	s_waitcnt vmcnt(10)
	v_lshlrev_b32_e32 v94, 16, v168
	v_and_b32_e32 v95, 0xffff0000, v168
	v_pk_add_f32 v[88:89], v[88:89], v[94:95]
	v_lshlrev_b32_e32 v94, 16, v169
	v_and_b32_e32 v95, 0xffff0000, v169
	v_pk_add_f32 v[90:91], v[90:91], v[94:95]
	v_cvt_pk_bf16_f32 v88, v88, v89
	v_cvt_pk_bf16_f32 v89, v90, v91
	v_lshlrev_b32_e32 v90, 16, v170
	v_and_b32_e32 v91, 0xffff0000, v170
	v_pk_add_f32 v[80:81], v[80:81], v[90:91]
	v_cvt_pk_bf16_f32 v99, v92, v93
	v_cvt_pk_bf16_f32 v90, v80, v81
	v_lshlrev_b32_e32 v80, 16, v171
	v_and_b32_e32 v81, 0xffff0000, v171
	v_pk_add_f32 v[80:81], v[82:83], v[80:81]
	s_waitcnt vmcnt(9)
	v_lshlrev_b32_e32 v82, 16, v173
	v_cvt_pk_bf16_f32 v91, v80, v81
	v_lshlrev_b32_e32 v80, 16, v172
	v_and_b32_e32 v81, 0xffff0000, v172
	v_and_b32_e32 v83, 0xffff0000, v173
	v_pk_add_f32 v[80:81], v[84:85], v[80:81]
	v_pk_add_f32 v[82:83], v[86:87], v[82:83]
	v_cvt_pk_bf16_f32 v80, v80, v81
	v_cvt_pk_bf16_f32 v81, v82, v83
	v_lshlrev_b32_e32 v82, 16, v174
	v_and_b32_e32 v83, 0xffff0000, v174
	v_pk_add_f32 v[76:77], v[76:77], v[82:83]
	v_lshl_add_u64 v[92:93], s[88:89], 0, v[220:221]
	v_cvt_pk_bf16_f32 v82, v76, v77
	v_lshlrev_b32_e32 v76, 16, v175
	v_and_b32_e32 v77, 0xffff0000, v175
	v_pk_add_f32 v[76:77], v[78:79], v[76:77]
	s_waitcnt vmcnt(8)
	v_lshlrev_b32_e32 v78, 16, v164
	v_and_b32_e32 v79, 0xffff0000, v164
	v_pk_add_f32 v[72:73], v[72:73], v[78:79]
	v_lshlrev_b32_e32 v78, 16, v165
	v_and_b32_e32 v79, 0xffff0000, v165
	v_pk_add_f32 v[74:75], v[74:75], v[78:79]
	v_cvt_pk_bf16_f32 v72, v72, v73
	v_cvt_pk_bf16_f32 v73, v74, v75
	v_lshlrev_b32_e32 v74, 16, v166
	v_and_b32_e32 v75, 0xffff0000, v166
	v_pk_add_f32 v[68:69], v[68:69], v[74:75]
	v_cvt_pk_bf16_f32 v83, v76, v77
	v_cvt_pk_bf16_f32 v74, v68, v69
	v_lshlrev_b32_e32 v68, 16, v167
	v_and_b32_e32 v69, 0xffff0000, v167
	v_pk_add_f32 v[68:69], v[70:71], v[68:69]
	v_lshl_add_u64 v[76:77], s[88:89], 0, v[212:213]
	v_cvt_pk_bf16_f32 v75, v68, v69
	s_waitcnt vmcnt(7)
	v_lshlrev_b32_e32 v68, 16, v160
	v_and_b32_e32 v69, 0xffff0000, v160
	v_pk_add_f32 v[64:65], v[64:65], v[68:69]
	v_lshlrev_b32_e32 v68, 16, v161
	v_and_b32_e32 v69, 0xffff0000, v161
	v_pk_add_f32 v[66:67], v[66:67], v[68:69]
	v_cvt_pk_bf16_f32 v64, v64, v65
	v_cvt_pk_bf16_f32 v65, v66, v67
	v_lshlrev_b32_e32 v66, 16, v162
	v_and_b32_e32 v67, 0xffff0000, v162
	v_pk_add_f32 v[60:61], v[60:61], v[66:67]
	v_lshl_add_u64 v[108:109], v[108:109], 0, v[202:203]
	v_cvt_pk_bf16_f32 v66, v60, v61
	v_lshlrev_b32_e32 v60, 16, v163
	v_and_b32_e32 v61, 0xffff0000, v163
	v_pk_add_f32 v[60:61], v[62:63], v[60:61]
	s_waitcnt vmcnt(6)
; __device__ __forceinline__ unsigned cvt_pk_bf16(float lo, float hi) { const f32x2 v = {lo, hi}; const bf16v2_ r = __builtin_convertvector(v, bf16v2_); return __builtin_bit_cast(unsigned, r); }
; __device__ __forceinline__ float bflo(unsigned w) { return __uint_as_float(w << 16); }
; __device__ __forceinline__ float bfhi(unsigned w) { return __uint_as_float(w & 0xffff0000u); }
;     __device__ __forceinline__ void operator()(const f32x4 (&acc)[2][2][4][2], const Unit& u, int wr, int wc, int, int) const {
;     ...
; #pragma unroll
;         for (int ai = 0; ai < 2; ++ai)
; #pragma unroll
;             for (int m = 0; m < 4; ++m)
; #pragma unroll
;                 for (int bj = 0; bj < 2; ++bj) { const u32x4 c = cin[ai][m][bj]; const f32x4 v0 = acc[ai][bj][m][0], v1 = acc[ai][bj][m][1];
;                     u32x4 w; w.x = cvt_pk_bf16(bflo(c.x) + v0[0], bfhi(c.x) + v0[1]); w.y = cvt_pk_bf16(bflo(c.y) + v0[2], bfhi(c.y) + v0[3]);
;                     w.z = cvt_pk_bf16(bflo(c.z) + v1[0], bfhi(c.z) + v1[1]); w.w = cvt_pk_bf16(bflo(c.w) + v1[2], bfhi(c.w) + v1[3]);
;                     *(u32x4*)(C + (size_t)(row0 + ai * HALF + m * 16) * ldc + col0 + bj * HALF) = w; }
	v_lshlrev_b32_e32 v62, 16, v156
	v_and_b32_e32 v63, 0xffff0000, v156
	v_pk_add_f32 v[56:57], v[56:57], v[62:63]
	v_lshlrev_b32_e32 v62, 16, v157
	v_and_b32_e32 v63, 0xffff0000, v157
	v_pk_add_f32 v[58:59], v[58:59], v[62:63]
	v_cvt_pk_bf16_f32 v56, v56, v57
	v_cvt_pk_bf16_f32 v57, v58, v59
	v_lshlrev_b32_e32 v58, 16, v158
	v_and_b32_e32 v59, 0xffff0000, v158
	v_pk_add_f32 v[48:49], v[48:49], v[58:59]
	v_cvt_pk_bf16_f32 v67, v60, v61
	v_cvt_pk_bf16_f32 v58, v48, v49
	v_lshlrev_b32_e32 v48, 16, v159
	v_and_b32_e32 v49, 0xffff0000, v159
	v_pk_add_f32 v[48:49], v[50:51], v[48:49]
	s_waitcnt vmcnt(5)
	v_lshlrev_b32_e32 v50, 16, v153
	v_cvt_pk_bf16_f32 v59, v48, v49
	v_lshlrev_b32_e32 v48, 16, v152
	v_and_b32_e32 v49, 0xffff0000, v152
	v_and_b32_e32 v51, 0xffff0000, v153
	v_pk_add_f32 v[48:49], v[52:53], v[48:49]
	v_pk_add_f32 v[50:51], v[54:55], v[50:51]
	v_cvt_pk_bf16_f32 v48, v48, v49
	v_cvt_pk_bf16_f32 v49, v50, v51
	v_lshlrev_b32_e32 v50, 16, v154
	v_and_b32_e32 v51, 0xffff0000, v154
	v_pk_add_f32 v[44:45], v[44:45], v[50:51]
	v_lshl_add_u64 v[60:61], s[88:89], 0, v[210:211]
	v_cvt_pk_bf16_f32 v50, v44, v45
	v_lshlrev_b32_e32 v44, 16, v155
	v_and_b32_e32 v45, 0xffff0000, v155
	v_pk_add_f32 v[44:45], v[46:47], v[44:45]
	s_waitcnt vmcnt(4)
	v_lshlrev_b32_e32 v46, 16, v148
	v_and_b32_e32 v47, 0xffff0000, v148
	v_pk_add_f32 v[40:41], v[40:41], v[46:47]
	v_lshlrev_b32_e32 v46, 16, v149
	v_and_b32_e32 v47, 0xffff0000, v149
	v_pk_add_f32 v[42:43], v[42:43], v[46:47]
	v_cvt_pk_bf16_f32 v40, v40, v41
	v_cvt_pk_bf16_f32 v41, v42, v43
	v_lshlrev_b32_e32 v42, 16, v150
	v_and_b32_e32 v43, 0xffff0000, v150
	v_pk_add_f32 v[32:33], v[32:33], v[42:43]
	v_cvt_pk_bf16_f32 v51, v44, v45
	v_cvt_pk_bf16_f32 v42, v32, v33
	v_lshlrev_b32_e32 v32, 16, v151
	v_and_b32_e32 v33, 0xffff0000, v151
	v_pk_add_f32 v[32:33], v[34:35], v[32:33]
	s_waitcnt vmcnt(3)
	v_lshlrev_b32_e32 v34, 16, v145
	v_cvt_pk_bf16_f32 v43, v32, v33
	v_lshlrev_b32_e32 v32, 16, v144
	v_and_b32_e32 v33, 0xffff0000, v144
	v_and_b32_e32 v35, 0xffff0000, v145
	v_pk_add_f32 v[32:33], v[36:37], v[32:33]
	v_pk_add_f32 v[34:35], v[38:39], v[34:35]
	v_cvt_pk_bf16_f32 v32, v32, v33
	v_cvt_pk_bf16_f32 v33, v34, v35
	v_lshlrev_b32_e32 v34, 16, v146
	v_and_b32_e32 v35, 0xffff0000, v146
	v_pk_add_f32 v[28:29], v[28:29], v[34:35]
	v_lshl_add_u64 v[44:45], s[88:89], 0, v[208:209]
	v_cvt_pk_bf16_f32 v34, v28, v29
	v_lshlrev_b32_e32 v28, 16, v147
	v_and_b32_e32 v29, 0xffff0000, v147
	v_pk_add_f32 v[28:29], v[30:31], v[28:29]
	s_waitcnt vmcnt(2)
	v_lshlrev_b32_e32 v30, 16, v140
	v_and_b32_e32 v31, 0xffff0000, v140
	v_pk_add_f32 v[24:25], v[24:25], v[30:31]
	v_lshlrev_b32_e32 v30, 16, v141
	v_and_b32_e32 v31, 0xffff0000, v141
	v_pk_add_f32 v[26:27], v[26:27], v[30:31]
	v_cvt_pk_bf16_f32 v24, v24, v25
	v_cvt_pk_bf16_f32 v25, v26, v27
	v_lshlrev_b32_e32 v26, 16, v142
	v_and_b32_e32 v27, 0xffff0000, v142
	v_pk_add_f32 v[16:17], v[16:17], v[26:27]
	v_cvt_pk_bf16_f32 v35, v28, v29
	v_cvt_pk_bf16_f32 v26, v16, v17
	v_lshlrev_b32_e32 v16, 16, v143
	v_and_b32_e32 v17, 0xffff0000, v143
	v_pk_add_f32 v[16:17], v[18:19], v[16:17]
	s_waitcnt vmcnt(1)
	v_lshlrev_b32_e32 v18, 16, v137
	v_cvt_pk_bf16_f32 v27, v16, v17
	v_lshlrev_b32_e32 v16, 16, v136
	v_and_b32_e32 v17, 0xffff0000, v136
	v_and_b32_e32 v19, 0xffff0000, v137
	v_pk_add_f32 v[16:17], v[20:21], v[16:17]
	v_pk_add_f32 v[18:19], v[22:23], v[18:19]
	v_cvt_pk_bf16_f32 v16, v16, v17
	v_cvt_pk_bf16_f32 v17, v18, v19
	v_lshlrev_b32_e32 v18, 16, v138
	v_and_b32_e32 v19, 0xffff0000, v138
	v_pk_add_f32 v[12:13], v[12:13], v[18:19]
	v_lshl_add_u64 v[28:29], s[88:89], 0, v[206:207]
	v_cvt_pk_bf16_f32 v18, v12, v13
	v_lshlrev_b32_e32 v12, 16, v139
	v_and_b32_e32 v13, 0xffff0000, v139
	v_pk_add_f32 v[12:13], v[14:15], v[12:13]
	s_waitcnt vmcnt(0)
	v_lshlrev_b32_e32 v14, 16, v132
	v_and_b32_e32 v15, 0xffff0000, v132
	v_pk_add_f32 v[8:9], v[8:9], v[14:15]
	v_lshlrev_b32_e32 v14, 16, v133
	v_and_b32_e32 v15, 0xffff0000, v133
	v_pk_add_f32 v[10:11], v[10:11], v[14:15]
	v_cvt_pk_bf16_f32 v8, v8, v9
	v_cvt_pk_bf16_f32 v9, v10, v11
	v_lshlrev_b32_e32 v10, 16, v134
	v_and_b32_e32 v11, 0xffff0000, v134
	v_pk_add_f32 v[4:5], v[4:5], v[10:11]
	v_cvt_pk_bf16_f32 v19, v12, v13
	v_cvt_pk_bf16_f32 v10, v4, v5
	v_lshlrev_b32_e32 v4, 16, v135
	v_and_b32_e32 v5, 0xffff0000, v135
	v_lshl_add_u64 v[12:13], s[88:89], 0, v[204:205]
	v_pk_add_f32 v[4:5], v[6:7], v[4:5]
	v_lshl_add_u64 v[92:93], v[92:93], 0, v[202:203]
	v_lshl_add_u64 v[76:77], v[76:77], 0, v[202:203]
	v_lshl_add_u64 v[60:61], v[60:61], 0, v[202:203]
	v_lshl_add_u64 v[44:45], v[44:45], 0, v[202:203]
	v_lshl_add_u64 v[28:29], v[28:29], 0, v[202:203]
	v_lshl_add_u64 v[12:13], v[12:13], 0, v[202:203]
	v_cvt_pk_bf16_f32 v11, v4, v5
	global_store_dwordx4 v[124:125], v[128:131], off sc1
	global_store_dwordx4 v[124:125], v[120:123], off offset:256 sc1
	global_store_dwordx4 v[108:109], v[112:115], off sc1
	global_store_dwordx4 v[108:109], v[104:107], off offset:256 sc1
	global_store_dwordx4 v[92:93], v[96:99], off sc1
	global_store_dwordx4 v[92:93], v[88:91], off offset:256 sc1
	global_store_dwordx4 v[76:77], v[80:83], off sc1
	global_store_dwordx4 v[76:77], v[72:75], off offset:256 sc1
	global_store_dwordx4 v[60:61], v[64:67], off sc1
	global_store_dwordx4 v[60:61], v[56:59], off offset:256 sc1
	global_store_dwordx4 v[44:45], v[48:51], off sc1
	global_store_dwordx4 v[44:45], v[40:43], off offset:256 sc1
	global_store_dwordx4 v[28:29], v[32:35], off sc1
	global_store_dwordx4 v[28:29], v[24:27], off offset:256 sc1
	global_store_dwordx4 v[12:13], v[16:19], off sc1
	global_store_dwordx4 v[12:13], v[8:11], off offset:256 sc1
	s_cbranch_vccz .LBB0_1655
	s_waitcnt vmcnt(0)
	s_cmpk_gt_u32 s2, 0xff
	s_cbranch_scc1 .LBB0_1670
	s_barrier
